# dpp wave_sum; hoisted epilogue loads (attention, E3); gemm_dma read prefetch
# speedup vs baseline: 1.0783x; 1.0105x over previous
; DI int get_tid() { int t = threadIdx.x; asm volatile("" : "+v"(t)); return t; }
; DI int get_bid() { int b = blockIdx.x; asm volatile("" : "+s"(b)); return b; }
; DI float bflo(unsigned u) { return __uint_as_float(u << 16); }
; DI float bfhi(unsigned u) { return __uint_as_float(u & 0xffff0000u); }
; DI float wave_sum(float v) {
; #pragma unroll
;   for (int o = 32; o; o >>= 1) v += __shfl_xor(v, o, 64);
;   return v;
; }
; DI void resid_norm(const Params& p, int layer, const u16* __restrict__ y) {
;     ...
;   for (int r = get_bid() * 4 + (get_tid() >> 6); r < M_TOK; r += gridDim.x * 4) {
;     const float* x;
;     if (layer == 0) x = r < M_PROMPT ? p.x_prompt + (size_t)r * 1024 : p.x_sample + (size_t)(r - M_PROMPT) * 1024;
;     else x = p.out + (size_t)r * 1024;
;     float4 yv[4], xv[4]; float ss = 0.f;
; #pragma unroll
;     for (int i = 0; i < 4; ++i) {
;       { const uint2 yq = *(const uint2*)(y + (size_t)r * 1024 + lane * 4 + 256 * i); yv[i] = make_float4(bflo(yq.x), bfhi(yq.x), bflo(yq.y), bfhi(yq.y)); }
;       { const f32x4 t4 = __builtin_nontemporal_load((const f32x4*)(x + lane * 4 + 256 * i)); xv[i] = make_float4(t4[0], t4[1], t4[2], t4[3]); }
;       ss += yv[i].x * yv[i].x + yv[i].y * yv[i].y + yv[i].z * yv[i].z + yv[i].w * yv[i].w;
;     }
;     ss = wave_sum(ss);
;     const float rs = rsqrtf(ss * (1.f / 1024.f) + 1e-6f);
;     float ss2 = 0.f;
; #pragma unroll
;     for (int i = 0; i < 4; ++i) {
;       const float4 gg = *(const float4*)(gpost + lane * 4 + 256 * i);
;       xv[i].x += yv[i].x * rs * gg.x; xv[i].y += yv[i].y * rs * gg.y; xv[i].z += yv[i].z * rs * gg.z; xv[i].w += yv[i].w * rs * gg.w;
;       __builtin_nontemporal_store((f32x4){xv[i].x, xv[i].y, xv[i].z, xv[i].w}, (f32x4*)(p.out + (size_t)r * 1024 + lane * 4 + 256 * i));
;       ss2 += xv[i].x * xv[i].x + xv[i].y * xv[i].y + xv[i].z * xv[i].z + xv[i].w * xv[i].w;
;     }
.LBB0_19:
	v_ashrrev_i32_e32 v1, 31, v0
	v_lshlrev_b64 v[14:15], 11, v[0:1]
	v_lshl_add_u64 v[14:15], v[2:3], 0, v[14:15]
	global_load_dwordx2 v[22:23], v[14:15], off
	global_load_dwordx2 v[24:25], v[14:15], off offset:512
	global_load_dwordx2 v[26:27], v[14:15], off offset:1024
	global_load_dwordx2 v[28:29], v[14:15], off offset:1536
	s_nop 0
	global_load_dwordx4 v[14:17], v[4:5], off
	s_waitcnt vmcnt(12)
	v_lshlrev_b64 v[18:19], 12, v[0:1]
	s_waitcnt vmcnt(9)
	v_lshl_add_u64 v[30:31], v[6:7], 0, v[18:19]
	global_load_dwordx4 v[18:21], v[30:31], off nt
	v_add_u32_e32 v0, s3, v0
	s_waitcnt vmcnt(5)
	v_and_b32_e32 v33, 0xffff0000, v22
	v_lshlrev_b32_e32 v32, 16, v22
	s_waitcnt vmcnt(4)
	v_and_b32_e32 v39, 0xffff0000, v24
	s_waitcnt vmcnt(3)
	v_and_b32_e32 v45, 0xffff0000, v26
	v_mov_b32_e32 v38, v33
	v_lshlrev_b32_e32 v34, 16, v23
	v_and_b32_e32 v35, 0xffff0000, v23
	v_lshlrev_b32_e32 v37, 16, v24
	v_lshlrev_b32_e32 v44, 16, v26
	s_waitcnt vmcnt(2)
	v_and_b32_e32 v49, 0xffff0000, v28
	v_mov_b32_e32 v36, v32
	v_mov_b32_e32 v48, v45
	v_pk_mul_f32 v[22:23], v[38:39], v[38:39]
	v_lshlrev_b32_e32 v41, 16, v25
	v_and_b32_e32 v43, 0xffff0000, v25
	v_lshlrev_b32_e32 v26, 16, v27
	v_lshlrev_b32_e32 v47, 16, v28
	v_mov_b32_e32 v40, v34
	v_mov_b32_e32 v46, v44
	v_pk_mul_f32 v[24:25], v[48:49], v[48:49]
	v_pk_fma_f32 v[22:23], v[36:37], v[36:37], v[22:23]
	v_and_b32_e32 v27, 0xffff0000, v27
	v_lshlrev_b32_e32 v51, 16, v29
	v_mov_b32_e32 v42, v35
	v_mov_b32_e32 v50, v26
	v_pk_fma_f32 v[24:25], v[46:47], v[46:47], v[24:25]
	v_pk_fma_f32 v[22:23], v[40:41], v[40:41], v[22:23]
	v_and_b32_e32 v29, 0xffff0000, v29
	v_mov_b32_e32 v28, v27
	v_pk_fma_f32 v[24:25], v[50:51], v[50:51], v[24:25]
	v_pk_fma_f32 v[22:23], v[42:43], v[42:43], v[22:23]
	v_pk_fma_f32 v[24:25], v[28:29], v[28:29], v[24:25]
	v_add_f32_e32 v1, v22, v23
	v_add_f32_e32 v1, v1, v24
	v_add_f32_e32 v1, v1, v25
	v_mov_b32_e32 v22, v1
	s_nop 1
	v_permlane32_swap_b32_e32 v1, v22
	v_mov_b32_e32 v38, v37
	v_mov_b32_e32 v42, v41
	v_mov_b32_e32 v48, v47
	s_waitcnt lgkmcnt(0)
	v_add_f32_e32 v1, v1, v22
	v_mov_b32_e32 v22, v1
	s_nop 1
	v_permlane16_swap_b32_e32 v1, v22
	s_waitcnt lgkmcnt(0)
	v_add_f32_e32 v1, v1, v22
	s_nop 1
	v_mov_b32_dpp v22, v1 row_ror:8 row_mask:0xf bank_mask:0xf
	s_waitcnt lgkmcnt(0)
	v_add_f32_e32 v1, v1, v22
	s_nop 1
	v_mov_b32_dpp v22, v1 row_ror:4 row_mask:0xf bank_mask:0xf
	s_waitcnt lgkmcnt(0)
	v_add_f32_e32 v1, v1, v22
	s_nop 1
	v_mov_b32_dpp v22, v1 quad_perm:[2,3,0,1] row_mask:0xf bank_mask:0xf
	s_waitcnt lgkmcnt(0)
	v_add_f32_e32 v1, v1, v22
	s_nop 1
	v_mov_b32_dpp v22, v1 quad_perm:[1,0,3,2] row_mask:0xf bank_mask:0xf
	s_waitcnt lgkmcnt(0)
	v_add_f32_e32 v1, v1, v22
	v_fmamk_f32 v1, v1, 0x3a800000, v184
	v_mul_f32_e32 v22, 0x4b800000, v1
	v_cmp_gt_f32_e32 vcc, s33, v1
	s_nop 1
	v_cndmask_b32_e32 v1, v1, v22, vcc
	v_rsq_f32_e32 v1, v1
	global_load_dwordx4 v[22:25], v[30:31], off offset:1024 nt
	v_mul_f32_e32 v28, 0x45800000, v1
	v_cndmask_b32_e32 v36, v1, v28, vcc
	v_pk_mul_f32 v[32:33], v[36:37], v[32:33] op_sel_hi:[0,1]
	v_pk_mul_f32 v[34:35], v[36:37], v[34:35] op_sel_hi:[0,1]
	s_waitcnt vmcnt(1)
	v_pk_fma_f32 v[16:17], v[16:17], v[34:35], v[20:21]
	v_pk_fma_f32 v[14:15], v[14:15], v[32:33], v[18:19]
	global_store_dwordx4 v[30:31], v[14:17], off nt
	global_load_dwordx4 v[14:17], v[4:5], off offset:1024
	v_pk_mul_f32 v[18:19], v[36:37], v[42:43] op_sel_hi:[0,1]
	v_pk_mul_f32 v[20:21], v[36:37], v[38:39] op_sel_hi:[0,1]
	v_pk_mul_f32 v[32:33], v[36:37], v[44:45] op_sel_hi:[0,1]
	v_pk_mul_f32 v[26:27], v[36:37], v[26:27] op_sel_hi:[0,1]
	v_mov_b32_e32 v28, v51
	v_cmp_lt_i32_e32 vcc, s64, v0
	s_or_b64 s[40:41], vcc, s[40:41]
	s_waitcnt vmcnt(0)
	v_pk_fma_f32 v[14:15], v[14:15], v[20:21], v[22:23]
	v_pk_fma_f32 v[16:17], v[16:17], v[18:19], v[24:25]
	global_store_dwordx4 v[30:31], v[14:17], off offset:1024 nt
	global_load_dwordx4 v[14:17], v[4:5], off offset:2048
	s_nop 0
	global_load_dwordx4 v[18:21], v[30:31], off offset:2048 nt
	global_load_dwordx4 v[22:25], v[30:31], off offset:3072 nt
	s_waitcnt vmcnt(1)
	v_pk_fma_f32 v[14:15], v[14:15], v[32:33], v[18:19]
	v_pk_fma_f32 v[16:17], v[26:27], v[16:17], v[20:21]
	global_store_dwordx4 v[30:31], v[14:17], off offset:2048 nt
	global_load_dwordx4 v[14:17], v[4:5], off offset:3072
	v_pk_mul_f32 v[18:19], v[36:37], v[28:29] op_sel_hi:[0,1]
	v_pk_mul_f32 v[20:21], v[36:37], v[48:49] op_sel_hi:[0,1]
	s_waitcnt vmcnt(0)
	v_pk_fma_f32 v[14:15], v[20:21], v[14:15], v[22:23]
	v_pk_fma_f32 v[16:17], v[18:19], v[16:17], v[24:25]
	global_store_dwordx4 v[30:31], v[14:17], off offset:3072 nt
	s_andn2_b64 exec, exec, s[40:41]
	s_cbranch_execnz .LBB0_19

; template <int N> DI void wait_vm() { asm volatile("s_waitcnt vmcnt(%0)" ::"n"(N) : "memory"); }
; template <int BM, class Epi>
; DI void gemm_dma(const u16* __restrict__ X, long ldx, const u16* __restrict__ W, long ldw, int K, char* smem,
;                  int m0, int n0, const Epi& epi) {
;     ...
;   const int nk = K >> 5;
;   __syncthreads();
; #pragma unroll
;   for (int s = 0; s < D - 1; ++s) GD_ISSUE(s)
;   int cur = 0, nxt = D - 1, kt = 0;
;   do {
;     if (kt + D - 2 < nk) wait_vm<PW * (D - 2)>(); else wait_vm<0>();
;     __syncthreads();
;     if (kt + D - 1 < nk) GD_ISSUE(nxt)
;     nxt = (nxt + 1 == D) ? 0 : nxt + 1;
;     const char* base = smem + cur * STG;
;     cur = (cur + 1 == D) ? 0 : cur + 1;
;     bf16x8 xf[MT];
; #pragma unroll
;     for (int i = 0; i < MT; ++i) xf[i] = *(const bf16x8*)(base + (xrow0 + i * 16) * 64 + rd);
; #pragma unroll
;     for (int nh = 0; nh < NT / 4; ++nh) {
;       bf16x8 wf[4];
; #pragma unroll
;       for (int i = 0; i < 4; ++i) wf[i] = *(const bf16x8*)(base + BM * 64 + (wrow0 + (nh * 4 + i) * 16) * 64 + rd);
; #pragma unroll
;       for (int i = 0; i < 4; ++i)
; #pragma unroll
;         for (int mt = 0; mt < MT; ++mt)
;           acc[nh * 4 + i][mt] = __builtin_amdgcn_mfma_f32_16x16x32_bf16(wf[i], xf[mt], acc[nh * 4 + i][mt], 0, 0, 0);
;     }
.LBB0_32:
	s_mul_i32 s12, s10, 0x6000
	v_lshl_add_u64 v[196:197], v[130:131], 0, s[40:41]
	s_waitcnt vmcnt(6)
	s_barrier
	s_mul_i32 s98, s11, 0x6000
	v_or_b32_e32 v137, s98, v134
	v_add_u32_e32 v150, v137, v136
	ds_read_b128 v[138:141], v150
	ds_read_b128 v[142:145], v150 offset:1024
	ds_read_b128 v[146:149], v150 offset:2048
	ds_read_b128 v[150:153], v150 offset:3072
	ds_read_b128 v[154:157], v137 offset:16384
	ds_read_b128 v[158:161], v137 offset:17408
	ds_read_b128 v[162:165], v137 offset:18432
	ds_read_b128 v[166:169], v137 offset:19456
	ds_read_b128 v[226:229], v137 offset:20480
	ds_read_b128 v[230:233], v137 offset:21504
	ds_read_b128 v[234:237], v137 offset:22528
	ds_read_b128 v[238:241], v137 offset:23552
	s_add_i32 s13, s12, s8
	s_mov_b32 s14, m0
	s_mov_b32 m0, s13
	s_nop 0
	global_load_lds_dwordx4 v[196:197], off
	s_mov_b32 m0, s14
	v_lshl_add_u64 v[224:225], v[196:197], 0, s[16:17]
	s_add_i32 s14, s13, 0x400
	s_mov_b32 s15, m0
	s_mov_b32 m0, s14
	s_nop 0
	global_load_lds_dwordx4 v[224:225], off
	s_mov_b32 m0, s15
	v_lshl_add_u64 v[224:225], v[196:197], 0, s[18:19]
	s_add_i32 s14, s13, 0x800
	s_mov_b32 s15, m0
	s_mov_b32 m0, s14
	s_nop 0
	global_load_lds_dwordx4 v[224:225], off
	s_mov_b32 m0, s15
	v_lshl_add_u64 v[196:197], v[196:197], 0, s[20:21]
	s_addk_i32 s13, 0xc00
	s_mov_b32 s14, m0
	s_mov_b32 m0, s13
	s_nop 0
	global_load_lds_dwordx4 v[196:197], off
	s_mov_b32 m0, s14
	s_add_i32 s12, s12, s9
	v_lshl_add_u64 v[194:195], v[128:129], 0, s[40:41]
	s_mov_b32 s13, m0
	s_mov_b32 m0, s12
	s_nop 0
	global_load_lds_dwordx4 v[194:195], off
	s_mov_b32 m0, s13
	s_addk_i32 s12, 0x400
	v_lshl_add_u64 v[194:195], v[194:195], 0, s[16:17]
	s_mov_b32 s13, m0
	s_mov_b32 m0, s12
	s_nop 0
	global_load_lds_dwordx4 v[194:195], off
	s_mov_b32 m0, s13
	s_waitcnt lgkmcnt(7)
	v_mfma_f32_16x16x32_bf16 v[124:127], v[154:157], v[138:141], v[124:127]
	s_add_i32 s10, s10, 1
	s_add_i32 s11, s11, 1
	s_cmp_lg_u32 s10, 3
	v_mfma_f32_16x16x32_bf16 v[120:123], v[154:157], v[142:145], v[120:123]
	s_cselect_b32 s10, s10, 0
	s_cmp_lg_u32 s11, 3
	s_cselect_b32 s11, s11, 0
	v_mfma_f32_16x16x32_bf16 v[116:119], v[154:157], v[146:149], v[116:119]
	s_add_u32 s40, s40, 64
	s_addc_u32 s41, s41, 0
	s_cmpk_lg_i32 s40, 0x780
	v_mfma_f32_16x16x32_bf16 v[112:115], v[154:157], v[150:153], v[112:115]
	s_waitcnt lgkmcnt(6)
	v_mfma_f32_16x16x32_bf16 v[108:111], v[158:161], v[138:141], v[108:111]
	v_mfma_f32_16x16x32_bf16 v[104:107], v[158:161], v[142:145], v[104:107]
	v_mfma_f32_16x16x32_bf16 v[100:103], v[158:161], v[146:149], v[100:103]
	v_mfma_f32_16x16x32_bf16 v[96:99], v[158:161], v[150:153], v[96:99]
	s_waitcnt lgkmcnt(5)
	v_mfma_f32_16x16x32_bf16 v[92:95], v[162:165], v[138:141], v[92:95]
	v_mfma_f32_16x16x32_bf16 v[88:91], v[162:165], v[142:145], v[88:91]
	v_mfma_f32_16x16x32_bf16 v[84:87], v[162:165], v[146:149], v[84:87]
	v_mfma_f32_16x16x32_bf16 v[80:83], v[162:165], v[150:153], v[80:83]
	s_waitcnt lgkmcnt(4)
	v_mfma_f32_16x16x32_bf16 v[76:79], v[166:169], v[138:141], v[76:79]
	v_mfma_f32_16x16x32_bf16 v[72:75], v[166:169], v[142:145], v[72:75]
	v_mfma_f32_16x16x32_bf16 v[68:71], v[166:169], v[146:149], v[68:71]
	v_mfma_f32_16x16x32_bf16 v[64:67], v[166:169], v[150:153], v[64:67]
	s_waitcnt lgkmcnt(3)
	v_mfma_f32_16x16x32_bf16 v[60:63], v[226:229], v[138:141], v[60:63]
	v_mfma_f32_16x16x32_bf16 v[56:59], v[226:229], v[142:145], v[56:59]
	v_mfma_f32_16x16x32_bf16 v[52:55], v[226:229], v[146:149], v[52:55]
	v_mfma_f32_16x16x32_bf16 v[48:51], v[226:229], v[150:153], v[48:51]
	s_waitcnt lgkmcnt(2)
	v_mfma_f32_16x16x32_bf16 v[44:47], v[230:233], v[138:141], v[44:47]
	v_mfma_f32_16x16x32_bf16 v[40:43], v[230:233], v[142:145], v[40:43]
	v_mfma_f32_16x16x32_bf16 v[36:39], v[230:233], v[146:149], v[36:39]
	v_mfma_f32_16x16x32_bf16 v[32:35], v[230:233], v[150:153], v[32:35]
	s_waitcnt lgkmcnt(1)
	v_mfma_f32_16x16x32_bf16 v[28:31], v[234:237], v[138:141], v[28:31]
	v_mfma_f32_16x16x32_bf16 v[24:27], v[234:237], v[142:145], v[24:27]
	v_mfma_f32_16x16x32_bf16 v[20:23], v[234:237], v[146:149], v[20:23]
	v_mfma_f32_16x16x32_bf16 v[16:19], v[234:237], v[150:153], v[16:19]
	s_waitcnt lgkmcnt(0)
	v_mfma_f32_16x16x32_bf16 v[12:15], v[238:241], v[138:141], v[12:15]
	v_mfma_f32_16x16x32_bf16 v[8:11], v[238:241], v[142:145], v[8:11]
	v_mfma_f32_16x16x32_bf16 v[4:7], v[238:241], v[146:149], v[4:7]
	v_mfma_f32_16x16x32_bf16 v[0:3], v[238:241], v[150:153], v[0:3]
	s_cbranch_scc1 .LBB0_32
	v_add_u32_e32 v180, v134, v136
	s_waitcnt vmcnt(6)
	s_barrier
	ds_read_b128 v[128:131], v180
	ds_read_b128 v[136:139], v180 offset:1024
	ds_read_b128 v[140:143], v180 offset:2048
	ds_read_b128 v[144:147], v180 offset:3072
	ds_read_b128 v[148:151], v134 offset:16384
	ds_read_b128 v[152:155], v134 offset:17408
	ds_read_b128 v[156:159], v134 offset:18432
	ds_read_b128 v[160:163], v134 offset:19456
	s_waitcnt lgkmcnt(3)
	v_mfma_f32_16x16x32_bf16 v[124:127], v[148:151], v[128:131], v[124:127]
	s_lshl_b32 s7, s7, 8
	v_lshl_or_b32 v182, v132, 3, s7
	v_mfma_f32_16x16x32_bf16 v[120:123], v[148:151], v[136:139], v[120:123]
	v_mfma_f32_16x16x32_bf16 v[116:119], v[148:151], v[140:143], v[116:119]
	v_mfma_f32_16x16x32_bf16 v[112:115], v[148:151], v[144:147], v[112:115]
	s_waitcnt lgkmcnt(2)
	v_mfma_f32_16x16x32_bf16 v[108:111], v[152:155], v[128:131], v[108:111]
	v_mfma_f32_16x16x32_bf16 v[104:107], v[152:155], v[136:139], v[104:107]
	v_mfma_f32_16x16x32_bf16 v[100:103], v[152:155], v[140:143], v[100:103]
	v_mfma_f32_16x16x32_bf16 v[96:99], v[152:155], v[144:147], v[96:99]
	s_waitcnt lgkmcnt(1)
	v_mfma_f32_16x16x32_bf16 v[92:95], v[156:159], v[128:131], v[92:95]
	v_mfma_f32_16x16x32_bf16 v[88:91], v[156:159], v[136:139], v[88:91]
	v_mfma_f32_16x16x32_bf16 v[84:87], v[156:159], v[140:143], v[84:87]
	v_mfma_f32_16x16x32_bf16 v[148:151], v[156:159], v[144:147], v[80:83]
	s_waitcnt lgkmcnt(0)
	v_mfma_f32_16x16x32_bf16 v[76:79], v[160:163], v[128:131], v[76:79]
	v_mfma_f32_16x16x32_bf16 v[152:155], v[160:163], v[136:139], v[72:75]
	v_mfma_f32_16x16x32_bf16 v[68:71], v[160:163], v[140:143], v[68:71]
	v_mfma_f32_16x16x32_bf16 v[156:159], v[160:163], v[144:147], v[64:67]
	s_nop 2
	ds_read_b128 v[64:67], v134 offset:20480
	ds_read_b128 v[72:75], v134 offset:21504
	ds_read_b128 v[80:83], v134 offset:22528
	ds_read_b128 v[160:163], v134 offset:23552
	s_waitcnt vmcnt(0)
	s_waitcnt lgkmcnt(0)
	v_mfma_f32_16x16x32_bf16 v[60:63], v[64:67], v[128:131], v[60:63]
	s_barrier
; DI void st_bf4(u16* p, float a, float b, float c, float d) { *(uint2*)p = make_uint2(pk2(a, b), pk2(c, d)); }
; template <int BM, class Epi>
; DI void gemm_dma(const u16* __restrict__ X, long ldx, const u16* __restrict__ W, long ldw, int K, char* smem,
;                  int m0, int n0, const Epi& epi) {
;     ...
;     bf16x8 xf[MT];
; #pragma unroll
;     for (int i = 0; i < MT; ++i) xf[i] = *(const bf16x8*)(base + (xrow0 + i * 16) * 64 + rd);
; #pragma unroll
;     for (int nh = 0; nh < NT / 4; ++nh) {
;       bf16x8 wf[4];
; #pragma unroll
;       for (int i = 0; i < 4; ++i) wf[i] = *(const bf16x8*)(base + BM * 64 + (wrow0 + (nh * 4 + i) * 16) * 64 + rd);
; #pragma unroll
;       for (int i = 0; i < 4; ++i)
; #pragma unroll
;         for (int mt = 0; mt < MT; ++mt)
;           acc[nh * 4 + i][mt] = __builtin_amdgcn_mfma_f32_16x16x32_bf16(wf[i], xf[mt], acc[nh * 4 + i][mt], 0, 0, 0);
;     }
;   template <int NT, int MT> DI void run(f32x4 (&acc)[NT][MT], int mb, int nb) const {
; #pragma unroll
;     for (int nt = 0; nt < NT; ++nt)
; #pragma unroll
;       for (int mt = 0; mt < MT; ++mt) {
;         f32x4 v = acc[nt][mt];
;         st_bf4(C + (size_t)(mb + mt * 16) * ldc + nb + nt * 16, v[0], v[1], v[2], v[3]);
;       }
	v_mfma_f32_16x16x32_bf16 v[164:167], v[64:67], v[136:139], v[56:59]
	v_mfma_f32_16x16x32_bf16 v[52:55], v[64:67], v[140:143], v[52:55]
	v_mfma_f32_16x16x32_bf16 v[168:171], v[64:67], v[144:147], v[48:51]
	v_mfma_f32_16x16x32_bf16 v[44:47], v[72:75], v[128:131], v[44:47]
	v_mfma_f32_16x16x32_bf16 v[172:175], v[72:75], v[136:139], v[40:43]
	v_mfma_f32_16x16x32_bf16 v[36:39], v[72:75], v[140:143], v[36:39]
	v_mfma_f32_16x16x32_bf16 v[176:179], v[72:75], v[144:147], v[32:35]
	v_mfma_f32_16x16x32_bf16 v[28:31], v[80:83], v[128:131], v[28:31]
	v_mfma_f32_16x16x32_bf16 v[24:27], v[80:83], v[136:139], v[24:27]
	v_mfma_f32_16x16x32_bf16 v[20:23], v[80:83], v[140:143], v[20:23]
	v_mfma_f32_16x16x32_bf16 v[16:19], v[80:83], v[144:147], v[16:19]
	v_mfma_f32_16x16x32_bf16 v[12:15], v[160:163], v[128:131], v[12:15]
	v_mfma_f32_16x16x32_bf16 v[8:11], v[160:163], v[136:139], v[8:11]
	v_mfma_f32_16x16x32_bf16 v[4:7], v[160:163], v[140:143], v[4:7]
	v_mfma_f32_16x16x32_bf16 v[0:3], v[160:163], v[144:147], v[0:3]
	ds_read_b128 v[128:131], v180 offset:24576
	ds_read_b128 v[136:139], v180 offset:25600
	ds_read_b128 v[140:143], v180 offset:26624
	ds_read_b128 v[144:147], v180 offset:27648
	ds_read_b128 v[32:35], v134 offset:40960
	ds_read_b128 v[40:43], v134 offset:41984
	ds_read_b128 v[48:51], v134 offset:43008
	ds_read_b128 v[160:163], v134 offset:44032
	s_waitcnt lgkmcnt(2)
	v_mfma_f32_16x16x32_bf16 v[108:111], v[40:43], v[128:131], v[108:111]
	v_mfma_f32_16x16x32_bf16 v[104:107], v[40:43], v[136:139], v[104:107]
	v_mfma_f32_16x16x32_bf16 v[100:103], v[40:43], v[140:143], v[100:103]
	s_nop 5
	v_cvt_pk_bf16_f32 v108, v108, v109
	v_cvt_pk_bf16_f32 v109, v110, v111
	v_cvt_pk_bf16_f32 v104, v104, v105
	v_mfma_f32_16x16x32_bf16 v[96:99], v[40:43], v[144:147], v[96:99]
	v_cvt_pk_bf16_f32 v105, v106, v107
	v_cvt_pk_bf16_f32 v100, v100, v101
	v_cvt_pk_bf16_f32 v101, v102, v103
	s_waitcnt lgkmcnt(1)
	v_mfma_f32_16x16x32_bf16 v[92:95], v[48:51], v[128:131], v[92:95]
	v_mfma_f32_16x16x32_bf16 v[80:83], v[48:51], v[136:139], v[88:91]
	s_nop 1
	v_cvt_pk_bf16_f32 v96, v96, v97
	v_cvt_pk_bf16_f32 v97, v98, v99
	s_nop 2
	v_cvt_pk_bf16_f32 v92, v92, v93
	v_mfma_f32_16x16x32_bf16 v[72:75], v[48:51], v[140:143], v[84:87]
	v_cvt_pk_bf16_f32 v93, v94, v95
	v_cvt_pk_bf16_f32 v80, v80, v81
	v_cvt_pk_bf16_f32 v81, v82, v83
	v_mfma_f32_16x16x32_bf16 v[64:67], v[48:51], v[144:147], v[148:151]
	s_waitcnt lgkmcnt(0)
	v_mfma_f32_16x16x32_bf16 v[48:51], v[160:163], v[136:139], v[152:155]
	s_nop 1
	v_cvt_pk_bf16_f32 v72, v72, v73
	v_cvt_pk_bf16_f32 v73, v74, v75
	s_nop 1
	v_cvt_pk_bf16_f32 v64, v64, v65
	v_mfma_f32_16x16x32_bf16 v[40:43], v[160:163], v[140:143], v[68:71]
	s_nop 2
	ds_read_b128 v[68:71], v134 offset:45056
	ds_read_b128 v[88:91], v134 offset:46080
	ds_read_b128 v[148:151], v134 offset:47104
	ds_read_b128 v[152:155], v134 offset:48128
	v_cvt_pk_bf16_f32 v65, v66, v67
	v_cvt_pk_bf16_f32 v48, v48, v49
	v_mfma_f32_16x16x32_bf16 v[124:127], v[32:35], v[128:131], v[124:127]
	v_cvt_pk_bf16_f32 v49, v50, v51
	v_cvt_pk_bf16_f32 v40, v40, v41
	v_cvt_pk_bf16_f32 v41, v42, v43
	v_mfma_f32_16x16x32_bf16 v[120:123], v[32:35], v[136:139], v[120:123]
	v_mfma_f32_16x16x32_bf16 v[116:119], v[32:35], v[140:143], v[116:119]
	v_mfma_f32_16x16x32_bf16 v[112:115], v[32:35], v[144:147], v[112:115]
	s_nop 5
	v_cvt_pk_bf16_f32 v120, v120, v121
	v_cvt_pk_bf16_f32 v121, v122, v123
	v_cvt_pk_bf16_f32 v116, v116, v117
	v_mfma_f32_16x16x32_bf16 v[56:59], v[160:163], v[128:131], v[76:79]
	v_cvt_pk_bf16_f32 v117, v118, v119
	v_cvt_pk_bf16_f32 v112, v112, v113
	v_cvt_pk_bf16_f32 v113, v114, v115
	v_mfma_f32_16x16x32_bf16 v[32:35], v[160:163], v[144:147], v[156:159]
	s_waitcnt lgkmcnt(3)
	v_mfma_f32_16x16x32_bf16 v[156:159], v[68:71], v[128:131], v[60:63]
	s_nop 1
	v_cvt_pk_bf16_f32 v56, v56, v57
	s_nop 2
	v_cvt_pk_bf16_f32 v32, v32, v33
	v_cvt_pk_bf16_f32 v33, v34, v35
	v_mfma_f32_16x16x32_bf16 v[76:79], v[68:71], v[140:143], v[52:55]
	v_cvt_pk_bf16_f32 v57, v58, v59
	s_waitcnt lgkmcnt(2)
	v_mfma_f32_16x16x32_bf16 v[60:63], v[88:91], v[128:131], v[44:47]
	v_mfma_f32_16x16x32_bf16 v[52:55], v[88:91], v[136:139], v[172:175]
	v_mfma_f32_16x16x32_bf16 v[44:47], v[88:91], v[140:143], v[36:39]
	v_mfma_f32_16x16x32_bf16 v[36:39], v[88:91], v[144:147], v[176:179]
	v_lshl_add_u32 v88, s38, 8, v135
	v_cvt_pk_bf16_f32 v90, v124, v125
	v_cvt_pk_bf16_f32 v91, v126, v127
	s_waitcnt lgkmcnt(1)
; DI void st_bf4(u16* p, float a, float b, float c, float d) { *(uint2*)p = make_uint2(pk2(a, b), pk2(c, d)); }
; template <int BM, class Epi>
; DI void gemm_dma(const u16* __restrict__ X, long ldx, const u16* __restrict__ W, long ldw, int K, char* smem,
;                  int m0, int n0, const Epi& epi) {
;     ...
;       for (int i = 0; i < 4; ++i)
; #pragma unroll
;         for (int mt = 0; mt < MT; ++mt)
;           acc[nh * 4 + i][mt] = __builtin_amdgcn_mfma_f32_16x16x32_bf16(wf[i], xf[mt], acc[nh * 4 + i][mt], 0, 0, 0);
;   template <int NT, int MT> DI void run(f32x4 (&acc)[NT][MT], int mb, int nb) const {
; #pragma unroll
;     for (int nt = 0; nt < NT; ++nt)
; #pragma unroll
;       for (int mt = 0; mt < MT; ++mt) {
;         f32x4 v = acc[nt][mt];
;         st_bf4(C + (size_t)(mb + mt * 16) * ldc + nb + nt * 16, v[0], v[1], v[2], v[3]);
;       }
	v_mfma_f32_16x16x32_bf16 v[28:31], v[148:151], v[128:131], v[28:31]
	s_waitcnt lgkmcnt(0)
	v_mfma_f32_16x16x32_bf16 v[12:15], v[152:155], v[128:131], v[12:15]
	v_or_b32_e32 v128, v88, v133
	v_ashrrev_i32_e32 v129, 31, v128
	v_lshlrev_b64 v[88:89], 11, v[128:129]
	v_lshl_add_u64 v[88:89], s[92:93], 0, v[88:89]
	v_lshl_add_u64 v[88:89], v[88:89], 0, v[182:183]
	global_store_dwordx2 v[88:89], v[90:91], off
	v_or_b32_e32 v90, 16, v128
	v_ashrrev_i32_e32 v91, 31, v90
	v_lshlrev_b64 v[90:91], 11, v[90:91]
	v_lshl_add_u64 v[90:91], s[92:93], 0, v[90:91]
	v_lshl_add_u64 v[90:91], v[90:91], 0, v[182:183]
	global_store_dwordx2 v[90:91], v[120:121], off
	v_or_b32_e32 v120, 32, v128
	v_ashrrev_i32_e32 v121, 31, v120
	v_lshlrev_b64 v[120:121], 11, v[120:121]
	v_lshl_add_u64 v[120:121], s[92:93], 0, v[120:121]
	v_lshl_add_u64 v[120:121], v[120:121], 0, v[182:183]
	global_store_dwordx2 v[120:121], v[116:117], off
	v_or_b32_e32 v116, 48, v128
	v_ashrrev_i32_e32 v117, 31, v116
	v_mfma_f32_16x16x32_bf16 v[84:87], v[68:71], v[136:139], v[164:167]
	v_lshlrev_b64 v[116:117], 11, v[116:117]
	v_lshl_add_u64 v[116:117], s[92:93], 0, v[116:117]
	v_lshl_add_u64 v[116:117], v[116:117], 0, v[182:183]
	v_mfma_f32_16x16x32_bf16 v[68:71], v[68:71], v[144:147], v[168:171]
	global_store_dwordx2 v[116:117], v[32:33], off offset:96
	v_cvt_pk_bf16_f32 v32, v156, v157
	v_cvt_pk_bf16_f32 v33, v158, v159
	global_store_dwordx2 v[88:89], v[32:33], off offset:128
	v_cvt_pk_bf16_f32 v32, v84, v85
	v_cvt_pk_bf16_f32 v33, v86, v87
	global_store_dwordx2 v[90:91], v[32:33], off offset:128
	v_cvt_pk_bf16_f32 v32, v76, v77
	v_cvt_pk_bf16_f32 v33, v78, v79
	v_mfma_f32_16x16x32_bf16 v[24:27], v[148:151], v[136:139], v[24:27]
	global_store_dwordx2 v[120:121], v[32:33], off offset:128
	v_cvt_pk_bf16_f32 v32, v68, v69
	v_cvt_pk_bf16_f32 v33, v70, v71
	v_mfma_f32_16x16x32_bf16 v[20:23], v[148:151], v[140:143], v[20:23]
	global_store_dwordx2 v[116:117], v[32:33], off offset:128
	v_cvt_pk_bf16_f32 v32, v60, v61
	v_cvt_pk_bf16_f32 v33, v62, v63
	v_mfma_f32_16x16x32_bf16 v[16:19], v[148:151], v[144:147], v[16:19]
	global_store_dwordx2 v[88:89], v[32:33], off offset:160
	v_cvt_pk_bf16_f32 v32, v52, v53
	v_cvt_pk_bf16_f32 v33, v54, v55
	v_mfma_f32_16x16x32_bf16 v[8:11], v[152:155], v[136:139], v[8:11]
	global_store_dwordx2 v[90:91], v[32:33], off offset:160
	v_cvt_pk_bf16_f32 v32, v44, v45
	v_cvt_pk_bf16_f32 v33, v46, v47
	v_mfma_f32_16x16x32_bf16 v[4:7], v[152:155], v[140:143], v[4:7]
	global_store_dwordx2 v[120:121], v[32:33], off offset:160
	v_cvt_pk_bf16_f32 v32, v36, v37
	v_cvt_pk_bf16_f32 v33, v38, v39
	v_mfma_f32_16x16x32_bf16 v[0:3], v[152:155], v[144:147], v[0:3]
	v_cvt_pk_bf16_f32 v28, v28, v29
	v_cvt_pk_bf16_f32 v29, v30, v31
	v_cvt_pk_bf16_f32 v24, v24, v25
	v_cvt_pk_bf16_f32 v25, v26, v27
	v_cvt_pk_bf16_f32 v20, v20, v21
	v_cvt_pk_bf16_f32 v21, v22, v23
	v_cvt_pk_bf16_f32 v16, v16, v17
	v_cvt_pk_bf16_f32 v17, v18, v19
	v_cvt_pk_bf16_f32 v12, v12, v13
	v_cvt_pk_bf16_f32 v13, v14, v15
	v_cvt_pk_bf16_f32 v8, v8, v9
	v_cvt_pk_bf16_f32 v9, v10, v11
	v_cvt_pk_bf16_f32 v4, v4, v5
	v_cvt_pk_bf16_f32 v5, v6, v7
	v_cvt_pk_bf16_f32 v0, v0, v1
	v_cvt_pk_bf16_f32 v1, v2, v3
	global_store_dwordx2 v[116:117], v[112:113], off
	global_store_dwordx2 v[88:89], v[108:109], off offset:32
	global_store_dwordx2 v[90:91], v[104:105], off offset:32
	global_store_dwordx2 v[120:121], v[100:101], off offset:32
	global_store_dwordx2 v[116:117], v[96:97], off offset:32
	global_store_dwordx2 v[88:89], v[92:93], off offset:64
	global_store_dwordx2 v[90:91], v[80:81], off offset:64
	global_store_dwordx2 v[120:121], v[72:73], off offset:64
	global_store_dwordx2 v[116:117], v[64:65], off offset:64
	global_store_dwordx2 v[88:89], v[56:57], off offset:96
	global_store_dwordx2 v[90:91], v[48:49], off offset:96
	global_store_dwordx2 v[120:121], v[40:41], off offset:96
	global_store_dwordx2 v[116:117], v[32:33], off offset:160
	global_store_dwordx2 v[88:89], v[28:29], off offset:192
	global_store_dwordx2 v[90:91], v[24:25], off offset:192
	global_store_dwordx2 v[120:121], v[20:21], off offset:192
	global_store_dwordx2 v[116:117], v[16:17], off offset:192
	global_store_dwordx2 v[88:89], v[12:13], off offset:224
	global_store_dwordx2 v[90:91], v[8:9], off offset:224
	global_store_dwordx2 v[120:121], v[4:5], off offset:224
	global_store_dwordx2 v[116:117], v[0:1], off offset:224
	s_branch .LBB0_25

; DI unsigned pk2(float a, float b) { f32x2_t f = {a, b}; return __builtin_bit_cast(unsigned, __builtin_convertvector(f, bf16x2_t)); }
; DI float bflo(unsigned u) { return __uint_as_float(u << 16); }
; DI float bfhi(unsigned u) { return __uint_as_float(u & 0xffff0000u); }
; DI void st_bf4(u16* p, float a, float b, float c, float d) { *(uint2*)p = make_uint2(pk2(a, b), pk2(c, d)); }
; DI void attn_item(const u16* __restrict__ qbuf, const u16* __restrict__ knope, const u16* __restrict__ krope, ...
;     ...
;         for (int j = 0; j < 16; ++j) { const float pv = __builtin_amdgcn_exp2f(st[mt][j] - m_new); st[mt][j] = pv; ps += pv; }
;       l_run = l_run * alpha + ps;
;       if (__any(alpha != 1.f)) {
; #pragma unroll
;         for (int i = 0; i < 4; ++i)
; #pragma unroll
;           for (int j = 0; j < 16; ++j) oacc[i][j] *= alpha;
;       }
; #pragma unroll
;       for (int mt = 0; mt < 2; ++mt)
; #pragma unroll
;         for (int s = 0; s < 2; ++s) {
;           union { bf16x8 v; unsigned u[4]; } pf;
; #pragma unroll
;           for (int k = 0; k < 4; ++k) pf.u[k] = pk2(st[mt][8 * s + 2 * k], st[mt][8 * s + 2 * k + 1]);
; #pragma unroll
;           for (int vt4 = 0; vt4 < 4; ++vt4) {
;             const bf16x8 vf = *(const bf16x8*)(cur + 24576 + koff[mt * 2 + s] + vt4 * 4096);
;             oacc[vt4] = __builtin_amdgcn_mfma_f32_32x32x16_bf16(vf, pf.v, oacc[vt4], 0, 0, 0);
;           }
;         }
;     }
;   }
;     ...
;   const float lt_probe = l_run + oacc[0][0] + oacc[1][5] + oacc[2][9] + oacc[3][15];
;   if (active && (!dry || lt_probe == 123456.789f)) {
;     const float lt = l_run + __shfl_xor(l_run, 32, 64);
;     const float inv = 1.f / lt;
;     u16* op = ao + (size_t)qrow * 1024 + head * 128 + 4 * h2;
; #pragma unroll
;     for (int vt4 = 0; vt4 < 4; ++vt4)
; #pragma unroll
;       for (int a = 0; a < 4; ++a) {
;         u16* q = op + vt4 * 32 + 8 * a;
;         const uint2 gt = *(const uint2*)q;
;         st_bf4(q, oacc[vt4][4 * a] * inv * bflo(gt.x), oacc[vt4][4 * a + 1] * inv * bfhi(gt.x),
;                oacc[vt4][4 * a + 2] * inv * bflo(gt.y), oacc[vt4][4 * a + 3] * inv * bfhi(gt.y));
;       }
.LBB0_55:
	v_sub_f32_e32 v64, v64, v82
	v_exp_f32_e32 v64, v64
	v_sub_f32_e32 v65, v65, v82
	v_exp_f32_e32 v65, v65
	v_sub_f32_e32 v66, v66, v82
	v_exp_f32_e32 v66, v66
	v_sub_f32_e32 v67, v67, v82
	v_exp_f32_e32 v67, v67
	v_sub_f32_e32 v68, v68, v82
	v_add_f32_e32 v83, 0, v64
	v_exp_f32_e32 v68, v68
	v_sub_f32_e32 v69, v69, v82
	v_add_f32_e32 v83, v65, v83
	v_exp_f32_e32 v69, v69
	v_sub_f32_e32 v70, v70, v82
	v_add_f32_e32 v83, v66, v83
	v_exp_f32_e32 v70, v70
	v_sub_f32_e32 v71, v71, v82
	v_add_f32_e32 v83, v67, v83
	v_exp_f32_e32 v71, v71
	v_add_f32_e32 v83, v68, v83
	v_add_f32_e32 v83, v69, v83
	v_add_f32_e32 v83, v70, v83
	v_add_f32_e32 v83, v71, v83
	v_cvt_pk_bf16_f32 v64, v64, v65
	v_cvt_pk_bf16_f32 v65, v66, v67
	v_cvt_pk_bf16_f32 v66, v68, v69
	v_cvt_pk_bf16_f32 v67, v70, v71
	ds_read_b128 v[68:71], v150 offset:24576
	v_sub_f32_e32 v72, v72, v82
	s_waitcnt lgkmcnt(0)
	v_mfma_f32_32x32x16_bf16 v[48:63], v[68:71], v[64:67], v[48:63]
	ds_read_b128 v[68:71], v150 offset:28672
	v_sub_f32_e32 v73, v73, v82
	v_sub_f32_e32 v74, v74, v82
	v_sub_f32_e32 v75, v75, v82
	v_sub_f32_e32 v76, v76, v82
	v_sub_f32_e32 v77, v77, v82
	v_sub_f32_e32 v78, v78, v82
	s_waitcnt lgkmcnt(0)
	v_mfma_f32_32x32x16_bf16 v[32:47], v[68:71], v[64:67], v[32:47]
	ds_read_b128 v[68:71], v150 offset:32768
	v_sub_f32_e32 v79, v79, v82
	v_exp_f32_e32 v72, v72
	v_exp_f32_e32 v73, v73
	v_exp_f32_e32 v74, v74
	v_exp_f32_e32 v75, v75
	v_exp_f32_e32 v76, v76
	s_waitcnt lgkmcnt(0)
	v_mfma_f32_32x32x16_bf16 v[16:31], v[68:71], v[64:67], v[16:31]
	ds_read_b128 v[68:71], v150 offset:36864
	v_exp_f32_e32 v77, v77
	v_exp_f32_e32 v78, v78
	v_exp_f32_e32 v79, v79
	v_sub_f32_e32 v82, 0xff800000, v82
	v_exp_f32_e32 v82, v82
	v_add_f32_e32 v83, v72, v83
	s_waitcnt lgkmcnt(0)
	v_mfma_f32_32x32x16_bf16 v[0:15], v[68:71], v[64:67], v[0:15]
	ds_read_b128 v[68:71], v149 offset:24576
	v_cvt_pk_bf16_f32 v64, v72, v73
	v_cvt_pk_bf16_f32 v65, v74, v75
	v_cvt_pk_bf16_f32 v66, v76, v77
	v_cvt_pk_bf16_f32 v67, v78, v79
	v_add_f32_e32 v83, v73, v83
	v_add_f32_e32 v83, v74, v83
	s_waitcnt lgkmcnt(0)
	v_mfma_f32_32x32x16_bf16 v[48:63], v[68:71], v[64:67], v[48:63]
	ds_read_b128 v[68:71], v149 offset:28672
	v_add_f32_e32 v83, v75, v83
	v_add_f32_e32 v83, v76, v83
	v_add_f32_e32 v83, v77, v83
	v_add_f32_e32 v83, v78, v83
	v_add_f32_e32 v83, v79, v83
	v_add_f32_e32 v83, v82, v83
	s_waitcnt lgkmcnt(0)
	v_mfma_f32_32x32x16_bf16 v[32:47], v[68:71], v[64:67], v[32:47]
	ds_read_b128 v[68:71], v149 offset:32768
	v_add_f32_e32 v83, v82, v83
	v_add_f32_e32 v83, v82, v83
	v_add_f32_e32 v83, v82, v83
	v_add_f32_e32 v83, v82, v83
	v_add_f32_e32 v83, v82, v83
	v_add_f32_e32 v83, v82, v83
	s_waitcnt lgkmcnt(0)
	v_mfma_f32_32x32x16_bf16 v[16:31], v[68:71], v[64:67], v[16:31]
	ds_read_b128 v[68:71], v149 offset:36864
	v_add_f32_e32 v83, v82, v83
	v_add_f32_e32 v83, v82, v83
	v_add_f32_e32 v83, v82, v83
	v_add_f32_e32 v83, v82, v83
	v_add_f32_e32 v83, v82, v83
	v_add_f32_e32 v83, v82, v83
	s_waitcnt lgkmcnt(0)
	v_mfma_f32_32x32x16_bf16 v[0:15], v[68:71], v[64:67], v[0:15]
	ds_read_b128 v[68:71], v148 offset:24576
	v_cvt_pk_bf16_f32 v64, v82, v82
	v_mov_b32_e32 v65, v64
	v_mov_b32_e32 v66, v64
	v_mov_b32_e32 v67, v64
	v_add_f32_e32 v83, v82, v83
	v_add_f32_e32 v83, v82, v83
	s_waitcnt lgkmcnt(0)
	v_mfma_f32_32x32x16_bf16 v[48:63], v[68:71], v[64:67], v[48:63]
	ds_read_b128 v[68:71], v148 offset:28672
	v_add_f32_e32 v83, v82, v83
	v_fmac_f32_e32 v83, v151, v80
	s_lshl_b32 s34, s6, 1
	v_lshlrev_b32_e32 v182, 3, v147
	s_waitcnt lgkmcnt(0)
	v_mfma_f32_32x32x16_bf16 v[32:47], v[68:71], v[64:67], v[32:47]
	ds_read_b128 v[68:71], v148 offset:32768
	s_waitcnt lgkmcnt(0)
	v_mfma_f32_32x32x16_bf16 v[16:31], v[68:71], v[64:67], v[16:31]
	ds_read_b128 v[68:71], v148 offset:36864
	s_waitcnt lgkmcnt(0)
	v_mfma_f32_32x32x16_bf16 v[0:15], v[68:71], v[64:67], v[0:15]
	ds_read_b128 v[68:71], v145 offset:24576
	s_waitcnt lgkmcnt(0)
	v_mfma_f32_32x32x16_bf16 v[48:63], v[68:71], v[64:67], v[48:63]
	ds_read_b128 v[68:71], v145 offset:28672
	s_waitcnt lgkmcnt(0)
	v_mfma_f32_32x32x16_bf16 v[32:47], v[68:71], v[64:67], v[32:47]
	ds_read_b128 v[68:71], v145 offset:32768
	s_waitcnt lgkmcnt(0)
	v_mfma_f32_32x32x16_bf16 v[16:31], v[68:71], v[64:67], v[16:31]
	ds_read_b128 v[68:71], v145 offset:36864
	v_ashrrev_i32_e32 v145, 31, v144
	s_waitcnt lgkmcnt(0)
	v_mfma_f32_32x32x16_bf16 v[0:15], v[68:71], v[64:67], v[0:15]
	ds_bpermute_b32 v64, v81, v83
	s_waitcnt lgkmcnt(0)
	v_readlane_b32 s8, v252, 24
	v_readlane_b32 s9, v252, 25
	v_lshlrev_b64 v[224:225], 11, v[144:145]
	s_nop 0
	v_lshl_add_u64 v[226:227], s[8:9], 0, v[224:225]
	v_lshl_add_u64 v[228:229], v[226:227], 0, s[34:35]
	v_lshl_add_u64 v[230:231], v[228:229], 0, v[182:183]
	global_load_dwordx2 v[232:233], v[230:231], off
	global_load_dwordx2 v[234:235], v[230:231], off offset:16
	global_load_dwordx2 v[236:237], v[230:231], off offset:32
	global_load_dwordx2 v[238:239], v[230:231], off offset:48
	global_load_dwordx2 v[240:241], v[230:231], off offset:64
	global_load_dwordx2 v[242:243], v[230:231], off offset:80
	global_load_dwordx2 v[244:245], v[230:231], off offset:96
	global_load_dwordx2 v[246:247], v[230:231], off offset:112
	global_load_dwordx2 v[248:249], v[230:231], off offset:128
	global_load_dwordx2 v[250:251], v[230:231], off offset:144
	global_load_dwordx2 v[186:187], v[230:231], off offset:160
	global_load_dwordx2 v[188:189], v[230:231], off offset:176
	global_load_dwordx2 v[190:191], v[230:231], off offset:192
	global_load_dwordx2 v[192:193], v[230:231], off offset:208
	global_load_dwordx2 v[194:195], v[230:231], off offset:224
	global_load_dwordx2 v[196:197], v[230:231], off offset:240
	v_add_f32_e32 v64, v83, v64
	v_div_scale_f32 v65, s[8:9], v64, v64, 1.0
	v_rcp_f32_e32 v66, v65
	s_nop 0
	s_nop 0
	v_fma_f32 v67, -v65, v66, 1.0
	v_fmac_f32_e32 v66, v67, v66
	v_div_scale_f32 v67, vcc, 1.0, v64, 1.0
	v_mul_f32_e32 v68, v67, v66
	v_fma_f32 v69, -v65, v68, v67
	v_fmac_f32_e32 v68, v69, v66
	v_fma_f32 v65, -v65, v68, v67
	v_div_fmas_f32 v65, v65, v66, v68
	s_nop 0
	s_nop 0
	s_nop 0
	s_nop 0
	s_nop 0
	v_div_fixup_f32 v64, v65, v64, 1.0
	v_pk_mul_f32 v[48:49], v[48:49], v[64:65] op_sel_hi:[1,0]
	v_pk_mul_f32 v[50:51], v[50:51], v[64:65] op_sel_hi:[1,0]
	v_pk_mul_f32 v[52:53], v[52:53], v[64:65] op_sel_hi:[1,0]
	v_pk_mul_f32 v[32:33], v[32:33], v[64:65] op_sel_hi:[1,0]
	v_pk_mul_f32 v[34:35], v[34:35], v[64:65] op_sel_hi:[1,0]
	v_pk_mul_f32 v[36:37], v[36:37], v[64:65] op_sel_hi:[1,0]
	v_pk_mul_f32 v[16:17], v[16:17], v[64:65] op_sel_hi:[1,0]
	v_pk_mul_f32 v[18:19], v[18:19], v[64:65] op_sel_hi:[1,0]
	v_pk_mul_f32 v[20:21], v[20:21], v[64:65] op_sel_hi:[1,0]
	v_pk_mul_f32 v[0:1], v[0:1], v[64:65] op_sel_hi:[1,0]
	v_pk_mul_f32 v[2:3], v[2:3], v[64:65] op_sel_hi:[1,0]
	v_pk_mul_f32 v[4:5], v[4:5], v[64:65] op_sel_hi:[1,0]
	s_waitcnt vmcnt(15)
; DI float bflo(unsigned u) { return __uint_as_float(u << 16); }
; DI float bfhi(unsigned u) { return __uint_as_float(u & 0xffff0000u); }
; DI void st_bf4(u16* p, float a, float b, float c, float d) { *(uint2*)p = make_uint2(pk2(a, b), pk2(c, d)); }
; DI void attn_item(const u16* __restrict__ qbuf, const u16* __restrict__ knope, const u16* __restrict__ krope, ...
;     ...
; #pragma unroll
;     for (int vt4 = 0; vt4 < 4; ++vt4)
; #pragma unroll
;       for (int a = 0; a < 4; ++a) {
;         u16* q = op + vt4 * 32 + 8 * a;
;         const uint2 gt = *(const uint2*)q;
;         st_bf4(q, oacc[vt4][4 * a] * inv * bflo(gt.x), oacc[vt4][4 * a + 1] * inv * bfhi(gt.x),
;                oacc[vt4][4 * a + 2] * inv * bflo(gt.y), oacc[vt4][4 * a + 3] * inv * bfhi(gt.y));
	v_lshlrev_b32_e32 v70, 16, v232
	v_and_b32_e32 v71, 0xffff0000, v232
	v_lshlrev_b32_e32 v68, 16, v233
	v_and_b32_e32 v69, 0xffff0000, v233
	v_pk_mul_f32 v[48:49], v[48:49], v[70:71]
	v_pk_mul_f32 v[50:51], v[50:51], v[68:69]
	v_cvt_pk_bf16_f32 v48, v48, v49
	v_cvt_pk_bf16_f32 v49, v50, v51
	global_store_dwordx2 v[230:231], v[48:49], off
	s_nop 0
	s_waitcnt vmcnt(14)
	v_lshlrev_b32_e32 v50, 16, v234
	v_and_b32_e32 v51, 0xffff0000, v234
	v_pk_mul_f32 v[50:51], v[52:53], v[50:51]
	v_lshlrev_b32_e32 v48, 16, v235
	v_and_b32_e32 v49, 0xffff0000, v235
	v_pk_mul_f32 v[52:53], v[54:55], v[64:65] op_sel_hi:[1,0]
	v_cvt_pk_bf16_f32 v50, v50, v51
	v_pk_mul_f32 v[48:49], v[52:53], v[48:49]
	v_pk_mul_f32 v[52:53], v[56:57], v[64:65] op_sel_hi:[1,0]
	v_cvt_pk_bf16_f32 v51, v48, v49
	s_nop 0
	s_nop 0
	global_store_dwordx2 v[230:231], v[50:51], off offset:16
	s_waitcnt vmcnt(14)
	v_lshlrev_b32_e32 v50, 16, v236
	v_and_b32_e32 v51, 0xffff0000, v236
	v_pk_mul_f32 v[50:51], v[52:53], v[50:51]
	v_lshlrev_b32_e32 v48, 16, v237
	v_and_b32_e32 v49, 0xffff0000, v237
	v_pk_mul_f32 v[52:53], v[58:59], v[64:65] op_sel_hi:[1,0]
	v_cvt_pk_bf16_f32 v50, v50, v51
	v_pk_mul_f32 v[48:49], v[52:53], v[48:49]
	v_pk_mul_f32 v[52:53], v[60:61], v[64:65] op_sel_hi:[1,0]
	v_cvt_pk_bf16_f32 v51, v48, v49
	s_nop 0
	s_nop 0
	global_store_dwordx2 v[230:231], v[50:51], off offset:32
	s_waitcnt vmcnt(13)
	v_lshlrev_b32_e32 v50, 16, v238
	v_and_b32_e32 v51, 0xffff0000, v238
	v_pk_mul_f32 v[50:51], v[52:53], v[50:51]
	v_lshlrev_b32_e32 v48, 16, v239
	v_and_b32_e32 v49, 0xffff0000, v239
	v_pk_mul_f32 v[52:53], v[62:63], v[64:65] op_sel_hi:[1,0]
	v_cvt_pk_bf16_f32 v50, v50, v51
	v_pk_mul_f32 v[48:49], v[52:53], v[48:49]
	s_nop 0
	v_cvt_pk_bf16_f32 v51, v48, v49
	s_nop 0
	s_nop 0
	global_store_dwordx2 v[230:231], v[50:51], off offset:48
	s_waitcnt vmcnt(12)
	v_lshlrev_b32_e32 v50, 16, v240
	v_and_b32_e32 v51, 0xffff0000, v240
	v_lshlrev_b32_e32 v48, 16, v241
	v_and_b32_e32 v49, 0xffff0000, v241
	v_pk_mul_f32 v[32:33], v[32:33], v[50:51]
	v_pk_mul_f32 v[34:35], v[34:35], v[48:49]
	v_cvt_pk_bf16_f32 v32, v32, v33
	v_cvt_pk_bf16_f32 v33, v34, v35
	global_store_dwordx2 v[230:231], v[32:33], off offset:64
	s_nop 0
	s_waitcnt vmcnt(10)
	v_lshlrev_b32_e32 v34, 16, v242
	v_and_b32_e32 v35, 0xffff0000, v242
	v_pk_mul_f32 v[34:35], v[36:37], v[34:35]
	v_lshlrev_b32_e32 v32, 16, v243
	v_and_b32_e32 v33, 0xffff0000, v243
	v_pk_mul_f32 v[36:37], v[38:39], v[64:65] op_sel_hi:[1,0]
	v_cvt_pk_bf16_f32 v34, v34, v35
	v_pk_mul_f32 v[32:33], v[36:37], v[32:33]
	v_pk_mul_f32 v[36:37], v[40:41], v[64:65] op_sel_hi:[1,0]
	v_cvt_pk_bf16_f32 v35, v32, v33
	s_nop 0
	s_nop 0
	global_store_dwordx2 v[230:231], v[34:35], off offset:80
	s_waitcnt vmcnt(10)
	v_lshlrev_b32_e32 v34, 16, v244
	v_and_b32_e32 v35, 0xffff0000, v244
	v_pk_mul_f32 v[34:35], v[36:37], v[34:35]
	v_lshlrev_b32_e32 v32, 16, v245
	v_and_b32_e32 v33, 0xffff0000, v245
	v_pk_mul_f32 v[36:37], v[42:43], v[64:65] op_sel_hi:[1,0]
	v_cvt_pk_bf16_f32 v34, v34, v35
	v_pk_mul_f32 v[32:33], v[36:37], v[32:33]
	v_pk_mul_f32 v[36:37], v[44:45], v[64:65] op_sel_hi:[1,0]
	v_cvt_pk_bf16_f32 v35, v32, v33
	s_nop 0
	s_nop 0
	global_store_dwordx2 v[230:231], v[34:35], off offset:96
	s_waitcnt vmcnt(9)
	v_lshlrev_b32_e32 v34, 16, v246
	v_and_b32_e32 v35, 0xffff0000, v246
	v_pk_mul_f32 v[34:35], v[36:37], v[34:35]
	v_lshlrev_b32_e32 v32, 16, v247
	v_and_b32_e32 v33, 0xffff0000, v247
	v_pk_mul_f32 v[36:37], v[46:47], v[64:65] op_sel_hi:[1,0]
	v_cvt_pk_bf16_f32 v34, v34, v35
	v_pk_mul_f32 v[32:33], v[36:37], v[32:33]
	s_nop 0
	v_cvt_pk_bf16_f32 v35, v32, v33
	s_nop 0
	s_nop 0
	global_store_dwordx2 v[230:231], v[34:35], off offset:112
	s_waitcnt vmcnt(8)
; DI float bflo(unsigned u) { return __uint_as_float(u << 16); }
; DI float bfhi(unsigned u) { return __uint_as_float(u & 0xffff0000u); }
; DI void st_bf4(u16* p, float a, float b, float c, float d) { *(uint2*)p = make_uint2(pk2(a, b), pk2(c, d)); }
; DI void attn_item(const u16* __restrict__ qbuf, const u16* __restrict__ knope, const u16* __restrict__ krope, ...
;     ...
; #pragma unroll
;     for (int vt4 = 0; vt4 < 4; ++vt4)
; #pragma unroll
;       for (int a = 0; a < 4; ++a) {
;         u16* q = op + vt4 * 32 + 8 * a;
;         const uint2 gt = *(const uint2*)q;
;         st_bf4(q, oacc[vt4][4 * a] * inv * bflo(gt.x), oacc[vt4][4 * a + 1] * inv * bfhi(gt.x),
;                oacc[vt4][4 * a + 2] * inv * bflo(gt.y), oacc[vt4][4 * a + 3] * inv * bfhi(gt.y));
	v_lshlrev_b32_e32 v34, 16, v248
	v_and_b32_e32 v35, 0xffff0000, v248
	v_lshlrev_b32_e32 v32, 16, v249
	v_and_b32_e32 v33, 0xffff0000, v249
	v_pk_mul_f32 v[16:17], v[16:17], v[34:35]
	v_pk_mul_f32 v[18:19], v[18:19], v[32:33]
	v_cvt_pk_bf16_f32 v16, v16, v17
	v_cvt_pk_bf16_f32 v17, v18, v19
	global_store_dwordx2 v[230:231], v[16:17], off offset:128
	s_nop 0
	s_waitcnt vmcnt(6)
	v_lshlrev_b32_e32 v18, 16, v250
	v_and_b32_e32 v19, 0xffff0000, v250
	v_pk_mul_f32 v[18:19], v[20:21], v[18:19]
	v_lshlrev_b32_e32 v16, 16, v251
	v_and_b32_e32 v17, 0xffff0000, v251
	v_pk_mul_f32 v[20:21], v[22:23], v[64:65] op_sel_hi:[1,0]
	v_cvt_pk_bf16_f32 v18, v18, v19
	v_pk_mul_f32 v[16:17], v[20:21], v[16:17]
	v_pk_mul_f32 v[20:21], v[24:25], v[64:65] op_sel_hi:[1,0]
	v_cvt_pk_bf16_f32 v19, v16, v17
	s_nop 0
	s_nop 0
	global_store_dwordx2 v[230:231], v[18:19], off offset:144
	s_waitcnt vmcnt(6)
	v_lshlrev_b32_e32 v18, 16, v186
	v_and_b32_e32 v19, 0xffff0000, v186
	v_pk_mul_f32 v[18:19], v[20:21], v[18:19]
	v_lshlrev_b32_e32 v16, 16, v187
	v_and_b32_e32 v17, 0xffff0000, v187
	v_pk_mul_f32 v[20:21], v[26:27], v[64:65] op_sel_hi:[1,0]
	v_cvt_pk_bf16_f32 v18, v18, v19
	v_pk_mul_f32 v[16:17], v[20:21], v[16:17]
	v_pk_mul_f32 v[20:21], v[28:29], v[64:65] op_sel_hi:[1,0]
	v_cvt_pk_bf16_f32 v19, v16, v17
	s_nop 0
	s_nop 0
	global_store_dwordx2 v[230:231], v[18:19], off offset:160
	s_waitcnt vmcnt(5)
	v_lshlrev_b32_e32 v18, 16, v188
	v_and_b32_e32 v19, 0xffff0000, v188
	v_pk_mul_f32 v[18:19], v[20:21], v[18:19]
	v_lshlrev_b32_e32 v16, 16, v189
	v_and_b32_e32 v17, 0xffff0000, v189
	v_pk_mul_f32 v[20:21], v[30:31], v[64:65] op_sel_hi:[1,0]
	v_cvt_pk_bf16_f32 v18, v18, v19
	v_pk_mul_f32 v[16:17], v[20:21], v[16:17]
	s_nop 0
	v_cvt_pk_bf16_f32 v19, v16, v17
	s_nop 0
	s_nop 0
	global_store_dwordx2 v[230:231], v[18:19], off offset:176
	s_waitcnt vmcnt(4)
	v_lshlrev_b32_e32 v18, 16, v190
	v_and_b32_e32 v19, 0xffff0000, v190
	v_lshlrev_b32_e32 v16, 16, v191
	v_and_b32_e32 v17, 0xffff0000, v191
	v_pk_mul_f32 v[0:1], v[0:1], v[18:19]
	v_pk_mul_f32 v[2:3], v[2:3], v[16:17]
	v_cvt_pk_bf16_f32 v0, v0, v1
	v_cvt_pk_bf16_f32 v1, v2, v3
	global_store_dwordx2 v[230:231], v[0:1], off offset:192
	s_nop 0
	s_waitcnt vmcnt(2)
	v_lshlrev_b32_e32 v2, 16, v192
	v_and_b32_e32 v3, 0xffff0000, v192
	v_pk_mul_f32 v[2:3], v[4:5], v[2:3]
	v_lshlrev_b32_e32 v0, 16, v193
	v_and_b32_e32 v1, 0xffff0000, v193
	v_pk_mul_f32 v[4:5], v[6:7], v[64:65] op_sel_hi:[1,0]
	v_cvt_pk_bf16_f32 v2, v2, v3
	v_pk_mul_f32 v[0:1], v[4:5], v[0:1]
	v_pk_mul_f32 v[4:5], v[8:9], v[64:65] op_sel_hi:[1,0]
	v_cvt_pk_bf16_f32 v3, v0, v1
	s_nop 0
	s_nop 0
	global_store_dwordx2 v[230:231], v[2:3], off offset:208
	s_waitcnt vmcnt(2)
	v_lshlrev_b32_e32 v2, 16, v194
	v_and_b32_e32 v3, 0xffff0000, v194
	v_pk_mul_f32 v[2:3], v[4:5], v[2:3]
	v_lshlrev_b32_e32 v0, 16, v195
	v_and_b32_e32 v1, 0xffff0000, v195
	v_pk_mul_f32 v[4:5], v[10:11], v[64:65] op_sel_hi:[1,0]
	v_cvt_pk_bf16_f32 v2, v2, v3
	v_pk_mul_f32 v[0:1], v[4:5], v[0:1]
	v_pk_mul_f32 v[4:5], v[12:13], v[64:65] op_sel_hi:[1,0]
	v_cvt_pk_bf16_f32 v3, v0, v1
	s_nop 0
	s_nop 0
	global_store_dwordx2 v[230:231], v[2:3], off offset:224
	s_waitcnt vmcnt(1)
	v_lshlrev_b32_e32 v2, 16, v196
	v_and_b32_e32 v3, 0xffff0000, v196
	v_pk_mul_f32 v[2:3], v[4:5], v[2:3]
	v_lshlrev_b32_e32 v0, 16, v197
	v_and_b32_e32 v1, 0xffff0000, v197
	v_pk_mul_f32 v[4:5], v[14:15], v[64:65] op_sel_hi:[1,0]
	v_cvt_pk_bf16_f32 v2, v2, v3
	v_pk_mul_f32 v[0:1], v[4:5], v[0:1]
	s_nop 0
	v_cvt_pk_bf16_f32 v3, v0, v1
	global_store_dwordx2 v[230:231], v[2:3], off offset:240
	v_mov_b32_e32 v66, v230
	v_mov_b32_e32 v67, v231

; DI float bflo(unsigned u) { return __uint_as_float(u << 16); }
; DI float bfhi(unsigned u) { return __uint_as_float(u & 0xffff0000u); }
; DI void st_bf4(u16* p, float a, float b, float c, float d) { *(uint2*)p = make_uint2(pk2(a, b), pk2(c, d)); }
; DI void attn_item(const u16* __restrict__ qbuf, const u16* __restrict__ knope, const u16* __restrict__ krope, ...
;     ...
;   const float lt_probe = l_run + oacc[0][0] + oacc[1][5] + oacc[2][9] + oacc[3][15];
;   if (active && (!dry || lt_probe == 123456.789f)) {
;     const float lt = l_run + __shfl_xor(l_run, 32, 64);
;     const float inv = 1.f / lt;
;     u16* op = ao + (size_t)qrow * 1024 + head * 128 + 4 * h2;
; #pragma unroll
;     for (int vt4 = 0; vt4 < 4; ++vt4)
; #pragma unroll
;       for (int a = 0; a < 4; ++a) {
;         u16* q = op + vt4 * 32 + 8 * a;
;         const uint2 gt = *(const uint2*)q;
;         st_bf4(q, oacc[vt4][4 * a] * inv * bflo(gt.x), oacc[vt4][4 * a + 1] * inv * bfhi(gt.x),
;                oacc[vt4][4 * a + 2] * inv * bflo(gt.y), oacc[vt4][4 * a + 3] * inv * bfhi(gt.y));
;       }
.LBB0_75:
	s_xor_b64 s[40:41], s[82:83], -1
	s_and_saveexec_b64 s[42:43], s[38:39]
	s_cbranch_execz .LBB0_59
	v_cmp_lt_i32_e32 vcc, v206, v205
	v_ashrrev_i32_e32 v145, 31, v144
	v_lshlrev_b32_e32 v182, 3, v147
	v_cndmask_b32_e32 v64, v204, v206, vcc
	v_lshlrev_b32_e32 v64, 2, v64
	ds_bpermute_b32 v64, v64, v164
	s_waitcnt lgkmcnt(0)
	v_lshlrev_b64 v[224:225], 11, v[144:145]
	v_lshl_add_u64 v[226:227], s[80:81], 0, v[224:225]
	v_lshl_add_u64 v[228:229], v[226:227], 0, v[182:183]
	global_load_dwordx2 v[230:231], v[228:229], off
	global_load_dwordx2 v[232:233], v[228:229], off offset:16
	global_load_dwordx2 v[234:235], v[228:229], off offset:32
	global_load_dwordx2 v[236:237], v[228:229], off offset:48
	global_load_dwordx2 v[238:239], v[228:229], off offset:64
	global_load_dwordx2 v[240:241], v[228:229], off offset:80
	global_load_dwordx2 v[242:243], v[228:229], off offset:96
	global_load_dwordx2 v[244:245], v[228:229], off offset:112
	global_load_dwordx2 v[246:247], v[228:229], off offset:128
	global_load_dwordx2 v[248:249], v[228:229], off offset:144
	global_load_dwordx2 v[250:251], v[228:229], off offset:160
	global_load_dwordx2 v[186:187], v[228:229], off offset:176
	global_load_dwordx2 v[188:189], v[228:229], off offset:192
	global_load_dwordx2 v[190:191], v[228:229], off offset:208
	global_load_dwordx2 v[192:193], v[228:229], off offset:224
	global_load_dwordx2 v[194:195], v[228:229], off offset:240
	v_add_f32_e32 v64, v164, v64
	v_div_scale_f32 v65, s[10:11], v64, v64, 1.0
	v_rcp_f32_e32 v66, v65
	s_nop 0
	v_fma_f32 v67, -v65, v66, 1.0
	v_fmac_f32_e32 v66, v67, v66
	v_div_scale_f32 v67, vcc, 1.0, v64, 1.0
	v_mul_f32_e32 v68, v67, v66
	v_fma_f32 v69, -v65, v68, v67
	v_fmac_f32_e32 v68, v69, v66
	v_fma_f32 v65, -v65, v68, v67
	v_div_fmas_f32 v65, v65, v66, v68
	s_nop 0
	s_nop 0
	s_nop 0
	s_nop 0
	v_div_fixup_f32 v64, v65, v64, 1.0
	v_pk_mul_f32 v[48:49], v[48:49], v[64:65] op_sel_hi:[1,0]
	v_pk_mul_f32 v[50:51], v[50:51], v[64:65] op_sel_hi:[1,0]
	v_pk_mul_f32 v[52:53], v[52:53], v[64:65] op_sel_hi:[1,0]
	v_pk_mul_f32 v[32:33], v[32:33], v[64:65] op_sel_hi:[1,0]
	v_pk_mul_f32 v[34:35], v[34:35], v[64:65] op_sel_hi:[1,0]
	v_pk_mul_f32 v[36:37], v[36:37], v[64:65] op_sel_hi:[1,0]
	v_pk_mul_f32 v[16:17], v[16:17], v[64:65] op_sel_hi:[1,0]
	v_pk_mul_f32 v[18:19], v[18:19], v[64:65] op_sel_hi:[1,0]
	v_pk_mul_f32 v[20:21], v[20:21], v[64:65] op_sel_hi:[1,0]
	v_pk_mul_f32 v[0:1], v[0:1], v[64:65] op_sel_hi:[1,0]
	v_pk_mul_f32 v[2:3], v[2:3], v[64:65] op_sel_hi:[1,0]
	v_pk_mul_f32 v[4:5], v[4:5], v[64:65] op_sel_hi:[1,0]
	s_waitcnt vmcnt(15)
	v_lshlrev_b32_e32 v70, 16, v230
	v_and_b32_e32 v71, 0xffff0000, v230
	v_lshlrev_b32_e32 v68, 16, v231
	v_and_b32_e32 v69, 0xffff0000, v231
	v_pk_mul_f32 v[48:49], v[48:49], v[70:71]
	v_pk_mul_f32 v[50:51], v[50:51], v[68:69]
	v_cvt_pk_bf16_f32 v48, v48, v49
	v_cvt_pk_bf16_f32 v49, v50, v51
	global_store_dwordx2 v[228:229], v[48:49], off
	s_nop 0
	s_waitcnt vmcnt(14)
	v_lshlrev_b32_e32 v50, 16, v232
	v_and_b32_e32 v51, 0xffff0000, v232
	v_pk_mul_f32 v[50:51], v[52:53], v[50:51]
	v_lshlrev_b32_e32 v48, 16, v233
	v_and_b32_e32 v49, 0xffff0000, v233
	v_pk_mul_f32 v[52:53], v[54:55], v[64:65] op_sel_hi:[1,0]
	v_cvt_pk_bf16_f32 v50, v50, v51
	v_pk_mul_f32 v[48:49], v[52:53], v[48:49]
	v_pk_mul_f32 v[52:53], v[56:57], v[64:65] op_sel_hi:[1,0]
	v_cvt_pk_bf16_f32 v51, v48, v49
	s_nop 0
	s_nop 0
	global_store_dwordx2 v[228:229], v[50:51], off offset:16
	s_waitcnt vmcnt(14)
	v_lshlrev_b32_e32 v50, 16, v234
	v_and_b32_e32 v51, 0xffff0000, v234
	v_pk_mul_f32 v[50:51], v[52:53], v[50:51]
	v_lshlrev_b32_e32 v48, 16, v235
	v_and_b32_e32 v49, 0xffff0000, v235
	v_pk_mul_f32 v[52:53], v[58:59], v[64:65] op_sel_hi:[1,0]
	v_cvt_pk_bf16_f32 v50, v50, v51
	v_pk_mul_f32 v[48:49], v[52:53], v[48:49]
	v_pk_mul_f32 v[52:53], v[60:61], v[64:65] op_sel_hi:[1,0]
	v_cvt_pk_bf16_f32 v51, v48, v49
	s_nop 0
	s_nop 0
	global_store_dwordx2 v[228:229], v[50:51], off offset:32
	s_waitcnt vmcnt(13)
	v_lshlrev_b32_e32 v50, 16, v236
	v_and_b32_e32 v51, 0xffff0000, v236
	v_pk_mul_f32 v[50:51], v[52:53], v[50:51]
	v_lshlrev_b32_e32 v48, 16, v237
	v_and_b32_e32 v49, 0xffff0000, v237
	v_pk_mul_f32 v[52:53], v[62:63], v[64:65] op_sel_hi:[1,0]
	v_cvt_pk_bf16_f32 v50, v50, v51
	v_pk_mul_f32 v[48:49], v[52:53], v[48:49]
	s_nop 0
	v_cvt_pk_bf16_f32 v51, v48, v49
	s_nop 0
	s_nop 0
	global_store_dwordx2 v[228:229], v[50:51], off offset:48
	s_waitcnt vmcnt(12)
	v_lshlrev_b32_e32 v50, 16, v238
	v_and_b32_e32 v51, 0xffff0000, v238
	v_lshlrev_b32_e32 v48, 16, v239
	v_and_b32_e32 v49, 0xffff0000, v239
	v_pk_mul_f32 v[32:33], v[32:33], v[50:51]
	v_pk_mul_f32 v[34:35], v[34:35], v[48:49]
	v_cvt_pk_bf16_f32 v32, v32, v33
	v_cvt_pk_bf16_f32 v33, v34, v35
	global_store_dwordx2 v[228:229], v[32:33], off offset:64
	s_nop 0
	s_waitcnt vmcnt(10)
; DI float bflo(unsigned u) { return __uint_as_float(u << 16); }
; DI float bfhi(unsigned u) { return __uint_as_float(u & 0xffff0000u); }
; DI void st_bf4(u16* p, float a, float b, float c, float d) { *(uint2*)p = make_uint2(pk2(a, b), pk2(c, d)); }
; DI void attn_item(const u16* __restrict__ qbuf, const u16* __restrict__ knope, const u16* __restrict__ krope, ...
;     ...
; #pragma unroll
;     for (int vt4 = 0; vt4 < 4; ++vt4)
; #pragma unroll
;       for (int a = 0; a < 4; ++a) {
;         u16* q = op + vt4 * 32 + 8 * a;
;         const uint2 gt = *(const uint2*)q;
;         st_bf4(q, oacc[vt4][4 * a] * inv * bflo(gt.x), oacc[vt4][4 * a + 1] * inv * bfhi(gt.x),
;                oacc[vt4][4 * a + 2] * inv * bflo(gt.y), oacc[vt4][4 * a + 3] * inv * bfhi(gt.y));
	v_lshlrev_b32_e32 v34, 16, v240
	v_and_b32_e32 v35, 0xffff0000, v240
	v_pk_mul_f32 v[34:35], v[36:37], v[34:35]
	v_lshlrev_b32_e32 v32, 16, v241
	v_and_b32_e32 v33, 0xffff0000, v241
	v_pk_mul_f32 v[36:37], v[38:39], v[64:65] op_sel_hi:[1,0]
	v_cvt_pk_bf16_f32 v34, v34, v35
	v_pk_mul_f32 v[32:33], v[36:37], v[32:33]
	v_pk_mul_f32 v[36:37], v[40:41], v[64:65] op_sel_hi:[1,0]
	v_cvt_pk_bf16_f32 v35, v32, v33
	s_nop 0
	s_nop 0
	global_store_dwordx2 v[228:229], v[34:35], off offset:80
	s_waitcnt vmcnt(10)
	v_lshlrev_b32_e32 v34, 16, v242
	v_and_b32_e32 v35, 0xffff0000, v242
	v_pk_mul_f32 v[34:35], v[36:37], v[34:35]
	v_lshlrev_b32_e32 v32, 16, v243
	v_and_b32_e32 v33, 0xffff0000, v243
	v_pk_mul_f32 v[36:37], v[42:43], v[64:65] op_sel_hi:[1,0]
	v_cvt_pk_bf16_f32 v34, v34, v35
	v_pk_mul_f32 v[32:33], v[36:37], v[32:33]
	v_pk_mul_f32 v[36:37], v[44:45], v[64:65] op_sel_hi:[1,0]
	v_cvt_pk_bf16_f32 v35, v32, v33
	s_nop 0
	s_nop 0
	global_store_dwordx2 v[228:229], v[34:35], off offset:96
	s_waitcnt vmcnt(9)
	v_lshlrev_b32_e32 v34, 16, v244
	v_and_b32_e32 v35, 0xffff0000, v244
	v_pk_mul_f32 v[34:35], v[36:37], v[34:35]
	v_lshlrev_b32_e32 v32, 16, v245
	v_and_b32_e32 v33, 0xffff0000, v245
	v_pk_mul_f32 v[36:37], v[46:47], v[64:65] op_sel_hi:[1,0]
	v_cvt_pk_bf16_f32 v34, v34, v35
	v_pk_mul_f32 v[32:33], v[36:37], v[32:33]
	s_nop 0
	v_cvt_pk_bf16_f32 v35, v32, v33
	s_nop 0
	s_nop 0
	global_store_dwordx2 v[228:229], v[34:35], off offset:112
	s_waitcnt vmcnt(8)
	v_lshlrev_b32_e32 v34, 16, v246
	v_and_b32_e32 v35, 0xffff0000, v246
	v_lshlrev_b32_e32 v32, 16, v247
	v_and_b32_e32 v33, 0xffff0000, v247
	v_pk_mul_f32 v[16:17], v[16:17], v[34:35]
	v_pk_mul_f32 v[18:19], v[18:19], v[32:33]
	v_cvt_pk_bf16_f32 v16, v16, v17
	v_cvt_pk_bf16_f32 v17, v18, v19
	global_store_dwordx2 v[228:229], v[16:17], off offset:128
	s_nop 0
	s_waitcnt vmcnt(6)
	v_lshlrev_b32_e32 v18, 16, v248
	v_and_b32_e32 v19, 0xffff0000, v248
	v_pk_mul_f32 v[18:19], v[20:21], v[18:19]
	v_lshlrev_b32_e32 v16, 16, v249
	v_and_b32_e32 v17, 0xffff0000, v249
	v_pk_mul_f32 v[20:21], v[22:23], v[64:65] op_sel_hi:[1,0]
	v_cvt_pk_bf16_f32 v18, v18, v19
	v_pk_mul_f32 v[16:17], v[20:21], v[16:17]
	v_pk_mul_f32 v[20:21], v[24:25], v[64:65] op_sel_hi:[1,0]
	v_cvt_pk_bf16_f32 v19, v16, v17
	s_nop 0
	s_nop 0
	global_store_dwordx2 v[228:229], v[18:19], off offset:144
	s_waitcnt vmcnt(6)
	v_lshlrev_b32_e32 v18, 16, v250
	v_and_b32_e32 v19, 0xffff0000, v250
	v_pk_mul_f32 v[18:19], v[20:21], v[18:19]
	v_lshlrev_b32_e32 v16, 16, v251
	v_and_b32_e32 v17, 0xffff0000, v251
	v_pk_mul_f32 v[20:21], v[26:27], v[64:65] op_sel_hi:[1,0]
	v_cvt_pk_bf16_f32 v18, v18, v19
	v_pk_mul_f32 v[16:17], v[20:21], v[16:17]
	v_pk_mul_f32 v[20:21], v[28:29], v[64:65] op_sel_hi:[1,0]
	v_cvt_pk_bf16_f32 v19, v16, v17
	s_nop 0
	s_nop 0
	global_store_dwordx2 v[228:229], v[18:19], off offset:160
	s_waitcnt vmcnt(5)
	v_lshlrev_b32_e32 v18, 16, v186
	v_and_b32_e32 v19, 0xffff0000, v186
	v_pk_mul_f32 v[18:19], v[20:21], v[18:19]
	v_lshlrev_b32_e32 v16, 16, v187
	v_and_b32_e32 v17, 0xffff0000, v187
	v_pk_mul_f32 v[20:21], v[30:31], v[64:65] op_sel_hi:[1,0]
	v_cvt_pk_bf16_f32 v18, v18, v19
	v_pk_mul_f32 v[16:17], v[20:21], v[16:17]
	s_nop 0
	v_cvt_pk_bf16_f32 v19, v16, v17
	s_nop 0
	s_nop 0
	global_store_dwordx2 v[228:229], v[18:19], off offset:176
	s_waitcnt vmcnt(4)
	v_lshlrev_b32_e32 v18, 16, v188
	v_and_b32_e32 v19, 0xffff0000, v188
	v_lshlrev_b32_e32 v16, 16, v189
	v_and_b32_e32 v17, 0xffff0000, v189
	v_pk_mul_f32 v[0:1], v[0:1], v[18:19]
	v_pk_mul_f32 v[2:3], v[2:3], v[16:17]
	v_cvt_pk_bf16_f32 v0, v0, v1
	v_cvt_pk_bf16_f32 v1, v2, v3
	global_store_dwordx2 v[228:229], v[0:1], off offset:192
	s_nop 0
	s_waitcnt vmcnt(2)
	v_lshlrev_b32_e32 v2, 16, v190
	v_and_b32_e32 v3, 0xffff0000, v190
	v_pk_mul_f32 v[2:3], v[4:5], v[2:3]
	v_lshlrev_b32_e32 v0, 16, v191
	v_and_b32_e32 v1, 0xffff0000, v191
	v_pk_mul_f32 v[4:5], v[6:7], v[64:65] op_sel_hi:[1,0]
	v_cvt_pk_bf16_f32 v2, v2, v3
	v_pk_mul_f32 v[0:1], v[4:5], v[0:1]
	v_pk_mul_f32 v[4:5], v[8:9], v[64:65] op_sel_hi:[1,0]
	v_cvt_pk_bf16_f32 v3, v0, v1
	s_nop 0
	s_nop 0
	global_store_dwordx2 v[228:229], v[2:3], off offset:208
	s_waitcnt vmcnt(2)
	v_lshlrev_b32_e32 v2, 16, v192
	v_and_b32_e32 v3, 0xffff0000, v192
	v_pk_mul_f32 v[2:3], v[4:5], v[2:3]
	v_lshlrev_b32_e32 v0, 16, v193
	v_and_b32_e32 v1, 0xffff0000, v193
	v_pk_mul_f32 v[4:5], v[10:11], v[64:65] op_sel_hi:[1,0]
	v_cvt_pk_bf16_f32 v2, v2, v3
	v_pk_mul_f32 v[0:1], v[4:5], v[0:1]
	v_pk_mul_f32 v[4:5], v[12:13], v[64:65] op_sel_hi:[1,0]
	v_cvt_pk_bf16_f32 v3, v0, v1
	s_nop 0
	s_nop 0
	global_store_dwordx2 v[228:229], v[2:3], off offset:224
	s_waitcnt vmcnt(1)
	v_lshlrev_b32_e32 v2, 16, v194
	v_and_b32_e32 v3, 0xffff0000, v194
	v_pk_mul_f32 v[2:3], v[4:5], v[2:3]
	v_lshlrev_b32_e32 v0, 16, v195
	v_and_b32_e32 v1, 0xffff0000, v195
	v_pk_mul_f32 v[4:5], v[14:15], v[64:65] op_sel_hi:[1,0]
	v_cvt_pk_bf16_f32 v2, v2, v3
	v_pk_mul_f32 v[0:1], v[4:5], v[0:1]
	s_nop 0
	v_cvt_pk_bf16_f32 v3, v0, v1
	global_store_dwordx2 v[228:229], v[2:3], off offset:240
	v_mov_b32_e32 v66, v228
	v_mov_b32_e32 v67, v229
	s_branch .LBB0_59

; DI int get_bid() { int b = blockIdx.x; asm volatile("" : "+s"(b)); return b; }
; DI unsigned pk2(float a, float b) { f32x2_t f = {a, b}; return __builtin_bit_cast(unsigned, __builtin_convertvector(f, bf16x2_t)); }
; DI float wave_sum(float v) {
; #pragma unroll
;   for (int o = 32; o; o >>= 1) v += __shfl_xor(v, o, 64);
;   return v;
; }
; DI void odd_rows(const Params& p, int o) {
;     ...
;   for (int r = get_bid() * 4 + (tid >> 6); r < M_TOK; r += gridDim.x * 4) {
;     const float* z = zq + (size_t)r * 704;
;     float2 qv[3]; float ss = 0.f;
; #pragma unroll
;     for (int i = 0; i < 3; ++i) { qv[i] = *(const float2*)(z + lane * 2 + 128 * i); ss += qv[i].x * qv[i].x + qv[i].y * qv[i].y; }
;     const float4 kv = *(const float4*)(z + 384 + lane * 4);
;     float sk = kv.x * kv.x + kv.y * kv.y + kv.z * kv.z + kv.w * kv.w;
;     const float kr = z[640 + lane];
;     ss = wave_sum(ss); sk = wave_sum(sk);
;     const float rq = rsqrtf(ss * (1.f / 384.f) + 1e-6f);
;     const float rk = rsqrtf(sk * (1.f / 256.f) + 1e-6f);
; #pragma unroll
;     for (int i = 0; i < 3; ++i) {
;       const float2 w = *(const float2*)(qnw + lane * 2 + 128 * i);
;       *(unsigned*)(qn + (size_t)r * 384 + lane * 2 + 128 * i) = pk2(qv[i].x * rq * w.x, qv[i].y * rq * w.y);
;     }
.LBB0_119:
	v_mov_b64_e32 v[2:3], s[84:85]
	s_movk_i32 s4, 0xb00
	v_mad_i64_i32 v[22:23], s[4:5], v6, s4, v[2:3]
	v_lshlrev_b32_e32 v24, 2, v8
	v_mov_b32_e32 v25, v183
	v_lshl_add_u64 v[2:3], v[22:23], 0, v[24:25]
	v_lshl_add_u64 v[26:27], v[22:23], 0, v[182:183]
	global_load_dwordx4 v[2:5], v[2:3], off offset:1536
	s_nop 0
	global_load_dwordx2 v[28:29], v[26:27], off offset:512
	global_load_dwordx2 v[30:31], v[26:27], off
	global_load_dwordx2 v[32:33], v[26:27], off offset:1024
	global_load_dwordx2 v[40:41], v[10:11], off offset:1536
	v_mov_b32_e32 v21, v183
	v_lshl_add_u64 v[22:23], v[22:23], 0, v[20:21]
	global_load_dword v21, v[22:23], off offset:2560
	s_mov_b32 s4, 0x3b800000
	s_mov_b32 s5, 0x3b2aaaab
	s_waitcnt vmcnt(4)
	v_pk_mul_f32 v[42:43], v[28:29], v[28:29]
	s_waitcnt vmcnt(3)
	v_mov_b32_e32 v46, v31
	s_waitcnt vmcnt(2)
	v_mov_b32_e32 v47, v33
	v_pk_mul_f32 v[22:23], v[2:3], v[2:3]
	v_mov_b32_e32 v44, v30
	v_mov_b32_e32 v45, v32
	v_pk_mul_f32 v[46:47], v[46:47], v[46:47]
	v_pk_mul_f32 v[26:27], v[4:5], v[4:5]
	v_mov_b32_e32 v48, v22
	v_mov_b32_e32 v49, v42
	v_mov_b32_e32 v42, v23
	v_pk_fma_f32 v[44:45], v[44:45], v[44:45], v[46:47]
	v_mov_b32_e32 v22, v26
	v_pk_add_f32 v[42:43], v[48:49], v[42:43]
	v_mov_b32_e32 v23, v44
	v_mov_b32_e32 v44, v27
	v_pk_add_f32 v[22:23], v[42:43], v[22:23]
	s_nop 0
	v_pk_add_f32 v[22:23], v[22:23], v[44:45]
	v_mov_b32_e32 v26, v22
	v_mov_b32_e32 v27, v23
	s_nop 1
	v_permlane32_swap_b32_e32 v22, v26
	v_permlane32_swap_b32_e32 v23, v27
	s_waitcnt lgkmcnt(0)
	v_pk_add_f32 v[22:23], v[22:23], v[26:27]
	v_mov_b32_e32 v26, v22
	v_mov_b32_e32 v27, v23
	s_nop 1
	v_permlane16_swap_b32_e32 v22, v26
	v_permlane16_swap_b32_e32 v23, v27
	s_waitcnt lgkmcnt(0)
	v_pk_add_f32 v[22:23], v[22:23], v[26:27]
	s_nop 1
	v_mov_b32_dpp v26, v22 row_ror:8 row_mask:0xf bank_mask:0xf
	v_mov_b32_dpp v27, v23 row_ror:8 row_mask:0xf bank_mask:0xf
	s_waitcnt lgkmcnt(0)
	v_pk_add_f32 v[22:23], v[22:23], v[26:27]
	s_nop 1
	v_mov_b32_dpp v26, v22 row_ror:4 row_mask:0xf bank_mask:0xf
	v_mov_b32_dpp v27, v23 row_ror:4 row_mask:0xf bank_mask:0xf
	s_waitcnt lgkmcnt(0)
	v_pk_add_f32 v[22:23], v[22:23], v[26:27]
	s_nop 1
	v_mov_b32_dpp v26, v22 quad_perm:[2,3,0,1] row_mask:0xf bank_mask:0xf
	v_mov_b32_dpp v27, v23 quad_perm:[2,3,0,1] row_mask:0xf bank_mask:0xf
	s_waitcnt lgkmcnt(0)
	v_pk_add_f32 v[22:23], v[22:23], v[26:27]
	s_nop 1
	v_mov_b32_dpp v26, v22 quad_perm:[1,0,3,2] row_mask:0xf bank_mask:0xf
	v_mov_b32_dpp v27, v23 quad_perm:[1,0,3,2] row_mask:0xf bank_mask:0xf
	s_waitcnt lgkmcnt(0)
	v_pk_add_f32 v[22:23], v[22:23], v[26:27]
	s_nop 0
	v_pk_fma_f32 v[26:27], v[22:23], s[4:5], v[184:185] op_sel_hi:[1,1,0]
	s_movk_i32 s4, 0x300
	v_mul_f32_e32 v7, 0x4b800000, v27
	v_cmp_gt_f32_e64 s[38:39], s33, v27
	v_mad_i64_i32 v[22:23], s[4:5], v6, s4, v[12:13]
	s_nop 0
	v_cndmask_b32_e64 v7, v27, v7, s[38:39]
	v_rsq_f32_e32 v7, v7
	s_movk_i32 s4, 0x3fff
	v_cmp_lt_i32_e64 s[40:41], s4, v6
	v_mul_f32_e32 v25, 0x45800000, v7
	v_cndmask_b32_e64 v42, v7, v25, s[38:39]
	v_pk_mul_f32 v[30:31], v[30:31], v[42:43] op_sel_hi:[1,0]
	v_pk_mul_f32 v[28:29], v[28:29], v[42:43] op_sel_hi:[1,0]
	s_waitcnt vmcnt(1)
	v_pk_mul_f32 v[30:31], v[40:41], v[30:31]
	v_cmp_gt_f32_e64 s[38:39], s33, v26
	v_cvt_pk_bf16_f32 v7, v30, v31
	global_store_dword v[22:23], v7, off
	global_load_dwordx2 v[30:31], v[10:11], off offset:2048
	s_waitcnt vmcnt(0)
	v_pk_mul_f32 v[28:29], v[30:31], v[28:29]
	s_nop 0
	v_cvt_pk_bf16_f32 v7, v28, v29
	global_store_dword v[22:23], v7, off offset:256
	global_load_dwordx2 v[28:29], v[10:11], off offset:2560
	v_pk_mul_f32 v[30:31], v[32:33], v[42:43] op_sel_hi:[1,0]
	v_ashrrev_i32_e32 v7, 31, v6
	s_waitcnt vmcnt(0)
	v_pk_mul_f32 v[28:29], v[30:31], v[28:29]
	s_nop 0
	v_cvt_pk_bf16_f32 v25, v28, v29
	global_store_dword v[22:23], v25, off offset:512
	s_and_saveexec_b64 s[4:5], s[40:41]
	s_xor_b64 s[40:41], exec, s[4:5]
	s_cbranch_execz .LBB0_121
	v_add_u32_e32 v22, 0xffffc000, v6
	v_lshrrev_b32_e32 v22, 5, v22
	s_movk_i32 s4, 0x480
	v_and_b32_e32 v25, 31, v6
	v_mul_lo_u32 v22, v22, s4
	s_movk_i32 s4, 0xc200
	v_or_b32_e32 v22, v22, v25
	s_mov_b32 s5, -1
	v_add_u32_e32 v22, 0x4400, v22
	v_mov_b32_e32 v23, v183
	v_or_b32_e32 v27, 0x400, v25
	v_lshl_add_u64 v[28:29], v[6:7], 0, s[4:5]

; DI int get_tid() { int t = threadIdx.x; asm volatile("" : "+v"(t)); return t; }
; DI int get_bid() { int b = blockIdx.x; asm volatile("" : "+s"(b)); return b; }
; DI float bflo(unsigned u) { return __uint_as_float(u << 16); }
; DI float bfhi(unsigned u) { return __uint_as_float(u & 0xffff0000u); }
; DI float wave_sum(float v) {
; #pragma unroll
;   for (int o = 32; o; o >>= 1) v += __shfl_xor(v, o, 64);
;   return v;
; }
; DI void resid_norm(const Params& p, int layer, const u16* __restrict__ y) {
;     ...
;   for (int r = get_bid() * 4 + (get_tid() >> 6); r < M_TOK; r += gridDim.x * 4) {
;     const float* x;
;     if (layer == 0) x = r < M_PROMPT ? p.x_prompt + (size_t)r * 1024 : p.x_sample + (size_t)(r - M_PROMPT) * 1024;
;     else x = p.out + (size_t)r * 1024;
;     float4 yv[4], xv[4]; float ss = 0.f;
; #pragma unroll
;     for (int i = 0; i < 4; ++i) {
;       { const uint2 yq = *(const uint2*)(y + (size_t)r * 1024 + lane * 4 + 256 * i); yv[i] = make_float4(bflo(yq.x), bfhi(yq.x), bflo(yq.y), bfhi(yq.y)); }
;       { const f32x4 t4 = __builtin_nontemporal_load((const f32x4*)(x + lane * 4 + 256 * i)); xv[i] = make_float4(t4[0], t4[1], t4[2], t4[3]); }
;       ss += yv[i].x * yv[i].x + yv[i].y * yv[i].y + yv[i].z * yv[i].z + yv[i].w * yv[i].w;
;     }
;     ss = wave_sum(ss);
;     const float rs = rsqrtf(ss * (1.f / 1024.f) + 1e-6f);
;     float ss2 = 0.f;
; #pragma unroll
;     for (int i = 0; i < 4; ++i) {
;       const float4 gg = *(const float4*)(gpost + lane * 4 + 256 * i);
;       xv[i].x += yv[i].x * rs * gg.x; xv[i].y += yv[i].y * rs * gg.y; xv[i].z += yv[i].z * rs * gg.z; xv[i].w += yv[i].w * rs * gg.w;
;       __builtin_nontemporal_store((f32x4){xv[i].x, xv[i].y, xv[i].z, xv[i].w}, (f32x4*)(p.out + (size_t)r * 1024 + lane * 4 + 256 * i));
;       ss2 += xv[i].x * xv[i].x + xv[i].y * xv[i].y + xv[i].z * xv[i].z + xv[i].w * xv[i].w;
.LBB0_249:
	v_ashrrev_i32_e32 v3, 31, v2
	v_lshlrev_b64 v[14:15], 11, v[2:3]
	v_lshl_add_u64 v[22:23], v[4:5], 0, v[14:15]
	global_load_dwordx2 v[30:31], v[22:23], off
	global_load_dwordx2 v[32:33], v[22:23], off offset:512
	global_load_dwordx2 v[34:35], v[22:23], off offset:1024
	global_load_dwordx2 v[36:37], v[22:23], off offset:1536
	s_nop 0
	global_load_dwordx4 v[22:25], v[6:7], off
	v_lshlrev_b64 v[26:27], 12, v[2:3]
	v_lshl_add_u64 v[42:43], v[12:13], 0, v[26:27]
	global_load_dwordx4 v[26:29], v[42:43], off nt
	v_lshl_add_u64 v[14:15], v[10:11], 0, v[14:15]
	v_add_u32_e32 v2, s3, v2
	s_waitcnt vmcnt(5)
	v_and_b32_e32 v39, 0xffff0000, v30
	s_waitcnt vmcnt(4)
	v_and_b32_e32 v45, 0xffff0000, v32
	v_lshlrev_b32_e32 v38, 16, v30
	v_lshlrev_b32_e32 v44, 16, v32
	v_lshlrev_b32_e32 v46, 16, v33
	v_and_b32_e32 v47, 0xffff0000, v33
	s_waitcnt vmcnt(3)
	v_and_b32_e32 v49, 0xffff0000, v34
	s_waitcnt vmcnt(2)
	v_and_b32_e32 v53, 0xffff0000, v36
	v_mov_b32_e32 v32, v39
	v_mov_b32_e32 v33, v45
	v_lshlrev_b32_e32 v40, 16, v31
	v_and_b32_e32 v41, 0xffff0000, v31
	v_lshlrev_b32_e32 v48, 16, v34
	v_lshlrev_b32_e32 v52, 16, v36
	v_mov_b32_e32 v30, v38
	v_mov_b32_e32 v31, v44
	v_mov_b32_e32 v58, v49
	v_mov_b32_e32 v59, v53
	v_pk_mul_f32 v[32:33], v[32:33], v[32:33]
	v_lshlrev_b32_e32 v50, 16, v35
	v_and_b32_e32 v51, 0xffff0000, v35
	v_lshlrev_b32_e32 v54, 16, v37
	v_mov_b32_e32 v34, v40
	v_mov_b32_e32 v35, v46
	v_mov_b32_e32 v56, v48
	v_mov_b32_e32 v57, v52
	v_pk_mul_f32 v[58:59], v[58:59], v[58:59]
	v_pk_fma_f32 v[30:31], v[30:31], v[30:31], v[32:33]
	v_and_b32_e32 v55, 0xffff0000, v37
	v_mov_b32_e32 v36, v41
	v_mov_b32_e32 v37, v47
	v_mov_b32_e32 v60, v50
	v_mov_b32_e32 v61, v54
	v_pk_fma_f32 v[32:33], v[56:57], v[56:57], v[58:59]
	v_pk_fma_f32 v[30:31], v[34:35], v[34:35], v[30:31]
	v_mov_b32_e32 v62, v51
	v_mov_b32_e32 v63, v55
	v_pk_fma_f32 v[32:33], v[60:61], v[60:61], v[32:33]
	v_pk_fma_f32 v[30:31], v[36:37], v[36:37], v[30:31]
	v_pk_fma_f32 v[32:33], v[62:63], v[62:63], v[32:33]
	v_add_f32_e32 v3, v30, v31
	v_add_f32_e32 v3, v3, v32
	v_add_f32_e32 v3, v3, v33
	v_mov_b32_e32 v21, v3
	s_nop 1
	v_permlane32_swap_b32_e32 v3, v21
	global_load_dwordx4 v[30:33], v[42:43], off offset:1024 nt
	s_waitcnt lgkmcnt(0)
	v_add_f32_e32 v3, v3, v21
	v_mov_b32_e32 v21, v3
	s_nop 1
	v_permlane16_swap_b32_e32 v3, v21
	s_waitcnt lgkmcnt(0)
	v_add_f32_e32 v3, v3, v21
	s_nop 1
	v_mov_b32_dpp v21, v3 row_ror:8 row_mask:0xf bank_mask:0xf
	s_waitcnt lgkmcnt(0)
	v_add_f32_e32 v3, v3, v21
	s_nop 1
	v_mov_b32_dpp v21, v3 row_ror:4 row_mask:0xf bank_mask:0xf
	s_waitcnt lgkmcnt(0)
	v_add_f32_e32 v3, v3, v21
	s_nop 1
	v_mov_b32_dpp v21, v3 quad_perm:[2,3,0,1] row_mask:0xf bank_mask:0xf
	s_waitcnt lgkmcnt(0)
	v_add_f32_e32 v3, v3, v21
	s_nop 1
	v_mov_b32_dpp v21, v3 quad_perm:[1,0,3,2] row_mask:0xf bank_mask:0xf
	s_waitcnt lgkmcnt(0)
	v_add_f32_e32 v3, v3, v21
	v_fmamk_f32 v3, v3, 0x3a800000, v184
	v_mul_f32_e32 v21, 0x4b800000, v3
	v_cmp_gt_f32_e32 vcc, s33, v3
	s_nop 1
	v_cndmask_b32_e32 v3, v3, v21, vcc
	v_rsq_f32_e32 v3, v3
	s_nop 0
	v_mul_f32_e32 v21, 0x45800000, v3
	v_cndmask_b32_e32 v56, v3, v21, vcc
	v_pk_mul_f32 v[34:35], v[56:57], v[38:39] op_sel_hi:[0,1]
	v_pk_mul_f32 v[36:37], v[56:57], v[40:41] op_sel_hi:[0,1]
	s_waitcnt vmcnt(1)
	v_pk_fma_f32 v[22:23], v[22:23], v[34:35], v[26:27]
	v_pk_fma_f32 v[24:25], v[24:25], v[36:37], v[28:29]
	global_store_dwordx4 v[42:43], v[22:25], off nt
	global_load_dwordx4 v[26:29], v[6:7], off offset:1024
	v_pk_mul_f32 v[34:35], v[56:57], v[44:45] op_sel_hi:[0,1]
	v_pk_mul_f32 v[36:37], v[56:57], v[46:47] op_sel_hi:[0,1]
	v_pk_mul_f32 v[44:45], v[56:57], v[48:49] op_sel_hi:[0,1]
	v_pk_mul_f32 v[46:47], v[56:57], v[50:51] op_sel_hi:[0,1]
	v_mov_b32_e32 v48, v25
	s_waitcnt vmcnt(0)
	v_pk_fma_f32 v[26:27], v[26:27], v[34:35], v[30:31]
	v_pk_fma_f32 v[28:29], v[28:29], v[36:37], v[32:33]
	global_store_dwordx4 v[42:43], v[26:29], off offset:1024 nt
	global_load_dwordx4 v[30:33], v[6:7], off offset:2048
	global_load_dwordx4 v[34:37], v[42:43], off offset:2048 nt
	global_load_dwordx4 v[38:41], v[42:43], off offset:3072 nt
	v_mov_b32_e32 v49, v29
	s_waitcnt vmcnt(1)
; DI void st_bf4(u16* p, float a, float b, float c, float d) { *(uint2*)p = make_uint2(pk2(a, b), pk2(c, d)); }
; DI float wave_sum(float v) {
; #pragma unroll
;   for (int o = 32; o; o >>= 1) v += __shfl_xor(v, o, 64);
;   return v;
; }
; DI void resid_norm(const Params& p, int layer, const u16* __restrict__ y) {
;     ...
;     for (int i = 0; i < 4; ++i) {
;       const float4 gg = *(const float4*)(gpost + lane * 4 + 256 * i);
;       xv[i].x += yv[i].x * rs * gg.x; xv[i].y += yv[i].y * rs * gg.y; xv[i].z += yv[i].z * rs * gg.z; xv[i].w += yv[i].w * rs * gg.w;
;       __builtin_nontemporal_store((f32x4){xv[i].x, xv[i].y, xv[i].z, xv[i].w}, (f32x4*)(p.out + (size_t)r * 1024 + lane * 4 + 256 * i));
;       ss2 += xv[i].x * xv[i].x + xv[i].y * xv[i].y + xv[i].z * xv[i].z + xv[i].w * xv[i].w;
;     }
;     if (layer < 3) {
;       ss2 = wave_sum(ss2);
;       const float rs2 = rsqrtf(ss2 * (1.f / 1024.f) + 1e-6f);
; #pragma unroll
;       for (int i = 0; i < 4; ++i) {
;         const float4 gg = *(const float4*)(gpre + lane * 4 + 256 * i);
;         st_bf4(h + (size_t)r * 1024 + lane * 4 + 256 * i, xv[i].x * rs2 * gg.x, xv[i].y * rs2 * gg.y, xv[i].z * rs2 * gg.z, xv[i].w * rs2 * gg.w);
;       }
;     }
	v_pk_fma_f32 v[30:31], v[30:31], v[44:45], v[34:35]
	v_pk_fma_f32 v[32:33], v[46:47], v[32:33], v[36:37]
	global_store_dwordx4 v[42:43], v[30:33], off offset:2048 nt
	global_load_dwordx4 v[34:37], v[6:7], off offset:3072
	v_pk_mul_f32 v[44:45], v[56:57], v[52:53] op_sel_hi:[0,1]
	v_pk_mul_f32 v[46:47], v[56:57], v[54:55] op_sel_hi:[0,1]
	s_waitcnt vmcnt(0)
	v_pk_fma_f32 v[34:35], v[44:45], v[34:35], v[38:39]
	v_pk_fma_f32 v[36:37], v[46:47], v[36:37], v[40:41]
	global_store_dwordx4 v[42:43], v[34:37], off offset:3072 nt
	global_load_dwordx4 v[38:41], v[8:9], off
	v_mov_b32_e32 v44, v23
	v_mov_b32_e32 v45, v27
	v_mov_b32_e32 v42, v22
	v_mov_b32_e32 v43, v26
	v_pk_mul_f32 v[44:45], v[44:45], v[44:45]
	v_mov_b32_e32 v46, v24
	v_mov_b32_e32 v47, v28
	v_pk_fma_f32 v[42:43], v[42:43], v[42:43], v[44:45]
	v_mov_b32_e32 v44, v31
	v_pk_fma_f32 v[42:43], v[46:47], v[46:47], v[42:43]
	v_mov_b32_e32 v45, v35
	v_pk_fma_f32 v[42:43], v[48:49], v[48:49], v[42:43]
	v_pk_mul_f32 v[44:45], v[44:45], v[44:45]
	v_add_f32_e32 v3, v42, v43
	v_mov_b32_e32 v42, v30
	v_mov_b32_e32 v43, v34
	v_mov_b32_e32 v46, v32
	v_mov_b32_e32 v47, v36
	v_pk_fma_f32 v[42:43], v[42:43], v[42:43], v[44:45]
	v_mov_b32_e32 v48, v33
	v_mov_b32_e32 v49, v37
	v_pk_fma_f32 v[42:43], v[46:47], v[46:47], v[42:43]
	s_nop 0
	v_pk_fma_f32 v[42:43], v[48:49], v[48:49], v[42:43]
	s_nop 0
	v_add_f32_e32 v3, v42, v3
	v_add_f32_e32 v3, v3, v43
	v_mov_b32_e32 v21, v3
	s_nop 1
	v_permlane32_swap_b32_e32 v3, v21
	s_waitcnt lgkmcnt(0)
	v_add_f32_e32 v3, v3, v21
	v_mov_b32_e32 v21, v3
	s_nop 1
	v_permlane16_swap_b32_e32 v3, v21
	s_waitcnt lgkmcnt(0)
	v_add_f32_e32 v3, v3, v21
	s_nop 1
	v_mov_b32_dpp v21, v3 row_ror:8 row_mask:0xf bank_mask:0xf
	s_waitcnt lgkmcnt(0)
	v_add_f32_e32 v3, v3, v21
	s_nop 1
	v_mov_b32_dpp v21, v3 row_ror:4 row_mask:0xf bank_mask:0xf
	s_waitcnt lgkmcnt(0)
	v_add_f32_e32 v3, v3, v21
	s_nop 1
	v_mov_b32_dpp v21, v3 quad_perm:[2,3,0,1] row_mask:0xf bank_mask:0xf
	s_waitcnt lgkmcnt(0)
	v_add_f32_e32 v3, v3, v21
	s_nop 1
	v_mov_b32_dpp v21, v3 quad_perm:[1,0,3,2] row_mask:0xf bank_mask:0xf
	s_waitcnt lgkmcnt(0)
	v_add_f32_e32 v3, v3, v21
	v_fmamk_f32 v3, v3, 0x3a800000, v184
	v_mul_f32_e32 v21, 0x4b800000, v3
	v_cmp_gt_f32_e32 vcc, s33, v3
	s_nop 1
	v_cndmask_b32_e32 v3, v3, v21, vcc
	v_rsq_f32_e32 v3, v3
	s_nop 0
	v_mul_f32_e32 v21, 0x45800000, v3
	v_cndmask_b32_e32 v42, v3, v21, vcc
	v_pk_mul_f32 v[22:23], v[22:23], v[42:43] op_sel_hi:[1,0]
	v_pk_mul_f32 v[24:25], v[24:25], v[42:43] op_sel_hi:[1,0]
	v_pk_mul_f32 v[26:27], v[26:27], v[42:43] op_sel_hi:[1,0]
	v_pk_mul_f32 v[28:29], v[28:29], v[42:43] op_sel_hi:[1,0]
	s_waitcnt vmcnt(0)
	v_pk_mul_f32 v[22:23], v[38:39], v[22:23]
	v_pk_mul_f32 v[24:25], v[40:41], v[24:25]
	v_cvt_pk_bf16_f32 v22, v22, v23
	v_cvt_pk_bf16_f32 v23, v24, v25
	global_store_dwordx2 v[14:15], v[22:23], off
	global_load_dwordx4 v[22:25], v[8:9], off offset:1024
	v_cmp_lt_i32_e32 vcc, s64, v2
	s_or_b64 s[40:41], vcc, s[40:41]
	s_waitcnt vmcnt(0)
	v_pk_mul_f32 v[22:23], v[22:23], v[26:27]
	v_pk_mul_f32 v[24:25], v[24:25], v[28:29]
	v_cvt_pk_bf16_f32 v22, v22, v23
	v_cvt_pk_bf16_f32 v23, v24, v25
	global_store_dwordx2 v[14:15], v[22:23], off offset:512
	global_load_dwordx4 v[22:25], v[8:9], off offset:2048
	v_pk_mul_f32 v[26:27], v[30:31], v[42:43] op_sel_hi:[1,0]
	v_pk_mul_f32 v[28:29], v[32:33], v[42:43] op_sel_hi:[1,0]
	s_waitcnt vmcnt(0)
	v_pk_mul_f32 v[22:23], v[26:27], v[22:23]
	v_pk_mul_f32 v[24:25], v[28:29], v[24:25]
	v_cvt_pk_bf16_f32 v22, v22, v23
	v_cvt_pk_bf16_f32 v23, v24, v25
	global_store_dwordx2 v[14:15], v[22:23], off offset:1024
	global_load_dwordx4 v[22:25], v[8:9], off offset:3072
	v_pk_mul_f32 v[26:27], v[34:35], v[42:43] op_sel_hi:[1,0]
	v_pk_mul_f32 v[28:29], v[36:37], v[42:43] op_sel_hi:[1,0]
	s_waitcnt vmcnt(0)
	v_pk_mul_f32 v[22:23], v[26:27], v[22:23]
	v_pk_mul_f32 v[24:25], v[28:29], v[24:25]
	v_cvt_pk_bf16_f32 v22, v22, v23
	v_cvt_pk_bf16_f32 v23, v24, v25
	global_store_dwordx2 v[14:15], v[22:23], off offset:1536
	s_andn2_b64 exec, exec, s[40:41]
	s_cbranch_execnz .LBB0_249

; template <int N> DI void wait_vm() { asm volatile("s_waitcnt vmcnt(%0)" ::"n"(N) : "memory"); }
; template <int BM, class Epi>
; DI void gemm_dma(const u16* __restrict__ X, long ldx, const u16* __restrict__ W, long ldw, int K, char* smem,
;                  int m0, int n0, const Epi& epi) {
;     ...
;   const int nk = K >> 5;
;   __syncthreads();
; #pragma unroll
;   for (int s = 0; s < D - 1; ++s) GD_ISSUE(s)
;   int cur = 0, nxt = D - 1, kt = 0;
;   do {
;     if (kt + D - 2 < nk) wait_vm<PW * (D - 2)>(); else wait_vm<0>();
;     __syncthreads();
;     if (kt + D - 1 < nk) GD_ISSUE(nxt)
;     nxt = (nxt + 1 == D) ? 0 : nxt + 1;
;     const char* base = smem + cur * STG;
;     cur = (cur + 1 == D) ? 0 : cur + 1;
;     bf16x8 xf[MT];
; #pragma unroll
;     for (int i = 0; i < MT; ++i) xf[i] = *(const bf16x8*)(base + (xrow0 + i * 16) * 64 + rd);
; #pragma unroll
;     for (int nh = 0; nh < NT / 4; ++nh) {
;       bf16x8 wf[4];
; #pragma unroll
;       for (int i = 0; i < 4; ++i) wf[i] = *(const bf16x8*)(base + BM * 64 + (wrow0 + (nh * 4 + i) * 16) * 64 + rd);
; #pragma unroll
;       for (int i = 0; i < 4; ++i)
; #pragma unroll
;         for (int mt = 0; mt < MT; ++mt)
;           acc[nh * 4 + i][mt] = __builtin_amdgcn_mfma_f32_16x16x32_bf16(wf[i], xf[mt], acc[nh * 4 + i][mt], 0, 0, 0);
;     }
.LBB0_292:
	s_mul_i32 s12, s10, 0x6000
	v_lshl_add_u64 v[196:197], v[132:133], 0, s[40:41]
	s_waitcnt vmcnt(6)
	s_barrier
	s_mul_i32 s98, s11, 0x6000
	v_or_b32_e32 v170, s98, v135
	v_add_u32_e32 v150, v170, v137
	ds_read_b128 v[138:141], v150
	ds_read_b128 v[142:145], v150 offset:1024
	ds_read_b128 v[146:149], v150 offset:2048
	ds_read_b128 v[150:153], v150 offset:3072
	ds_read_b128 v[154:157], v170 offset:16384
	ds_read_b128 v[158:161], v170 offset:17408
	ds_read_b128 v[162:165], v170 offset:18432
	ds_read_b128 v[166:169], v170 offset:19456
	ds_read_b128 v[226:229], v170 offset:20480
	ds_read_b128 v[230:233], v170 offset:21504
	ds_read_b128 v[234:237], v170 offset:22528
	ds_read_b128 v[238:241], v170 offset:23552
	s_add_i32 s13, s12, s8
	s_mov_b32 s14, m0
	s_mov_b32 m0, s13
	s_nop 0
	global_load_lds_dwordx4 v[196:197], off
	s_mov_b32 m0, s14
	v_lshl_add_u64 v[224:225], v[196:197], 0, s[16:17]
	s_add_i32 s14, s13, 0x400
	s_mov_b32 s15, m0
	s_mov_b32 m0, s14
	s_nop 0
	global_load_lds_dwordx4 v[224:225], off
	s_mov_b32 m0, s15
	v_lshl_add_u64 v[224:225], v[196:197], 0, s[20:21]
	s_add_i32 s14, s13, 0x800
	s_mov_b32 s15, m0
	s_mov_b32 m0, s14
	s_nop 0
	global_load_lds_dwordx4 v[224:225], off
	s_mov_b32 m0, s15
	v_lshl_add_u64 v[196:197], v[196:197], 0, s[22:23]
	s_addk_i32 s13, 0xc00
	s_mov_b32 s14, m0
	s_mov_b32 m0, s13
	s_nop 0
	global_load_lds_dwordx4 v[196:197], off
	s_mov_b32 m0, s14
	s_add_i32 s12, s12, s9
	v_lshl_add_u64 v[194:195], v[130:131], 0, s[40:41]
	s_mov_b32 s13, m0
	s_mov_b32 m0, s12
	s_nop 0
	global_load_lds_dwordx4 v[194:195], off
	s_mov_b32 m0, s13
	s_addk_i32 s12, 0x400
	v_lshl_add_u64 v[194:195], v[194:195], 0, s[16:17]
	s_mov_b32 s13, m0
	s_mov_b32 m0, s12
	s_nop 0
	global_load_lds_dwordx4 v[194:195], off
	s_mov_b32 m0, s13
	s_waitcnt lgkmcnt(7)
	v_mfma_f32_16x16x32_bf16 v[126:129], v[154:157], v[138:141], v[126:129]
	s_add_i32 s10, s10, 1
	s_add_i32 s11, s11, 1
	s_cmp_lg_u32 s10, 3
	v_mfma_f32_16x16x32_bf16 v[122:125], v[154:157], v[142:145], v[122:125]
	s_cselect_b32 s10, s10, 0
	s_cmp_lg_u32 s11, 3
	s_cselect_b32 s11, s11, 0
	v_mfma_f32_16x16x32_bf16 v[118:121], v[154:157], v[146:149], v[118:121]
	s_add_u32 s40, s40, 64
	s_addc_u32 s41, s41, 0
	s_cmpk_lg_i32 s40, 0xf80
	v_mfma_f32_16x16x32_bf16 v[114:117], v[154:157], v[150:153], v[114:117]
	s_waitcnt lgkmcnt(6)
	v_mfma_f32_16x16x32_bf16 v[110:113], v[158:161], v[138:141], v[110:113]
	v_mfma_f32_16x16x32_bf16 v[106:109], v[158:161], v[142:145], v[106:109]
	v_mfma_f32_16x16x32_bf16 v[102:105], v[158:161], v[146:149], v[102:105]
	v_mfma_f32_16x16x32_bf16 v[98:101], v[158:161], v[150:153], v[98:101]
	s_waitcnt lgkmcnt(5)
	v_mfma_f32_16x16x32_bf16 v[94:97], v[162:165], v[138:141], v[94:97]
	v_mfma_f32_16x16x32_bf16 v[90:93], v[162:165], v[142:145], v[90:93]
	v_mfma_f32_16x16x32_bf16 v[86:89], v[162:165], v[146:149], v[86:89]
	v_mfma_f32_16x16x32_bf16 v[82:85], v[162:165], v[150:153], v[82:85]
	s_waitcnt lgkmcnt(4)
	v_mfma_f32_16x16x32_bf16 v[78:81], v[166:169], v[138:141], v[78:81]
	v_mfma_f32_16x16x32_bf16 v[74:77], v[166:169], v[142:145], v[74:77]
	v_mfma_f32_16x16x32_bf16 v[70:73], v[166:169], v[146:149], v[70:73]
	v_mfma_f32_16x16x32_bf16 v[66:69], v[166:169], v[150:153], v[66:69]
	s_waitcnt lgkmcnt(3)
	v_mfma_f32_16x16x32_bf16 v[62:65], v[226:229], v[138:141], v[62:65]
	v_mfma_f32_16x16x32_bf16 v[58:61], v[226:229], v[142:145], v[58:61]
	v_mfma_f32_16x16x32_bf16 v[54:57], v[226:229], v[146:149], v[54:57]
	v_mfma_f32_16x16x32_bf16 v[50:53], v[226:229], v[150:153], v[50:53]
	s_waitcnt lgkmcnt(2)
	v_mfma_f32_16x16x32_bf16 v[46:49], v[230:233], v[138:141], v[46:49]
	v_mfma_f32_16x16x32_bf16 v[42:45], v[230:233], v[142:145], v[42:45]
	v_mfma_f32_16x16x32_bf16 v[38:41], v[230:233], v[146:149], v[38:41]
	v_mfma_f32_16x16x32_bf16 v[34:37], v[230:233], v[150:153], v[34:37]
	s_waitcnt lgkmcnt(1)
	v_mfma_f32_16x16x32_bf16 v[30:33], v[234:237], v[138:141], v[30:33]
	v_mfma_f32_16x16x32_bf16 v[26:29], v[234:237], v[142:145], v[26:29]
	v_mfma_f32_16x16x32_bf16 v[22:25], v[234:237], v[146:149], v[22:25]
	v_mfma_f32_16x16x32_bf16 v[18:21], v[234:237], v[150:153], v[18:21]
	s_waitcnt lgkmcnt(0)
	v_mfma_f32_16x16x32_bf16 v[14:17], v[238:241], v[138:141], v[14:17]
	v_mfma_f32_16x16x32_bf16 v[10:13], v[238:241], v[142:145], v[10:13]
	v_mfma_f32_16x16x32_bf16 v[6:9], v[238:241], v[146:149], v[6:9]
	v_mfma_f32_16x16x32_bf16 v[2:5], v[238:241], v[150:153], v[2:5]
	s_cbranch_scc1 .LBB0_292
	v_add_u32_e32 v137, v135, v137
	v_or_b32_e32 v150, 0x10000, v135
	v_or_b32_e32 v154, 0x10400, v135
	v_or_b32_e32 v158, 0x10800, v135
	v_or_b32_e32 v162, 0x10c00, v135
	s_waitcnt vmcnt(6)
	s_barrier
; template <int BM, class Epi>
; DI void gemm_dma(const u16* __restrict__ X, long ldx, const u16* __restrict__ W, long ldw, int K, char* smem,
;                  int m0, int n0, const Epi& epi) {
;     ...
;     bf16x8 xf[MT];
; #pragma unroll
;     for (int i = 0; i < MT; ++i) xf[i] = *(const bf16x8*)(base + (xrow0 + i * 16) * 64 + rd);
; #pragma unroll
;     for (int nh = 0; nh < NT / 4; ++nh) {
;       bf16x8 wf[4];
; #pragma unroll
;       for (int i = 0; i < 4; ++i) wf[i] = *(const bf16x8*)(base + BM * 64 + (wrow0 + (nh * 4 + i) * 16) * 64 + rd);
; #pragma unroll
;       for (int i = 0; i < 4; ++i)
; #pragma unroll
;         for (int mt = 0; mt < MT; ++mt)
;           acc[nh * 4 + i][mt] = __builtin_amdgcn_mfma_f32_16x16x32_bf16(wf[i], xf[mt], acc[nh * 4 + i][mt], 0, 0, 0);
;     }
	ds_read_b128 v[130:133], v137 offset:49152
	ds_read_b128 v[138:141], v137 offset:50176
	ds_read_b128 v[142:145], v137 offset:51200
	ds_read_b128 v[146:149], v137 offset:52224
	ds_read_b128 v[150:153], v150
	ds_read_b128 v[154:157], v154
	ds_read_b128 v[158:161], v158
	ds_read_b128 v[162:165], v162
	s_waitcnt lgkmcnt(3)
	v_mfma_f32_16x16x32_bf16 v[126:129], v[150:153], v[130:133], v[126:129]
	v_readlane_b32 s8, v252, 33
	v_readlane_b32 s9, v252, 34
	s_lshl_b32 s7, s7, 8
	v_mfma_f32_16x16x32_bf16 v[122:125], v[150:153], v[138:141], v[122:125]
	v_lshl_or_b32 v182, v1, 3, s7
	v_mfma_f32_16x16x32_bf16 v[118:121], v[150:153], v[142:145], v[118:121]
	v_mfma_f32_16x16x32_bf16 v[114:117], v[150:153], v[146:149], v[114:117]
	s_waitcnt lgkmcnt(2)
	v_mfma_f32_16x16x32_bf16 v[110:113], v[154:157], v[130:133], v[110:113]
	v_mfma_f32_16x16x32_bf16 v[106:109], v[154:157], v[138:141], v[106:109]
	v_mfma_f32_16x16x32_bf16 v[102:105], v[154:157], v[142:145], v[102:105]
	v_mfma_f32_16x16x32_bf16 v[98:101], v[154:157], v[146:149], v[98:101]
	s_waitcnt lgkmcnt(1)
	v_mfma_f32_16x16x32_bf16 v[94:97], v[158:161], v[130:133], v[94:97]
	v_mfma_f32_16x16x32_bf16 v[150:153], v[158:161], v[138:141], v[90:93]
	v_mfma_f32_16x16x32_bf16 v[86:89], v[158:161], v[142:145], v[86:89]
	s_nop 1
	v_or_b32_e32 v90, 0x11c00, v135
	ds_read_b128 v[90:93], v90
	v_mfma_f32_16x16x32_bf16 v[154:157], v[158:161], v[146:149], v[82:85]
	s_waitcnt lgkmcnt(1)
	v_mfma_f32_16x16x32_bf16 v[78:81], v[162:165], v[130:133], v[78:81]
	s_nop 0
	v_or_b32_e32 v82, 0x11800, v135
	ds_read_b128 v[82:85], v82
	v_mfma_f32_16x16x32_bf16 v[158:161], v[162:165], v[138:141], v[74:77]
	v_mfma_f32_16x16x32_bf16 v[70:73], v[162:165], v[142:145], v[70:73]
	s_nop 1
	v_or_b32_e32 v74, 0x11400, v135
	ds_read_b128 v[74:77], v74
	v_mfma_f32_16x16x32_bf16 v[162:165], v[162:165], v[146:149], v[66:69]
	s_nop 2
	v_or_b32_e32 v66, 0x11000, v135
	ds_read_b128 v[66:69], v66
	s_waitcnt lgkmcnt(1)
	v_mfma_f32_16x16x32_bf16 v[46:49], v[74:77], v[130:133], v[46:49]
	s_waitcnt vmcnt(0)
	s_waitcnt lgkmcnt(0)
	s_barrier
	v_mfma_f32_16x16x32_bf16 v[62:65], v[66:69], v[130:133], v[62:65]
	v_mfma_f32_16x16x32_bf16 v[166:169], v[66:69], v[138:141], v[58:61]
	v_mfma_f32_16x16x32_bf16 v[54:57], v[66:69], v[142:145], v[54:57]
	v_mfma_f32_16x16x32_bf16 v[170:173], v[66:69], v[146:149], v[50:53]
	v_mfma_f32_16x16x32_bf16 v[174:177], v[74:77], v[138:141], v[42:45]
	v_mfma_f32_16x16x32_bf16 v[38:41], v[74:77], v[142:145], v[38:41]
	v_mfma_f32_16x16x32_bf16 v[178:181], v[74:77], v[146:149], v[34:37]
	v_mfma_f32_16x16x32_bf16 v[30:33], v[82:85], v[130:133], v[30:33]
	v_mfma_f32_16x16x32_bf16 v[26:29], v[82:85], v[138:141], v[26:29]
	v_mfma_f32_16x16x32_bf16 v[22:25], v[82:85], v[142:145], v[22:25]
	v_mfma_f32_16x16x32_bf16 v[18:21], v[82:85], v[146:149], v[18:21]
	v_mfma_f32_16x16x32_bf16 v[14:17], v[90:93], v[130:133], v[14:17]
	v_mfma_f32_16x16x32_bf16 v[10:13], v[90:93], v[138:141], v[10:13]
	v_mfma_f32_16x16x32_bf16 v[6:9], v[90:93], v[142:145], v[6:9]
	v_mfma_f32_16x16x32_bf16 v[2:5], v[90:93], v[146:149], v[2:5]
	ds_read_b128 v[130:133], v137
	ds_read_b128 v[138:141], v137 offset:1024
	ds_read_b128 v[142:145], v137 offset:2048
	ds_read_b128 v[146:149], v137 offset:3072
	ds_read_b128 v[34:37], v135 offset:16384
	ds_read_b128 v[42:45], v135 offset:17408
	ds_read_b128 v[50:53], v135 offset:18432
	ds_read_b128 v[186:189], v135 offset:19456
	s_waitcnt lgkmcnt(2)
	v_mfma_f32_16x16x32_bf16 v[110:113], v[42:45], v[130:133], v[110:113]
	v_mfma_f32_16x16x32_bf16 v[106:109], v[42:45], v[138:141], v[106:109]
	v_mfma_f32_16x16x32_bf16 v[102:105], v[42:45], v[142:145], v[102:105]
	s_nop 5
	v_cvt_pk_bf16_f32 v110, v110, v111
	v_cvt_pk_bf16_f32 v111, v112, v113
	v_cvt_pk_bf16_f32 v106, v106, v107
	v_mfma_f32_16x16x32_bf16 v[190:193], v[42:45], v[146:149], v[98:101]
	v_cvt_pk_bf16_f32 v107, v108, v109
	v_cvt_pk_bf16_f32 v102, v102, v103
	v_cvt_pk_bf16_f32 v103, v104, v105
	s_waitcnt lgkmcnt(1)
	v_mfma_f32_16x16x32_bf16 v[82:85], v[50:53], v[138:141], v[150:153]
	v_mfma_f32_16x16x32_bf16 v[66:69], v[50:53], v[146:149], v[154:157]
	s_waitcnt lgkmcnt(0)
	v_mfma_f32_16x16x32_bf16 v[42:45], v[186:189], v[142:145], v[70:73]
	s_nop 2
	ds_read_b128 v[70:73], v135 offset:20480
	ds_read_b128 v[98:101], v135 offset:21504
	ds_read_b128 v[150:153], v135 offset:22528
	ds_read_b128 v[154:157], v135 offset:23552
	v_cvt_pk_bf16_f32 v82, v82, v83
	v_cvt_pk_bf16_f32 v83, v84, v85
	v_mfma_f32_16x16x32_bf16 v[90:93], v[50:53], v[130:133], v[94:97]
	v_cvt_pk_bf16_f32 v66, v66, v67
	v_cvt_pk_bf16_f32 v67, v68, v69
	v_cvt_pk_bf16_f32 v42, v42, v43
	v_mfma_f32_16x16x32_bf16 v[58:61], v[186:189], v[130:133], v[78:81]
	v_cvt_pk_bf16_f32 v43, v44, v45
	s_nop 2
	v_cvt_pk_bf16_f32 v90, v90, v91
	v_cvt_pk_bf16_f32 v91, v92, v93
	s_waitcnt lgkmcnt(3)
	v_mfma_f32_16x16x32_bf16 v[94:97], v[70:73], v[130:133], v[62:65]
	v_mfma_f32_16x16x32_bf16 v[78:81], v[70:73], v[142:145], v[54:57]
	v_cvt_pk_bf16_f32 v58, v58, v59
	v_cvt_pk_bf16_f32 v59, v60, v61
	s_waitcnt lgkmcnt(2)
	v_mfma_f32_16x16x32_bf16 v[62:65], v[98:101], v[130:133], v[46:49]
	v_mfma_f32_16x16x32_bf16 v[54:57], v[98:101], v[138:141], v[174:177]
	v_mfma_f32_16x16x32_bf16 v[46:49], v[98:101], v[142:145], v[38:41]
	v_mfma_f32_16x16x32_bf16 v[38:41], v[98:101], v[146:149], v[178:181]
	v_lshl_add_u32 v98, s38, 8, v136
	v_mfma_f32_16x16x32_bf16 v[126:129], v[34:37], v[130:133], v[126:129]
	s_waitcnt lgkmcnt(1)
; DI void st_bf4(u16* p, float a, float b, float c, float d) { *(uint2*)p = make_uint2(pk2(a, b), pk2(c, d)); }
; template <int BM, class Epi>
; DI void gemm_dma(const u16* __restrict__ X, long ldx, const u16* __restrict__ W, long ldw, int K, char* smem,
;                  int m0, int n0, const Epi& epi) {
;     ...
;       for (int i = 0; i < 4; ++i)
; #pragma unroll
;         for (int mt = 0; mt < MT; ++mt)
;           acc[nh * 4 + i][mt] = __builtin_amdgcn_mfma_f32_16x16x32_bf16(wf[i], xf[mt], acc[nh * 4 + i][mt], 0, 0, 0);
;   template <int NT, int MT> DI void run(f32x4 (&acc)[NT][MT], int mb, int nb) const {
; #pragma unroll
;     for (int nt = 0; nt < NT; ++nt)
; #pragma unroll
;       for (int mt = 0; mt < MT; ++mt) {
;         f32x4 v = acc[nt][mt];
;         st_bf4(C + (size_t)(mb + mt * 16) * ldc + nb + nt * 16, v[0], v[1], v[2], v[3]);
;       }
	v_mfma_f32_16x16x32_bf16 v[30:33], v[150:153], v[130:133], v[30:33]
	s_waitcnt lgkmcnt(0)
	v_mfma_f32_16x16x32_bf16 v[14:17], v[154:157], v[130:133], v[14:17]
	v_or_b32_e32 v130, v98, v134
	v_ashrrev_i32_e32 v131, 31, v130
	v_lshlrev_b64 v[98:99], 11, v[130:131]
	v_lshl_add_u64 v[98:99], s[8:9], 0, v[98:99]
	v_lshl_add_u64 v[98:99], v[98:99], 0, v[182:183]
	v_cvt_pk_bf16_f32 v100, v126, v127
	v_cvt_pk_bf16_f32 v101, v128, v129
	v_mfma_f32_16x16x32_bf16 v[122:125], v[34:37], v[138:141], v[122:125]
	global_store_dwordx2 v[98:99], v[100:101], off
	v_or_b32_e32 v100, 16, v130
	v_ashrrev_i32_e32 v101, 31, v100
	v_lshlrev_b64 v[100:101], 11, v[100:101]
	v_lshl_add_u64 v[100:101], s[8:9], 0, v[100:101]
	v_lshl_add_u64 v[100:101], v[100:101], 0, v[182:183]
	s_nop 1
	v_cvt_pk_bf16_f32 v122, v122, v123
	v_cvt_pk_bf16_f32 v123, v124, v125
	v_mfma_f32_16x16x32_bf16 v[118:121], v[34:37], v[142:145], v[118:121]
	global_store_dwordx2 v[100:101], v[122:123], off
	v_or_b32_e32 v122, 32, v130
	v_ashrrev_i32_e32 v123, 31, v122
	v_lshlrev_b64 v[122:123], 11, v[122:123]
	v_lshl_add_u64 v[122:123], s[8:9], 0, v[122:123]
	v_lshl_add_u64 v[122:123], v[122:123], 0, v[182:183]
	s_nop 1
	v_cvt_pk_bf16_f32 v118, v118, v119
	v_cvt_pk_bf16_f32 v119, v120, v121
	v_mfma_f32_16x16x32_bf16 v[114:117], v[34:37], v[146:149], v[114:117]
	global_store_dwordx2 v[122:123], v[118:119], off
	v_or_b32_e32 v118, 48, v130
	v_ashrrev_i32_e32 v119, 31, v118
	v_mfma_f32_16x16x32_bf16 v[34:37], v[186:189], v[146:149], v[162:165]
	v_lshlrev_b64 v[118:119], 11, v[118:119]
	v_lshl_add_u64 v[118:119], s[8:9], 0, v[118:119]
	v_lshl_add_u64 v[118:119], v[118:119], 0, v[182:183]
	v_mfma_f32_16x16x32_bf16 v[74:77], v[50:53], v[142:145], v[86:89]
	v_cvt_pk_bf16_f32 v114, v114, v115
	s_nop 2
	v_cvt_pk_bf16_f32 v34, v34, v35
	v_cvt_pk_bf16_f32 v35, v36, v37
	v_mfma_f32_16x16x32_bf16 v[86:89], v[70:73], v[138:141], v[166:169]
	global_store_dwordx2 v[118:119], v[34:35], off offset:96
	v_cvt_pk_bf16_f32 v34, v94, v95
	v_cvt_pk_bf16_f32 v35, v96, v97
	v_mfma_f32_16x16x32_bf16 v[70:73], v[70:73], v[146:149], v[170:173]
	global_store_dwordx2 v[98:99], v[34:35], off offset:128
	s_nop 2
	v_cvt_pk_bf16_f32 v34, v86, v87
	v_cvt_pk_bf16_f32 v35, v88, v89
	global_store_dwordx2 v[100:101], v[34:35], off offset:128
	v_cvt_pk_bf16_f32 v34, v78, v79
	v_cvt_pk_bf16_f32 v35, v80, v81
	v_mfma_f32_16x16x32_bf16 v[50:53], v[186:189], v[138:141], v[158:161]
	global_store_dwordx2 v[122:123], v[34:35], off offset:128
	v_cvt_pk_bf16_f32 v34, v70, v71
	v_cvt_pk_bf16_f32 v35, v72, v73
	v_mfma_f32_16x16x32_bf16 v[26:29], v[150:153], v[138:141], v[26:29]
	global_store_dwordx2 v[118:119], v[34:35], off offset:128
	v_cvt_pk_bf16_f32 v34, v62, v63
	v_cvt_pk_bf16_f32 v35, v64, v65
	v_mfma_f32_16x16x32_bf16 v[22:25], v[150:153], v[142:145], v[22:25]
	global_store_dwordx2 v[98:99], v[34:35], off offset:160
	v_cvt_pk_bf16_f32 v34, v54, v55
	v_cvt_pk_bf16_f32 v35, v56, v57
	v_mfma_f32_16x16x32_bf16 v[18:21], v[150:153], v[146:149], v[18:21]
	global_store_dwordx2 v[100:101], v[34:35], off offset:160
	v_cvt_pk_bf16_f32 v34, v46, v47
	v_cvt_pk_bf16_f32 v35, v48, v49
	v_mfma_f32_16x16x32_bf16 v[10:13], v[154:157], v[138:141], v[10:13]
	v_cvt_pk_bf16_f32 v115, v116, v117
	global_store_dwordx2 v[122:123], v[102:103], off offset:32
	v_cvt_pk_bf16_f32 v102, v190, v191
	v_mfma_f32_16x16x32_bf16 v[6:9], v[154:157], v[142:145], v[6:9]
	v_cvt_pk_bf16_f32 v103, v192, v193
	v_cvt_pk_bf16_f32 v74, v74, v75
	v_cvt_pk_bf16_f32 v75, v76, v77
	v_mfma_f32_16x16x32_bf16 v[2:5], v[154:157], v[146:149], v[2:5]
	v_cvt_pk_bf16_f32 v50, v50, v51
	v_cvt_pk_bf16_f32 v51, v52, v53
	global_store_dwordx2 v[122:123], v[34:35], off offset:160
	v_cvt_pk_bf16_f32 v34, v38, v39
	v_cvt_pk_bf16_f32 v35, v40, v41
	v_cvt_pk_bf16_f32 v30, v30, v31
	v_cvt_pk_bf16_f32 v31, v32, v33
	v_cvt_pk_bf16_f32 v26, v26, v27
	v_cvt_pk_bf16_f32 v27, v28, v29
	v_cvt_pk_bf16_f32 v22, v22, v23
	v_cvt_pk_bf16_f32 v23, v24, v25
	v_cvt_pk_bf16_f32 v18, v18, v19
	v_cvt_pk_bf16_f32 v19, v20, v21
	v_cvt_pk_bf16_f32 v14, v14, v15
	v_cvt_pk_bf16_f32 v15, v16, v17
	v_cvt_pk_bf16_f32 v10, v10, v11
	v_cvt_pk_bf16_f32 v11, v12, v13
	v_cvt_pk_bf16_f32 v6, v6, v7
	v_cvt_pk_bf16_f32 v7, v8, v9
	v_cvt_pk_bf16_f32 v2, v2, v3
	v_cvt_pk_bf16_f32 v3, v4, v5
	global_store_dwordx2 v[118:119], v[114:115], off
	global_store_dwordx2 v[98:99], v[110:111], off offset:32
	global_store_dwordx2 v[100:101], v[106:107], off offset:32
	global_store_dwordx2 v[118:119], v[102:103], off offset:32
	global_store_dwordx2 v[98:99], v[90:91], off offset:64
	global_store_dwordx2 v[100:101], v[82:83], off offset:64
	global_store_dwordx2 v[122:123], v[74:75], off offset:64
	global_store_dwordx2 v[118:119], v[66:67], off offset:64
	global_store_dwordx2 v[98:99], v[58:59], off offset:96
	global_store_dwordx2 v[100:101], v[50:51], off offset:96
	global_store_dwordx2 v[122:123], v[42:43], off offset:96
	global_store_dwordx2 v[118:119], v[34:35], off offset:160
	global_store_dwordx2 v[98:99], v[30:31], off offset:192
	global_store_dwordx2 v[100:101], v[26:27], off offset:192
	global_store_dwordx2 v[122:123], v[22:23], off offset:192
	global_store_dwordx2 v[118:119], v[18:19], off offset:192
	global_store_dwordx2 v[98:99], v[14:15], off offset:224
	global_store_dwordx2 v[100:101], v[10:11], off offset:224
	global_store_dwordx2 v[122:123], v[6:7], off offset:224
	global_store_dwordx2 v[118:119], v[2:3], off offset:224
	s_branch .LBB0_285

; template <int MT, class Epi>
; DI void gemm_tile(const u16* __restrict__ X, long ldx, const u16* __restrict__ W, long ldw, int K, char* smem,
;                   int m0, int n0, const Epi& epi, bool pre = false, const u16* Xn = nullptr, const u16* Wn = nullptr) {
;     ...
;   const int r8 = lane >> 3, c0 = (lane & 7) ^ (r8 >> 1);
;   const long oxe = (long)(wu * MT * 8 + r8) * ldx + (c0 << 3), oxo = (long)(wu * MT * 8 + r8) * ldx + ((c0 ^ 4) << 3);
;   const long owe = (long)(wu * 32 + r8) * ldw + (c0 << 3), owo = (long)(wu * 32 + r8) * ldw + ((c0 ^ 4) << 3);
;   const u16 *xe = X + oxe, *xo = X + oxo, *we = W + owe, *wo = W + owo;
;   const long ldx8 = 8 * ldx, ldw8 = 8 * ldw;
;   const unsigned xdst = sbase + wu * MT * 1024, wdst = sbase + 16384 + wu * 4096;
;     ...
;   if (!pre) {
;     __syncthreads();
;     GT_DMA(0u)
;   } else {
;     xe += 64; xo += 64; we += 64; wo += 64;
;   }
;   const int nk = K >> 6;
;   int kt = 0;
;   do {
;     asm volatile("s_waitcnt vmcnt(0)" ::: "memory");
;     __syncthreads();
;     if (kt + 1 < nk) GT_DMA((unsigned)((kt + 1) & 1) * 32768u)
;     else if (Xn != nullptr) { xe = Xn + oxe; xo = Xn + oxo; we = Wn + owe; wo = Wn + owo; GT_DMA(0u) }
;     const char* cur = smem + (kt & 1) * 32768;
; #pragma unroll
;     for (int ks = 0; ks < 2; ++ks) {
;       bf16x8 xf[MT], wf[4];
;       const int ch = ((ks * 4 + g) ^ rsw) << 4;
; #pragma unroll
;       for (int i = 0; i < MT; ++i) xf[i] = *(const bf16x8*)(cur + (wm * 16 * MT + i * 16 + lr) * 128 + ch);
; #pragma unroll
;       for (int i = 0; i < 4; ++i) wf[i] = *(const bf16x8*)(cur + 16384 + (wn * 64 + i * 16 + lr) * 128 + ch);
; DI void phase_even(const Params& p, int e, int sub, char* smem) {
;     ...
;         const int u = t - 1056, c = u >> 3, g = (u >> 1) & 3, tn = u & 1;
;         EpiSgu epi{p.b_spatial + (e * 4 + g) * 128, uvbuf, gbuf, g, c < 128 ? c * 128 : M_PROMPT + (c - 128) * 32, c < 128 ? 128 : 32};
;         gemm_tile<4>(W + WE_WS + (size_t)g * 16384, 128, vT + ((size_t)c * 1024 + g * 256 + tn * 128) * 128, 128, 128, smem, 0, tn * 128, epi);
.LBB0_299:
	s_cmpk_gt_i32 s4, 0x41f
	s_mov_b64 s[38:39], -1
	s_cbranch_scc0 .LBB0_309
	s_add_i32 s7, s4, 0xfffffbe0
	s_bfe_u32 s8, s4, 0x20001
	v_readlane_b32 s56, v252, 8
	s_lshr_b32 s34, s7, 3
	s_lshl_b32 s9, s8, 9
	v_readlane_b32 s66, v252, 18
	v_readlane_b32 s67, v252, 19
	s_add_u32 s38, s66, s9
	s_addc_u32 s39, s67, 0
	s_lshl_b32 s9, s34, 5
	s_lshl_b32 s10, s34, 7
	s_add_i32 s11, s9, 0x3000
	s_cmpk_lt_u32 s7, 0x400
	s_cselect_b32 s9, 0x80, 32
	s_cselect_b32 s7, s10, s11
	s_lshl_b32 s10, s8, 15
	v_readlane_b32 s12, v252, 41
	v_readlane_b32 s13, v252, 42
	s_add_u32 s12, s12, s10
	s_addc_u32 s13, s13, 0
	s_lshl_b64 s[14:15], s[34:35], 10
	s_lshl_b32 s8, s8, 8
	v_mov_b32_e32 v1, v185
	s_or_b32 s11, s14, s8
	s_and_b32 s10, s5, 0x80
	s_or_b32 s14, s11, s10
	v_ashrrev_i32_e32 v3, 6, v1
	v_bfe_u32 v4, v1, 3, 3
	v_readfirstlane_b32 s11, v3
	s_waitcnt vmcnt(3)
	v_bfe_u32 v111, v1, 4, 2
	v_bitop3_b32 v8, v111, v1, 7 bitop3:0x78
	v_lshl_or_b32 v4, s11, 5, v4
	v_ashrrev_i32_e32 v5, 31, v4
	s_lshl_b64 s[14:15], s[14:15], 8
	v_readlane_b32 s16, v252, 37
	v_lshlrev_b64 v[4:5], 8, v[4:5]
	v_lshlrev_b32_e32 v182, 4, v8
	v_readlane_b32 s17, v252, 38
	s_add_u32 s14, s16, s14
	v_mov_b32_e32 v2, v183
	v_lshl_add_u64 v[6:7], s[12:13], 0, v[4:5]
	v_xor_b32_e32 v10, 64, v182
	v_mov_b32_e32 v11, v183
	s_addc_u32 s15, s17, s15
	v_lshl_add_u64 v[8:9], v[6:7], 0, v[182:183]
	v_lshl_add_u64 v[6:7], v[6:7], 0, v[10:11]
	s_lshl_b32 s11, s11, 12
	s_barrier
	s_mov_b32 s12, m0
	s_mov_b32 m0, s11
	s_nop 0
	global_load_lds_dwordx4 v[8:9], off
	s_mov_b32 m0, s12
	s_mov_b64 s[18:19], 0x800
	v_lshl_add_u64 v[4:5], s[14:15], 0, v[4:5]
	v_lshl_add_u64 v[14:15], v[6:7], 0, s[18:19]
	s_or_b32 s12, s11, 0x400
	s_mov_b32 s13, m0
	s_mov_b32 m0, s12
	s_nop 0
	global_load_lds_dwordx4 v[14:15], off
	s_mov_b32 m0, s13
	s_mov_b64 s[14:15], 0x1000
	v_lshl_add_u64 v[14:15], v[8:9], 0, s[14:15]
	s_or_b32 s12, s11, 0x800
	s_mov_b32 s13, m0
	s_mov_b32 m0, s12
	s_nop 0
	global_load_lds_dwordx4 v[14:15], off
	s_mov_b32 m0, s13
	s_mov_b64 s[16:17], 0x1800
	v_lshl_add_u64 v[14:15], v[6:7], 0, s[16:17]
	s_or_b32 s12, s11, 0xc00
	s_mov_b32 s13, m0
	s_mov_b32 m0, s12
	s_nop 0
	global_load_lds_dwordx4 v[14:15], off
	s_mov_b32 m0, s13
	v_lshl_add_u64 v[12:13], v[4:5], 0, v[182:183]
	v_lshl_add_u64 v[4:5], v[4:5], 0, v[10:11]
	s_add_i32 s12, s11, 0x4000
	s_mov_b32 s13, m0
	s_mov_b32 m0, s12
	s_nop 0
	global_load_lds_dwordx4 v[12:13], off
	s_mov_b32 m0, s13
	v_lshl_add_u64 v[10:11], v[4:5], 0, s[18:19]
	s_add_i32 s12, s11, 0x4400
	s_mov_b32 s13, m0
	s_mov_b32 m0, s12
	s_nop 0
	global_load_lds_dwordx4 v[10:11], off
	s_mov_b32 m0, s13
	v_lshl_add_u64 v[10:11], v[12:13], 0, s[14:15]
	s_add_i32 s12, s11, 0x4800
	s_mov_b32 s13, m0
	s_mov_b32 m0, s12
	s_nop 0
	global_load_lds_dwordx4 v[10:11], off
	s_mov_b32 m0, s13
	v_lshl_add_u64 v[10:11], v[4:5], 0, s[16:17]
	s_add_i32 s12, s11, 0x4c00
	s_mov_b32 s13, m0
	s_mov_b32 m0, s12
	s_nop 0
	global_load_lds_dwordx4 v[10:11], off
	s_mov_b32 m0, s13
	s_waitcnt vmcnt(0)
	s_barrier
	s_add_i32 s13, s11, 0x8000
	v_lshl_add_u64 v[10:11], v[8:9], 0, s[28:29]
	s_mov_b32 s14, m0
	s_mov_b32 m0, s13
	s_nop 0
	global_load_lds_dwordx4 v[10:11], off
	s_mov_b32 m0, s14
	s_mov_b64 s[18:19], 0x880
	v_lshl_add_u64 v[10:11], v[6:7], 0, s[18:19]
	s_add_i32 s13, s11, 0x8400
	s_mov_b32 s14, m0
	s_mov_b32 m0, s13
	s_nop 0
	global_load_lds_dwordx4 v[10:11], off
	s_mov_b32 m0, s14
	s_mov_b64 s[20:21], 0x1080
	v_lshl_add_u64 v[8:9], v[8:9], 0, s[20:21]
	s_add_i32 s13, s11, 0x8800
	s_mov_b32 s14, m0
	s_mov_b32 m0, s13
	s_nop 0
	global_load_lds_dwordx4 v[8:9], off
	s_mov_b32 m0, s14
	s_mov_b64 s[16:17], 0x1880
	v_lshl_add_u64 v[6:7], v[6:7], 0, s[16:17]
	s_add_i32 s13, s11, 0x8c00
	s_mov_b32 s14, m0
	s_mov_b32 m0, s13
	s_nop 0
	global_load_lds_dwordx4 v[6:7], off
	s_mov_b32 m0, s14
	s_add_i32 s12, s11, 0xc000
	v_lshl_add_u64 v[14:15], v[12:13], 0, s[28:29]
	s_mov_b32 s13, m0
	s_mov_b32 m0, s12
	s_nop 0
	global_load_lds_dwordx4 v[14:15], off
	s_mov_b32 m0, s13
	v_lshl_add_u64 v[6:7], v[4:5], 0, s[18:19]
	s_add_i32 s12, s11, 0xc400
	s_mov_b32 s13, m0
	s_mov_b32 m0, s12
	s_nop 0
	global_load_lds_dwordx4 v[6:7], off
	s_mov_b32 m0, s13
	v_lshrrev_b32_e32 v16, 1, v1
	v_lshl_add_u64 v[6:7], v[12:13], 0, s[20:21]
	s_add_i32 s12, s11, 0xc800
	s_mov_b32 s13, m0
	s_mov_b32 m0, s12
	s_nop 0
	global_load_lds_dwordx4 v[6:7], off
	s_mov_b32 m0, s13
	v_lshl_add_u64 v[4:5], v[4:5], 0, s[16:17]
	v_and_b32_e32 v110, 15, v1
	v_ashrrev_i32_e32 v112, 7, v1
	s_add_i32 s11, s11, 0xcc00
	s_mov_b32 s12, m0
	s_mov_b32 m0, s11
	s_nop 0
	global_load_lds_dwordx4 v[4:5], off
	s_mov_b32 m0, s12
	v_bitop3_b32 v4, v111, v16, 7 bitop3:0x78
	v_lshlrev_b32_e32 v4, 4, v4
	v_lshlrev_b32_e32 v78, 7, v110
	v_lshlrev_b32_e32 v74, 13, v112
	s_waitcnt vmcnt(1)
	v_or3_b32 v102, v4, v74, v78
	ds_read_b128 v[6:9], v102 offset:16384
	ds_read_b128 v[38:41], v102 offset:18432
	ds_read_b128 v[54:57], v102 offset:20480
	ds_read_b128 v[70:73], v102 offset:22528
	v_bfe_u32 v1, v1, 1, 3
	v_and_b32_e32 v113, 1, v3
	v_bitop3_b32 v1, v111, v1, 4 bitop3:0x36
	v_lshlrev_b32_e32 v79, 13, v113
	v_lshlrev_b32_e32 v1, 4, v1
	v_or3_b32 v86, v4, v79, v78
	v_or_b32_e32 v74, v1, v74
	ds_read_b128 v[10:13], v86
	ds_read_b128 v[18:21], v86 offset:2048
	ds_read_b128 v[26:29], v86 offset:4096
	ds_read_b128 v[34:37], v86 offset:6144
	v_add_u32_e32 v114, v74, v78
	ds_read_b128 v[74:77], v114 offset:16384
	v_or_b32_e32 v1, v1, v79
	v_mov_b32_e32 v3, v2
	v_mov_b32_e32 v4, v2
	v_mov_b32_e32 v5, v2
	v_add_u32_e32 v1, v1, v78
	ds_read_b128 v[78:81], v1 offset:4096
	ds_read_b128 v[82:85], v1 offset:6144
	s_waitcnt lgkmcnt(6)
; template <int MT, class Epi>
; DI void gemm_tile(const u16* __restrict__ X, long ldx, const u16* __restrict__ W, long ldw, int K, char* smem,
;                   int m0, int n0, const Epi& epi, bool pre = false, const u16* Xn = nullptr, const u16* Wn = nullptr) {
;     ...
; #pragma unroll
;     for (int ks = 0; ks < 2; ++ks) {
;       bf16x8 xf[MT], wf[4];
;       const int ch = ((ks * 4 + g) ^ rsw) << 4;
; #pragma unroll
;       for (int i = 0; i < MT; ++i) xf[i] = *(const bf16x8*)(cur + (wm * 16 * MT + i * 16 + lr) * 128 + ch);
; #pragma unroll
;       for (int i = 0; i < 4; ++i) wf[i] = *(const bf16x8*)(cur + 16384 + (wn * 64 + i * 16 + lr) * 128 + ch);
; #pragma unroll
;       for (int nt = 0; nt < 4; ++nt)
; #pragma unroll
;         for (int mt = 0; mt < MT; ++mt)
;           acc[nt][mt] = __builtin_amdgcn_mfma_f32_16x16x32_bf16(wf[nt], xf[mt], acc[nt][mt], 0, 0, 0);
;     }
;   } while (++kt < nk);
;   template <int NT, int MT> DI void run(f32x4 (&acc)[NT][MT], int mb, int nb) const {
; #pragma unroll
;     for (int mt = 0; mt < MT; ++mt) {
;       const int i = mb + mt * 16;
;       if (i < nvalid) {
	v_mfma_f32_16x16x32_bf16 v[14:17], v[6:9], v[10:13], v[2:5]
	v_readlane_b32 s57, v252, 9
	v_readlane_b32 s58, v252, 10
	v_readlane_b32 s59, v252, 11
	s_waitcnt lgkmcnt(5)
	v_mfma_f32_16x16x32_bf16 v[22:25], v[6:9], v[18:21], v[2:5]
	v_readlane_b32 s60, v252, 12
	v_readlane_b32 s61, v252, 13
	v_readlane_b32 s62, v252, 14
	s_waitcnt lgkmcnt(4)
	v_mfma_f32_16x16x32_bf16 v[30:33], v[6:9], v[26:29], v[2:5]
	v_readlane_b32 s63, v252, 15
	v_readlane_b32 s64, v252, 16
	v_readlane_b32 s65, v252, 17
	s_waitcnt lgkmcnt(3)
	v_mfma_f32_16x16x32_bf16 v[6:9], v[6:9], v[34:37], v[2:5]
	v_readlane_b32 s68, v252, 20
	v_readlane_b32 s69, v252, 21
	v_readlane_b32 s70, v252, 22
	v_mfma_f32_16x16x32_bf16 v[42:45], v[38:41], v[10:13], v[2:5]
	v_readlane_b32 s71, v252, 23
	v_mfma_f32_16x16x32_bf16 v[46:49], v[38:41], v[18:21], v[2:5]
	v_mfma_f32_16x16x32_bf16 v[50:53], v[38:41], v[26:29], v[2:5]
	v_mfma_f32_16x16x32_bf16 v[38:41], v[38:41], v[34:37], v[2:5]
	v_mfma_f32_16x16x32_bf16 v[58:61], v[54:57], v[10:13], v[2:5]
	v_mfma_f32_16x16x32_bf16 v[62:65], v[54:57], v[18:21], v[2:5]
	v_mfma_f32_16x16x32_bf16 v[66:69], v[54:57], v[26:29], v[2:5]
	v_mfma_f32_16x16x32_bf16 v[54:57], v[54:57], v[34:37], v[2:5]
	v_mfma_f32_16x16x32_bf16 v[10:13], v[70:73], v[10:13], v[2:5]
	v_mfma_f32_16x16x32_bf16 v[18:21], v[70:73], v[18:21], v[2:5]
	v_mfma_f32_16x16x32_bf16 v[26:29], v[70:73], v[26:29], v[2:5]
	v_mfma_f32_16x16x32_bf16 v[2:5], v[70:73], v[34:37], v[2:5]
	ds_read_b128 v[34:37], v1
	ds_read_b128 v[70:73], v1 offset:2048
	s_waitcnt lgkmcnt(1)
	v_mfma_f32_16x16x32_bf16 v[14:17], v[74:77], v[34:37], v[14:17]
	s_waitcnt lgkmcnt(0)
	v_mfma_f32_16x16x32_bf16 v[22:25], v[74:77], v[70:73], v[22:25]
	v_mfma_f32_16x16x32_bf16 v[30:33], v[74:77], v[78:81], v[30:33]
	v_mfma_f32_16x16x32_bf16 v[6:9], v[74:77], v[82:85], v[6:9]
	ds_read_b128 v[74:77], v114 offset:18432
	s_waitcnt lgkmcnt(0)
	v_mfma_f32_16x16x32_bf16 v[42:45], v[74:77], v[34:37], v[42:45]
	v_mfma_f32_16x16x32_bf16 v[46:49], v[74:77], v[70:73], v[46:49]
	v_mfma_f32_16x16x32_bf16 v[50:53], v[74:77], v[78:81], v[50:53]
	v_mfma_f32_16x16x32_bf16 v[38:41], v[74:77], v[82:85], v[38:41]
	ds_read_b128 v[74:77], v114 offset:20480
	s_waitcnt lgkmcnt(0)
	v_mfma_f32_16x16x32_bf16 v[58:61], v[74:77], v[34:37], v[58:61]
	v_mfma_f32_16x16x32_bf16 v[62:65], v[74:77], v[70:73], v[62:65]
	v_mfma_f32_16x16x32_bf16 v[66:69], v[74:77], v[78:81], v[66:69]
	v_mfma_f32_16x16x32_bf16 v[54:57], v[74:77], v[82:85], v[54:57]
	ds_read_b128 v[74:77], v114 offset:22528
	s_waitcnt vmcnt(0)
	s_waitcnt lgkmcnt(0)
	v_mfma_f32_16x16x32_bf16 v[10:13], v[74:77], v[34:37], v[10:13]
	s_barrier
	ds_read_b128 v[34:37], v102 offset:49152
	v_mfma_f32_16x16x32_bf16 v[18:21], v[74:77], v[70:73], v[18:21]
	ds_read_b128 v[70:73], v86 offset:32768
	ds_read_b128 v[106:109], v1 offset:38912
	v_mfma_f32_16x16x32_bf16 v[26:29], v[74:77], v[78:81], v[26:29]
	ds_read_b128 v[78:81], v86 offset:36864
	v_mfma_f32_16x16x32_bf16 v[2:5], v[74:77], v[82:85], v[2:5]
	ds_read_b128 v[74:77], v86 offset:34816
	ds_read_b128 v[82:85], v86 offset:38912
	s_waitcnt lgkmcnt(4)
	v_mfma_f32_16x16x32_bf16 v[14:17], v[34:37], v[70:73], v[14:17]
	s_waitcnt lgkmcnt(1)
	v_mfma_f32_16x16x32_bf16 v[22:25], v[34:37], v[74:77], v[22:25]
	v_mfma_f32_16x16x32_bf16 v[30:33], v[34:37], v[78:81], v[30:33]
	s_waitcnt lgkmcnt(0)
	v_mfma_f32_16x16x32_bf16 v[6:9], v[34:37], v[82:85], v[6:9]
	ds_read_b128 v[34:37], v102 offset:51200
	s_waitcnt lgkmcnt(0)
	v_mfma_f32_16x16x32_bf16 v[42:45], v[34:37], v[70:73], v[42:45]
	v_mfma_f32_16x16x32_bf16 v[86:89], v[34:37], v[74:77], v[46:49]
	v_mfma_f32_16x16x32_bf16 v[50:53], v[34:37], v[78:81], v[50:53]
	v_mfma_f32_16x16x32_bf16 v[34:37], v[34:37], v[82:85], v[38:41]
	s_nop 2
	ds_read_b128 v[38:41], v102 offset:53248
	s_waitcnt lgkmcnt(0)
	v_mfma_f32_16x16x32_bf16 v[90:93], v[38:41], v[70:73], v[58:61]
	s_waitcnt vmcnt(0)
	v_mfma_f32_16x16x32_bf16 v[94:97], v[38:41], v[74:77], v[62:65]
	v_mfma_f32_16x16x32_bf16 v[66:69], v[38:41], v[78:81], v[66:69]
	v_mfma_f32_16x16x32_bf16 v[98:101], v[38:41], v[82:85], v[54:57]
	ds_read_b128 v[38:41], v102 offset:55296
	ds_read_b128 v[102:105], v1 offset:36864
	s_waitcnt lgkmcnt(1)
	v_mfma_f32_16x16x32_bf16 v[70:73], v[38:41], v[70:73], v[10:13]
	s_nop 2
	ds_read_b128 v[10:13], v114 offset:49152
	v_mfma_f32_16x16x32_bf16 v[18:21], v[38:41], v[74:77], v[18:21]
	v_mfma_f32_16x16x32_bf16 v[74:77], v[38:41], v[78:81], v[26:29]
	ds_read_b128 v[78:81], v1 offset:32768
	v_mfma_f32_16x16x32_bf16 v[2:5], v[38:41], v[82:85], v[2:5]
	ds_read_b128 v[82:85], v1 offset:34816
	v_lshl_add_u32 v1, v112, 6, s10
	v_lshl_or_b32 v1, v111, 2, v1
	s_waitcnt lgkmcnt(1)
	v_mfma_f32_16x16x32_bf16 v[62:65], v[10:13], v[78:81], v[14:17]
	v_mfma_f32_16x16x32_bf16 v[14:17], v[10:13], v[106:109], v[6:9]
	s_nop 2
	ds_read_b128 v[6:9], v114 offset:51200
	s_waitcnt lgkmcnt(1)
	v_mfma_f32_16x16x32_bf16 v[46:49], v[10:13], v[82:85], v[22:25]
	v_mfma_f32_16x16x32_bf16 v[30:33], v[10:13], v[102:105], v[30:33]
	s_waitcnt lgkmcnt(0)
	v_mfma_f32_16x16x32_bf16 v[58:61], v[6:9], v[78:81], v[42:45]
	v_mfma_f32_16x16x32_bf16 v[42:45], v[6:9], v[82:85], v[86:89]
	v_mfma_f32_16x16x32_bf16 v[26:29], v[6:9], v[102:105], v[50:53]
	s_nop 1
	ds_read_b128 v[86:89], v114 offset:55296
	v_mfma_f32_16x16x32_bf16 v[10:13], v[6:9], v[106:109], v[34:37]
	ds_read_b128 v[6:9], v114 offset:53248
	s_waitcnt lgkmcnt(0)
	v_mfma_f32_16x16x32_bf16 v[54:57], v[6:9], v[78:81], v[90:93]
	v_mfma_f32_16x16x32_bf16 v[38:41], v[6:9], v[82:85], v[94:97]
	v_mfma_f32_16x16x32_bf16 v[22:25], v[6:9], v[102:105], v[66:69]
	v_mfma_f32_16x16x32_bf16 v[6:9], v[6:9], v[106:109], v[98:101]
	s_nop 1
	v_lshl_or_b32 v67, v113, 6, v110
	v_cmp_gt_u32_e32 vcc, s9, v67
	v_mfma_f32_16x16x32_bf16 v[50:53], v[86:89], v[78:81], v[70:73]
	v_mfma_f32_16x16x32_bf16 v[34:37], v[86:89], v[82:85], v[18:21]
	v_mfma_f32_16x16x32_bf16 v[18:21], v[86:89], v[102:105], v[74:77]
	v_mfma_f32_16x16x32_bf16 v[2:5], v[86:89], v[106:109], v[2:5]
	s_and_saveexec_b64 s[40:41], vcc
	s_cbranch_execz .LBB0_302
; DI float bflo(unsigned u) { return __uint_as_float(u << 16); }
; DI float bfhi(unsigned u) { return __uint_as_float(u & 0xffff0000u); }
; DI void st_bf4(u16* p, float a, float b, float c, float d) { *(uint2*)p = make_uint2(pk2(a, b), pk2(c, d)); }
;   template <int NT, int MT> DI void run(f32x4 (&acc)[NT][MT], int mb, int nb) const {
; #pragma unroll
;     for (int mt = 0; mt < MT; ++mt) {
;       const int i = mb + mt * 16;
;       if (i < nvalid) {
;         const float bias = bs[i];
;         const size_t row = (size_t)(rowbase + i);
; #pragma unroll
;         for (int nt = 0; nt < NT; ++nt) {
;           const int ch = g * 256 + nb + nt * 16;
;           const uint2 uu = *(const uint2*)(uv + row * 2048 + ch);
;           u16* q = mix + row * 2048 + 1024 + ch;
;           const uint2 gt = *(const uint2*)q;
;           f32x4 v = acc[nt][mt];
;           st_bf4(q, (v[0] + bias) * bflo(uu.x) * bflo(gt.x), (v[1] + bias) * bfhi(uu.x) * bfhi(gt.x),
;                  (v[2] + bias) * bflo(uu.y) * bflo(gt.y), (v[3] + bias) * bfhi(uu.y) * bfhi(gt.y));
;         }
;       }
	v_mov_b32_e32 v135, v183
	v_add_u32_e32 v134, s7, v67
	v_readlane_b32 s10, v252, 33
	v_add_u32_e32 v136, s8, v1
	v_lshlrev_b64 v[138:139], 12, v[134:135]
	v_readlane_b32 s11, v252, 34
	v_ashrrev_i32_e32 v137, 31, v136
	v_lshlrev_b64 v[140:141], 1, v[136:137]
	v_lshl_add_u64 v[142:143], s[10:11], 0, v[138:139]
	v_readlane_b32 s10, v252, 35
	v_readlane_b32 s11, v252, 36
	v_lshlrev_b32_e32 v144, 2, v67
	v_lshl_add_u64 v[146:147], v[142:143], 0, v[140:141]
	v_lshl_add_u64 v[148:149], s[10:11], 0, v[138:139]
	global_load_dword v145, v144, s[38:39] offset:2048
	v_lshl_add_u64 v[150:151], v[148:149], 0, v[140:141]
	global_load_dwordx2 v[152:153], v[146:147], off
	global_load_dwordx2 v[154:155], v[150:151], off offset:2048
	v_add_u32_e32 v156, 16, v136
	v_ashrrev_i32_e32 v157, 31, v156
	v_lshlrev_b64 v[158:159], 1, v[156:157]
	v_lshl_add_u64 v[160:161], v[142:143], 0, v[158:159]
	global_load_dwordx2 v[162:163], v[160:161], off
	v_lshl_add_u64 v[164:165], v[148:149], 0, v[158:159]
	global_load_dwordx2 v[166:167], v[164:165], off offset:2048
	v_add_u32_e32 v168, 32, v136
	v_ashrrev_i32_e32 v169, 31, v168
	v_lshlrev_b64 v[170:171], 1, v[168:169]
	v_lshl_add_u64 v[172:173], v[142:143], 0, v[170:171]
	global_load_dwordx2 v[174:175], v[172:173], off
	v_lshl_add_u64 v[176:177], v[148:149], 0, v[170:171]
	global_load_dwordx2 v[178:179], v[176:177], off offset:2048
	v_add_u32_e32 v180, 48, v136
	v_ashrrev_i32_e32 v181, 31, v180
	v_lshlrev_b64 v[186:187], 1, v[180:181]
	v_lshl_add_u64 v[188:189], v[142:143], 0, v[186:187]
	global_load_dwordx2 v[190:191], v[188:189], off
	v_lshl_add_u64 v[192:193], v[148:149], 0, v[186:187]
	global_load_dwordx2 v[194:195], v[192:193], off offset:2048
	s_nop 0
	s_nop 0
	s_nop 0
	s_nop 0
	s_nop 0
	s_nop 0
	s_nop 0
	s_nop 0
	s_nop 0
	s_nop 0
	s_nop 0
	s_nop 0
	s_nop 0
	s_nop 0
	s_nop 0
	s_nop 0
	s_waitcnt vmcnt(8)
	v_mov_b32_e32 v196, v145
	v_mov_b32_e32 v197, v67
	v_pk_add_f32 v[62:63], v[62:63], v[196:197] op_sel_hi:[1,0]
	s_nop 0
	s_waitcnt vmcnt(7)
	v_lshlrev_b32_e32 v80, 16, v152
	v_and_b32_e32 v81, 0xffff0000, v152
	v_lshlrev_b32_e32 v76, 16, v153
	v_and_b32_e32 v77, 0xffff0000, v153
	v_mov_b32_e32 v224, v145
	v_mov_b32_e32 v225, v67
	v_pk_add_f32 v[64:65], v[64:65], v[224:225] op_sel_hi:[1,0]
	v_pk_mul_f32 v[62:63], v[62:63], v[80:81]
	v_pk_mul_f32 v[64:65], v[64:65], v[76:77]
	v_mov_b32_e32 v226, v145
	v_mov_b32_e32 v227, v67
	v_pk_add_f32 v[58:59], v[58:59], v[226:227] op_sel_hi:[1,0]
	v_mov_b32_e32 v228, v145
	v_mov_b32_e32 v229, v67
	v_pk_add_f32 v[60:61], v[60:61], v[228:229] op_sel_hi:[1,0]
	v_mov_b32_e32 v230, v145
	v_mov_b32_e32 v231, v67
	v_pk_add_f32 v[54:55], v[54:55], v[230:231] op_sel_hi:[1,0]
	v_mov_b32_e32 v232, v145
	v_mov_b32_e32 v233, v67
	v_pk_add_f32 v[56:57], v[56:57], v[232:233] op_sel_hi:[1,0]
	v_mov_b32_e32 v234, v145
	v_mov_b32_e32 v235, v67
	v_pk_add_f32 v[50:51], v[50:51], v[234:235] op_sel_hi:[1,0]
	v_mov_b32_e32 v236, v145
	v_mov_b32_e32 v237, v67
	v_pk_add_f32 v[52:53], v[52:53], v[236:237] op_sel_hi:[1,0]
	s_waitcnt vmcnt(6)
	v_lshlrev_b32_e32 v82, 16, v154
	v_and_b32_e32 v83, 0xffff0000, v154
	v_lshlrev_b32_e32 v78, 16, v155
	v_and_b32_e32 v79, 0xffff0000, v155
	v_pk_mul_f32 v[62:63], v[62:63], v[82:83]
	v_pk_mul_f32 v[64:65], v[64:65], v[78:79]
	v_cvt_pk_bf16_f32 v62, v62, v63
	v_cvt_pk_bf16_f32 v63, v64, v65
	global_store_dwordx2 v[150:151], v[62:63], off offset:2048
	s_nop 0
	s_nop 0
	s_nop 0
	s_nop 0
	s_nop 0
	s_nop 0
	s_nop 0
	s_waitcnt vmcnt(5)
	v_lshlrev_b32_e32 v76, 16, v162
	v_and_b32_e32 v77, 0xffff0000, v162
	v_lshlrev_b32_e32 v64, 16, v163
	v_and_b32_e32 v65, 0xffff0000, v163
	s_waitcnt vmcnt(4)
	v_lshlrev_b32_e32 v78, 16, v166
	v_and_b32_e32 v79, 0xffff0000, v166
	v_pk_mul_f32 v[58:59], v[58:59], v[76:77]
	v_lshlrev_b32_e32 v74, 16, v167
	v_and_b32_e32 v75, 0xffff0000, v167
	v_pk_mul_f32 v[60:61], v[60:61], v[64:65]
	v_pk_mul_f32 v[58:59], v[58:59], v[78:79]
	v_pk_mul_f32 v[60:61], v[60:61], v[74:75]
	v_cvt_pk_bf16_f32 v58, v58, v59
	v_cvt_pk_bf16_f32 v59, v60, v61
	global_store_dwordx2 v[164:165], v[58:59], off offset:2048
	s_nop 0
	s_nop 0
	s_nop 0
	s_nop 0
	s_nop 0
	s_nop 0
	s_nop 0
	s_waitcnt vmcnt(3)
	v_lshlrev_b32_e32 v64, 16, v174
	v_and_b32_e32 v65, 0xffff0000, v174
	v_lshlrev_b32_e32 v60, 16, v175
	v_and_b32_e32 v61, 0xffff0000, v175
	s_waitcnt vmcnt(2)
	v_lshlrev_b32_e32 v74, 16, v178
	v_and_b32_e32 v75, 0xffff0000, v178
	v_pk_mul_f32 v[54:55], v[54:55], v[64:65]
	v_lshlrev_b32_e32 v62, 16, v179
	v_and_b32_e32 v63, 0xffff0000, v179
	v_pk_mul_f32 v[56:57], v[56:57], v[60:61]
	v_pk_mul_f32 v[54:55], v[54:55], v[74:75]
	v_pk_mul_f32 v[56:57], v[56:57], v[62:63]
	v_cvt_pk_bf16_f32 v54, v54, v55
	v_cvt_pk_bf16_f32 v55, v56, v57
	global_store_dwordx2 v[176:177], v[54:55], off offset:2048
	s_nop 0
	s_nop 0
	s_nop 0
	s_nop 0
	s_nop 0
	s_nop 0
	s_nop 0
	s_waitcnt vmcnt(1)
	v_lshlrev_b32_e32 v60, 16, v190
	v_and_b32_e32 v61, 0xffff0000, v190
	v_lshlrev_b32_e32 v56, 16, v191
	v_and_b32_e32 v57, 0xffff0000, v191
	s_waitcnt vmcnt(0)
	v_lshlrev_b32_e32 v62, 16, v194
	v_and_b32_e32 v63, 0xffff0000, v194
	v_pk_mul_f32 v[50:51], v[50:51], v[60:61]
	v_lshlrev_b32_e32 v58, 16, v195
	v_and_b32_e32 v59, 0xffff0000, v195
	v_pk_mul_f32 v[52:53], v[52:53], v[56:57]
	v_pk_mul_f32 v[50:51], v[50:51], v[62:63]
	v_pk_mul_f32 v[52:53], v[52:53], v[58:59]
	v_cvt_pk_bf16_f32 v50, v50, v51
	v_cvt_pk_bf16_f32 v51, v52, v53
	global_store_dwordx2 v[192:193], v[50:51], off offset:2048
	v_mov_b32_e32 v54, v192
	v_mov_b32_e32 v55, v193
	v_mov_b32_e32 v66, v145
	v_mov_b32_e32 v68, v142
	v_mov_b32_e32 v69, v143
	v_mov_b32_e32 v70, v136
	v_mov_b32_e32 v71, v137
	v_mov_b32_e32 v72, v148
	v_mov_b32_e32 v73, v149
	v_mov_b32_e32 v182, v134
; DI float bflo(unsigned u) { return __uint_as_float(u << 16); }
; DI float bfhi(unsigned u) { return __uint_as_float(u & 0xffff0000u); }
; DI void st_bf4(u16* p, float a, float b, float c, float d) { *(uint2*)p = make_uint2(pk2(a, b), pk2(c, d)); }
;   template <int NT, int MT> DI void run(f32x4 (&acc)[NT][MT], int mb, int nb) const {
; #pragma unroll
;     for (int mt = 0; mt < MT; ++mt) {
;       const int i = mb + mt * 16;
;       if (i < nvalid) {
;         const float bias = bs[i];
;         const size_t row = (size_t)(rowbase + i);
; #pragma unroll
;         for (int nt = 0; nt < NT; ++nt) {
;           const int ch = g * 256 + nb + nt * 16;
;           const uint2 uu = *(const uint2*)(uv + row * 2048 + ch);
;           u16* q = mix + row * 2048 + 1024 + ch;
;           const uint2 gt = *(const uint2*)q;
;           f32x4 v = acc[nt][mt];
;           st_bf4(q, (v[0] + bias) * bflo(uu.x) * bflo(gt.x), (v[1] + bias) * bfhi(uu.x) * bfhi(gt.x),
;                  (v[2] + bias) * bflo(uu.y) * bflo(gt.y), (v[3] + bias) * bfhi(uu.y) * bfhi(gt.y));
;         }
;       }
.LBB0_302:
	s_or_b64 exec, exec, s[40:41]
	s_nop 1
	v_or_b32_e32 v51, 16, v67
	v_cmp_gt_u32_e32 vcc, s9, v51
	s_and_saveexec_b64 s[40:41], vcc
	s_cbranch_execz .LBB0_304
	v_mov_b32_e32 v135, v183
	v_add_u32_e32 v134, s7, v51
	v_readlane_b32 s10, v252, 33
	v_add_u32_e32 v136, s8, v1
	v_lshlrev_b64 v[138:139], 12, v[134:135]
	v_readlane_b32 s11, v252, 34
	v_ashrrev_i32_e32 v137, 31, v136
	v_lshlrev_b64 v[140:141], 1, v[136:137]
	v_lshl_add_u64 v[142:143], s[10:11], 0, v[138:139]
	v_readlane_b32 s10, v252, 35
	v_readlane_b32 s11, v252, 36
	v_lshlrev_b32_e32 v144, 2, v67
	v_lshl_add_u64 v[146:147], v[142:143], 0, v[140:141]
	v_lshl_add_u64 v[148:149], s[10:11], 0, v[138:139]
	global_load_dword v145, v144, s[38:39] offset:2112
	v_lshl_add_u64 v[150:151], v[148:149], 0, v[140:141]
	global_load_dwordx2 v[152:153], v[146:147], off
	global_load_dwordx2 v[154:155], v[150:151], off offset:2048
	v_add_u32_e32 v156, 16, v136
	v_ashrrev_i32_e32 v157, 31, v156
	v_lshlrev_b64 v[158:159], 1, v[156:157]
	v_lshl_add_u64 v[160:161], v[142:143], 0, v[158:159]
	global_load_dwordx2 v[162:163], v[160:161], off
	v_lshl_add_u64 v[164:165], v[148:149], 0, v[158:159]
	global_load_dwordx2 v[166:167], v[164:165], off offset:2048
	v_add_u32_e32 v168, 32, v136
	v_ashrrev_i32_e32 v169, 31, v168
	v_lshlrev_b64 v[170:171], 1, v[168:169]
	v_lshl_add_u64 v[172:173], v[142:143], 0, v[170:171]
	global_load_dwordx2 v[174:175], v[172:173], off
	v_lshl_add_u64 v[176:177], v[148:149], 0, v[170:171]
	global_load_dwordx2 v[178:179], v[176:177], off offset:2048
	v_add_u32_e32 v180, 48, v136
	v_ashrrev_i32_e32 v181, 31, v180
	v_lshlrev_b64 v[186:187], 1, v[180:181]
	v_lshl_add_u64 v[188:189], v[142:143], 0, v[186:187]
	global_load_dwordx2 v[190:191], v[188:189], off
	v_lshl_add_u64 v[192:193], v[148:149], 0, v[186:187]
	global_load_dwordx2 v[194:195], v[192:193], off offset:2048
	s_nop 0
	s_nop 0
	s_nop 0
	s_nop 0
	s_nop 0
	s_nop 0
	s_nop 0
	s_nop 0
	s_nop 0
	s_nop 0
	s_nop 0
	s_nop 0
	s_nop 0
	s_nop 0
	s_nop 0
	s_nop 0
	s_waitcnt vmcnt(8)
	v_mov_b32_e32 v196, v145
	v_mov_b32_e32 v197, v51
	v_pk_add_f32 v[46:47], v[46:47], v[196:197] op_sel_hi:[1,0]
	s_nop 0
	s_waitcnt vmcnt(7)
	v_lshlrev_b32_e32 v64, 16, v152
	v_and_b32_e32 v65, 0xffff0000, v152
	v_lshlrev_b32_e32 v60, 16, v153
	v_and_b32_e32 v61, 0xffff0000, v153
	v_mov_b32_e32 v224, v145
	v_mov_b32_e32 v225, v51
	v_pk_add_f32 v[48:49], v[48:49], v[224:225] op_sel_hi:[1,0]
	v_pk_mul_f32 v[46:47], v[46:47], v[64:65]
	v_pk_mul_f32 v[48:49], v[48:49], v[60:61]
	v_mov_b32_e32 v226, v145
	v_mov_b32_e32 v227, v51
	v_pk_add_f32 v[42:43], v[42:43], v[226:227] op_sel_hi:[1,0]
	v_mov_b32_e32 v228, v145
	v_mov_b32_e32 v229, v51
	v_pk_add_f32 v[44:45], v[44:45], v[228:229] op_sel_hi:[1,0]
	v_mov_b32_e32 v230, v145
	v_mov_b32_e32 v231, v51
	v_pk_add_f32 v[38:39], v[38:39], v[230:231] op_sel_hi:[1,0]
	v_mov_b32_e32 v232, v145
	v_mov_b32_e32 v233, v51
	v_pk_add_f32 v[40:41], v[40:41], v[232:233] op_sel_hi:[1,0]
	v_mov_b32_e32 v234, v145
	v_mov_b32_e32 v235, v51
	v_pk_add_f32 v[34:35], v[34:35], v[234:235] op_sel_hi:[1,0]
	v_mov_b32_e32 v236, v145
	v_mov_b32_e32 v237, v51
	v_pk_add_f32 v[36:37], v[36:37], v[236:237] op_sel_hi:[1,0]
	s_waitcnt vmcnt(6)
	v_lshlrev_b32_e32 v68, 16, v154
	v_and_b32_e32 v69, 0xffff0000, v154
	v_lshlrev_b32_e32 v62, 16, v155
	v_and_b32_e32 v63, 0xffff0000, v155
	v_pk_mul_f32 v[46:47], v[46:47], v[68:69]
	v_pk_mul_f32 v[48:49], v[48:49], v[62:63]
	v_cvt_pk_bf16_f32 v46, v46, v47
	v_cvt_pk_bf16_f32 v47, v48, v49
	global_store_dwordx2 v[150:151], v[46:47], off offset:2048
	s_nop 0
	s_nop 0
	s_nop 0
	s_nop 0
	s_nop 0
	s_nop 0
	s_nop 0
	s_waitcnt vmcnt(5)
	v_lshlrev_b32_e32 v60, 16, v162
	v_and_b32_e32 v61, 0xffff0000, v162
	v_lshlrev_b32_e32 v48, 16, v163
	v_and_b32_e32 v49, 0xffff0000, v163
	s_waitcnt vmcnt(4)
	v_lshlrev_b32_e32 v62, 16, v166
	v_and_b32_e32 v63, 0xffff0000, v166
	v_pk_mul_f32 v[42:43], v[42:43], v[60:61]
	v_lshlrev_b32_e32 v58, 16, v167
	v_and_b32_e32 v59, 0xffff0000, v167
	v_pk_mul_f32 v[44:45], v[44:45], v[48:49]
	v_pk_mul_f32 v[42:43], v[42:43], v[62:63]
	v_pk_mul_f32 v[44:45], v[44:45], v[58:59]
	v_cvt_pk_bf16_f32 v42, v42, v43
	v_cvt_pk_bf16_f32 v43, v44, v45
	global_store_dwordx2 v[164:165], v[42:43], off offset:2048
	s_nop 0
	s_nop 0
	s_nop 0
	s_nop 0
	s_nop 0
	s_nop 0
	s_nop 0
	s_waitcnt vmcnt(3)
	v_lshlrev_b32_e32 v48, 16, v174
	v_and_b32_e32 v49, 0xffff0000, v174
	v_lshlrev_b32_e32 v44, 16, v175
	v_and_b32_e32 v45, 0xffff0000, v175
	s_waitcnt vmcnt(2)
	v_lshlrev_b32_e32 v58, 16, v178
	v_and_b32_e32 v59, 0xffff0000, v178
	v_pk_mul_f32 v[38:39], v[38:39], v[48:49]
	v_lshlrev_b32_e32 v46, 16, v179
	v_and_b32_e32 v47, 0xffff0000, v179
	v_pk_mul_f32 v[40:41], v[40:41], v[44:45]
	v_pk_mul_f32 v[38:39], v[38:39], v[58:59]
	v_pk_mul_f32 v[40:41], v[40:41], v[46:47]
	v_cvt_pk_bf16_f32 v38, v38, v39
	v_cvt_pk_bf16_f32 v39, v40, v41
	global_store_dwordx2 v[176:177], v[38:39], off offset:2048
	s_nop 0
	s_nop 0
	s_nop 0
	s_nop 0
	s_nop 0
	s_nop 0
	s_nop 0
	s_waitcnt vmcnt(1)
	v_lshlrev_b32_e32 v44, 16, v190
	v_and_b32_e32 v45, 0xffff0000, v190
	v_lshlrev_b32_e32 v40, 16, v191
	v_and_b32_e32 v41, 0xffff0000, v191
	s_waitcnt vmcnt(0)
	v_lshlrev_b32_e32 v46, 16, v194
	v_and_b32_e32 v47, 0xffff0000, v194
	v_pk_mul_f32 v[34:35], v[34:35], v[44:45]
	v_lshlrev_b32_e32 v42, 16, v195
	v_and_b32_e32 v43, 0xffff0000, v195
	v_pk_mul_f32 v[36:37], v[36:37], v[40:41]
	v_pk_mul_f32 v[34:35], v[34:35], v[46:47]
	v_pk_mul_f32 v[36:37], v[36:37], v[42:43]
	v_cvt_pk_bf16_f32 v34, v34, v35
	v_cvt_pk_bf16_f32 v35, v36, v37
	global_store_dwordx2 v[192:193], v[34:35], off offset:2048
	v_mov_b32_e32 v38, v192
	v_mov_b32_e32 v39, v193
	v_mov_b32_e32 v50, v145
	v_mov_b32_e32 v52, v142
	v_mov_b32_e32 v53, v143
	v_mov_b32_e32 v54, v136
	v_mov_b32_e32 v55, v137
	v_mov_b32_e32 v56, v148
	v_mov_b32_e32 v57, v149
	v_mov_b32_e32 v182, v134
; DI float bflo(unsigned u) { return __uint_as_float(u << 16); }
; DI float bfhi(unsigned u) { return __uint_as_float(u & 0xffff0000u); }
; DI void st_bf4(u16* p, float a, float b, float c, float d) { *(uint2*)p = make_uint2(pk2(a, b), pk2(c, d)); }
;   template <int NT, int MT> DI void run(f32x4 (&acc)[NT][MT], int mb, int nb) const {
; #pragma unroll
;     for (int mt = 0; mt < MT; ++mt) {
;       const int i = mb + mt * 16;
;       if (i < nvalid) {
;         const float bias = bs[i];
;         const size_t row = (size_t)(rowbase + i);
; #pragma unroll
;         for (int nt = 0; nt < NT; ++nt) {
;           const int ch = g * 256 + nb + nt * 16;
;           const uint2 uu = *(const uint2*)(uv + row * 2048 + ch);
;           u16* q = mix + row * 2048 + 1024 + ch;
;           const uint2 gt = *(const uint2*)q;
;           f32x4 v = acc[nt][mt];
;           st_bf4(q, (v[0] + bias) * bflo(uu.x) * bflo(gt.x), (v[1] + bias) * bfhi(uu.x) * bfhi(gt.x),
;                  (v[2] + bias) * bflo(uu.y) * bflo(gt.y), (v[3] + bias) * bfhi(uu.y) * bfhi(gt.y));
;         }
;       }
.LBB0_304:
	s_or_b64 exec, exec, s[40:41]
	v_or_b32_e32 v35, 32, v67
	v_cmp_gt_u32_e32 vcc, s9, v35
	s_and_saveexec_b64 s[40:41], vcc
	s_mov_b64 s[68:69], s[24:25]
	s_mov_b64 s[70:71], s[26:27]
	s_movk_i32 s64, 0x41ff
	s_mov_b64 s[66:67], 0x5a8080
	s_mov_b32 s65, 0x2aaaaaab
	s_cbranch_execz .LBB0_306
	v_mov_b32_e32 v135, v183
	v_add_u32_e32 v134, s7, v35
	v_readlane_b32 s10, v252, 33
	v_add_u32_e32 v136, s8, v1
	v_lshlrev_b64 v[138:139], 12, v[134:135]
	v_readlane_b32 s11, v252, 34
	v_ashrrev_i32_e32 v137, 31, v136
	v_lshlrev_b64 v[140:141], 1, v[136:137]
	v_lshl_add_u64 v[142:143], s[10:11], 0, v[138:139]
	v_readlane_b32 s10, v252, 35
	v_readlane_b32 s11, v252, 36
	v_lshlrev_b32_e32 v144, 2, v67
	v_lshl_add_u64 v[146:147], v[142:143], 0, v[140:141]
	v_lshl_add_u64 v[148:149], s[10:11], 0, v[138:139]
	global_load_dword v145, v144, s[38:39] offset:2176
	v_lshl_add_u64 v[150:151], v[148:149], 0, v[140:141]
	global_load_dwordx2 v[152:153], v[146:147], off
	global_load_dwordx2 v[154:155], v[150:151], off offset:2048
	v_add_u32_e32 v156, 16, v136
	v_ashrrev_i32_e32 v157, 31, v156
	v_lshlrev_b64 v[158:159], 1, v[156:157]
	v_lshl_add_u64 v[160:161], v[142:143], 0, v[158:159]
	global_load_dwordx2 v[162:163], v[160:161], off
	v_lshl_add_u64 v[164:165], v[148:149], 0, v[158:159]
	global_load_dwordx2 v[166:167], v[164:165], off offset:2048
	v_add_u32_e32 v168, 32, v136
	v_ashrrev_i32_e32 v169, 31, v168
	v_lshlrev_b64 v[170:171], 1, v[168:169]
	v_lshl_add_u64 v[172:173], v[142:143], 0, v[170:171]
	global_load_dwordx2 v[174:175], v[172:173], off
	v_lshl_add_u64 v[176:177], v[148:149], 0, v[170:171]
	global_load_dwordx2 v[178:179], v[176:177], off offset:2048
	v_add_u32_e32 v180, 48, v136
	v_ashrrev_i32_e32 v181, 31, v180
	v_lshlrev_b64 v[186:187], 1, v[180:181]
	v_lshl_add_u64 v[188:189], v[142:143], 0, v[186:187]
	global_load_dwordx2 v[190:191], v[188:189], off
	v_lshl_add_u64 v[192:193], v[148:149], 0, v[186:187]
	global_load_dwordx2 v[194:195], v[192:193], off offset:2048
	s_nop 0
	s_nop 0
	s_nop 0
	s_nop 0
	s_nop 0
	s_nop 0
	s_nop 0
	s_nop 0
	s_nop 0
	s_nop 0
	s_nop 0
	s_nop 0
	s_nop 0
	s_nop 0
	s_nop 0
	s_nop 0
	s_waitcnt vmcnt(8)
	v_mov_b32_e32 v196, v145
	v_mov_b32_e32 v197, v35
	v_pk_add_f32 v[30:31], v[30:31], v[196:197] op_sel_hi:[1,0]
	s_nop 0
	s_waitcnt vmcnt(7)
	v_lshlrev_b32_e32 v48, 16, v152
	v_and_b32_e32 v49, 0xffff0000, v152
	v_lshlrev_b32_e32 v44, 16, v153
	v_and_b32_e32 v45, 0xffff0000, v153
	v_mov_b32_e32 v224, v145
	v_mov_b32_e32 v225, v35
	v_pk_add_f32 v[32:33], v[32:33], v[224:225] op_sel_hi:[1,0]
	v_pk_mul_f32 v[30:31], v[30:31], v[48:49]
	v_pk_mul_f32 v[32:33], v[32:33], v[44:45]
	v_mov_b32_e32 v226, v145
	v_mov_b32_e32 v227, v35
	v_pk_add_f32 v[26:27], v[26:27], v[226:227] op_sel_hi:[1,0]
	v_mov_b32_e32 v228, v145
	v_mov_b32_e32 v229, v35
	v_pk_add_f32 v[28:29], v[28:29], v[228:229] op_sel_hi:[1,0]
	v_mov_b32_e32 v230, v145
	v_mov_b32_e32 v231, v35
	v_pk_add_f32 v[22:23], v[22:23], v[230:231] op_sel_hi:[1,0]
	v_mov_b32_e32 v232, v145
	v_mov_b32_e32 v233, v35
	v_pk_add_f32 v[24:25], v[24:25], v[232:233] op_sel_hi:[1,0]
	v_mov_b32_e32 v234, v145
	v_mov_b32_e32 v235, v35
	v_pk_add_f32 v[18:19], v[18:19], v[234:235] op_sel_hi:[1,0]
	v_mov_b32_e32 v236, v145
	v_mov_b32_e32 v237, v35
	v_pk_add_f32 v[20:21], v[20:21], v[236:237] op_sel_hi:[1,0]
	s_waitcnt vmcnt(6)
	v_lshlrev_b32_e32 v50, 16, v154
	v_and_b32_e32 v51, 0xffff0000, v154
	v_lshlrev_b32_e32 v46, 16, v155
	v_and_b32_e32 v47, 0xffff0000, v155
	v_pk_mul_f32 v[30:31], v[30:31], v[50:51]
	v_pk_mul_f32 v[32:33], v[32:33], v[46:47]
	v_cvt_pk_bf16_f32 v30, v30, v31
	v_cvt_pk_bf16_f32 v31, v32, v33
	global_store_dwordx2 v[150:151], v[30:31], off offset:2048
	s_nop 0
	s_nop 0
	s_nop 0
	s_nop 0
	s_nop 0
	s_nop 0
	s_nop 0
	s_waitcnt vmcnt(5)
	v_lshlrev_b32_e32 v44, 16, v162
	v_and_b32_e32 v45, 0xffff0000, v162
	v_lshlrev_b32_e32 v32, 16, v163
	v_and_b32_e32 v33, 0xffff0000, v163
	s_waitcnt vmcnt(4)
	v_lshlrev_b32_e32 v46, 16, v166
	v_and_b32_e32 v47, 0xffff0000, v166
	v_pk_mul_f32 v[26:27], v[26:27], v[44:45]
	v_lshlrev_b32_e32 v42, 16, v167
	v_and_b32_e32 v43, 0xffff0000, v167
	v_pk_mul_f32 v[28:29], v[28:29], v[32:33]
	v_pk_mul_f32 v[26:27], v[26:27], v[46:47]
	v_pk_mul_f32 v[28:29], v[28:29], v[42:43]
	v_cvt_pk_bf16_f32 v26, v26, v27
	v_cvt_pk_bf16_f32 v27, v28, v29
	global_store_dwordx2 v[164:165], v[26:27], off offset:2048
	s_nop 0
	s_nop 0
	s_nop 0
	s_nop 0
	s_nop 0
	s_nop 0
	s_nop 0
	s_waitcnt vmcnt(3)
	v_lshlrev_b32_e32 v32, 16, v174
	v_and_b32_e32 v33, 0xffff0000, v174
	v_lshlrev_b32_e32 v28, 16, v175
	v_and_b32_e32 v29, 0xffff0000, v175
	s_waitcnt vmcnt(2)
	v_lshlrev_b32_e32 v42, 16, v178
	v_and_b32_e32 v43, 0xffff0000, v178
	v_pk_mul_f32 v[22:23], v[22:23], v[32:33]
	v_lshlrev_b32_e32 v30, 16, v179
	v_and_b32_e32 v31, 0xffff0000, v179
	v_pk_mul_f32 v[24:25], v[24:25], v[28:29]
	v_pk_mul_f32 v[22:23], v[22:23], v[42:43]
	v_pk_mul_f32 v[24:25], v[24:25], v[30:31]
	v_cvt_pk_bf16_f32 v22, v22, v23
	v_cvt_pk_bf16_f32 v23, v24, v25
	global_store_dwordx2 v[176:177], v[22:23], off offset:2048
	s_nop 0
	s_nop 0
	s_nop 0
	s_nop 0
	s_nop 0
	s_nop 0
	s_nop 0
	s_waitcnt vmcnt(1)
	v_lshlrev_b32_e32 v28, 16, v190
	v_and_b32_e32 v29, 0xffff0000, v190
	v_lshlrev_b32_e32 v24, 16, v191
	v_and_b32_e32 v25, 0xffff0000, v191
	s_waitcnt vmcnt(0)
	v_lshlrev_b32_e32 v30, 16, v194
	v_and_b32_e32 v31, 0xffff0000, v194
	v_pk_mul_f32 v[18:19], v[18:19], v[28:29]
	v_lshlrev_b32_e32 v26, 16, v195
	v_and_b32_e32 v27, 0xffff0000, v195
	v_pk_mul_f32 v[20:21], v[20:21], v[24:25]
	v_pk_mul_f32 v[18:19], v[18:19], v[30:31]
	v_pk_mul_f32 v[20:21], v[20:21], v[26:27]
	v_cvt_pk_bf16_f32 v18, v18, v19
	v_cvt_pk_bf16_f32 v19, v20, v21
	global_store_dwordx2 v[192:193], v[18:19], off offset:2048
	v_mov_b32_e32 v22, v192
	v_mov_b32_e32 v23, v193
	v_mov_b32_e32 v34, v145
	v_mov_b32_e32 v36, v142
	v_mov_b32_e32 v37, v143
	v_mov_b32_e32 v38, v136
	v_mov_b32_e32 v39, v137
	v_mov_b32_e32 v40, v148
	v_mov_b32_e32 v41, v149
	v_mov_b32_e32 v182, v134
; DI float bflo(unsigned u) { return __uint_as_float(u << 16); }
; DI float bfhi(unsigned u) { return __uint_as_float(u & 0xffff0000u); }
; DI void st_bf4(u16* p, float a, float b, float c, float d) { *(uint2*)p = make_uint2(pk2(a, b), pk2(c, d)); }
;   template <int NT, int MT> DI void run(f32x4 (&acc)[NT][MT], int mb, int nb) const {
; #pragma unroll
;     for (int mt = 0; mt < MT; ++mt) {
;       const int i = mb + mt * 16;
;       if (i < nvalid) {
;         const float bias = bs[i];
;         const size_t row = (size_t)(rowbase + i);
; #pragma unroll
;         for (int nt = 0; nt < NT; ++nt) {
;           const int ch = g * 256 + nb + nt * 16;
;           const uint2 uu = *(const uint2*)(uv + row * 2048 + ch);
;           u16* q = mix + row * 2048 + 1024 + ch;
;           const uint2 gt = *(const uint2*)q;
;           f32x4 v = acc[nt][mt];
;           st_bf4(q, (v[0] + bias) * bflo(uu.x) * bflo(gt.x), (v[1] + bias) * bfhi(uu.x) * bfhi(gt.x),
;                  (v[2] + bias) * bflo(uu.y) * bflo(gt.y), (v[3] + bias) * bfhi(uu.y) * bfhi(gt.y));
;         }
;       }
.LBB0_306:
	s_or_b64 exec, exec, s[40:41]
	v_or_b32_e32 v19, 48, v67
	v_cmp_gt_u32_e32 vcc, s9, v19
	s_and_saveexec_b64 s[40:41], vcc
	s_cbranch_execz .LBB0_308
	v_mov_b32_e32 v135, v183
	v_add_u32_e32 v134, s7, v19
	v_add_u32_e32 v136, s8, v1
	v_readlane_b32 s8, v252, 33
	v_lshlrev_b64 v[138:139], 12, v[134:135]
	v_readlane_b32 s9, v252, 34
	v_ashrrev_i32_e32 v137, 31, v136
	v_lshlrev_b64 v[140:141], 1, v[136:137]
	v_lshl_add_u64 v[142:143], s[8:9], 0, v[138:139]
	v_readlane_b32 s8, v252, 35
	v_readlane_b32 s9, v252, 36
	v_lshlrev_b32_e32 v144, 2, v67
	v_lshl_add_u64 v[146:147], v[142:143], 0, v[140:141]
	v_lshl_add_u64 v[148:149], s[8:9], 0, v[138:139]
	global_load_dword v145, v144, s[38:39] offset:2240
	v_lshl_add_u64 v[150:151], v[148:149], 0, v[140:141]
	global_load_dwordx2 v[152:153], v[146:147], off
	global_load_dwordx2 v[154:155], v[150:151], off offset:2048
	v_add_u32_e32 v156, 16, v136
	v_ashrrev_i32_e32 v157, 31, v156
	v_lshlrev_b64 v[158:159], 1, v[156:157]
	v_lshl_add_u64 v[160:161], v[142:143], 0, v[158:159]
	global_load_dwordx2 v[162:163], v[160:161], off
	v_lshl_add_u64 v[164:165], v[148:149], 0, v[158:159]
	global_load_dwordx2 v[166:167], v[164:165], off offset:2048
	v_add_u32_e32 v168, 32, v136
	v_ashrrev_i32_e32 v169, 31, v168
	v_lshlrev_b64 v[170:171], 1, v[168:169]
	v_lshl_add_u64 v[172:173], v[142:143], 0, v[170:171]
	global_load_dwordx2 v[174:175], v[172:173], off
	v_lshl_add_u64 v[176:177], v[148:149], 0, v[170:171]
	global_load_dwordx2 v[178:179], v[176:177], off offset:2048
	v_add_u32_e32 v180, 48, v136
	v_ashrrev_i32_e32 v181, 31, v180
	v_lshlrev_b64 v[186:187], 1, v[180:181]
	v_lshl_add_u64 v[188:189], v[142:143], 0, v[186:187]
	global_load_dwordx2 v[190:191], v[188:189], off
	v_lshl_add_u64 v[192:193], v[148:149], 0, v[186:187]
	global_load_dwordx2 v[194:195], v[192:193], off offset:2048
	s_nop 0
	s_nop 0
	s_nop 0
	s_nop 0
	s_nop 0
	s_nop 0
	s_nop 0
	s_nop 0
	s_nop 0
	s_nop 0
	s_nop 0
	s_nop 0
	s_nop 0
	s_nop 0
	s_nop 0
	s_nop 0
	s_waitcnt vmcnt(8)
	v_mov_b32_e32 v196, v145
	v_mov_b32_e32 v197, v19
	v_pk_add_f32 v[14:15], v[14:15], v[196:197] op_sel_hi:[1,0]
	s_nop 0
	s_waitcnt vmcnt(7)
	v_lshlrev_b32_e32 v32, 16, v152
	v_and_b32_e32 v33, 0xffff0000, v152
	v_lshlrev_b32_e32 v28, 16, v153
	v_and_b32_e32 v29, 0xffff0000, v153
	v_mov_b32_e32 v224, v145
	v_mov_b32_e32 v225, v19
	v_pk_add_f32 v[16:17], v[16:17], v[224:225] op_sel_hi:[1,0]
	v_pk_mul_f32 v[14:15], v[14:15], v[32:33]
	v_pk_mul_f32 v[16:17], v[16:17], v[28:29]
	v_mov_b32_e32 v226, v145
	v_mov_b32_e32 v227, v19
	v_pk_add_f32 v[10:11], v[10:11], v[226:227] op_sel_hi:[1,0]
	v_mov_b32_e32 v228, v145
	v_mov_b32_e32 v229, v19
	v_pk_add_f32 v[12:13], v[12:13], v[228:229] op_sel_hi:[1,0]
	v_mov_b32_e32 v230, v145
	v_mov_b32_e32 v231, v19
	v_pk_add_f32 v[6:7], v[6:7], v[230:231] op_sel_hi:[1,0]
	v_mov_b32_e32 v232, v145
	v_mov_b32_e32 v233, v19
	v_pk_add_f32 v[8:9], v[8:9], v[232:233] op_sel_hi:[1,0]
	v_mov_b32_e32 v234, v145
	v_mov_b32_e32 v235, v19
	v_pk_add_f32 v[2:3], v[2:3], v[234:235] op_sel_hi:[1,0]
	v_mov_b32_e32 v236, v145
	v_mov_b32_e32 v237, v19
	v_pk_add_f32 v[4:5], v[4:5], v[236:237] op_sel_hi:[1,0]
	s_waitcnt vmcnt(6)
	v_lshlrev_b32_e32 v34, 16, v154
	v_and_b32_e32 v35, 0xffff0000, v154
	v_lshlrev_b32_e32 v30, 16, v155
	v_and_b32_e32 v31, 0xffff0000, v155
	v_pk_mul_f32 v[14:15], v[14:15], v[34:35]
	v_pk_mul_f32 v[16:17], v[16:17], v[30:31]
	v_cvt_pk_bf16_f32 v14, v14, v15
	v_cvt_pk_bf16_f32 v15, v16, v17
	global_store_dwordx2 v[150:151], v[14:15], off offset:2048
	s_nop 0
	s_nop 0
	s_nop 0
	s_nop 0
	s_nop 0
	s_nop 0
	s_nop 0
	s_waitcnt vmcnt(5)
	v_lshlrev_b32_e32 v28, 16, v162
	v_and_b32_e32 v29, 0xffff0000, v162
	v_lshlrev_b32_e32 v16, 16, v163
	v_and_b32_e32 v17, 0xffff0000, v163
	s_waitcnt vmcnt(4)
	v_lshlrev_b32_e32 v30, 16, v166
	v_and_b32_e32 v31, 0xffff0000, v166
	v_pk_mul_f32 v[10:11], v[10:11], v[28:29]
	v_lshlrev_b32_e32 v26, 16, v167
	v_and_b32_e32 v27, 0xffff0000, v167
	v_pk_mul_f32 v[12:13], v[12:13], v[16:17]
	v_pk_mul_f32 v[10:11], v[10:11], v[30:31]
	v_pk_mul_f32 v[12:13], v[12:13], v[26:27]
	v_cvt_pk_bf16_f32 v10, v10, v11
	v_cvt_pk_bf16_f32 v11, v12, v13
	global_store_dwordx2 v[164:165], v[10:11], off offset:2048
	s_nop 0
	s_nop 0
	s_nop 0
	s_nop 0
	s_nop 0
	s_nop 0
	s_nop 0
	s_waitcnt vmcnt(3)
	v_lshlrev_b32_e32 v16, 16, v174
	v_and_b32_e32 v17, 0xffff0000, v174
	v_lshlrev_b32_e32 v12, 16, v175
	v_and_b32_e32 v13, 0xffff0000, v175
	s_waitcnt vmcnt(2)
	v_lshlrev_b32_e32 v26, 16, v178
	v_and_b32_e32 v27, 0xffff0000, v178
	v_pk_mul_f32 v[6:7], v[6:7], v[16:17]
	v_lshlrev_b32_e32 v14, 16, v179
	v_and_b32_e32 v15, 0xffff0000, v179
	v_pk_mul_f32 v[8:9], v[8:9], v[12:13]
	v_pk_mul_f32 v[6:7], v[6:7], v[26:27]
	v_pk_mul_f32 v[8:9], v[8:9], v[14:15]
	v_cvt_pk_bf16_f32 v6, v6, v7
	v_cvt_pk_bf16_f32 v7, v8, v9
	global_store_dwordx2 v[176:177], v[6:7], off offset:2048
	s_nop 0
	s_nop 0
	s_nop 0
	s_nop 0
	s_nop 0
	s_nop 0
	s_nop 0
	s_waitcnt vmcnt(1)
	v_lshlrev_b32_e32 v12, 16, v190
	v_and_b32_e32 v13, 0xffff0000, v190
	v_lshlrev_b32_e32 v8, 16, v191
	v_and_b32_e32 v9, 0xffff0000, v191
	s_waitcnt vmcnt(0)
	v_lshlrev_b32_e32 v14, 16, v194
	v_and_b32_e32 v15, 0xffff0000, v194
	v_pk_mul_f32 v[2:3], v[2:3], v[12:13]
	v_lshlrev_b32_e32 v10, 16, v195
	v_and_b32_e32 v11, 0xffff0000, v195
	v_pk_mul_f32 v[4:5], v[4:5], v[8:9]
	v_pk_mul_f32 v[2:3], v[2:3], v[14:15]
	v_pk_mul_f32 v[4:5], v[4:5], v[10:11]
	v_cvt_pk_bf16_f32 v2, v2, v3
	v_cvt_pk_bf16_f32 v3, v4, v5
	global_store_dwordx2 v[192:193], v[2:3], off offset:2048
	v_mov_b32_e32 v6, v192
	v_mov_b32_e32 v7, v193
	v_mov_b32_e32 v18, v145
	v_mov_b32_e32 v20, v142
	v_mov_b32_e32 v21, v143
	v_mov_b32_e32 v22, v136
	v_mov_b32_e32 v23, v137
	v_mov_b32_e32 v24, v148
	v_mov_b32_e32 v25, v149
	v_mov_b32_e32 v182, v134

; template <int MT, class Epi>
; DI void gemm_tile(const u16* __restrict__ X, long ldx, const u16* __restrict__ W, long ldw, int K, char* smem,
;                   int m0, int n0, const Epi& epi, bool pre = false, const u16* Xn = nullptr, const u16* Wn = nullptr) {
;     ...
;   const int r8 = lane >> 3, c0 = (lane & 7) ^ (r8 >> 1);
;   const long oxe = (long)(wu * MT * 8 + r8) * ldx + (c0 << 3), oxo = (long)(wu * MT * 8 + r8) * ldx + ((c0 ^ 4) << 3);
;   const long owe = (long)(wu * 32 + r8) * ldw + (c0 << 3), owo = (long)(wu * 32 + r8) * ldw + ((c0 ^ 4) << 3);
;   const u16 *xe = X + oxe, *xo = X + oxo, *we = W + owe, *wo = W + owo;
;   const long ldx8 = 8 * ldx, ldw8 = 8 * ldw;
;   const unsigned xdst = sbase + wu * MT * 1024, wdst = sbase + 16384 + wu * 4096;
;     ...
;   if (!pre) {
;     __syncthreads();
;     GT_DMA(0u)
;   } else {
;     xe += 64; xo += 64; we += 64; wo += 64;
;   }
;   const int nk = K >> 6;
;   int kt = 0;
;   do {
;     asm volatile("s_waitcnt vmcnt(0)" ::: "memory");
;     __syncthreads();
;     if (kt + 1 < nk) GT_DMA((unsigned)((kt + 1) & 1) * 32768u)
;     else if (Xn != nullptr) { xe = Xn + oxe; xo = Xn + oxo; we = Wn + owe; wo = Wn + owo; GT_DMA(0u) }
;     const char* cur = smem + (kt & 1) * 32768;
; DI void phase_even(const Params& p, int e, int sub, char* smem) {
;     ...
;         const int g = t / 264, r = t % 264, tm = r >> 1, tn = r & 1;
;         EpiPool epi{p.pool_scale + e * 1024, gbuf, g};
;         gemm_tile<4>(hbuf + (size_t)tm * 128 * 1024 + g * 256, 1024, W + WE_POOL + (size_t)g * 65536 + (size_t)tn * 128 * 256, 256, 256, smem,
.LBB0_309:
	s_and_b64 vcc, exec, s[38:39]
	s_cbranch_vccz .LBB0_298
	s_mul_hi_i32 s7, s4, 0x3e0f83e1
	s_lshr_b32 s8, s7, 31
	s_ashr_i32 s7, s7, 6
	s_add_i32 s8, s7, s8
	s_mul_i32 s7, s8, 0xfffffef8
	s_add_i32 s7, s4, s7
	s_ashr_i32 s10, s7, 1
	s_ashr_i32 s11, s10, 31
	s_and_b32 s16, s7, 1
	s_lshl_b64 s[12:13], s[10:11], 18
	s_add_u32 s7, s0, s12
	s_addc_u32 s9, s1, s13
	s_lshl_b32 s38, s8, 8
	s_ashr_i32 s39, s38, 31
	s_lshl_b64 s[12:13], s[38:39], 1
	s_add_u32 s12, s7, s12
	s_addc_u32 s13, s9, s13
	s_ashr_i32 s9, s8, 31
	s_lshl_b64 s[8:9], s[8:9], 17
	v_readlane_b32 s7, v252, 43
	s_add_u32 s7, s7, s8
	v_readlane_b32 s8, v252, 44
	s_waitcnt vmcnt(7)
	v_mov_b32_e32 v18, v185
	s_addc_u32 s8, s8, s9
	s_lshl_b32 s9, s16, 16
	s_add_u32 s14, s7, s9
	v_ashrrev_i32_e32 v2, 6, v18
	v_and_b32_e32 v54, 1, v2
	v_readfirstlane_b32 s9, v2
	v_bfe_u32 v2, v18, 3, 3
	v_bfe_u32 v55, v18, 4, 2
	v_lshl_or_b32 v2, s9, 5, v2
	v_bitop3_b32 v6, v55, v18, 7 bitop3:0x78
	v_ashrrev_i32_e32 v3, 31, v2
	v_lshlrev_b64 v[4:5], 11, v[2:3]
	v_lshlrev_b32_e32 v182, 4, v6
	v_mov_b32_e32 v12, v183
	v_lshl_add_u64 v[4:5], s[12:13], 0, v[4:5]
	v_xor_b32_e32 v8, 64, v182
	v_mov_b32_e32 v9, v183
	s_addc_u32 s15, s8, 0
	s_lshl_b32 s7, s10, 7
	v_lshl_add_u64 v[6:7], v[4:5], 0, v[182:183]
	v_lshl_add_u64 v[4:5], v[4:5], 0, v[8:9]
	s_lshl_b32 s17, s9, 12
	s_barrier
	s_mov_b32 s9, m0
	s_mov_b32 m0, s17
	s_nop 0
	global_load_lds_dwordx4 v[6:7], off
	s_mov_b32 m0, s9
	s_mov_b64 s[10:11], 0x4000
	v_lshl_add_u64 v[16:17], v[4:5], 0, s[10:11]
	s_or_b32 s18, s17, 0x400
	s_mov_b32 s9, m0
	s_mov_b32 m0, s18
	s_nop 0
	global_load_lds_dwordx4 v[16:17], off
	s_mov_b32 m0, s9
	s_mov_b64 s[10:11], 0x8000
	v_lshlrev_b64 v[2:3], 9, v[2:3]
	v_lshl_add_u64 v[16:17], v[6:7], 0, s[10:11]
	s_or_b32 s19, s17, 0x800
	s_mov_b32 s9, m0
	s_mov_b32 m0, s19
	s_nop 0
	global_load_lds_dwordx4 v[16:17], off
	s_mov_b32 m0, s9
	s_mov_b64 s[10:11], 0xc000
	v_lshl_add_u64 v[10:11], s[14:15], 0, v[2:3]
	v_lshl_add_u64 v[16:17], v[4:5], 0, s[10:11]
	s_or_b32 s34, s17, 0xc00
	s_mov_b32 s9, m0
	s_mov_b32 m0, s34
	s_nop 0
	global_load_lds_dwordx4 v[16:17], off
	s_mov_b32 m0, s9
	v_lshl_add_u64 v[2:3], v[10:11], 0, v[182:183]
	v_lshl_add_u64 v[8:9], v[10:11], 0, v[8:9]
	s_add_i32 s39, s17, 0x4000
	s_mov_b32 s9, m0
	s_mov_b32 m0, s39
	s_nop 0
	global_load_lds_dwordx4 v[2:3], off
	s_mov_b32 m0, s9
	s_mov_b64 s[10:11], 0x1000
	v_lshl_add_u64 v[10:11], v[8:9], 0, s[10:11]
	s_add_i32 s40, s17, 0x4400
	s_mov_b32 s9, m0
	s_mov_b32 m0, s40
	s_nop 0
	global_load_lds_dwordx4 v[10:11], off
	s_mov_b32 m0, s9
	s_mov_b64 s[10:11], 0x2000
	v_lshl_add_u64 v[10:11], v[2:3], 0, s[10:11]
	s_add_i32 s41, s17, 0x4800
	s_mov_b32 s9, m0
	s_mov_b32 m0, s41
	s_nop 0
	global_load_lds_dwordx4 v[10:11], off
	s_mov_b32 m0, s9
	s_mov_b64 s[10:11], 0x3000
	v_lshl_add_u64 v[10:11], v[8:9], 0, s[10:11]
	s_add_i32 s42, s17, 0x4c00
	s_mov_b32 s9, m0
	s_mov_b32 m0, s42
	s_nop 0
	global_load_lds_dwordx4 v[10:11], off
	s_mov_b32 m0, s9
	s_waitcnt vmcnt(0)
	s_barrier
	v_lshl_add_u64 v[10:11], v[6:7], 0, s[28:29]
	s_add_i32 s12, s17, 0x8000
	s_mov_b32 s9, m0
	s_mov_b32 m0, s12
	s_nop 0
	global_load_lds_dwordx4 v[10:11], off
	s_mov_b32 m0, s9
	v_lshl_add_u64 v[10:11], v[4:5], 0, s[94:95]
	s_add_i32 s10, s17, 0x8400
	s_mov_b32 s9, m0
	s_mov_b32 m0, s10
	s_nop 0
	global_load_lds_dwordx4 v[10:11], off
	s_mov_b32 m0, s9
	v_lshl_add_u64 v[10:11], v[6:7], 0, s[78:79]
	s_add_i32 s9, s17, 0x8800
	s_mov_b32 s11, m0
	s_mov_b32 m0, s9
	s_nop 0
	global_load_lds_dwordx4 v[10:11], off
	s_mov_b32 m0, s11
	v_lshl_add_u64 v[10:11], v[4:5], 0, s[54:55]
	s_add_i32 s13, s17, 0x8c00
	s_mov_b32 s11, m0
	s_mov_b32 m0, s13
	s_nop 0
	global_load_lds_dwordx4 v[10:11], off
	s_mov_b32 m0, s11
	v_lshl_add_u64 v[16:17], v[2:3], 0, s[28:29]
	s_add_i32 s11, s17, 0xc000
	s_mov_b32 s14, m0
	s_mov_b32 m0, s11
	s_nop 0
	global_load_lds_dwordx4 v[16:17], off
	s_mov_b32 m0, s14
	s_mov_b64 s[14:15], 0x1080
	v_lshl_add_u64 v[10:11], v[8:9], 0, s[14:15]
	s_mov_b64 s[20:21], 0x2080
	s_add_i32 s15, s17, 0xc400
	s_mov_b32 s14, m0
	s_mov_b32 m0, s15
	s_nop 0
	global_load_lds_dwordx4 v[10:11], off
	s_mov_b32 m0, s14
	v_lshl_add_u64 v[10:11], v[2:3], 0, s[20:21]
	s_mov_b64 s[20:21], 0x3080
	s_lshl_b32 s8, s16, 7
	v_lshrrev_b32_e32 v19, 1, v18
	s_add_i32 s14, s17, 0xc800
	s_mov_b32 s16, m0
	s_mov_b32 m0, s14
	s_nop 0
	global_load_lds_dwordx4 v[10:11], off
	s_mov_b32 m0, s16
	v_lshl_add_u64 v[10:11], v[8:9], 0, s[20:21]
	v_and_b32_e32 v1, 15, v18
	v_ashrrev_i32_e32 v56, 7, v18
	s_add_i32 s16, s17, 0xcc00
	s_mov_b32 s43, m0
	s_mov_b32 m0, s16
	s_nop 0
	global_load_lds_dwordx4 v[10:11], off
	s_mov_b32 m0, s43
	v_bitop3_b32 v10, v55, v19, 7 bitop3:0x78
	v_lshlrev_b32_e32 v11, 4, v10
	v_lshlrev_b32_e32 v90, 13, v54
	s_waitcnt vmcnt(1)
	v_lshlrev_b32_e32 v102, 7, v1
	v_lshlrev_b32_e32 v103, 13, v56
	v_or3_b32 v10, v11, v90, v102
	v_or3_b32 v11, v11, v103, v102
	v_bfe_u32 v57, v18, 1, 3
	ds_read_b128 v[16:19], v10
	ds_read_b128 v[20:23], v10 offset:2048
	ds_read_b128 v[24:27], v10 offset:4096
	ds_read_b128 v[28:31], v10 offset:6144
	ds_read_b128 v[32:35], v11 offset:16384
	ds_read_b128 v[36:39], v11 offset:18432
	ds_read_b128 v[40:43], v11 offset:20480
	ds_read_b128 v[44:47], v11 offset:22528
	v_mov_b32_e32 v13, v12
	v_mov_b32_e32 v14, v12
	v_mov_b32_e32 v15, v12
	s_mov_b64 s[20:21], 0x100
	v_lshl_add_u64 v[52:53], v[6:7], 0, s[20:21]
	s_waitcnt lgkmcnt(3)
	v_mfma_f32_16x16x32_bf16 v[48:51], v[32:35], v[16:19], v[12:15]
	v_lshl_add_u64 v[118:119], v[2:3], 0, s[20:21]
	s_mov_b64 s[20:21], 0x4100
	v_lshlrev_b32_e32 v54, 6, v54
	v_mfma_f32_16x16x32_bf16 v[58:61], v[32:35], v[20:23], v[12:15]
	v_mfma_f32_16x16x32_bf16 v[62:65], v[32:35], v[24:27], v[12:15]
	v_mfma_f32_16x16x32_bf16 v[32:35], v[32:35], v[28:31], v[12:15]
	s_waitcnt lgkmcnt(2)
; template <int MT, class Epi>
; DI void gemm_tile(const u16* __restrict__ X, long ldx, const u16* __restrict__ W, long ldw, int K, char* smem,
;                   int m0, int n0, const Epi& epi, bool pre = false, const u16* Xn = nullptr, const u16* Wn = nullptr) {
;     ...
;   do {
;     asm volatile("s_waitcnt vmcnt(0)" ::: "memory");
;     __syncthreads();
;     if (kt + 1 < nk) GT_DMA((unsigned)((kt + 1) & 1) * 32768u)
;     else if (Xn != nullptr) { xe = Xn + oxe; xo = Xn + oxo; we = Wn + owe; wo = Wn + owo; GT_DMA(0u) }
;     const char* cur = smem + (kt & 1) * 32768;
; #pragma unroll
;     for (int ks = 0; ks < 2; ++ks) {
;       bf16x8 xf[MT], wf[4];
;       const int ch = ((ks * 4 + g) ^ rsw) << 4;
; #pragma unroll
;       for (int i = 0; i < MT; ++i) xf[i] = *(const bf16x8*)(cur + (wm * 16 * MT + i * 16 + lr) * 128 + ch);
; #pragma unroll
;       for (int i = 0; i < 4; ++i) wf[i] = *(const bf16x8*)(cur + 16384 + (wn * 64 + i * 16 + lr) * 128 + ch);
; #pragma unroll
;       for (int nt = 0; nt < 4; ++nt)
; #pragma unroll
;         for (int mt = 0; mt < MT; ++mt)
;           acc[nt][mt] = __builtin_amdgcn_mfma_f32_16x16x32_bf16(wf[nt], xf[mt], acc[nt][mt], 0, 0, 0);
;     }
;   } while (++kt < nk);
	v_mfma_f32_16x16x32_bf16 v[66:69], v[36:39], v[16:19], v[12:15]
	v_mfma_f32_16x16x32_bf16 v[70:73], v[36:39], v[20:23], v[12:15]
	v_mfma_f32_16x16x32_bf16 v[74:77], v[36:39], v[24:27], v[12:15]
	v_mfma_f32_16x16x32_bf16 v[36:39], v[36:39], v[28:31], v[12:15]
	s_waitcnt lgkmcnt(1)
	v_mfma_f32_16x16x32_bf16 v[78:81], v[40:43], v[16:19], v[12:15]
	v_mfma_f32_16x16x32_bf16 v[82:85], v[40:43], v[20:23], v[12:15]
	v_mfma_f32_16x16x32_bf16 v[86:89], v[40:43], v[24:27], v[12:15]
	v_mfma_f32_16x16x32_bf16 v[40:43], v[40:43], v[28:31], v[12:15]
	s_waitcnt lgkmcnt(0)
	v_mfma_f32_16x16x32_bf16 v[16:19], v[44:47], v[16:19], v[12:15]
	v_mfma_f32_16x16x32_bf16 v[20:23], v[44:47], v[20:23], v[12:15]
	v_mfma_f32_16x16x32_bf16 v[24:27], v[44:47], v[24:27], v[12:15]
	v_mfma_f32_16x16x32_bf16 v[28:31], v[44:47], v[28:31], v[12:15]
	s_nop 2
	v_bitop3_b32 v12, v55, v57, 4 bitop3:0x36
	v_lshlrev_b32_e32 v13, 4, v12
	v_or_b32_e32 v12, v13, v90
	v_or_b32_e32 v13, v13, v103
	v_add_u32_e32 v12, v12, v102
	v_add_u32_e32 v13, v13, v102
	ds_read_b128 v[44:47], v12
	ds_read_b128 v[90:93], v12 offset:2048
	s_waitcnt vmcnt(0)
	ds_read_b128 v[94:97], v12 offset:4096
	ds_read_b128 v[98:101], v12 offset:6144
	ds_read_b128 v[102:105], v13 offset:16384
	ds_read_b128 v[106:109], v13 offset:18432
	ds_read_b128 v[110:113], v13 offset:20480
	ds_read_b128 v[114:117], v13 offset:22528
	s_waitcnt vmcnt(0)
	s_waitcnt lgkmcnt(0)
	s_barrier
	s_mov_b32 s43, m0
	s_mov_b32 m0, s17
	s_nop 0
	global_load_lds_dwordx4 v[52:53], off
	s_mov_b32 m0, s43
	v_mfma_f32_16x16x32_bf16 v[14:17], v[114:117], v[44:47], v[16:19]
	v_mfma_f32_16x16x32_bf16 v[18:21], v[114:117], v[90:93], v[20:23]
	v_mfma_f32_16x16x32_bf16 v[22:25], v[114:117], v[94:97], v[24:27]
	v_mfma_f32_16x16x32_bf16 v[26:29], v[114:117], v[98:101], v[28:31]
	s_nop 2
	v_lshl_add_u64 v[30:31], v[4:5], 0, s[20:21]
	s_mov_b32 s17, m0
	s_mov_b32 m0, s18
	s_nop 0
	global_load_lds_dwordx4 v[30:31], off
	s_mov_b32 m0, s17
	s_mov_b64 s[20:21], 0x8100
	v_lshl_add_u64 v[30:31], v[6:7], 0, s[20:21]
	s_mov_b32 s17, m0
	s_mov_b32 m0, s19
	s_nop 0
	global_load_lds_dwordx4 v[30:31], off
	s_mov_b32 m0, s17
	s_mov_b64 s[18:19], 0xc100
	v_lshl_add_u64 v[30:31], v[4:5], 0, s[18:19]
	s_mov_b32 s17, m0
	s_mov_b32 m0, s34
	s_nop 0
	global_load_lds_dwordx4 v[30:31], off
	s_mov_b32 m0, s17
	s_mov_b64 s[18:19], 0x1100
	s_mov_b32 s17, m0
	s_mov_b32 m0, s39
	s_nop 0
	global_load_lds_dwordx4 v[118:119], off
	s_mov_b32 m0, s17
	v_lshl_add_u64 v[30:31], v[8:9], 0, s[18:19]
	s_mov_b32 s17, m0
	s_mov_b32 m0, s40
	s_nop 0
	global_load_lds_dwordx4 v[30:31], off
	s_mov_b32 m0, s17
	s_mov_b64 s[18:19], 0x2100
	v_lshl_add_u64 v[30:31], v[2:3], 0, s[18:19]
	s_mov_b32 s17, m0
	s_mov_b32 m0, s41
	s_nop 0
	global_load_lds_dwordx4 v[30:31], off
	s_mov_b32 m0, s17
	s_mov_b64 s[18:19], 0x3100
	v_lshl_add_u64 v[30:31], v[8:9], 0, s[18:19]
	s_mov_b32 s17, m0
	s_mov_b32 m0, s42
	s_nop 0
	global_load_lds_dwordx4 v[30:31], off
	s_mov_b32 m0, s17
	v_mfma_f32_16x16x32_bf16 v[48:51], v[102:105], v[44:47], v[48:51]
	s_mov_b64 s[18:19], 0x180
	v_lshl_add_u64 v[118:119], v[6:7], 0, s[18:19]
	v_lshl_add_u64 v[120:121], v[2:3], 0, s[18:19]
	v_mfma_f32_16x16x32_bf16 v[58:61], v[102:105], v[90:93], v[58:61]
	s_mov_b64 s[18:19], 0x4180
	v_mfma_f32_16x16x32_bf16 v[62:65], v[102:105], v[94:97], v[62:65]
	v_mfma_f32_16x16x32_bf16 v[32:35], v[102:105], v[98:101], v[32:35]
	v_mfma_f32_16x16x32_bf16 v[66:69], v[106:109], v[44:47], v[66:69]
	v_mfma_f32_16x16x32_bf16 v[70:73], v[106:109], v[90:93], v[70:73]
	v_mfma_f32_16x16x32_bf16 v[74:77], v[106:109], v[94:97], v[74:77]
	v_mfma_f32_16x16x32_bf16 v[36:39], v[106:109], v[98:101], v[36:39]
	v_mfma_f32_16x16x32_bf16 v[78:81], v[110:113], v[44:47], v[78:81]
	v_mfma_f32_16x16x32_bf16 v[82:85], v[110:113], v[90:93], v[82:85]
	v_mfma_f32_16x16x32_bf16 v[86:89], v[110:113], v[94:97], v[86:89]
	v_mfma_f32_16x16x32_bf16 v[40:43], v[110:113], v[98:101], v[40:43]
	ds_read_b128 v[44:47], v10 offset:32768
	ds_read_b128 v[90:93], v10 offset:34816
	ds_read_b128 v[94:97], v10 offset:36864
	ds_read_b128 v[98:101], v10 offset:38912
	ds_read_b128 v[102:105], v11 offset:49152
	ds_read_b128 v[106:109], v11 offset:51200
	ds_read_b128 v[110:113], v11 offset:53248
	ds_read_b128 v[114:117], v11 offset:55296
	s_waitcnt lgkmcnt(3)
	v_mfma_f32_16x16x32_bf16 v[48:51], v[102:105], v[44:47], v[48:51]
	v_mfma_f32_16x16x32_bf16 v[58:61], v[102:105], v[90:93], v[58:61]
	v_mfma_f32_16x16x32_bf16 v[62:65], v[102:105], v[94:97], v[62:65]
	v_mfma_f32_16x16x32_bf16 v[30:33], v[102:105], v[98:101], v[32:35]
	s_waitcnt lgkmcnt(2)
	v_mfma_f32_16x16x32_bf16 v[66:69], v[106:109], v[44:47], v[66:69]
	v_mfma_f32_16x16x32_bf16 v[70:73], v[106:109], v[90:93], v[70:73]
	v_mfma_f32_16x16x32_bf16 v[74:77], v[106:109], v[94:97], v[74:77]
	v_mfma_f32_16x16x32_bf16 v[34:37], v[106:109], v[98:101], v[36:39]
	s_waitcnt lgkmcnt(1)
	v_mfma_f32_16x16x32_bf16 v[78:81], v[110:113], v[44:47], v[78:81]
	v_mfma_f32_16x16x32_bf16 v[82:85], v[110:113], v[90:93], v[82:85]
	v_mfma_f32_16x16x32_bf16 v[86:89], v[110:113], v[94:97], v[86:89]
	v_mfma_f32_16x16x32_bf16 v[38:41], v[110:113], v[98:101], v[40:43]
	s_waitcnt lgkmcnt(0)
	v_mfma_f32_16x16x32_bf16 v[14:17], v[114:117], v[44:47], v[14:17]
	v_mfma_f32_16x16x32_bf16 v[18:21], v[114:117], v[90:93], v[18:21]
	v_mfma_f32_16x16x32_bf16 v[22:25], v[114:117], v[94:97], v[22:25]
	v_mfma_f32_16x16x32_bf16 v[26:29], v[114:117], v[98:101], v[26:29]
	ds_read_b128 v[42:45], v12 offset:32768
	ds_read_b128 v[90:93], v12 offset:34816
	ds_read_b128 v[94:97], v12 offset:36864
	ds_read_b128 v[98:101], v12 offset:38912
	ds_read_b128 v[102:105], v13 offset:49152
	ds_read_b128 v[106:109], v13 offset:51200
	ds_read_b128 v[110:113], v13 offset:53248
	ds_read_b128 v[114:117], v13 offset:55296
	s_waitcnt vmcnt(0)
	s_waitcnt lgkmcnt(0)
	s_barrier
; template <int MT, class Epi>
; DI void gemm_tile(const u16* __restrict__ X, long ldx, const u16* __restrict__ W, long ldw, int K, char* smem,
;                   int m0, int n0, const Epi& epi, bool pre = false, const u16* Xn = nullptr, const u16* Wn = nullptr) {
;     ...
;   do {
;     asm volatile("s_waitcnt vmcnt(0)" ::: "memory");
;     __syncthreads();
;     if (kt + 1 < nk) GT_DMA((unsigned)((kt + 1) & 1) * 32768u)
;     else if (Xn != nullptr) { xe = Xn + oxe; xo = Xn + oxo; we = Wn + owe; wo = Wn + owo; GT_DMA(0u) }
;     const char* cur = smem + (kt & 1) * 32768;
; #pragma unroll
;     for (int ks = 0; ks < 2; ++ks) {
;       bf16x8 xf[MT], wf[4];
;       const int ch = ((ks * 4 + g) ^ rsw) << 4;
; #pragma unroll
;       for (int i = 0; i < MT; ++i) xf[i] = *(const bf16x8*)(cur + (wm * 16 * MT + i * 16 + lr) * 128 + ch);
; #pragma unroll
;       for (int i = 0; i < 4; ++i) wf[i] = *(const bf16x8*)(cur + 16384 + (wn * 64 + i * 16 + lr) * 128 + ch);
; #pragma unroll
;       for (int nt = 0; nt < 4; ++nt)
; #pragma unroll
;         for (int mt = 0; mt < MT; ++mt)
;           acc[nt][mt] = __builtin_amdgcn_mfma_f32_16x16x32_bf16(wf[nt], xf[mt], acc[nt][mt], 0, 0, 0);
;     }
;   } while (++kt < nk);
;   template <int NT, int MT> DI void run(f32x4 (&acc)[NT][MT], int mb, int nb) const {
; #pragma unroll
;     for (int nt = 0; nt < NT; ++nt) {
;       const int ch = g * 256 + nb + nt * 16;
;       const float4 sc = *(const float4*)(scale + ch);
; #pragma unroll
;       for (int mt = 0; mt < MT; ++mt) {
;         const int m = mb + mt * 16;
;         u16* q = mix + (size_t)m * 2048 + ch;
;         const uint2 gt = *(const uint2*)q;
	s_mov_b32 s17, m0
	s_mov_b32 m0, s12
	s_nop 0
	global_load_lds_dwordx4 v[118:119], off
	s_mov_b32 m0, s17
	v_mfma_f32_16x16x32_bf16 v[46:49], v[102:105], v[42:45], v[48:51]
	v_mfma_f32_16x16x32_bf16 v[50:53], v[102:105], v[90:93], v[58:61]
	v_mfma_f32_16x16x32_bf16 v[58:61], v[102:105], v[94:97], v[62:65]
	v_mfma_f32_16x16x32_bf16 v[62:65], v[106:109], v[42:45], v[66:69]
	v_mfma_f32_16x16x32_bf16 v[66:69], v[106:109], v[90:93], v[70:73]
	v_mfma_f32_16x16x32_bf16 v[70:73], v[106:109], v[94:97], v[74:77]
	v_mfma_f32_16x16x32_bf16 v[74:77], v[110:113], v[42:45], v[78:81]
	v_mfma_f32_16x16x32_bf16 v[14:17], v[114:117], v[42:45], v[14:17]
	v_lshl_add_u64 v[42:43], v[4:5], 0, s[18:19]
	s_mov_b32 s12, m0
	s_mov_b32 m0, s10
	s_nop 0
	global_load_lds_dwordx4 v[42:43], off
	s_mov_b32 m0, s12
	s_mov_b64 s[18:19], 0x8180
	v_lshl_add_u64 v[6:7], v[6:7], 0, s[18:19]
	s_mov_b32 s10, m0
	s_mov_b32 m0, s9
	s_nop 0
	global_load_lds_dwordx4 v[6:7], off
	s_mov_b32 m0, s10
	s_mov_b64 s[18:19], 0xc180
	v_lshl_add_u64 v[4:5], v[4:5], 0, s[18:19]
	s_mov_b32 s9, m0
	s_mov_b32 m0, s13
	s_nop 0
	global_load_lds_dwordx4 v[4:5], off
	s_mov_b32 m0, s9
	v_mfma_f32_16x16x32_bf16 v[30:33], v[102:105], v[98:101], v[30:33]
	s_mov_b32 s9, m0
	s_mov_b32 m0, s11
	s_nop 0
	global_load_lds_dwordx4 v[120:121], off
	s_mov_b32 m0, s9
	s_mov_b64 s[10:11], 0x1180
	v_lshl_add_u64 v[4:5], v[8:9], 0, s[10:11]
	s_mov_b32 s9, m0
	s_mov_b32 m0, s15
	s_nop 0
	global_load_lds_dwordx4 v[4:5], off
	s_mov_b32 m0, s9
	s_mov_b64 s[10:11], 0x2180
	v_lshl_add_u64 v[2:3], v[2:3], 0, s[10:11]
	s_mov_b32 s9, m0
	s_mov_b32 m0, s14
	s_nop 0
	global_load_lds_dwordx4 v[2:3], off
	s_mov_b32 m0, s9
	s_mov_b64 s[10:11], 0x3180
	v_lshl_add_u64 v[2:3], v[8:9], 0, s[10:11]
	s_mov_b32 s9, m0
	s_mov_b32 m0, s16
	s_nop 0
	global_load_lds_dwordx4 v[2:3], off
	s_mov_b32 m0, s9
	v_mfma_f32_16x16x32_bf16 v[34:37], v[106:109], v[98:101], v[34:37]
	v_mfma_f32_16x16x32_bf16 v[78:81], v[110:113], v[90:93], v[82:85]
	v_mfma_f32_16x16x32_bf16 v[82:85], v[110:113], v[94:97], v[86:89]
	v_mfma_f32_16x16x32_bf16 v[38:41], v[110:113], v[98:101], v[38:41]
	v_mfma_f32_16x16x32_bf16 v[18:21], v[114:117], v[90:93], v[18:21]
	v_mfma_f32_16x16x32_bf16 v[22:25], v[114:117], v[94:97], v[22:25]
	v_mfma_f32_16x16x32_bf16 v[26:29], v[114:117], v[98:101], v[26:29]
	ds_read_b128 v[2:5], v10
	ds_read_b128 v[6:9], v10 offset:2048
	ds_read_b128 v[42:45], v10 offset:4096
	ds_read_b128 v[86:89], v10 offset:6144
	ds_read_b128 v[90:93], v11 offset:16384
	ds_read_b128 v[94:97], v11 offset:18432
	ds_read_b128 v[98:101], v11 offset:20480
	ds_read_b128 v[102:105], v11 offset:22528
	s_waitcnt lgkmcnt(3)
	v_mfma_f32_16x16x32_bf16 v[46:49], v[90:93], v[2:5], v[46:49]
	v_mfma_f32_16x16x32_bf16 v[50:53], v[90:93], v[6:9], v[50:53]
	v_mfma_f32_16x16x32_bf16 v[58:61], v[90:93], v[42:45], v[58:61]
	v_mfma_f32_16x16x32_bf16 v[30:33], v[90:93], v[86:89], v[30:33]
	s_waitcnt lgkmcnt(2)
	v_mfma_f32_16x16x32_bf16 v[62:65], v[94:97], v[2:5], v[62:65]
	v_mfma_f32_16x16x32_bf16 v[66:69], v[94:97], v[6:9], v[66:69]
	v_mfma_f32_16x16x32_bf16 v[70:73], v[94:97], v[42:45], v[70:73]
	v_mfma_f32_16x16x32_bf16 v[34:37], v[94:97], v[86:89], v[34:37]
	s_waitcnt lgkmcnt(1)
	v_mfma_f32_16x16x32_bf16 v[74:77], v[98:101], v[2:5], v[74:77]
	v_mfma_f32_16x16x32_bf16 v[78:81], v[98:101], v[6:9], v[78:81]
	v_mfma_f32_16x16x32_bf16 v[82:85], v[98:101], v[42:45], v[82:85]
	v_mfma_f32_16x16x32_bf16 v[38:41], v[98:101], v[86:89], v[38:41]
	s_waitcnt lgkmcnt(0)
	v_mfma_f32_16x16x32_bf16 v[2:5], v[102:105], v[2:5], v[14:17]
	v_mfma_f32_16x16x32_bf16 v[6:9], v[102:105], v[6:9], v[18:21]
	v_mfma_f32_16x16x32_bf16 v[14:17], v[102:105], v[42:45], v[22:25]
	v_mfma_f32_16x16x32_bf16 v[18:21], v[102:105], v[86:89], v[26:29]
	s_nop 1
	ds_read_b128 v[22:25], v12
	ds_read_b128 v[26:29], v12 offset:2048
	ds_read_b128 v[42:45], v12 offset:4096
	ds_read_b128 v[86:89], v12 offset:6144
	ds_read_b128 v[90:93], v13 offset:16384
	ds_read_b128 v[94:97], v13 offset:18432
	ds_read_b128 v[98:101], v13 offset:20480
	ds_read_b128 v[102:105], v13 offset:22528
	s_waitcnt vmcnt(0)
	s_waitcnt lgkmcnt(0)
	v_mfma_f32_16x16x32_bf16 v[70:73], v[94:97], v[42:45], v[70:73]
	s_barrier
	v_or3_b32 v134, v54, s7, v1
	v_lshl_add_u32 v135, v56, 6, s8
	v_lshl_or_b32 v136, v55, 2, v135
	v_ashrrev_i32_e32 v137, 31, v134
	v_readlane_b32 s8, v252, 35
	v_mov_b32_e32 v230, v134
	v_mov_b32_e32 v231, v137
	v_lshlrev_b64 v[138:139], 12, v[230:231]
	v_readlane_b32 s9, v252, 36
	v_add_u32_e32 v140, s38, v136
	v_ashrrev_i32_e32 v141, 31, v140
	v_lshl_add_u64 v[142:143], s[8:9], 0, v[138:139]
	v_lshl_add_u64 v[144:145], v[140:141], 2, s[46:47]
	global_load_dwordx4 v[146:149], v[144:145], off
	v_lshlrev_b64 v[150:151], 1, v[140:141]
	v_lshl_add_u64 v[152:153], v[142:143], 0, v[150:151]
	global_load_dwordx2 v[154:155], v[152:153], off
	v_or_b32_e32 v156, 16, v134
	v_ashrrev_i32_e32 v157, 31, v156
	v_lshlrev_b64 v[158:159], 12, v[156:157]
	v_lshl_add_u64 v[160:161], s[8:9], 0, v[158:159]
	v_lshl_add_u64 v[162:163], v[160:161], 0, v[150:151]
	global_load_dwordx2 v[164:165], v[162:163], off
	v_or_b32_e32 v166, 32, v134
	v_ashrrev_i32_e32 v167, 31, v166
	v_lshlrev_b64 v[168:169], 12, v[166:167]
	v_lshl_add_u64 v[170:171], s[8:9], 0, v[168:169]
	v_lshl_add_u64 v[172:173], v[170:171], 0, v[150:151]
	global_load_dwordx2 v[174:175], v[172:173], off
	v_or_b32_e32 v176, 48, v134
	v_ashrrev_i32_e32 v177, 31, v176
	v_lshlrev_b64 v[178:179], 12, v[176:177]
	v_lshl_add_u64 v[180:181], s[8:9], 0, v[178:179]
	v_lshl_add_u64 v[186:187], v[180:181], 0, v[150:151]
	global_load_dwordx2 v[188:189], v[186:187], off
	v_or_b32_e32 v190, 16, v140
; DI float bflo(unsigned u) { return __uint_as_float(u << 16); }
; DI float bfhi(unsigned u) { return __uint_as_float(u & 0xffff0000u); }
; DI void st_bf4(u16* p, float a, float b, float c, float d) { *(uint2*)p = make_uint2(pk2(a, b), pk2(c, d)); }
; template <int MT, class Epi>
; DI void gemm_tile(const u16* __restrict__ X, long ldx, const u16* __restrict__ W, long ldw, int K, char* smem,
;                   int m0, int n0, const Epi& epi, bool pre = false, const u16* Xn = nullptr, const u16* Wn = nullptr) {
;     ...
; #pragma unroll
;       for (int nt = 0; nt < 4; ++nt)
; #pragma unroll
;         for (int mt = 0; mt < MT; ++mt)
;           acc[nt][mt] = __builtin_amdgcn_mfma_f32_16x16x32_bf16(wf[nt], xf[mt], acc[nt][mt], 0, 0, 0);
;   template <int NT, int MT> DI void run(f32x4 (&acc)[NT][MT], int mb, int nb) const {
; #pragma unroll
;     for (int nt = 0; nt < NT; ++nt) {
;       const int ch = g * 256 + nb + nt * 16;
;       const float4 sc = *(const float4*)(scale + ch);
; #pragma unroll
;       for (int mt = 0; mt < MT; ++mt) {
;         const int m = mb + mt * 16;
;         u16* q = mix + (size_t)m * 2048 + ch;
;         const uint2 gt = *(const uint2*)q;
;         f32x4 v = acc[nt][mt];
;         st_bf4(q, v[0] * sc.x * bflo(gt.x), v[1] * sc.y * bfhi(gt.x), v[2] * sc.z * bflo(gt.y), v[3] * sc.w * bfhi(gt.y));
;       }
	v_ashrrev_i32_e32 v191, 31, v190
	v_lshlrev_b64 v[192:193], 1, v[190:191]
	v_lshl_add_u64 v[194:195], v[190:191], 2, s[46:47]
	v_lshl_add_u64 v[196:197], v[142:143], 0, v[192:193]
	global_load_dwordx2 v[224:225], v[196:197], off
	global_load_dwordx4 v[226:229], v[194:195], off
	v_mfma_f32_16x16x32_bf16 v[46:49], v[90:93], v[22:25], v[46:49]
	v_mfma_f32_16x16x32_bf16 v[50:53], v[90:93], v[26:29], v[50:53]
	v_mfma_f32_16x16x32_bf16 v[58:61], v[90:93], v[42:45], v[58:61]
	v_mfma_f32_16x16x32_bf16 v[30:33], v[90:93], v[86:89], v[30:33]
	v_mfma_f32_16x16x32_bf16 v[62:65], v[94:97], v[22:25], v[62:65]
	v_mfma_f32_16x16x32_bf16 v[66:69], v[94:97], v[26:29], v[66:69]
	v_mfma_f32_16x16x32_bf16 v[34:37], v[94:97], v[86:89], v[34:37]
	v_mfma_f32_16x16x32_bf16 v[74:77], v[98:101], v[22:25], v[74:77]
	v_mfma_f32_16x16x32_bf16 v[78:81], v[98:101], v[26:29], v[78:81]
	v_mfma_f32_16x16x32_bf16 v[82:85], v[98:101], v[42:45], v[82:85]
	v_mfma_f32_16x16x32_bf16 v[38:41], v[98:101], v[86:89], v[38:41]
	v_mfma_f32_16x16x32_bf16 v[2:5], v[102:105], v[22:25], v[2:5]
	v_mfma_f32_16x16x32_bf16 v[6:9], v[102:105], v[26:29], v[6:9]
	v_mfma_f32_16x16x32_bf16 v[14:17], v[102:105], v[42:45], v[14:17]
	v_mfma_f32_16x16x32_bf16 v[18:21], v[102:105], v[86:89], v[18:21]
	ds_read_b128 v[86:89], v13 offset:55296
	ds_read_b128 v[90:93], v13 offset:53248
	ds_read_b128 v[22:25], v13 offset:51200
	ds_read_b128 v[26:29], v13 offset:49152
	ds_read_b128 v[94:97], v12 offset:38912
	ds_read_b128 v[98:101], v12 offset:36864
	ds_read_b128 v[102:105], v12 offset:34816
	ds_read_b128 v[106:109], v12 offset:32768
	ds_read_b128 v[42:45], v11 offset:55296
	ds_read_b128 v[110:113], v11 offset:53248
	ds_read_b128 v[114:117], v11 offset:51200
	ds_read_b128 v[118:121], v11 offset:49152
	ds_read_b128 v[122:125], v10 offset:38912
	ds_read_b128 v[126:129], v10 offset:36864
	ds_read_b128 v[130:133], v10 offset:34816
	ds_read_b128 v[10:13], v10 offset:32768
	s_waitcnt lgkmcnt(2)
	v_mfma_f32_16x16x32_bf16 v[70:73], v[114:117], v[126:129], v[70:73]
	s_waitcnt lgkmcnt(1)
	v_mfma_f32_16x16x32_bf16 v[66:69], v[114:117], v[130:133], v[66:69]
	v_mfma_f32_16x16x32_bf16 v[50:53], v[118:121], v[130:133], v[50:53]
	v_mfma_f32_16x16x32_bf16 v[30:33], v[118:121], v[122:125], v[30:33]
	s_waitcnt lgkmcnt(0)
	v_mfma_f32_16x16x32_bf16 v[74:77], v[110:113], v[10:13], v[74:77]
	v_mfma_f32_16x16x32_bf16 v[78:81], v[110:113], v[130:133], v[78:81]
	v_mfma_f32_16x16x32_bf16 v[82:85], v[110:113], v[126:129], v[82:85]
	v_mfma_f32_16x16x32_bf16 v[110:113], v[110:113], v[122:125], v[38:41]
	v_mfma_f32_16x16x32_bf16 v[38:41], v[22:25], v[98:101], v[70:73]
	s_nop 2
	s_nop 0
	s_nop 0
	s_nop 0
	v_mfma_f32_16x16x32_bf16 v[46:49], v[118:121], v[10:13], v[46:49]
	s_nop 0
	s_nop 0
	s_nop 0
	v_mfma_f32_16x16x32_bf16 v[58:61], v[118:121], v[126:129], v[58:61]
	s_nop 0
	v_mfma_f32_16x16x32_bf16 v[118:121], v[114:117], v[10:13], v[62:65]
	v_mfma_f32_16x16x32_bf16 v[34:37], v[114:117], v[122:125], v[34:37]
	v_mfma_f32_16x16x32_bf16 v[2:5], v[42:45], v[10:13], v[2:5]
	v_mfma_f32_16x16x32_bf16 v[6:9], v[42:45], v[130:133], v[6:9]
	v_mfma_f32_16x16x32_bf16 v[114:117], v[42:45], v[126:129], v[14:17]
	v_mfma_f32_16x16x32_bf16 v[122:125], v[42:45], v[122:125], v[18:21]
	v_mfma_f32_16x16x32_bf16 v[42:45], v[22:25], v[102:105], v[66:69]
	s_nop 2
	s_nop 0
	s_nop 0
	v_mfma_f32_16x16x32_bf16 v[62:65], v[26:29], v[102:105], v[50:53]
	s_nop 0
	s_nop 0
	s_nop 0
	v_mfma_f32_16x16x32_bf16 v[50:53], v[26:29], v[94:97], v[30:33]
	v_mfma_f32_16x16x32_bf16 v[30:33], v[90:93], v[106:109], v[74:77]
	s_waitcnt vmcnt(6)
	s_nop 1
	v_pk_mul_f32 v[62:63], v[62:63], v[146:147]
	s_nop 0
	s_nop 0
	s_nop 0
	v_mfma_f32_16x16x32_bf16 v[126:129], v[26:29], v[106:109], v[46:49]
	v_mul_f32_e64 v64, v64, v148
	v_mul_f32_e64 v65, v65, v149
	v_pk_mul_f32 v[50:51], v[50:51], v[146:147]
	v_pk_mul_f32 v[52:53], v[52:53], v[148:149]
	v_mfma_f32_16x16x32_bf16 v[58:61], v[26:29], v[98:101], v[58:61]
	v_mfma_f32_16x16x32_bf16 v[26:29], v[90:93], v[102:105], v[78:81]
	s_nop 2
	v_mul_f32_e64 v80, v126, v146
	v_mul_f32_e64 v81, v127, v147
	s_nop 1
	v_pk_mul_f32 v[58:59], v[58:59], v[146:147]
	v_pk_mul_f32 v[60:61], v[60:61], v[148:149]
	v_mfma_f32_16x16x32_bf16 v[46:49], v[22:25], v[106:109], v[118:121]
	s_waitcnt vmcnt(5)
	v_lshlrev_b32_e32 v78, 16, v154
	v_and_b32_e32 v79, 0xffff0000, v154
	v_pk_mul_f32 v[78:79], v[80:81], v[78:79]
	v_lshlrev_b32_e32 v76, 16, v155
	v_and_b32_e32 v77, 0xffff0000, v155
	v_pk_mul_f32 v[80:81], v[128:129], v[148:149]
	v_cvt_pk_bf16_f32 v78, v78, v79
	v_pk_mul_f32 v[76:77], v[80:81], v[76:77]
	v_mfma_f32_16x16x32_bf16 v[34:37], v[22:25], v[94:97], v[34:37]
	v_cvt_pk_bf16_f32 v79, v76, v77
	global_store_dwordx2 v[152:153], v[78:79], off
	s_nop 0
	s_nop 0
	s_nop 0
	s_nop 0
	s_nop 0
	s_nop 0
	v_mfma_f32_16x16x32_bf16 v[22:25], v[90:93], v[98:101], v[82:85]
	s_waitcnt vmcnt(4)
	v_lshlrev_b32_e32 v80, 16, v164
	v_and_b32_e32 v81, 0xffff0000, v164
	v_lshlrev_b32_e32 v78, 16, v165
	v_and_b32_e32 v79, 0xffff0000, v165
	v_pk_mul_f32 v[62:63], v[62:63], v[80:81]
	v_pk_mul_f32 v[64:65], v[64:65], v[78:79]
	v_cvt_pk_bf16_f32 v62, v62, v63
	v_cvt_pk_bf16_f32 v63, v64, v65
	global_store_dwordx2 v[162:163], v[62:63], off
	s_nop 0
	s_nop 0
	s_nop 0
	s_nop 0
	s_nop 0
	s_nop 0
	v_mfma_f32_16x16x32_bf16 v[18:21], v[90:93], v[94:97], v[110:113]
	s_waitcnt vmcnt(3)
	v_lshlrev_b32_e32 v78, 16, v174
	v_and_b32_e32 v79, 0xffff0000, v174
	v_lshlrev_b32_e32 v76, 16, v175
	v_and_b32_e32 v77, 0xffff0000, v175
	v_pk_mul_f32 v[58:59], v[58:59], v[78:79]
	v_pk_mul_f32 v[60:61], v[60:61], v[76:77]
	v_cvt_pk_bf16_f32 v58, v58, v59
	v_cvt_pk_bf16_f32 v59, v60, v61
	global_store_dwordx2 v[172:173], v[58:59], off
	s_nop 0
	s_nop 0
	s_nop 0
	s_nop 0
	s_nop 0
	s_nop 0
	v_mfma_f32_16x16x32_bf16 v[14:17], v[86:89], v[106:109], v[2:5]
	s_waitcnt vmcnt(2)
; DI float bflo(unsigned u) { return __uint_as_float(u << 16); }
; DI float bfhi(unsigned u) { return __uint_as_float(u & 0xffff0000u); }
; DI void st_bf4(u16* p, float a, float b, float c, float d) { *(uint2*)p = make_uint2(pk2(a, b), pk2(c, d)); }
;   template <int NT, int MT> DI void run(f32x4 (&acc)[NT][MT], int mb, int nb) const {
; #pragma unroll
;     for (int nt = 0; nt < NT; ++nt) {
;       const int ch = g * 256 + nb + nt * 16;
;       const float4 sc = *(const float4*)(scale + ch);
; #pragma unroll
;       for (int mt = 0; mt < MT; ++mt) {
;         const int m = mb + mt * 16;
;         u16* q = mix + (size_t)m * 2048 + ch;
;         const uint2 gt = *(const uint2*)q;
;         f32x4 v = acc[nt][mt];
;         st_bf4(q, v[0] * sc.x * bflo(gt.x), v[1] * sc.y * bfhi(gt.x), v[2] * sc.z * bflo(gt.y), v[3] * sc.w * bfhi(gt.y));
;       }
	v_lshlrev_b32_e32 v72, 16, v188
	v_and_b32_e32 v73, 0xffff0000, v188
	v_lshlrev_b32_e32 v54, 16, v189
	v_and_b32_e32 v55, 0xffff0000, v189
	v_pk_mul_f32 v[50:51], v[50:51], v[72:73]
	v_pk_mul_f32 v[52:53], v[52:53], v[54:55]
	v_cvt_pk_bf16_f32 v50, v50, v51
	v_cvt_pk_bf16_f32 v51, v52, v53
	global_store_dwordx2 v[186:187], v[50:51], off
	s_nop 0
	s_nop 0
	s_nop 0
	s_nop 0
	s_nop 0
	s_nop 0
	v_mfma_f32_16x16x32_bf16 v[10:13], v[86:89], v[102:105], v[6:9]
	s_nop 0
	s_waitcnt vmcnt(1)
	v_lshlrev_b32_e32 v64, 16, v224
	v_and_b32_e32 v65, 0xffff0000, v224
	s_waitcnt vmcnt(0)
	v_pk_mul_f32 v[46:47], v[46:47], v[226:227]
	v_lshlrev_b32_e32 v60, 16, v225
	v_and_b32_e32 v61, 0xffff0000, v225
	v_pk_mul_f32 v[48:49], v[48:49], v[228:229]
	v_pk_mul_f32 v[46:47], v[46:47], v[64:65]
	v_pk_mul_f32 v[48:49], v[48:49], v[60:61]
	v_cvt_pk_bf16_f32 v46, v46, v47
	v_cvt_pk_bf16_f32 v47, v48, v49
	global_store_dwordx2 v[196:197], v[46:47], off
	v_mov_b32_e32 v1, v136
	v_mov_b32_e32 v50, v226
	v_mov_b32_e32 v51, v227
	v_mov_b32_e32 v52, v228
	v_mov_b32_e32 v53, v229
	v_mov_b32_e32 v54, v192
	v_mov_b32_e32 v55, v193
	v_mov_b32_e32 v56, v196
	v_mov_b32_e32 v57, v197
	v_mov_b32_e32 v58, v180
	v_mov_b32_e32 v59, v181
	v_mov_b32_e32 v62, v170
	v_mov_b32_e32 v63, v171
	v_mov_b32_e32 v66, v140
	v_mov_b32_e32 v67, v141
	v_mov_b32_e32 v68, v142
	v_mov_b32_e32 v69, v143
	v_mov_b32_e32 v70, v160
	v_mov_b32_e32 v71, v161
	v_mov_b32_e32 v74, v150
	v_mov_b32_e32 v75, v151
	v_lshl_add_u64 v[134:135], v[70:71], 0, v[54:55]
	global_load_dwordx2 v[136:137], v[134:135], off
	v_lshl_add_u64 v[138:139], v[62:63], 0, v[54:55]
	global_load_dwordx2 v[140:141], v[138:139], off
	v_lshl_add_u64 v[142:143], v[58:59], 0, v[54:55]
	global_load_dwordx2 v[144:145], v[142:143], off
	v_or_b32_e32 v146, 32, v66
	v_ashrrev_i32_e32 v147, 31, v146
	v_lshl_add_u64 v[148:149], v[146:147], 2, s[46:47]
	v_lshlrev_b64 v[150:151], 1, v[146:147]
	v_lshl_add_u64 v[152:153], v[68:69], 0, v[150:151]
	global_load_dwordx4 v[154:157], v[148:149], off
	global_load_dwordx2 v[158:159], v[152:153], off
	v_lshl_add_u64 v[160:161], v[70:71], 0, v[150:151]
	global_load_dwordx2 v[162:163], v[160:161], off
	v_lshl_add_u64 v[164:165], v[62:63], 0, v[150:151]
	global_load_dwordx2 v[166:167], v[164:165], off
	v_lshl_add_u64 v[168:169], v[58:59], 0, v[150:151]
	global_load_dwordx2 v[170:171], v[168:169], off
	v_or_b32_e32 v172, 48, v66
	v_ashrrev_i32_e32 v173, 31, v172
	v_lshl_add_u64 v[174:175], v[172:173], 2, s[46:47]
	v_lshlrev_b64 v[176:177], 1, v[172:173]
	v_lshl_add_u64 v[178:179], v[68:69], 0, v[176:177]
	global_load_dwordx4 v[186:189], v[174:175], off
	global_load_dwordx2 v[180:181], v[178:179], off
	v_lshl_add_u64 v[190:191], v[70:71], 0, v[176:177]
	global_load_dwordx2 v[192:193], v[190:191], off
	v_lshl_add_u64 v[194:195], v[62:63], 0, v[176:177]
	global_load_dwordx2 v[196:197], v[194:195], off
	v_lshl_add_u64 v[224:225], v[58:59], 0, v[176:177]
	global_load_dwordx2 v[226:227], v[224:225], off
	s_nop 0
	s_nop 0
	v_pk_mul_f32 v[42:43], v[42:43], v[50:51]
	v_pk_mul_f32 v[44:45], v[44:45], v[52:53]
	v_pk_mul_f32 v[38:39], v[38:39], v[50:51]
	v_pk_mul_f32 v[40:41], v[40:41], v[52:53]
	v_pk_mul_f32 v[34:35], v[34:35], v[50:51]
	v_pk_mul_f32 v[36:37], v[36:37], v[52:53]
	v_mfma_f32_16x16x32_bf16 v[6:9], v[86:89], v[98:101], v[114:117]
	s_waitcnt vmcnt(12)
	v_lshlrev_b32_e32 v56, 16, v136
	v_and_b32_e32 v57, 0xffff0000, v136
	v_lshlrev_b32_e32 v48, 16, v137
	v_and_b32_e32 v49, 0xffff0000, v137
	v_pk_mul_f32 v[42:43], v[42:43], v[56:57]
	v_pk_mul_f32 v[44:45], v[44:45], v[48:49]
	v_cvt_pk_bf16_f32 v42, v42, v43
	v_cvt_pk_bf16_f32 v43, v44, v45
	global_store_dwordx2 v[134:135], v[42:43], off
	s_nop 0
	s_nop 0
	v_mfma_f32_16x16x32_bf16 v[2:5], v[86:89], v[94:97], v[122:125]
	s_waitcnt vmcnt(11)
	v_lshlrev_b32_e32 v46, 16, v140
	v_and_b32_e32 v47, 0xffff0000, v140
	v_lshlrev_b32_e32 v44, 16, v141
	v_and_b32_e32 v45, 0xffff0000, v141
	v_pk_mul_f32 v[38:39], v[38:39], v[46:47]
	v_pk_mul_f32 v[40:41], v[40:41], v[44:45]
	v_cvt_pk_bf16_f32 v38, v38, v39
	v_cvt_pk_bf16_f32 v39, v40, v41
	global_store_dwordx2 v[138:139], v[38:39], off
	s_nop 0
	s_nop 0
	s_waitcnt vmcnt(10)
; DI float bflo(unsigned u) { return __uint_as_float(u << 16); }
; DI float bfhi(unsigned u) { return __uint_as_float(u & 0xffff0000u); }
; DI void st_bf4(u16* p, float a, float b, float c, float d) { *(uint2*)p = make_uint2(pk2(a, b), pk2(c, d)); }
;   template <int NT, int MT> DI void run(f32x4 (&acc)[NT][MT], int mb, int nb) const {
; #pragma unroll
;     for (int nt = 0; nt < NT; ++nt) {
;       const int ch = g * 256 + nb + nt * 16;
;       const float4 sc = *(const float4*)(scale + ch);
; #pragma unroll
;       for (int mt = 0; mt < MT; ++mt) {
;         const int m = mb + mt * 16;
;         u16* q = mix + (size_t)m * 2048 + ch;
;         const uint2 gt = *(const uint2*)q;
;         f32x4 v = acc[nt][mt];
;         st_bf4(q, v[0] * sc.x * bflo(gt.x), v[1] * sc.y * bfhi(gt.x), v[2] * sc.z * bflo(gt.y), v[3] * sc.w * bfhi(gt.y));
;       }
	v_lshlrev_b32_e32 v42, 16, v144
	v_and_b32_e32 v43, 0xffff0000, v144
	v_lshlrev_b32_e32 v40, 16, v145
	v_and_b32_e32 v41, 0xffff0000, v145
	v_pk_mul_f32 v[34:35], v[34:35], v[42:43]
	v_pk_mul_f32 v[36:37], v[36:37], v[40:41]
	v_cvt_pk_bf16_f32 v34, v34, v35
	v_cvt_pk_bf16_f32 v35, v36, v37
	global_store_dwordx2 v[142:143], v[34:35], off
	s_nop 0
	s_nop 0
	s_nop 0
	s_nop 0
	s_nop 0
	s_nop 0
	s_waitcnt vmcnt(9)
	v_pk_mul_f32 v[30:31], v[30:31], v[154:155]
	s_nop 0
	v_pk_mul_f32 v[32:33], v[32:33], v[156:157]
	v_pk_mul_f32 v[26:27], v[26:27], v[154:155]
	v_pk_mul_f32 v[28:29], v[28:29], v[156:157]
	v_pk_mul_f32 v[22:23], v[22:23], v[154:155]
	v_pk_mul_f32 v[24:25], v[24:25], v[156:157]
	v_pk_mul_f32 v[18:19], v[18:19], v[154:155]
	v_pk_mul_f32 v[20:21], v[20:21], v[156:157]
	s_waitcnt vmcnt(8)
	v_lshlrev_b32_e32 v44, 16, v158
	v_and_b32_e32 v45, 0xffff0000, v158
	v_lshlrev_b32_e32 v42, 16, v159
	v_and_b32_e32 v43, 0xffff0000, v159
	v_pk_mul_f32 v[30:31], v[30:31], v[44:45]
	v_pk_mul_f32 v[32:33], v[32:33], v[42:43]
	v_cvt_pk_bf16_f32 v30, v30, v31
	v_cvt_pk_bf16_f32 v31, v32, v33
	global_store_dwordx2 v[152:153], v[30:31], off
	s_nop 0
	s_nop 0
	s_waitcnt vmcnt(7)
	v_lshlrev_b32_e32 v40, 16, v162
	v_and_b32_e32 v41, 0xffff0000, v162
	v_lshlrev_b32_e32 v32, 16, v163
	v_and_b32_e32 v33, 0xffff0000, v163
	v_pk_mul_f32 v[26:27], v[26:27], v[40:41]
	v_pk_mul_f32 v[28:29], v[28:29], v[32:33]
	v_cvt_pk_bf16_f32 v26, v26, v27
	v_cvt_pk_bf16_f32 v27, v28, v29
	global_store_dwordx2 v[160:161], v[26:27], off
	s_nop 0
	s_nop 0
	s_waitcnt vmcnt(6)
	v_lshlrev_b32_e32 v30, 16, v166
	v_and_b32_e32 v31, 0xffff0000, v166
	v_lshlrev_b32_e32 v28, 16, v167
	v_and_b32_e32 v29, 0xffff0000, v167
	v_pk_mul_f32 v[22:23], v[22:23], v[30:31]
	v_pk_mul_f32 v[24:25], v[24:25], v[28:29]
	v_cvt_pk_bf16_f32 v22, v22, v23
	v_cvt_pk_bf16_f32 v23, v24, v25
	global_store_dwordx2 v[164:165], v[22:23], off
	s_nop 0
	s_nop 0
	s_waitcnt vmcnt(5)
	v_lshlrev_b32_e32 v26, 16, v170
	v_and_b32_e32 v27, 0xffff0000, v170
	v_lshlrev_b32_e32 v24, 16, v171
	v_and_b32_e32 v25, 0xffff0000, v171
	v_pk_mul_f32 v[18:19], v[18:19], v[26:27]
	v_pk_mul_f32 v[20:21], v[20:21], v[24:25]
	v_cvt_pk_bf16_f32 v18, v18, v19
	v_cvt_pk_bf16_f32 v19, v20, v21
	global_store_dwordx2 v[168:169], v[18:19], off
	s_nop 0
	s_nop 0
	s_nop 0
	s_nop 0
	s_nop 0
	s_nop 0
	s_waitcnt vmcnt(4)
	v_pk_mul_f32 v[14:15], v[14:15], v[186:187]
	s_nop 0
	v_pk_mul_f32 v[16:17], v[16:17], v[188:189]
	v_pk_mul_f32 v[10:11], v[10:11], v[186:187]
	v_pk_mul_f32 v[12:13], v[12:13], v[188:189]
	v_pk_mul_f32 v[6:7], v[6:7], v[186:187]
	v_pk_mul_f32 v[8:9], v[8:9], v[188:189]
	v_pk_mul_f32 v[2:3], v[2:3], v[186:187]
	v_pk_mul_f32 v[4:5], v[4:5], v[188:189]
	s_waitcnt vmcnt(3)
	v_lshlrev_b32_e32 v28, 16, v180
	v_and_b32_e32 v29, 0xffff0000, v180
	v_lshlrev_b32_e32 v26, 16, v181
	v_and_b32_e32 v27, 0xffff0000, v181
	v_pk_mul_f32 v[14:15], v[14:15], v[28:29]
	v_pk_mul_f32 v[16:17], v[16:17], v[26:27]
	v_cvt_pk_bf16_f32 v14, v14, v15
	v_cvt_pk_bf16_f32 v15, v16, v17
	global_store_dwordx2 v[178:179], v[14:15], off
	s_nop 0
	s_nop 0
	s_waitcnt vmcnt(2)
	v_lshlrev_b32_e32 v24, 16, v192
	v_and_b32_e32 v25, 0xffff0000, v192
	v_lshlrev_b32_e32 v16, 16, v193
	v_and_b32_e32 v17, 0xffff0000, v193
	v_pk_mul_f32 v[10:11], v[10:11], v[24:25]
	v_pk_mul_f32 v[12:13], v[12:13], v[16:17]
	v_cvt_pk_bf16_f32 v10, v10, v11
	v_cvt_pk_bf16_f32 v11, v12, v13
	global_store_dwordx2 v[190:191], v[10:11], off
	s_nop 0
	s_nop 0
	s_waitcnt vmcnt(1)
	v_lshlrev_b32_e32 v14, 16, v196
	v_and_b32_e32 v15, 0xffff0000, v196
	v_lshlrev_b32_e32 v12, 16, v197
	v_and_b32_e32 v13, 0xffff0000, v197
	v_pk_mul_f32 v[6:7], v[6:7], v[14:15]
	v_pk_mul_f32 v[8:9], v[8:9], v[12:13]
	v_cvt_pk_bf16_f32 v6, v6, v7
	v_cvt_pk_bf16_f32 v7, v8, v9
	global_store_dwordx2 v[194:195], v[6:7], off
	s_nop 0
	s_nop 0
	s_waitcnt vmcnt(0)
	v_lshlrev_b32_e32 v10, 16, v226
	v_and_b32_e32 v11, 0xffff0000, v226
	v_lshlrev_b32_e32 v8, 16, v227
	v_and_b32_e32 v9, 0xffff0000, v227
	v_pk_mul_f32 v[2:3], v[2:3], v[10:11]
	v_pk_mul_f32 v[4:5], v[4:5], v[8:9]
	v_cvt_pk_bf16_f32 v2, v2, v3
	v_cvt_pk_bf16_f32 v3, v4, v5
	global_store_dwordx2 v[224:225], v[2:3], off
	v_mov_b32_e32 v6, v224
	v_mov_b32_e32 v7, v225
	v_mov_b32_e32 v18, v186
	v_mov_b32_e32 v19, v187
	v_mov_b32_e32 v20, v188
	v_mov_b32_e32 v21, v189
	v_mov_b32_e32 v22, v176
	v_mov_b32_e32 v23, v177
	v_mov_b32_e32 v34, v154
	v_mov_b32_e32 v35, v155
	v_mov_b32_e32 v36, v156
	v_mov_b32_e32 v37, v157
	v_mov_b32_e32 v38, v150
	v_mov_b32_e32 v39, v151
	s_branch .LBB0_298

; DI float bflo(unsigned u) { return __uint_as_float(u << 16); }
; DI float bfhi(unsigned u) { return __uint_as_float(u & 0xffff0000u); }
; DI float wave_sum(float v) {
; #pragma unroll
;   for (int o = 32; o; o >>= 1) v += __shfl_xor(v, o, 64);
;   return v;
; }
; DI void sgu_ln_items(const Params& p, int e, char* smem) {
;     ...
;     for (int b8 = 0; b8 < 32; b8 += 8) {
;       u32x4 q[8][2];
; #pragma unroll
;       for (int k = 0; k < 8; ++k) {
;         const int i = wave * 32 + b8 + k;
;         const int ic = i < nvalid ? i : 0;
;         const u16* src = uv + (size_t)(rowbase + ic) * 2048 + 1024 + lane * 8;
;         q[k][0] = *(const u32x4*)src;
;         q[k][1] = *(const u32x4*)(src + 512);
;       }
; #pragma unroll
;       for (int k = 0; k < 8; ++k) {
;         const int i = wave * 32 + b8 + k;
;         float s = 0.f, s2 = 0.f;
; #pragma unroll
;         for (int j = 0; j < 2; ++j)
; #pragma unroll
;           for (int w4 = 0; w4 < 4; ++w4) {
;             const float lo = bflo(q[k][j][w4]), hi = bfhi(q[k][j][w4]);
;             s += lo + hi; s2 += lo * lo + hi * hi;
;           }
;         s = wave_sum(s); s2 = wave_sum(s2);
;         const float mu = s * (1.f / 1024.f);
;         const float var = fmaxf(s2 * (1.f / 1024.f) - mu * mu, 0.f);
;         const float rstd = rsqrtf(var + 1e-6f);
;         if (lane == 0) st[i] = i < nvalid ? make_float2(mu, rstd) : make_float2(0.f, 0.f);
;       }
.LBB0_319:
	s_waitcnt lgkmcnt(0)
	v_add_u32_e32 v4, s7, v1
	v_add_u32_e32 v2, 8, v4
	v_cmp_gt_i32_e64 s[52:53], s6, v2
	v_add_u32_e32 v5, 9, v4
	v_add_u32_e32 v6, 10, v4
	v_cndmask_b32_e64 v2, 0, v2, s[52:53]
	v_add_u32_e32 v2, s5, v2
	v_ashrrev_i32_e32 v3, 31, v2
	v_lshlrev_b64 v[2:3], 12, v[2:3]
	v_lshl_add_u64 v[2:3], v[118:119], 0, v[2:3]
	global_load_dwordx4 v[58:61], v[2:3], off offset:2048
	global_load_dwordx4 v[64:67], v[2:3], off offset:3072
	v_add_u32_e32 v7, 11, v4
	v_add_u32_e32 v8, 12, v4
	v_add_u32_e32 v9, 13, v4
	v_add_u32_e32 v10, 14, v4
	v_add_u32_e32 v4, 15, v4
	v_cmp_gt_i32_e64 s[50:51], s6, v5
	v_cmp_gt_i32_e64 s[48:49], s6, v6
	v_cmp_gt_i32_e64 s[46:47], s6, v7
	v_cmp_gt_i32_e64 s[44:45], s6, v8
	v_cmp_gt_i32_e64 s[42:43], s6, v9
	v_cmp_gt_i32_e64 s[40:41], s6, v10
	v_cndmask_b32_e64 v5, 0, v5, s[50:51]
	v_cndmask_b32_e64 v3, 0, v6, s[48:49]
	v_cndmask_b32_e64 v6, 0, v7, s[46:47]
	v_cndmask_b32_e64 v7, 0, v8, s[44:45]
	v_cndmask_b32_e64 v9, 0, v9, s[42:43]
	v_cndmask_b32_e64 v11, 0, v10, s[40:41]
	v_cmp_gt_i32_e32 vcc, s6, v4
	v_add_u32_e32 v2, s5, v5
	v_add_u32_e32 v6, s5, v6
	v_cndmask_b32_e32 v13, 0, v4, vcc
	v_add_u32_e32 v4, s5, v3
	v_add_u32_e32 v8, s5, v7
	v_add_u32_e32 v10, s5, v9
	v_add_u32_e32 v12, s5, v11
	v_add_u32_e32 v14, s5, v13
	v_ashrrev_i32_e32 v3, 31, v2
	v_ashrrev_i32_e32 v5, 31, v4
	v_ashrrev_i32_e32 v7, 31, v6
	v_ashrrev_i32_e32 v9, 31, v8
	v_ashrrev_i32_e32 v11, 31, v10
	v_ashrrev_i32_e32 v13, 31, v12
	v_ashrrev_i32_e32 v15, 31, v14
	v_lshlrev_b64 v[2:3], 12, v[2:3]
	v_lshlrev_b64 v[4:5], 12, v[4:5]
	v_lshlrev_b64 v[6:7], 12, v[6:7]
	v_lshlrev_b64 v[8:9], 12, v[8:9]
	v_lshlrev_b64 v[10:11], 12, v[10:11]
	v_lshlrev_b64 v[12:13], 12, v[12:13]
	v_lshlrev_b64 v[14:15], 12, v[14:15]
	v_lshl_add_u64 v[2:3], v[118:119], 0, v[2:3]
	v_lshl_add_u64 v[4:5], v[118:119], 0, v[4:5]
	v_lshl_add_u64 v[6:7], v[118:119], 0, v[6:7]
	v_lshl_add_u64 v[8:9], v[118:119], 0, v[8:9]
	v_lshl_add_u64 v[10:11], v[118:119], 0, v[10:11]
	v_lshl_add_u64 v[12:13], v[118:119], 0, v[12:13]
	v_lshl_add_u64 v[68:69], v[118:119], 0, v[14:15]
	global_load_dwordx4 v[54:57], v[2:3], off offset:2048
	global_load_dwordx4 v[50:53], v[2:3], off offset:3072
	global_load_dwordx4 v[46:49], v[4:5], off offset:2048
	global_load_dwordx4 v[42:45], v[4:5], off offset:3072
	global_load_dwordx4 v[38:41], v[6:7], off offset:2048
	global_load_dwordx4 v[34:37], v[6:7], off offset:3072
	global_load_dwordx4 v[30:33], v[8:9], off offset:2048
	global_load_dwordx4 v[26:29], v[8:9], off offset:3072
	global_load_dwordx4 v[22:25], v[10:11], off offset:2048
	global_load_dwordx4 v[18:21], v[10:11], off offset:3072
	global_load_dwordx4 v[14:17], v[12:13], off offset:2048
	s_nop 0
	global_load_dwordx4 v[10:13], v[12:13], off offset:3072
	s_nop 0
	global_load_dwordx4 v[6:9], v[68:69], off offset:2048
	global_load_dwordx4 v[2:5], v[68:69], off offset:3072
	s_waitcnt vmcnt(15)
	v_and_b32_e32 v69, 0xffff0000, v59
	v_lshlrev_b32_e32 v59, 16, v59
	v_and_b32_e32 v63, 0xffff0000, v58
	v_lshlrev_b32_e32 v71, 16, v60
	v_and_b32_e32 v73, 0xffff0000, v60
	v_lshlrev_b32_e32 v58, 16, v58
	v_mov_b32_e32 v60, v59
	v_mul_f32_e32 v74, v58, v58
	v_mov_b32_e32 v75, v59
	v_pk_add_f32 v[76:77], v[58:59], v[62:63] op_sel:[1,0] op_sel_hi:[0,1]
	v_pk_mul_f32 v[58:59], v[58:59], v[60:61] op_sel:[1,0] op_sel_hi:[0,1]
	v_mul_f32_e32 v182, v69, v69
	v_mul_f32_e32 v68, v63, v63
	v_mov_b32_e32 v59, v77
	v_pk_add_f32 v[68:69], v[74:75], v[68:69]
	v_pk_add_f32 v[58:59], v[58:59], v[182:183]
	v_mul_f32_e32 v70, v71, v71
	v_mul_f32_e32 v72, v73, v73
	v_pk_add_f32 v[58:59], v[68:69], v[58:59]
	v_lshlrev_b32_e32 v69, 16, v61
	v_and_b32_e32 v61, 0xffff0000, v61
	v_pk_add_f32 v[70:71], v[70:71], v[72:73]
	v_mul_f32_e32 v68, v69, v69
	v_mul_f32_e32 v60, v61, v61
	v_pk_add_f32 v[58:59], v[70:71], v[58:59]
	v_pk_add_f32 v[60:61], v[68:69], v[60:61]
	s_waitcnt vmcnt(14)
	v_lshlrev_b32_e32 v69, 16, v64
	v_and_b32_e32 v71, 0xffff0000, v64
	v_mul_f32_e32 v68, v69, v69
	v_mul_f32_e32 v70, v71, v71
	v_lshlrev_b32_e32 v73, 16, v65
	v_and_b32_e32 v65, 0xffff0000, v65
	v_mul_f32_e32 v72, v73, v73
	v_mul_f32_e32 v64, v65, v65
	v_lshlrev_b32_e32 v75, 16, v66
	v_and_b32_e32 v77, 0xffff0000, v66
	v_pk_add_f32 v[58:59], v[60:61], v[58:59]
	v_pk_add_f32 v[60:61], v[68:69], v[70:71]
	v_mul_f32_e32 v74, v75, v75
	v_mul_f32_e32 v76, v77, v77
	v_lshlrev_b32_e32 v79, 16, v67
	v_and_b32_e32 v67, 0xffff0000, v67
	v_pk_add_f32 v[58:59], v[60:61], v[58:59]
	v_pk_add_f32 v[60:61], v[72:73], v[64:65]
	v_mul_f32_e32 v78, v79, v79
	v_mul_f32_e32 v66, v67, v67
	v_pk_add_f32 v[58:59], v[60:61], v[58:59]
	v_pk_add_f32 v[60:61], v[74:75], v[76:77]
	s_nop 0
	v_pk_add_f32 v[58:59], v[60:61], v[58:59]
	v_pk_add_f32 v[60:61], v[78:79], v[66:67]
	s_nop 0
	v_pk_add_f32 v[58:59], v[60:61], v[58:59]
	v_mov_b32_e32 v61, v59
	v_mov_b32_e32 v60, v58
	s_nop 1
	v_permlane32_swap_b32_e32 v59, v61
	v_permlane32_swap_b32_e32 v58, v60
	s_waitcnt lgkmcnt(0)
	v_pk_add_f32 v[58:59], v[58:59], v[60:61]
	v_mov_b32_e32 v61, v59
	v_mov_b32_e32 v60, v58
	s_nop 1
	v_permlane16_swap_b32_e32 v59, v61
	v_permlane16_swap_b32_e32 v58, v60
	s_waitcnt lgkmcnt(0)
	v_pk_add_f32 v[58:59], v[58:59], v[60:61]
	s_nop 1
	v_mov_b32_dpp v61, v59 row_ror:8 row_mask:0xf bank_mask:0xf
	v_mov_b32_dpp v60, v58 row_ror:8 row_mask:0xf bank_mask:0xf
	s_waitcnt lgkmcnt(0)
	v_pk_add_f32 v[58:59], v[58:59], v[60:61]
	s_nop 1
	v_mov_b32_dpp v61, v59 row_ror:4 row_mask:0xf bank_mask:0xf
	v_mov_b32_dpp v60, v58 row_ror:4 row_mask:0xf bank_mask:0xf
	s_waitcnt lgkmcnt(0)
	v_pk_add_f32 v[58:59], v[58:59], v[60:61]
	s_nop 1
	v_mov_b32_dpp v61, v59 quad_perm:[2,3,0,1] row_mask:0xf bank_mask:0xf
	v_mov_b32_dpp v60, v58 quad_perm:[2,3,0,1] row_mask:0xf bank_mask:0xf
	s_waitcnt lgkmcnt(0)
	v_pk_add_f32 v[58:59], v[58:59], v[60:61]
	ds_bpermute_b32 v61, v124, v59
	ds_bpermute_b32 v60, v124, v58
	s_and_saveexec_b64 s[60:61], s[38:39]
	s_cbranch_execz .LBB0_321
	s_waitcnt lgkmcnt(0)
	v_pk_add_f32 v[58:59], v[58:59], v[60:61]
	s_nop 0
	v_pk_mul_f32 v[58:59], v[58:59], s[36:37] op_sel_hi:[1,0]
	s_nop 0
	v_fma_f32 v58, -v59, v59, v58
	v_max_f32_e32 v58, 0, v58
	v_add_f32_e32 v58, 0x358637bd, v58
	v_mul_f32_e32 v60, 0x4b800000, v58
	v_cmp_gt_f32_e64 s[56:57], s33, v58
	s_nop 1
	v_cndmask_b32_e64 v58, v58, v60, s[56:57]
	v_rsq_f32_e32 v58, v58
	s_nop 0
	v_mul_f32_e32 v60, 0x45800000, v58
	v_cndmask_b32_e64 v58, v58, v60, s[56:57]
	v_cndmask_b32_e64 v61, 0, v58, s[52:53]
	v_cndmask_b32_e64 v60, 0, v59, s[52:53]
	ds_write_b64 v62, v[60:61]
; DI float bflo(unsigned u) { return __uint_as_float(u << 16); }
; DI float bfhi(unsigned u) { return __uint_as_float(u & 0xffff0000u); }
; DI float wave_sum(float v) {
; #pragma unroll
;   for (int o = 32; o; o >>= 1) v += __shfl_xor(v, o, 64);
;   return v;
; }
; DI void sgu_ln_items(const Params& p, int e, char* smem) {
;     ...
;       for (int k = 0; k < 8; ++k) {
;         const int i = wave * 32 + b8 + k;
;         float s = 0.f, s2 = 0.f;
; #pragma unroll
;         for (int j = 0; j < 2; ++j)
; #pragma unroll
;           for (int w4 = 0; w4 < 4; ++w4) {
;             const float lo = bflo(q[k][j][w4]), hi = bfhi(q[k][j][w4]);
;             s += lo + hi; s2 += lo * lo + hi * hi;
;           }
;         s = wave_sum(s); s2 = wave_sum(s2);
;         const float mu = s * (1.f / 1024.f);
;         const float var = fmaxf(s2 * (1.f / 1024.f) - mu * mu, 0.f);
;         const float rstd = rsqrtf(var + 1e-6f);
;         if (lane == 0) st[i] = i < nvalid ? make_float2(mu, rstd) : make_float2(0.f, 0.f);
;       }
.LBB0_321:
	s_or_b64 exec, exec, s[60:61]
	s_waitcnt vmcnt(13)
	v_and_b32_e32 v59, 0xffff0000, v54
	s_waitcnt lgkmcnt(1)
	v_and_b32_e32 v61, 0xffff0000, v55
	v_lshlrev_b32_e32 v55, 16, v55
	v_lshlrev_b32_e32 v54, 16, v54
	v_lshlrev_b32_e32 v65, 16, v56
	v_and_b32_e32 v67, 0xffff0000, v56
	v_mul_f32_e32 v68, v54, v54
	v_mov_b32_e32 v56, v55
	v_mov_b32_e32 v69, v55
	s_waitcnt lgkmcnt(0)
	v_mul_f32_e32 v60, v59, v59
	v_mul_f32_e32 v182, v61, v61
	v_pk_add_f32 v[60:61], v[68:69], v[60:61]
	v_pk_mul_f32 v[68:69], v[54:55], v[56:57] op_sel:[1,0] op_sel_hi:[0,1]
	v_pk_add_f32 v[54:55], v[54:55], v[58:59] op_sel:[1,0] op_sel_hi:[0,1]
	v_mov_b32_e32 v69, v55
	v_mul_f32_e32 v64, v65, v65
	v_mul_f32_e32 v66, v67, v67
	v_pk_add_f32 v[54:55], v[68:69], v[182:183]
	v_pk_add_f32 v[58:59], v[64:65], v[66:67]
	v_pk_add_f32 v[54:55], v[60:61], v[54:55]
	s_waitcnt vmcnt(12)
	v_and_b32_e32 v61, 0xffff0000, v50
	v_pk_add_f32 v[54:55], v[58:59], v[54:55]
	v_lshlrev_b32_e32 v59, 16, v57
	v_and_b32_e32 v57, 0xffff0000, v57
	v_mul_f32_e32 v58, v59, v59
	v_mul_f32_e32 v56, v57, v57
	v_pk_add_f32 v[56:57], v[58:59], v[56:57]
	v_lshlrev_b32_e32 v59, 16, v50
	v_mul_f32_e32 v58, v59, v59
	v_mul_f32_e32 v60, v61, v61
	v_lshlrev_b32_e32 v65, 16, v51
	v_and_b32_e32 v51, 0xffff0000, v51
	v_mul_f32_e32 v64, v65, v65
	v_mul_f32_e32 v50, v51, v51
	v_lshlrev_b32_e32 v67, 16, v52
	v_and_b32_e32 v69, 0xffff0000, v52
	v_pk_add_f32 v[54:55], v[56:57], v[54:55]
	v_pk_add_f32 v[56:57], v[58:59], v[60:61]
	v_mul_f32_e32 v66, v67, v67
	v_mul_f32_e32 v68, v69, v69
	v_lshlrev_b32_e32 v71, 16, v53
	v_and_b32_e32 v53, 0xffff0000, v53
	v_pk_add_f32 v[54:55], v[56:57], v[54:55]
	v_pk_add_f32 v[50:51], v[64:65], v[50:51]
	v_mul_f32_e32 v70, v71, v71
	v_mul_f32_e32 v52, v53, v53
	v_pk_add_f32 v[50:51], v[50:51], v[54:55]
	v_pk_add_f32 v[54:55], v[66:67], v[68:69]
	v_pk_add_f32 v[52:53], v[70:71], v[52:53]
	v_pk_add_f32 v[50:51], v[54:55], v[50:51]
	s_nop 0
	v_pk_add_f32 v[50:51], v[52:53], v[50:51]
	v_mov_b32_e32 v53, v51
	v_mov_b32_e32 v52, v50
	s_nop 1
	v_permlane32_swap_b32_e32 v51, v53
	v_permlane32_swap_b32_e32 v50, v52
	s_waitcnt lgkmcnt(0)
	v_pk_add_f32 v[50:51], v[50:51], v[52:53]
	v_mov_b32_e32 v53, v51
	v_mov_b32_e32 v52, v50
	s_nop 1
	v_permlane16_swap_b32_e32 v51, v53
	v_permlane16_swap_b32_e32 v50, v52
	s_waitcnt lgkmcnt(0)
	v_pk_add_f32 v[50:51], v[50:51], v[52:53]
	s_nop 1
	v_mov_b32_dpp v53, v51 row_ror:8 row_mask:0xf bank_mask:0xf
	v_mov_b32_dpp v52, v50 row_ror:8 row_mask:0xf bank_mask:0xf
	s_waitcnt lgkmcnt(0)
	v_pk_add_f32 v[50:51], v[50:51], v[52:53]
	s_nop 1
	v_mov_b32_dpp v53, v51 row_ror:4 row_mask:0xf bank_mask:0xf
	v_mov_b32_dpp v52, v50 row_ror:4 row_mask:0xf bank_mask:0xf
	s_waitcnt lgkmcnt(0)
	v_pk_add_f32 v[50:51], v[50:51], v[52:53]
	s_nop 1
	v_mov_b32_dpp v53, v51 quad_perm:[2,3,0,1] row_mask:0xf bank_mask:0xf
	v_mov_b32_dpp v52, v50 quad_perm:[2,3,0,1] row_mask:0xf bank_mask:0xf
	s_waitcnt lgkmcnt(0)
	v_pk_add_f32 v[50:51], v[50:51], v[52:53]
	ds_bpermute_b32 v53, v124, v51
	ds_bpermute_b32 v52, v124, v50
	s_and_saveexec_b64 s[56:57], s[38:39]
	s_cbranch_execz .LBB0_323
	s_waitcnt lgkmcnt(0)
	v_pk_add_f32 v[50:51], v[50:51], v[52:53]
	s_nop 0
	v_pk_mul_f32 v[50:51], v[50:51], s[36:37] op_sel_hi:[1,0]
	s_nop 0
	v_fma_f32 v50, -v51, v51, v50
	v_max_f32_e32 v50, 0, v50
	v_add_f32_e32 v50, 0x358637bd, v50
	v_mul_f32_e32 v52, 0x4b800000, v50
	v_cmp_gt_f32_e64 s[52:53], s33, v50
	s_nop 1
	v_cndmask_b32_e64 v50, v50, v52, s[52:53]
	v_rsq_f32_e32 v50, v50
	s_nop 0
	v_mul_f32_e32 v52, 0x45800000, v50
	v_cndmask_b32_e64 v50, v50, v52, s[52:53]
	v_cndmask_b32_e64 v53, 0, v50, s[50:51]
	v_cndmask_b32_e64 v52, 0, v51, s[50:51]
	ds_write_b64 v62, v[52:53] offset:8
.LBB0_323:
	s_or_b64 exec, exec, s[56:57]
	s_waitcnt vmcnt(11)
	v_and_b32_e32 v51, 0xffff0000, v46
	s_waitcnt lgkmcnt(1)
	v_and_b32_e32 v53, 0xffff0000, v47
	v_lshlrev_b32_e32 v47, 16, v47
	v_lshlrev_b32_e32 v46, 16, v46
	v_lshlrev_b32_e32 v55, 16, v48
	v_and_b32_e32 v57, 0xffff0000, v48
	v_mul_f32_e32 v58, v46, v46
	v_mov_b32_e32 v48, v47
	v_mov_b32_e32 v59, v47
	s_waitcnt lgkmcnt(0)
	v_mul_f32_e32 v52, v51, v51
	v_mul_f32_e32 v182, v53, v53
	v_pk_add_f32 v[52:53], v[58:59], v[52:53]
	v_pk_mul_f32 v[58:59], v[46:47], v[48:49] op_sel:[1,0] op_sel_hi:[0,1]
	v_pk_add_f32 v[46:47], v[46:47], v[50:51] op_sel:[1,0] op_sel_hi:[0,1]
	v_mov_b32_e32 v59, v47
	v_mul_f32_e32 v54, v55, v55
	v_mul_f32_e32 v56, v57, v57
	v_pk_add_f32 v[46:47], v[58:59], v[182:183]
	v_pk_add_f32 v[50:51], v[54:55], v[56:57]
	v_pk_add_f32 v[46:47], v[52:53], v[46:47]
	s_waitcnt vmcnt(10)
	v_and_b32_e32 v53, 0xffff0000, v42
	v_pk_add_f32 v[46:47], v[50:51], v[46:47]
	v_lshlrev_b32_e32 v51, 16, v49
	v_and_b32_e32 v49, 0xffff0000, v49
	v_mul_f32_e32 v50, v51, v51
	v_mul_f32_e32 v48, v49, v49
	v_pk_add_f32 v[48:49], v[50:51], v[48:49]
	v_lshlrev_b32_e32 v51, 16, v42
	v_mul_f32_e32 v50, v51, v51
	v_mul_f32_e32 v52, v53, v53
	v_lshlrev_b32_e32 v55, 16, v43
	v_and_b32_e32 v43, 0xffff0000, v43
	v_mul_f32_e32 v54, v55, v55
	v_mul_f32_e32 v42, v43, v43
	v_lshlrev_b32_e32 v57, 16, v44
	v_and_b32_e32 v59, 0xffff0000, v44
	v_pk_add_f32 v[46:47], v[48:49], v[46:47]
	v_pk_add_f32 v[48:49], v[50:51], v[52:53]
	v_mul_f32_e32 v56, v57, v57
	v_mul_f32_e32 v58, v59, v59
	v_lshlrev_b32_e32 v61, 16, v45
	v_and_b32_e32 v45, 0xffff0000, v45
	v_pk_add_f32 v[46:47], v[48:49], v[46:47]
	v_pk_add_f32 v[42:43], v[54:55], v[42:43]
	v_mul_f32_e32 v60, v61, v61
	v_mul_f32_e32 v44, v45, v45
	v_pk_add_f32 v[42:43], v[42:43], v[46:47]
	v_pk_add_f32 v[46:47], v[56:57], v[58:59]
	v_pk_add_f32 v[44:45], v[60:61], v[44:45]
	v_pk_add_f32 v[42:43], v[46:47], v[42:43]
	s_nop 0
	v_pk_add_f32 v[42:43], v[44:45], v[42:43]
	v_mov_b32_e32 v45, v43
	v_mov_b32_e32 v44, v42
	s_nop 1
	v_permlane32_swap_b32_e32 v43, v45
	v_permlane32_swap_b32_e32 v42, v44
	s_waitcnt lgkmcnt(0)
	v_pk_add_f32 v[42:43], v[42:43], v[44:45]
	v_mov_b32_e32 v45, v43
	v_mov_b32_e32 v44, v42
	s_nop 1
	v_permlane16_swap_b32_e32 v43, v45
	v_permlane16_swap_b32_e32 v42, v44
	s_waitcnt lgkmcnt(0)
	v_pk_add_f32 v[42:43], v[42:43], v[44:45]
	s_nop 1
	v_mov_b32_dpp v45, v43 row_ror:8 row_mask:0xf bank_mask:0xf
	v_mov_b32_dpp v44, v42 row_ror:8 row_mask:0xf bank_mask:0xf
	s_waitcnt lgkmcnt(0)
	v_pk_add_f32 v[42:43], v[42:43], v[44:45]
	s_nop 1
	v_mov_b32_dpp v45, v43 row_ror:4 row_mask:0xf bank_mask:0xf
	v_mov_b32_dpp v44, v42 row_ror:4 row_mask:0xf bank_mask:0xf
	s_waitcnt lgkmcnt(0)
	v_pk_add_f32 v[42:43], v[42:43], v[44:45]
	s_nop 1
	v_mov_b32_dpp v45, v43 quad_perm:[2,3,0,1] row_mask:0xf bank_mask:0xf
	v_mov_b32_dpp v44, v42 quad_perm:[2,3,0,1] row_mask:0xf bank_mask:0xf
	s_waitcnt lgkmcnt(0)
	v_pk_add_f32 v[42:43], v[42:43], v[44:45]
	ds_bpermute_b32 v45, v124, v43
	ds_bpermute_b32 v44, v124, v42
	s_and_saveexec_b64 s[52:53], s[38:39]
	s_cbranch_execz .LBB0_325
; DI float bflo(unsigned u) { return __uint_as_float(u << 16); }
; DI float bfhi(unsigned u) { return __uint_as_float(u & 0xffff0000u); }
; DI float wave_sum(float v) {
; #pragma unroll
;   for (int o = 32; o; o >>= 1) v += __shfl_xor(v, o, 64);
;   return v;
; }
; DI void sgu_ln_items(const Params& p, int e, char* smem) {
;     ...
;       for (int k = 0; k < 8; ++k) {
;         const int i = wave * 32 + b8 + k;
;         float s = 0.f, s2 = 0.f;
; #pragma unroll
;         for (int j = 0; j < 2; ++j)
; #pragma unroll
;           for (int w4 = 0; w4 < 4; ++w4) {
;             const float lo = bflo(q[k][j][w4]), hi = bfhi(q[k][j][w4]);
;             s += lo + hi; s2 += lo * lo + hi * hi;
;           }
;         s = wave_sum(s); s2 = wave_sum(s2);
;         const float mu = s * (1.f / 1024.f);
;         const float var = fmaxf(s2 * (1.f / 1024.f) - mu * mu, 0.f);
;         const float rstd = rsqrtf(var + 1e-6f);
;         if (lane == 0) st[i] = i < nvalid ? make_float2(mu, rstd) : make_float2(0.f, 0.f);
;       }
	s_waitcnt lgkmcnt(0)
	v_pk_add_f32 v[42:43], v[42:43], v[44:45]
	s_nop 0
	v_pk_mul_f32 v[42:43], v[42:43], s[36:37] op_sel_hi:[1,0]
	s_nop 0
	v_fma_f32 v42, -v43, v43, v42
	v_max_f32_e32 v42, 0, v42
	v_add_f32_e32 v42, 0x358637bd, v42
	v_mul_f32_e32 v44, 0x4b800000, v42
	v_cmp_gt_f32_e64 s[50:51], s33, v42
	s_nop 1
	v_cndmask_b32_e64 v42, v42, v44, s[50:51]
	v_rsq_f32_e32 v42, v42
	s_nop 0
	v_mul_f32_e32 v44, 0x45800000, v42
	v_cndmask_b32_e64 v42, v42, v44, s[50:51]
	v_cndmask_b32_e64 v45, 0, v42, s[48:49]
	v_cndmask_b32_e64 v44, 0, v43, s[48:49]
	ds_write_b64 v62, v[44:45] offset:16
.LBB0_325:
	s_or_b64 exec, exec, s[52:53]
	s_waitcnt vmcnt(9)
	v_and_b32_e32 v43, 0xffff0000, v38
	s_waitcnt lgkmcnt(1)
	v_and_b32_e32 v45, 0xffff0000, v39
	v_lshlrev_b32_e32 v39, 16, v39
	v_lshlrev_b32_e32 v38, 16, v38
	v_lshlrev_b32_e32 v47, 16, v40
	v_and_b32_e32 v49, 0xffff0000, v40
	v_mul_f32_e32 v50, v38, v38
	v_mov_b32_e32 v40, v39
	v_mov_b32_e32 v51, v39
	s_waitcnt lgkmcnt(0)
	v_mul_f32_e32 v44, v43, v43
	v_mul_f32_e32 v182, v45, v45
	v_pk_add_f32 v[44:45], v[50:51], v[44:45]
	v_pk_mul_f32 v[50:51], v[38:39], v[40:41] op_sel:[1,0] op_sel_hi:[0,1]
	v_pk_add_f32 v[38:39], v[38:39], v[42:43] op_sel:[1,0] op_sel_hi:[0,1]
	v_mov_b32_e32 v51, v39
	v_mul_f32_e32 v46, v47, v47
	v_mul_f32_e32 v48, v49, v49
	v_pk_add_f32 v[38:39], v[50:51], v[182:183]
	v_pk_add_f32 v[42:43], v[46:47], v[48:49]
	v_pk_add_f32 v[38:39], v[44:45], v[38:39]
	s_waitcnt vmcnt(8)
	v_and_b32_e32 v45, 0xffff0000, v34
	v_pk_add_f32 v[38:39], v[42:43], v[38:39]
	v_lshlrev_b32_e32 v43, 16, v41
	v_and_b32_e32 v41, 0xffff0000, v41
	v_mul_f32_e32 v42, v43, v43
	v_mul_f32_e32 v40, v41, v41
	v_pk_add_f32 v[40:41], v[42:43], v[40:41]
	v_lshlrev_b32_e32 v43, 16, v34
	v_mul_f32_e32 v42, v43, v43
	v_mul_f32_e32 v44, v45, v45
	v_lshlrev_b32_e32 v47, 16, v35
	v_and_b32_e32 v35, 0xffff0000, v35
	v_mul_f32_e32 v46, v47, v47
	v_mul_f32_e32 v34, v35, v35
	v_lshlrev_b32_e32 v49, 16, v36
	v_and_b32_e32 v51, 0xffff0000, v36
	v_pk_add_f32 v[38:39], v[40:41], v[38:39]
	v_pk_add_f32 v[40:41], v[42:43], v[44:45]
	v_mul_f32_e32 v48, v49, v49
	v_mul_f32_e32 v50, v51, v51
	v_lshlrev_b32_e32 v53, 16, v37
	v_and_b32_e32 v37, 0xffff0000, v37
	v_pk_add_f32 v[38:39], v[40:41], v[38:39]
	v_pk_add_f32 v[34:35], v[46:47], v[34:35]
	v_mul_f32_e32 v52, v53, v53
	v_mul_f32_e32 v36, v37, v37
	v_pk_add_f32 v[34:35], v[34:35], v[38:39]
	v_pk_add_f32 v[38:39], v[48:49], v[50:51]
	v_pk_add_f32 v[36:37], v[52:53], v[36:37]
	v_pk_add_f32 v[34:35], v[38:39], v[34:35]
	s_nop 0
	v_pk_add_f32 v[34:35], v[36:37], v[34:35]
	v_mov_b32_e32 v37, v35
	v_mov_b32_e32 v36, v34
	s_nop 1
	v_permlane32_swap_b32_e32 v35, v37
	v_permlane32_swap_b32_e32 v34, v36
	s_waitcnt lgkmcnt(0)
	v_pk_add_f32 v[34:35], v[34:35], v[36:37]
	v_mov_b32_e32 v37, v35
	v_mov_b32_e32 v36, v34
	s_nop 1
	v_permlane16_swap_b32_e32 v35, v37
	v_permlane16_swap_b32_e32 v34, v36
	s_waitcnt lgkmcnt(0)
	v_pk_add_f32 v[34:35], v[34:35], v[36:37]
	s_nop 1
	v_mov_b32_dpp v37, v35 row_ror:8 row_mask:0xf bank_mask:0xf
	v_mov_b32_dpp v36, v34 row_ror:8 row_mask:0xf bank_mask:0xf
	s_waitcnt lgkmcnt(0)
	v_pk_add_f32 v[34:35], v[34:35], v[36:37]
	s_nop 1
	v_mov_b32_dpp v37, v35 row_ror:4 row_mask:0xf bank_mask:0xf
	v_mov_b32_dpp v36, v34 row_ror:4 row_mask:0xf bank_mask:0xf
	s_waitcnt lgkmcnt(0)
	v_pk_add_f32 v[34:35], v[34:35], v[36:37]
	s_nop 1
	v_mov_b32_dpp v37, v35 quad_perm:[2,3,0,1] row_mask:0xf bank_mask:0xf
	v_mov_b32_dpp v36, v34 quad_perm:[2,3,0,1] row_mask:0xf bank_mask:0xf
	s_waitcnt lgkmcnt(0)
	v_pk_add_f32 v[34:35], v[34:35], v[36:37]
	ds_bpermute_b32 v37, v124, v35
	ds_bpermute_b32 v36, v124, v34
	s_and_saveexec_b64 s[50:51], s[38:39]
	s_cbranch_execz .LBB0_327
	s_waitcnt lgkmcnt(0)
	v_pk_add_f32 v[34:35], v[34:35], v[36:37]
	s_nop 0
	v_pk_mul_f32 v[34:35], v[34:35], s[36:37] op_sel_hi:[1,0]
	s_nop 0
	v_fma_f32 v34, -v35, v35, v34
	v_max_f32_e32 v34, 0, v34
	v_add_f32_e32 v34, 0x358637bd, v34
	v_mul_f32_e32 v36, 0x4b800000, v34
	v_cmp_gt_f32_e64 s[48:49], s33, v34
	s_nop 1
	v_cndmask_b32_e64 v34, v34, v36, s[48:49]
	v_rsq_f32_e32 v34, v34
	s_nop 0
	v_mul_f32_e32 v36, 0x45800000, v34
	v_cndmask_b32_e64 v34, v34, v36, s[48:49]
	v_cndmask_b32_e64 v37, 0, v34, s[46:47]
	v_cndmask_b32_e64 v36, 0, v35, s[46:47]
	ds_write_b64 v62, v[36:37] offset:24
; DI float bflo(unsigned u) { return __uint_as_float(u << 16); }
; DI float bfhi(unsigned u) { return __uint_as_float(u & 0xffff0000u); }
; DI float wave_sum(float v) {
; #pragma unroll
;   for (int o = 32; o; o >>= 1) v += __shfl_xor(v, o, 64);
;   return v;
; }
; DI void sgu_ln_items(const Params& p, int e, char* smem) {
;     ...
;       for (int k = 0; k < 8; ++k) {
;         const int i = wave * 32 + b8 + k;
;         float s = 0.f, s2 = 0.f;
; #pragma unroll
;         for (int j = 0; j < 2; ++j)
; #pragma unroll
;           for (int w4 = 0; w4 < 4; ++w4) {
;             const float lo = bflo(q[k][j][w4]), hi = bfhi(q[k][j][w4]);
;             s += lo + hi; s2 += lo * lo + hi * hi;
;           }
;         s = wave_sum(s); s2 = wave_sum(s2);
;         const float mu = s * (1.f / 1024.f);
;         const float var = fmaxf(s2 * (1.f / 1024.f) - mu * mu, 0.f);
;         const float rstd = rsqrtf(var + 1e-6f);
;         if (lane == 0) st[i] = i < nvalid ? make_float2(mu, rstd) : make_float2(0.f, 0.f);
;       }
.LBB0_327:
	s_or_b64 exec, exec, s[50:51]
	s_waitcnt vmcnt(7)
	v_and_b32_e32 v35, 0xffff0000, v30
	s_waitcnt lgkmcnt(1)
	v_and_b32_e32 v37, 0xffff0000, v31
	v_lshlrev_b32_e32 v31, 16, v31
	v_lshlrev_b32_e32 v30, 16, v30
	v_lshlrev_b32_e32 v39, 16, v32
	v_and_b32_e32 v41, 0xffff0000, v32
	v_mul_f32_e32 v42, v30, v30
	v_mov_b32_e32 v32, v31
	v_mov_b32_e32 v43, v31
	s_waitcnt lgkmcnt(0)
	v_mul_f32_e32 v36, v35, v35
	v_mul_f32_e32 v182, v37, v37
	v_pk_add_f32 v[36:37], v[42:43], v[36:37]
	v_pk_mul_f32 v[42:43], v[30:31], v[32:33] op_sel:[1,0] op_sel_hi:[0,1]
	v_pk_add_f32 v[30:31], v[30:31], v[34:35] op_sel:[1,0] op_sel_hi:[0,1]
	v_mov_b32_e32 v43, v31
	v_mul_f32_e32 v38, v39, v39
	v_mul_f32_e32 v40, v41, v41
	v_pk_add_f32 v[30:31], v[42:43], v[182:183]
	v_pk_add_f32 v[34:35], v[38:39], v[40:41]
	v_pk_add_f32 v[30:31], v[36:37], v[30:31]
	s_waitcnt vmcnt(6)
	v_and_b32_e32 v37, 0xffff0000, v26
	v_pk_add_f32 v[30:31], v[34:35], v[30:31]
	v_lshlrev_b32_e32 v35, 16, v33
	v_and_b32_e32 v33, 0xffff0000, v33
	v_mul_f32_e32 v34, v35, v35
	v_mul_f32_e32 v32, v33, v33
	v_pk_add_f32 v[32:33], v[34:35], v[32:33]
	v_lshlrev_b32_e32 v35, 16, v26
	v_mul_f32_e32 v34, v35, v35
	v_mul_f32_e32 v36, v37, v37
	v_lshlrev_b32_e32 v39, 16, v27
	v_and_b32_e32 v27, 0xffff0000, v27
	v_mul_f32_e32 v38, v39, v39
	v_mul_f32_e32 v26, v27, v27
	v_lshlrev_b32_e32 v41, 16, v28
	v_and_b32_e32 v43, 0xffff0000, v28
	v_pk_add_f32 v[30:31], v[32:33], v[30:31]
	v_pk_add_f32 v[32:33], v[34:35], v[36:37]
	v_mul_f32_e32 v40, v41, v41
	v_mul_f32_e32 v42, v43, v43
	v_lshlrev_b32_e32 v45, 16, v29
	v_and_b32_e32 v29, 0xffff0000, v29
	v_pk_add_f32 v[30:31], v[32:33], v[30:31]
	v_pk_add_f32 v[26:27], v[38:39], v[26:27]
	v_mul_f32_e32 v44, v45, v45
	v_mul_f32_e32 v28, v29, v29
	v_pk_add_f32 v[26:27], v[26:27], v[30:31]
	v_pk_add_f32 v[30:31], v[40:41], v[42:43]
	v_pk_add_f32 v[28:29], v[44:45], v[28:29]
	v_pk_add_f32 v[26:27], v[30:31], v[26:27]
	s_nop 0
	v_pk_add_f32 v[26:27], v[28:29], v[26:27]
	v_mov_b32_e32 v29, v27
	v_mov_b32_e32 v28, v26
	s_nop 1
	v_permlane32_swap_b32_e32 v27, v29
	v_permlane32_swap_b32_e32 v26, v28
	s_waitcnt lgkmcnt(0)
	v_pk_add_f32 v[26:27], v[26:27], v[28:29]
	v_mov_b32_e32 v29, v27
	v_mov_b32_e32 v28, v26
	s_nop 1
	v_permlane16_swap_b32_e32 v27, v29
	v_permlane16_swap_b32_e32 v26, v28
	s_waitcnt lgkmcnt(0)
	v_pk_add_f32 v[26:27], v[26:27], v[28:29]
	s_nop 1
	v_mov_b32_dpp v29, v27 row_ror:8 row_mask:0xf bank_mask:0xf
	v_mov_b32_dpp v28, v26 row_ror:8 row_mask:0xf bank_mask:0xf
	s_waitcnt lgkmcnt(0)
	v_pk_add_f32 v[26:27], v[26:27], v[28:29]
	s_nop 1
	v_mov_b32_dpp v29, v27 row_ror:4 row_mask:0xf bank_mask:0xf
	v_mov_b32_dpp v28, v26 row_ror:4 row_mask:0xf bank_mask:0xf
	s_waitcnt lgkmcnt(0)
	v_pk_add_f32 v[26:27], v[26:27], v[28:29]
	s_nop 1
	v_mov_b32_dpp v29, v27 quad_perm:[2,3,0,1] row_mask:0xf bank_mask:0xf
	v_mov_b32_dpp v28, v26 quad_perm:[2,3,0,1] row_mask:0xf bank_mask:0xf
	s_waitcnt lgkmcnt(0)
	v_pk_add_f32 v[26:27], v[26:27], v[28:29]
	ds_bpermute_b32 v29, v124, v27
	ds_bpermute_b32 v28, v124, v26
	s_and_saveexec_b64 s[48:49], s[38:39]
	s_cbranch_execz .LBB0_329
	s_waitcnt lgkmcnt(0)
	v_pk_add_f32 v[26:27], v[26:27], v[28:29]
	s_nop 0
	v_pk_mul_f32 v[26:27], v[26:27], s[36:37] op_sel_hi:[1,0]
	s_nop 0
	v_fma_f32 v26, -v27, v27, v26
	v_max_f32_e32 v26, 0, v26
	v_add_f32_e32 v26, 0x358637bd, v26
	v_mul_f32_e32 v28, 0x4b800000, v26
	v_cmp_gt_f32_e64 s[46:47], s33, v26
	s_nop 1
	v_cndmask_b32_e64 v26, v26, v28, s[46:47]
	v_rsq_f32_e32 v26, v26
	s_nop 0
	v_mul_f32_e32 v28, 0x45800000, v26
	v_cndmask_b32_e64 v26, v26, v28, s[46:47]
	v_cndmask_b32_e64 v29, 0, v26, s[44:45]
	v_cndmask_b32_e64 v28, 0, v27, s[44:45]
	ds_write_b64 v62, v[28:29] offset:32
.LBB0_329:
	s_or_b64 exec, exec, s[48:49]
	s_waitcnt vmcnt(5)
	v_and_b32_e32 v27, 0xffff0000, v22
	s_waitcnt lgkmcnt(1)
	v_and_b32_e32 v29, 0xffff0000, v23
	v_lshlrev_b32_e32 v23, 16, v23
	v_lshlrev_b32_e32 v22, 16, v22
	v_lshlrev_b32_e32 v31, 16, v24
	v_and_b32_e32 v33, 0xffff0000, v24
	v_mul_f32_e32 v34, v22, v22
	v_mov_b32_e32 v24, v23
	v_mov_b32_e32 v35, v23
	s_waitcnt lgkmcnt(0)
	v_mul_f32_e32 v28, v27, v27
	v_mul_f32_e32 v182, v29, v29
	v_pk_add_f32 v[28:29], v[34:35], v[28:29]
	v_pk_mul_f32 v[34:35], v[22:23], v[24:25] op_sel:[1,0] op_sel_hi:[0,1]
	v_pk_add_f32 v[22:23], v[22:23], v[26:27] op_sel:[1,0] op_sel_hi:[0,1]
	v_mov_b32_e32 v35, v23
	v_mul_f32_e32 v30, v31, v31
	v_mul_f32_e32 v32, v33, v33
	v_pk_add_f32 v[22:23], v[34:35], v[182:183]
	v_pk_add_f32 v[26:27], v[30:31], v[32:33]
	v_pk_add_f32 v[22:23], v[28:29], v[22:23]
	s_waitcnt vmcnt(4)
	v_and_b32_e32 v29, 0xffff0000, v18
	v_pk_add_f32 v[22:23], v[26:27], v[22:23]
	v_lshlrev_b32_e32 v27, 16, v25
	v_and_b32_e32 v25, 0xffff0000, v25
	v_mul_f32_e32 v26, v27, v27
	v_mul_f32_e32 v24, v25, v25
	v_pk_add_f32 v[24:25], v[26:27], v[24:25]
	v_lshlrev_b32_e32 v27, 16, v18
	v_mul_f32_e32 v26, v27, v27
	v_mul_f32_e32 v28, v29, v29
	v_lshlrev_b32_e32 v31, 16, v19
	v_and_b32_e32 v19, 0xffff0000, v19
	v_mul_f32_e32 v30, v31, v31
	v_mul_f32_e32 v18, v19, v19
	v_lshlrev_b32_e32 v33, 16, v20
	v_and_b32_e32 v35, 0xffff0000, v20
	v_pk_add_f32 v[22:23], v[24:25], v[22:23]
	v_pk_add_f32 v[24:25], v[26:27], v[28:29]
	v_mul_f32_e32 v32, v33, v33
	v_mul_f32_e32 v34, v35, v35
	v_lshlrev_b32_e32 v37, 16, v21
	v_and_b32_e32 v21, 0xffff0000, v21
	v_pk_add_f32 v[22:23], v[24:25], v[22:23]
	v_pk_add_f32 v[18:19], v[30:31], v[18:19]
	v_mul_f32_e32 v36, v37, v37
	v_mul_f32_e32 v20, v21, v21
	v_pk_add_f32 v[18:19], v[18:19], v[22:23]
	v_pk_add_f32 v[22:23], v[32:33], v[34:35]
	v_pk_add_f32 v[20:21], v[36:37], v[20:21]
	v_pk_add_f32 v[18:19], v[22:23], v[18:19]
	s_nop 0
	v_pk_add_f32 v[18:19], v[20:21], v[18:19]
	v_mov_b32_e32 v21, v19
	v_mov_b32_e32 v20, v18
	s_nop 1
	v_permlane32_swap_b32_e32 v19, v21
	v_permlane32_swap_b32_e32 v18, v20
	s_waitcnt lgkmcnt(0)
	v_pk_add_f32 v[18:19], v[18:19], v[20:21]
	v_mov_b32_e32 v21, v19
	v_mov_b32_e32 v20, v18
	s_nop 1
	v_permlane16_swap_b32_e32 v19, v21
	v_permlane16_swap_b32_e32 v18, v20
	s_waitcnt lgkmcnt(0)
	v_pk_add_f32 v[18:19], v[18:19], v[20:21]
	s_nop 1
	v_mov_b32_dpp v21, v19 row_ror:8 row_mask:0xf bank_mask:0xf
	v_mov_b32_dpp v20, v18 row_ror:8 row_mask:0xf bank_mask:0xf
	s_waitcnt lgkmcnt(0)
	v_pk_add_f32 v[18:19], v[18:19], v[20:21]
	s_nop 1
	v_mov_b32_dpp v21, v19 row_ror:4 row_mask:0xf bank_mask:0xf
	v_mov_b32_dpp v20, v18 row_ror:4 row_mask:0xf bank_mask:0xf
	s_waitcnt lgkmcnt(0)
	v_pk_add_f32 v[18:19], v[18:19], v[20:21]
	s_nop 1
	v_mov_b32_dpp v21, v19 quad_perm:[2,3,0,1] row_mask:0xf bank_mask:0xf
	v_mov_b32_dpp v20, v18 quad_perm:[2,3,0,1] row_mask:0xf bank_mask:0xf
	s_waitcnt lgkmcnt(0)
	v_pk_add_f32 v[18:19], v[18:19], v[20:21]
	ds_bpermute_b32 v21, v124, v19
	ds_bpermute_b32 v20, v124, v18
	s_and_saveexec_b64 s[46:47], s[38:39]
	s_cbranch_execz .LBB0_331
; DI float bflo(unsigned u) { return __uint_as_float(u << 16); }
; DI float bfhi(unsigned u) { return __uint_as_float(u & 0xffff0000u); }
; DI float wave_sum(float v) {
; #pragma unroll
;   for (int o = 32; o; o >>= 1) v += __shfl_xor(v, o, 64);
;   return v;
; }
; DI void sgu_ln_items(const Params& p, int e, char* smem) {
;     ...
;       for (int k = 0; k < 8; ++k) {
;         const int i = wave * 32 + b8 + k;
;         float s = 0.f, s2 = 0.f;
; #pragma unroll
;         for (int j = 0; j < 2; ++j)
; #pragma unroll
;           for (int w4 = 0; w4 < 4; ++w4) {
;             const float lo = bflo(q[k][j][w4]), hi = bfhi(q[k][j][w4]);
;             s += lo + hi; s2 += lo * lo + hi * hi;
;           }
;         s = wave_sum(s); s2 = wave_sum(s2);
;         const float mu = s * (1.f / 1024.f);
;         const float var = fmaxf(s2 * (1.f / 1024.f) - mu * mu, 0.f);
;         const float rstd = rsqrtf(var + 1e-6f);
;         if (lane == 0) st[i] = i < nvalid ? make_float2(mu, rstd) : make_float2(0.f, 0.f);
;       }
	s_waitcnt lgkmcnt(0)
	v_pk_add_f32 v[18:19], v[18:19], v[20:21]
	s_nop 0
	v_pk_mul_f32 v[18:19], v[18:19], s[36:37] op_sel_hi:[1,0]
	s_nop 0
	v_fma_f32 v18, -v19, v19, v18
	v_max_f32_e32 v18, 0, v18
	v_add_f32_e32 v18, 0x358637bd, v18
	v_mul_f32_e32 v20, 0x4b800000, v18
	v_cmp_gt_f32_e64 s[44:45], s33, v18
	s_nop 1
	v_cndmask_b32_e64 v18, v18, v20, s[44:45]
	v_rsq_f32_e32 v18, v18
	s_nop 0
	v_mul_f32_e32 v20, 0x45800000, v18
	v_cndmask_b32_e64 v18, v18, v20, s[44:45]
	v_cndmask_b32_e64 v21, 0, v18, s[42:43]
	v_cndmask_b32_e64 v20, 0, v19, s[42:43]
	ds_write_b64 v62, v[20:21] offset:40
.LBB0_331:
	s_or_b64 exec, exec, s[46:47]
	s_waitcnt vmcnt(3)
	v_and_b32_e32 v19, 0xffff0000, v14
	s_waitcnt lgkmcnt(1)
	v_and_b32_e32 v21, 0xffff0000, v15
	v_lshlrev_b32_e32 v15, 16, v15
	v_lshlrev_b32_e32 v14, 16, v14
	v_lshlrev_b32_e32 v23, 16, v16
	v_and_b32_e32 v25, 0xffff0000, v16
	v_mul_f32_e32 v26, v14, v14
	v_mov_b32_e32 v16, v15
	v_mov_b32_e32 v27, v15
	s_waitcnt lgkmcnt(0)
	v_mul_f32_e32 v20, v19, v19
	v_mul_f32_e32 v182, v21, v21
	v_pk_add_f32 v[20:21], v[26:27], v[20:21]
	v_pk_mul_f32 v[26:27], v[14:15], v[16:17] op_sel:[1,0] op_sel_hi:[0,1]
	v_pk_add_f32 v[14:15], v[14:15], v[18:19] op_sel:[1,0] op_sel_hi:[0,1]
	v_mov_b32_e32 v27, v15
	v_mul_f32_e32 v22, v23, v23
	v_mul_f32_e32 v24, v25, v25
	v_pk_add_f32 v[14:15], v[26:27], v[182:183]
	v_pk_add_f32 v[18:19], v[22:23], v[24:25]
	v_pk_add_f32 v[14:15], v[20:21], v[14:15]
	s_waitcnt vmcnt(2)
	v_and_b32_e32 v21, 0xffff0000, v10
	v_pk_add_f32 v[14:15], v[18:19], v[14:15]
	v_lshlrev_b32_e32 v19, 16, v17
	v_and_b32_e32 v17, 0xffff0000, v17
	v_mul_f32_e32 v18, v19, v19
	v_mul_f32_e32 v16, v17, v17
	v_pk_add_f32 v[16:17], v[18:19], v[16:17]
	v_lshlrev_b32_e32 v19, 16, v10
	v_mul_f32_e32 v18, v19, v19
	v_mul_f32_e32 v20, v21, v21
	v_lshlrev_b32_e32 v23, 16, v11
	v_and_b32_e32 v11, 0xffff0000, v11
	v_mul_f32_e32 v22, v23, v23
	v_mul_f32_e32 v10, v11, v11
	v_lshlrev_b32_e32 v25, 16, v12
	v_and_b32_e32 v27, 0xffff0000, v12
	v_pk_add_f32 v[14:15], v[16:17], v[14:15]
	v_pk_add_f32 v[16:17], v[18:19], v[20:21]
	v_mul_f32_e32 v24, v25, v25
	v_mul_f32_e32 v26, v27, v27
	v_lshlrev_b32_e32 v29, 16, v13
	v_and_b32_e32 v13, 0xffff0000, v13
	v_pk_add_f32 v[14:15], v[16:17], v[14:15]
	v_pk_add_f32 v[10:11], v[22:23], v[10:11]
	v_mul_f32_e32 v28, v29, v29
	v_mul_f32_e32 v12, v13, v13
	v_pk_add_f32 v[10:11], v[10:11], v[14:15]
	v_pk_add_f32 v[14:15], v[24:25], v[26:27]
	v_pk_add_f32 v[12:13], v[28:29], v[12:13]
	v_pk_add_f32 v[10:11], v[14:15], v[10:11]
	s_nop 0
	v_pk_add_f32 v[10:11], v[12:13], v[10:11]
	v_mov_b32_e32 v13, v11
	v_mov_b32_e32 v12, v10
	s_nop 1
	v_permlane32_swap_b32_e32 v11, v13
	v_permlane32_swap_b32_e32 v10, v12
	s_waitcnt lgkmcnt(0)
	v_pk_add_f32 v[10:11], v[10:11], v[12:13]
	v_mov_b32_e32 v13, v11
	v_mov_b32_e32 v12, v10
	s_nop 1
	v_permlane16_swap_b32_e32 v11, v13
	v_permlane16_swap_b32_e32 v10, v12
	s_waitcnt lgkmcnt(0)
	v_pk_add_f32 v[10:11], v[10:11], v[12:13]
	s_nop 1
	v_mov_b32_dpp v13, v11 row_ror:8 row_mask:0xf bank_mask:0xf
	v_mov_b32_dpp v12, v10 row_ror:8 row_mask:0xf bank_mask:0xf
	s_waitcnt lgkmcnt(0)
	v_pk_add_f32 v[10:11], v[10:11], v[12:13]
	s_nop 1
	v_mov_b32_dpp v13, v11 row_ror:4 row_mask:0xf bank_mask:0xf
	v_mov_b32_dpp v12, v10 row_ror:4 row_mask:0xf bank_mask:0xf
	s_waitcnt lgkmcnt(0)
	v_pk_add_f32 v[10:11], v[10:11], v[12:13]
	s_nop 1
	v_mov_b32_dpp v13, v11 quad_perm:[2,3,0,1] row_mask:0xf bank_mask:0xf
	v_mov_b32_dpp v12, v10 quad_perm:[2,3,0,1] row_mask:0xf bank_mask:0xf
	s_waitcnt lgkmcnt(0)
	v_pk_add_f32 v[10:11], v[10:11], v[12:13]
	ds_bpermute_b32 v13, v124, v11
	ds_bpermute_b32 v12, v124, v10
	s_and_saveexec_b64 s[44:45], s[38:39]
	s_cbranch_execz .LBB0_333
	s_waitcnt lgkmcnt(0)
	v_pk_add_f32 v[10:11], v[10:11], v[12:13]
	s_nop 0
	v_pk_mul_f32 v[10:11], v[10:11], s[36:37] op_sel_hi:[1,0]
	s_nop 0
	v_fma_f32 v10, -v11, v11, v10
	v_max_f32_e32 v10, 0, v10
	v_add_f32_e32 v10, 0x358637bd, v10
	v_mul_f32_e32 v12, 0x4b800000, v10
	v_cmp_gt_f32_e64 s[42:43], s33, v10
	s_nop 1
	v_cndmask_b32_e64 v10, v10, v12, s[42:43]
	v_rsq_f32_e32 v10, v10
	s_nop 0
	v_mul_f32_e32 v12, 0x45800000, v10
	v_cndmask_b32_e64 v10, v10, v12, s[42:43]
	v_cndmask_b32_e64 v13, 0, v10, s[40:41]
	v_cndmask_b32_e64 v12, 0, v11, s[40:41]
	ds_write_b64 v62, v[12:13] offset:48
; DI float bflo(unsigned u) { return __uint_as_float(u << 16); }
; DI float bfhi(unsigned u) { return __uint_as_float(u & 0xffff0000u); }
; DI float wave_sum(float v) {
; #pragma unroll
;   for (int o = 32; o; o >>= 1) v += __shfl_xor(v, o, 64);
;   return v;
; }
; DI void sgu_ln_items(const Params& p, int e, char* smem) {
;     ...
;       for (int k = 0; k < 8; ++k) {
;         const int i = wave * 32 + b8 + k;
;         float s = 0.f, s2 = 0.f;
; #pragma unroll
;         for (int j = 0; j < 2; ++j)
; #pragma unroll
;           for (int w4 = 0; w4 < 4; ++w4) {
;             const float lo = bflo(q[k][j][w4]), hi = bfhi(q[k][j][w4]);
;             s += lo + hi; s2 += lo * lo + hi * hi;
;           }
;         s = wave_sum(s); s2 = wave_sum(s2);
;         const float mu = s * (1.f / 1024.f);
;         const float var = fmaxf(s2 * (1.f / 1024.f) - mu * mu, 0.f);
;         const float rstd = rsqrtf(var + 1e-6f);
;         if (lane == 0) st[i] = i < nvalid ? make_float2(mu, rstd) : make_float2(0.f, 0.f);
;       }
.LBB0_333:
	s_or_b64 exec, exec, s[44:45]
	s_waitcnt vmcnt(1)
	v_and_b32_e32 v11, 0xffff0000, v6
	s_waitcnt lgkmcnt(1)
	v_and_b32_e32 v13, 0xffff0000, v7
	v_lshlrev_b32_e32 v7, 16, v7
	v_lshlrev_b32_e32 v6, 16, v6
	v_lshlrev_b32_e32 v15, 16, v8
	v_and_b32_e32 v17, 0xffff0000, v8
	v_mul_f32_e32 v18, v6, v6
	v_mov_b32_e32 v8, v7
	v_mov_b32_e32 v19, v7
	s_waitcnt lgkmcnt(0)
	v_mul_f32_e32 v12, v11, v11
	v_mul_f32_e32 v182, v13, v13
	v_pk_add_f32 v[12:13], v[18:19], v[12:13]
	v_pk_mul_f32 v[18:19], v[6:7], v[8:9] op_sel:[1,0] op_sel_hi:[0,1]
	v_pk_add_f32 v[6:7], v[6:7], v[10:11] op_sel:[1,0] op_sel_hi:[0,1]
	v_mov_b32_e32 v19, v7
	v_mul_f32_e32 v14, v15, v15
	v_mul_f32_e32 v16, v17, v17
	v_pk_add_f32 v[6:7], v[18:19], v[182:183]
	v_pk_add_f32 v[10:11], v[14:15], v[16:17]
	v_pk_add_f32 v[6:7], v[12:13], v[6:7]
	s_waitcnt vmcnt(0)
	v_and_b32_e32 v13, 0xffff0000, v2
	v_pk_add_f32 v[6:7], v[10:11], v[6:7]
	v_lshlrev_b32_e32 v11, 16, v9
	v_and_b32_e32 v9, 0xffff0000, v9
	v_mul_f32_e32 v10, v11, v11
	v_mul_f32_e32 v8, v9, v9
	v_pk_add_f32 v[8:9], v[10:11], v[8:9]
	v_lshlrev_b32_e32 v11, 16, v2
	v_mul_f32_e32 v10, v11, v11
	v_mul_f32_e32 v12, v13, v13
	v_lshlrev_b32_e32 v15, 16, v3
	v_and_b32_e32 v3, 0xffff0000, v3
	v_mul_f32_e32 v14, v15, v15
	v_mul_f32_e32 v2, v3, v3
	v_lshlrev_b32_e32 v17, 16, v4
	v_and_b32_e32 v19, 0xffff0000, v4
	v_pk_add_f32 v[6:7], v[8:9], v[6:7]
	v_pk_add_f32 v[8:9], v[10:11], v[12:13]
	v_mul_f32_e32 v16, v17, v17
	v_mul_f32_e32 v18, v19, v19
	v_lshlrev_b32_e32 v21, 16, v5
	v_and_b32_e32 v5, 0xffff0000, v5
	v_pk_add_f32 v[6:7], v[8:9], v[6:7]
	v_pk_add_f32 v[2:3], v[14:15], v[2:3]
	v_mul_f32_e32 v20, v21, v21
	v_mul_f32_e32 v4, v5, v5
	v_pk_add_f32 v[2:3], v[2:3], v[6:7]
	v_pk_add_f32 v[6:7], v[16:17], v[18:19]
	v_pk_add_f32 v[4:5], v[20:21], v[4:5]
	v_pk_add_f32 v[2:3], v[6:7], v[2:3]
	s_nop 0
	v_pk_add_f32 v[2:3], v[4:5], v[2:3]
	v_mov_b32_e32 v5, v3
	v_mov_b32_e32 v4, v2
	s_nop 1
	v_permlane32_swap_b32_e32 v3, v5
	v_permlane32_swap_b32_e32 v2, v4
	s_waitcnt lgkmcnt(0)
	v_pk_add_f32 v[2:3], v[2:3], v[4:5]
	v_mov_b32_e32 v5, v3
	v_mov_b32_e32 v4, v2
	s_nop 1
	v_permlane16_swap_b32_e32 v3, v5
	v_permlane16_swap_b32_e32 v2, v4
	s_waitcnt lgkmcnt(0)
	v_pk_add_f32 v[2:3], v[2:3], v[4:5]
	s_nop 1
	v_mov_b32_dpp v5, v3 row_ror:8 row_mask:0xf bank_mask:0xf
	v_mov_b32_dpp v4, v2 row_ror:8 row_mask:0xf bank_mask:0xf
	s_waitcnt lgkmcnt(0)
	v_pk_add_f32 v[2:3], v[2:3], v[4:5]
	s_nop 1
	v_mov_b32_dpp v5, v3 row_ror:4 row_mask:0xf bank_mask:0xf
	v_mov_b32_dpp v4, v2 row_ror:4 row_mask:0xf bank_mask:0xf
	s_waitcnt lgkmcnt(0)
	v_pk_add_f32 v[2:3], v[2:3], v[4:5]
	s_nop 1
	v_mov_b32_dpp v5, v3 quad_perm:[2,3,0,1] row_mask:0xf bank_mask:0xf
	v_mov_b32_dpp v4, v2 quad_perm:[2,3,0,1] row_mask:0xf bank_mask:0xf
	s_waitcnt lgkmcnt(0)
	v_pk_add_f32 v[2:3], v[2:3], v[4:5]
	ds_bpermute_b32 v5, v124, v3
	ds_bpermute_b32 v4, v124, v2
	s_and_saveexec_b64 s[42:43], s[38:39]
	s_cbranch_execz .LBB0_318
	s_waitcnt lgkmcnt(0)
	v_pk_add_f32 v[2:3], v[2:3], v[4:5]
	s_nop 0
	v_pk_mul_f32 v[2:3], v[2:3], s[36:37] op_sel_hi:[1,0]
	s_nop 0
	v_fma_f32 v2, -v3, v3, v2
	v_max_f32_e32 v2, 0, v2
	v_add_f32_e32 v2, 0x358637bd, v2
	v_mul_f32_e32 v4, 0x4b800000, v2
	v_cmp_gt_f32_e64 s[40:41], s33, v2
	s_nop 1
	v_cndmask_b32_e64 v2, v2, v4, s[40:41]
	v_rsq_f32_e32 v2, v2
	s_nop 0
	v_mul_f32_e32 v4, 0x45800000, v2
	v_cndmask_b32_e64 v2, v2, v4, s[40:41]
	v_cndmask_b32_e32 v5, 0, v2, vcc
	v_cndmask_b32_e32 v4, 0, v3, vcc
	ds_write_b64 v62, v[4:5] offset:56
	s_branch .LBB0_318

; DI int get_tid() { int t = threadIdx.x; asm volatile("" : "+v"(t)); return t; }
; DI int get_bid() { int b = blockIdx.x; asm volatile("" : "+s"(b)); return b; }
; DI float bflo(unsigned u) { return __uint_as_float(u << 16); }
; DI float bfhi(unsigned u) { return __uint_as_float(u & 0xffff0000u); }
; DI float wave_sum(float v) {
; #pragma unroll
;   for (int o = 32; o; o >>= 1) v += __shfl_xor(v, o, 64);
;   return v;
; }
; DI void resid_norm(const Params& p, int layer, const u16* __restrict__ y) {
;     ...
;   for (int r = get_bid() * 4 + (get_tid() >> 6); r < M_TOK; r += gridDim.x * 4) {
;     const float* x;
;     if (layer == 0) x = r < M_PROMPT ? p.x_prompt + (size_t)r * 1024 : p.x_sample + (size_t)(r - M_PROMPT) * 1024;
;     else x = p.out + (size_t)r * 1024;
;     float4 yv[4], xv[4]; float ss = 0.f;
; #pragma unroll
;     for (int i = 0; i < 4; ++i) {
;       { const uint2 yq = *(const uint2*)(y + (size_t)r * 1024 + lane * 4 + 256 * i); yv[i] = make_float4(bflo(yq.x), bfhi(yq.x), bflo(yq.y), bfhi(yq.y)); }
;       { const f32x4 t4 = __builtin_nontemporal_load((const f32x4*)(x + lane * 4 + 256 * i)); xv[i] = make_float4(t4[0], t4[1], t4[2], t4[3]); }
;       ss += yv[i].x * yv[i].x + yv[i].y * yv[i].y + yv[i].z * yv[i].z + yv[i].w * yv[i].w;
;     }
;     ss = wave_sum(ss);
;     const float rs = rsqrtf(ss * (1.f / 1024.f) + 1e-6f);
;     float ss2 = 0.f;
; #pragma unroll
;     for (int i = 0; i < 4; ++i) {
;       const float4 gg = *(const float4*)(gpost + lane * 4 + 256 * i);
;       xv[i].x += yv[i].x * rs * gg.x; xv[i].y += yv[i].y * rs * gg.y; xv[i].z += yv[i].z * rs * gg.z; xv[i].w += yv[i].w * rs * gg.w;
;       __builtin_nontemporal_store((f32x4){xv[i].x, xv[i].y, xv[i].z, xv[i].w}, (f32x4*)(p.out + (size_t)r * 1024 + lane * 4 + 256 * i));
;       ss2 += xv[i].x * xv[i].x + xv[i].y * xv[i].y + xv[i].z * xv[i].z + xv[i].w * xv[i].w;
.LBB0_880:
	v_ashrrev_i32_e32 v1, 31, v0
	v_lshlrev_b64 v[12:13], 11, v[0:1]
	s_waitcnt vmcnt(5)
	v_lshl_add_u64 v[20:21], v[2:3], 0, v[12:13]
	global_load_dwordx2 v[28:29], v[20:21], off
	global_load_dwordx2 v[30:31], v[20:21], off offset:512
	global_load_dwordx2 v[32:33], v[20:21], off offset:1024
	global_load_dwordx2 v[34:35], v[20:21], off offset:1536
	s_nop 0
	global_load_dwordx4 v[20:23], v[4:5], off
	s_waitcnt vmcnt(10)
	v_lshlrev_b64 v[24:25], 12, v[0:1]
	v_lshl_add_u64 v[40:41], v[10:11], 0, v[24:25]
	global_load_dwordx4 v[24:27], v[40:41], off nt
	v_lshl_add_u64 v[12:13], v[8:9], 0, v[12:13]
	v_add_u32_e32 v0, s3, v0
	s_waitcnt vmcnt(5)
	v_and_b32_e32 v37, 0xffff0000, v28
	s_waitcnt vmcnt(4)
	v_and_b32_e32 v43, 0xffff0000, v30
	v_lshlrev_b32_e32 v36, 16, v28
	v_lshlrev_b32_e32 v42, 16, v30
	v_lshlrev_b32_e32 v44, 16, v31
	v_and_b32_e32 v45, 0xffff0000, v31
	s_waitcnt vmcnt(3)
	v_and_b32_e32 v47, 0xffff0000, v32
	s_waitcnt vmcnt(2)
	v_and_b32_e32 v51, 0xffff0000, v34
	v_mov_b32_e32 v30, v37
	v_mov_b32_e32 v31, v43
	v_lshlrev_b32_e32 v38, 16, v29
	v_and_b32_e32 v39, 0xffff0000, v29
	v_lshlrev_b32_e32 v46, 16, v32
	v_lshlrev_b32_e32 v50, 16, v34
	v_mov_b32_e32 v28, v36
	v_mov_b32_e32 v29, v42
	v_mov_b32_e32 v56, v47
	v_mov_b32_e32 v57, v51
	v_pk_mul_f32 v[30:31], v[30:31], v[30:31]
	v_lshlrev_b32_e32 v48, 16, v33
	v_and_b32_e32 v49, 0xffff0000, v33
	v_lshlrev_b32_e32 v52, 16, v35
	v_mov_b32_e32 v32, v38
	v_mov_b32_e32 v33, v44
	v_mov_b32_e32 v54, v46
	v_mov_b32_e32 v55, v50
	v_pk_mul_f32 v[56:57], v[56:57], v[56:57]
	v_pk_fma_f32 v[28:29], v[28:29], v[28:29], v[30:31]
	v_and_b32_e32 v53, 0xffff0000, v35
	v_mov_b32_e32 v34, v39
	v_mov_b32_e32 v35, v45
	v_mov_b32_e32 v58, v48
	v_mov_b32_e32 v59, v52
	v_pk_fma_f32 v[30:31], v[54:55], v[54:55], v[56:57]
	v_pk_fma_f32 v[28:29], v[32:33], v[32:33], v[28:29]
	v_mov_b32_e32 v60, v49
	v_mov_b32_e32 v61, v53
	v_pk_fma_f32 v[30:31], v[58:59], v[58:59], v[30:31]
	v_pk_fma_f32 v[28:29], v[34:35], v[34:35], v[28:29]
	v_pk_fma_f32 v[30:31], v[60:61], v[60:61], v[30:31]
	v_add_f32_e32 v1, v28, v29
	v_add_f32_e32 v1, v1, v30
	v_add_f32_e32 v1, v1, v31
	v_mov_b32_e32 v28, v1
	s_nop 1
	v_permlane32_swap_b32_e32 v1, v28
	s_waitcnt lgkmcnt(0)
	v_add_f32_e32 v1, v1, v28
	v_mov_b32_e32 v28, v1
	s_nop 1
	v_permlane16_swap_b32_e32 v1, v28
	s_waitcnt lgkmcnt(0)
	v_add_f32_e32 v1, v1, v28
	s_nop 1
	v_mov_b32_dpp v28, v1 row_ror:8 row_mask:0xf bank_mask:0xf
	s_waitcnt lgkmcnt(0)
	v_add_f32_e32 v1, v1, v28
	s_nop 1
	v_mov_b32_dpp v28, v1 row_ror:4 row_mask:0xf bank_mask:0xf
	s_waitcnt lgkmcnt(0)
	v_add_f32_e32 v1, v1, v28
	s_nop 1
	v_mov_b32_dpp v28, v1 quad_perm:[2,3,0,1] row_mask:0xf bank_mask:0xf
	s_waitcnt lgkmcnt(0)
	v_add_f32_e32 v1, v1, v28
	s_nop 1
	v_mov_b32_dpp v28, v1 quad_perm:[1,0,3,2] row_mask:0xf bank_mask:0xf
	s_waitcnt lgkmcnt(0)
	v_add_f32_e32 v1, v1, v28
	v_fmamk_f32 v1, v1, 0x3a800000, v184
	v_mul_f32_e32 v28, 0x4b800000, v1
	v_cmp_gt_f32_e32 vcc, s33, v1
	s_nop 1
	v_cndmask_b32_e32 v1, v1, v28, vcc
	v_rsq_f32_e32 v1, v1
	global_load_dwordx4 v[28:31], v[40:41], off offset:1024 nt
	v_mul_f32_e32 v32, 0x45800000, v1
	v_cndmask_b32_e32 v54, v1, v32, vcc
	v_pk_mul_f32 v[32:33], v[54:55], v[36:37] op_sel_hi:[0,1]
	v_pk_mul_f32 v[34:35], v[54:55], v[38:39] op_sel_hi:[0,1]
	s_waitcnt vmcnt(1)
	v_pk_fma_f32 v[20:21], v[20:21], v[32:33], v[24:25]
	v_pk_fma_f32 v[22:23], v[22:23], v[34:35], v[26:27]
	global_store_dwordx4 v[40:41], v[20:23], off nt
	global_load_dwordx4 v[24:27], v[4:5], off offset:1024
	v_pk_mul_f32 v[32:33], v[54:55], v[42:43] op_sel_hi:[0,1]
	v_pk_mul_f32 v[34:35], v[54:55], v[44:45] op_sel_hi:[0,1]
	v_pk_mul_f32 v[42:43], v[54:55], v[46:47] op_sel_hi:[0,1]
	v_pk_mul_f32 v[44:45], v[54:55], v[48:49] op_sel_hi:[0,1]
	v_mov_b32_e32 v46, v23
	s_waitcnt vmcnt(0)
	v_pk_fma_f32 v[24:25], v[24:25], v[32:33], v[28:29]
	v_pk_fma_f32 v[26:27], v[26:27], v[34:35], v[30:31]
	global_store_dwordx4 v[40:41], v[24:27], off offset:1024 nt
	global_load_dwordx4 v[28:31], v[4:5], off offset:2048
	global_load_dwordx4 v[32:35], v[40:41], off offset:2048 nt
	global_load_dwordx4 v[36:39], v[40:41], off offset:3072 nt
	v_mov_b32_e32 v47, v27
	s_waitcnt vmcnt(1)
; DI void st_bf4(u16* p, float a, float b, float c, float d) { *(uint2*)p = make_uint2(pk2(a, b), pk2(c, d)); }
; DI float wave_sum(float v) {
; #pragma unroll
;   for (int o = 32; o; o >>= 1) v += __shfl_xor(v, o, 64);
;   return v;
; }
; DI void resid_norm(const Params& p, int layer, const u16* __restrict__ y) {
;     ...
;       ss2 += xv[i].x * xv[i].x + xv[i].y * xv[i].y + xv[i].z * xv[i].z + xv[i].w * xv[i].w;
;     }
;     if (layer < 3) {
;       ss2 = wave_sum(ss2);
;       const float rs2 = rsqrtf(ss2 * (1.f / 1024.f) + 1e-6f);
; #pragma unroll
;       for (int i = 0; i < 4; ++i) {
;         const float4 gg = *(const float4*)(gpre + lane * 4 + 256 * i);
;         st_bf4(h + (size_t)r * 1024 + lane * 4 + 256 * i, xv[i].x * rs2 * gg.x, xv[i].y * rs2 * gg.y, xv[i].z * rs2 * gg.z, xv[i].w * rs2 * gg.w);
;       }
;     }
	v_pk_fma_f32 v[28:29], v[28:29], v[42:43], v[32:33]
	v_pk_fma_f32 v[30:31], v[44:45], v[30:31], v[34:35]
	global_store_dwordx4 v[40:41], v[28:31], off offset:2048 nt
	global_load_dwordx4 v[32:35], v[4:5], off offset:3072
	v_pk_mul_f32 v[42:43], v[54:55], v[50:51] op_sel_hi:[0,1]
	v_pk_mul_f32 v[44:45], v[54:55], v[52:53] op_sel_hi:[0,1]
	s_waitcnt vmcnt(0)
	v_pk_fma_f32 v[32:33], v[42:43], v[32:33], v[36:37]
	v_pk_fma_f32 v[34:35], v[44:45], v[34:35], v[38:39]
	global_store_dwordx4 v[40:41], v[32:35], off offset:3072 nt
	global_load_dwordx4 v[36:39], v[6:7], off
	v_mov_b32_e32 v42, v21
	v_mov_b32_e32 v43, v25
	v_mov_b32_e32 v40, v20
	v_mov_b32_e32 v41, v24
	v_pk_mul_f32 v[42:43], v[42:43], v[42:43]
	v_mov_b32_e32 v44, v22
	v_mov_b32_e32 v45, v26
	v_pk_fma_f32 v[40:41], v[40:41], v[40:41], v[42:43]
	v_mov_b32_e32 v42, v29
	v_pk_fma_f32 v[40:41], v[44:45], v[44:45], v[40:41]
	v_mov_b32_e32 v43, v33
	v_pk_fma_f32 v[40:41], v[46:47], v[46:47], v[40:41]
	v_pk_mul_f32 v[42:43], v[42:43], v[42:43]
	v_add_f32_e32 v1, v40, v41
	v_mov_b32_e32 v40, v28
	v_mov_b32_e32 v41, v32
	v_mov_b32_e32 v44, v30
	v_mov_b32_e32 v45, v34
	v_pk_fma_f32 v[40:41], v[40:41], v[40:41], v[42:43]
	v_mov_b32_e32 v46, v31
	v_mov_b32_e32 v47, v35
	v_pk_fma_f32 v[40:41], v[44:45], v[44:45], v[40:41]
	s_nop 0
	v_pk_fma_f32 v[40:41], v[46:47], v[46:47], v[40:41]
	s_nop 0
	v_add_f32_e32 v1, v40, v1
	v_add_f32_e32 v1, v1, v41
	v_mov_b32_e32 v40, v1
	s_nop 1
	v_permlane32_swap_b32_e32 v1, v40
	s_waitcnt lgkmcnt(0)
	v_add_f32_e32 v1, v1, v40
	v_mov_b32_e32 v40, v1
	s_nop 1
	v_permlane16_swap_b32_e32 v1, v40
	s_waitcnt lgkmcnt(0)
	v_add_f32_e32 v1, v1, v40
	s_nop 1
	v_mov_b32_dpp v40, v1 row_ror:8 row_mask:0xf bank_mask:0xf
	s_waitcnt lgkmcnt(0)
	v_add_f32_e32 v1, v1, v40
	s_nop 1
	v_mov_b32_dpp v40, v1 row_ror:4 row_mask:0xf bank_mask:0xf
	s_waitcnt lgkmcnt(0)
	v_add_f32_e32 v1, v1, v40
	s_nop 1
	v_mov_b32_dpp v40, v1 quad_perm:[2,3,0,1] row_mask:0xf bank_mask:0xf
	s_waitcnt lgkmcnt(0)
	v_add_f32_e32 v1, v1, v40
	s_nop 1
	v_mov_b32_dpp v40, v1 quad_perm:[1,0,3,2] row_mask:0xf bank_mask:0xf
	s_waitcnt lgkmcnt(0)
	v_add_f32_e32 v1, v1, v40
	v_fmamk_f32 v1, v1, 0x3a800000, v184
	v_mul_f32_e32 v40, 0x4b800000, v1
	v_cmp_gt_f32_e32 vcc, s33, v1
	s_nop 1
	v_cndmask_b32_e32 v1, v1, v40, vcc
	v_rsq_f32_e32 v1, v1
	s_nop 0
	v_mul_f32_e32 v40, 0x45800000, v1
	v_cndmask_b32_e32 v40, v1, v40, vcc
	v_pk_mul_f32 v[20:21], v[20:21], v[40:41] op_sel_hi:[1,0]
	v_pk_mul_f32 v[22:23], v[22:23], v[40:41] op_sel_hi:[1,0]
	v_pk_mul_f32 v[24:25], v[24:25], v[40:41] op_sel_hi:[1,0]
	v_pk_mul_f32 v[26:27], v[26:27], v[40:41] op_sel_hi:[1,0]
	s_waitcnt vmcnt(0)
	v_pk_mul_f32 v[20:21], v[36:37], v[20:21]
	v_pk_mul_f32 v[22:23], v[38:39], v[22:23]
	v_cvt_pk_bf16_f32 v20, v20, v21
	v_cvt_pk_bf16_f32 v21, v22, v23
	global_store_dwordx2 v[12:13], v[20:21], off
	global_load_dwordx4 v[20:23], v[6:7], off offset:1024
	v_cmp_lt_i32_e32 vcc, s64, v0
	s_or_b64 s[40:41], vcc, s[40:41]
	s_waitcnt vmcnt(0)
	v_pk_mul_f32 v[20:21], v[20:21], v[24:25]
	v_pk_mul_f32 v[22:23], v[22:23], v[26:27]
	v_cvt_pk_bf16_f32 v20, v20, v21
	v_cvt_pk_bf16_f32 v21, v22, v23
	global_store_dwordx2 v[12:13], v[20:21], off offset:512
	global_load_dwordx4 v[20:23], v[6:7], off offset:2048
	v_pk_mul_f32 v[24:25], v[28:29], v[40:41] op_sel_hi:[1,0]
	v_pk_mul_f32 v[26:27], v[30:31], v[40:41] op_sel_hi:[1,0]
	s_waitcnt vmcnt(0)
	v_pk_mul_f32 v[20:21], v[24:25], v[20:21]
	v_pk_mul_f32 v[22:23], v[26:27], v[22:23]
	v_cvt_pk_bf16_f32 v20, v20, v21
	v_cvt_pk_bf16_f32 v21, v22, v23
	global_store_dwordx2 v[12:13], v[20:21], off offset:1024
	global_load_dwordx4 v[20:23], v[6:7], off offset:3072
	v_pk_mul_f32 v[24:25], v[32:33], v[40:41] op_sel_hi:[1,0]
	v_pk_mul_f32 v[26:27], v[34:35], v[40:41] op_sel_hi:[1,0]
	s_waitcnt vmcnt(0)
	v_pk_mul_f32 v[20:21], v[24:25], v[20:21]
	v_pk_mul_f32 v[22:23], v[26:27], v[22:23]
	v_cvt_pk_bf16_f32 v20, v20, v21
	v_cvt_pk_bf16_f32 v21, v22, v23
	global_store_dwordx2 v[12:13], v[20:21], off offset:1536
	s_andn2_b64 exec, exec, s[40:41]
	s_cbranch_execnz .LBB0_880

; DI int get_bid() { int b = blockIdx.x; asm volatile("" : "+s"(b)); return b; }
; DI unsigned pk2(float a, float b) { f32x2_t f = {a, b}; return __builtin_bit_cast(unsigned, __builtin_convertvector(f, bf16x2_t)); }
; DI float wave_sum(float v) {
; #pragma unroll
;   for (int o = 32; o; o >>= 1) v += __shfl_xor(v, o, 64);
;   return v;
; }
; DI void odd_rows(const Params& p, int o) {
;     ...
;   for (int r = get_bid() * 4 + (tid >> 6); r < M_TOK; r += gridDim.x * 4) {
;     const float* z = zq + (size_t)r * 704;
;     float2 qv[3]; float ss = 0.f;
; #pragma unroll
;     for (int i = 0; i < 3; ++i) { qv[i] = *(const float2*)(z + lane * 2 + 128 * i); ss += qv[i].x * qv[i].x + qv[i].y * qv[i].y; }
;     const float4 kv = *(const float4*)(z + 384 + lane * 4);
;     float sk = kv.x * kv.x + kv.y * kv.y + kv.z * kv.z + kv.w * kv.w;
;     const float kr = z[640 + lane];
;     ss = wave_sum(ss); sk = wave_sum(sk);
;     const float rq = rsqrtf(ss * (1.f / 384.f) + 1e-6f);
;     const float rk = rsqrtf(sk * (1.f / 256.f) + 1e-6f);
; #pragma unroll
;     for (int i = 0; i < 3; ++i) {
;       const float2 w = *(const float2*)(qnw + lane * 2 + 128 * i);
;       *(unsigned*)(qn + (size_t)r * 384 + lane * 2 + 128 * i) = pk2(qv[i].x * rq * w.x, qv[i].y * rq * w.y);
;     }
.LBB0_1001:
	v_mov_b64_e32 v[0:1], s[84:85]
	s_movk_i32 s4, 0xb00
	v_mad_i64_i32 v[20:21], s[4:5], v4, s4, v[0:1]
	v_lshlrev_b32_e32 v22, 2, v6
	v_mov_b32_e32 v23, v183
	v_lshl_add_u64 v[0:1], v[20:21], 0, v[22:23]
	v_lshl_add_u64 v[24:25], v[20:21], 0, v[182:183]
	global_load_dwordx4 v[0:3], v[0:1], off offset:1536
	s_nop 0
	global_load_dwordx2 v[26:27], v[24:25], off offset:512
	global_load_dwordx2 v[28:29], v[24:25], off
	global_load_dwordx2 v[30:31], v[24:25], off offset:1024
	global_load_dwordx2 v[40:41], v[8:9], off
	v_mov_b32_e32 v19, v183
	v_lshl_add_u64 v[20:21], v[20:21], 0, v[18:19]
	global_load_dword v19, v[20:21], off offset:2560
	s_mov_b32 s4, 0x3b800000
	s_mov_b32 s5, 0x3b2aaaab
	s_waitcnt vmcnt(4)
	v_pk_mul_f32 v[42:43], v[26:27], v[26:27]
	s_waitcnt vmcnt(3)
	v_mov_b32_e32 v46, v29
	s_waitcnt vmcnt(2)
	v_mov_b32_e32 v47, v31
	v_pk_mul_f32 v[20:21], v[0:1], v[0:1]
	v_mov_b32_e32 v44, v28
	v_mov_b32_e32 v45, v30
	v_pk_mul_f32 v[46:47], v[46:47], v[46:47]
	v_pk_mul_f32 v[24:25], v[2:3], v[2:3]
	v_mov_b32_e32 v48, v20
	v_mov_b32_e32 v49, v42
	v_mov_b32_e32 v42, v21
	v_pk_fma_f32 v[44:45], v[44:45], v[44:45], v[46:47]
	v_mov_b32_e32 v20, v24
	v_pk_add_f32 v[42:43], v[48:49], v[42:43]
	v_mov_b32_e32 v21, v44
	v_mov_b32_e32 v44, v25
	v_pk_add_f32 v[20:21], v[42:43], v[20:21]
	s_nop 0
	v_pk_add_f32 v[20:21], v[20:21], v[44:45]
	v_mov_b32_e32 v24, v20
	v_mov_b32_e32 v25, v21
	s_nop 1
	v_permlane32_swap_b32_e32 v20, v24
	v_permlane32_swap_b32_e32 v21, v25
	s_waitcnt lgkmcnt(0)
	v_pk_add_f32 v[20:21], v[20:21], v[24:25]
	v_mov_b32_e32 v24, v20
	v_mov_b32_e32 v25, v21
	s_nop 1
	v_permlane16_swap_b32_e32 v20, v24
	v_permlane16_swap_b32_e32 v21, v25
	s_waitcnt lgkmcnt(0)
	v_pk_add_f32 v[20:21], v[20:21], v[24:25]
	s_nop 1
	v_mov_b32_dpp v24, v20 row_ror:8 row_mask:0xf bank_mask:0xf
	v_mov_b32_dpp v25, v21 row_ror:8 row_mask:0xf bank_mask:0xf
	s_waitcnt lgkmcnt(0)
	v_pk_add_f32 v[20:21], v[20:21], v[24:25]
	s_nop 1
	v_mov_b32_dpp v24, v20 row_ror:4 row_mask:0xf bank_mask:0xf
	v_mov_b32_dpp v25, v21 row_ror:4 row_mask:0xf bank_mask:0xf
	s_waitcnt lgkmcnt(0)
	v_pk_add_f32 v[20:21], v[20:21], v[24:25]
	s_nop 1
	v_mov_b32_dpp v24, v20 quad_perm:[2,3,0,1] row_mask:0xf bank_mask:0xf
	v_mov_b32_dpp v25, v21 quad_perm:[2,3,0,1] row_mask:0xf bank_mask:0xf
	s_waitcnt lgkmcnt(0)
	v_pk_add_f32 v[20:21], v[20:21], v[24:25]
	s_nop 1
	v_mov_b32_dpp v24, v20 quad_perm:[1,0,3,2] row_mask:0xf bank_mask:0xf
	v_mov_b32_dpp v25, v21 quad_perm:[1,0,3,2] row_mask:0xf bank_mask:0xf
	s_waitcnt lgkmcnt(0)
	v_pk_add_f32 v[20:21], v[20:21], v[24:25]
	s_nop 0
	v_pk_fma_f32 v[24:25], v[20:21], s[4:5], v[184:185] op_sel_hi:[1,1,0]
	s_movk_i32 s4, 0x300
	v_mul_f32_e32 v5, 0x4b800000, v25
	v_cmp_gt_f32_e64 s[38:39], s33, v25
	v_mad_i64_i32 v[20:21], s[4:5], v4, s4, v[10:11]
	s_nop 0
	v_cndmask_b32_e64 v5, v25, v5, s[38:39]
	v_rsq_f32_e32 v5, v5
	s_movk_i32 s4, 0x3fff
	v_cmp_lt_i32_e64 s[40:41], s4, v4
	v_mul_f32_e32 v23, 0x45800000, v5
	v_cndmask_b32_e64 v42, v5, v23, s[38:39]
	v_pk_mul_f32 v[28:29], v[28:29], v[42:43] op_sel_hi:[1,0]
	v_pk_mul_f32 v[26:27], v[26:27], v[42:43] op_sel_hi:[1,0]
	s_waitcnt vmcnt(1)
	v_pk_mul_f32 v[28:29], v[40:41], v[28:29]
	v_cmp_gt_f32_e64 s[38:39], s33, v24
	v_cvt_pk_bf16_f32 v5, v28, v29
	global_store_dword v[20:21], v5, off
	global_load_dwordx2 v[28:29], v[8:9], off offset:512
	s_waitcnt vmcnt(0)
	v_pk_mul_f32 v[26:27], v[28:29], v[26:27]
	s_nop 0
	v_cvt_pk_bf16_f32 v5, v26, v27
	global_store_dword v[20:21], v5, off offset:256
	global_load_dwordx2 v[26:27], v[8:9], off offset:1024
	v_pk_mul_f32 v[28:29], v[30:31], v[42:43] op_sel_hi:[1,0]
	v_ashrrev_i32_e32 v5, 31, v4
	s_waitcnt vmcnt(0)
	v_pk_mul_f32 v[26:27], v[28:29], v[26:27]
	s_nop 0
	v_cvt_pk_bf16_f32 v23, v26, v27
	global_store_dword v[20:21], v23, off offset:512
	s_and_saveexec_b64 s[4:5], s[40:41]
	s_xor_b64 s[40:41], exec, s[4:5]
	s_cbranch_execz .LBB0_1003
	v_add_u32_e32 v26, 0xffffc000, v4
	v_lshrrev_b32_e32 v5, 5, v26
	s_movk_i32 s4, 0x480
	v_and_b32_e32 v23, 31, v4
	v_mul_lo_u32 v5, v5, s4
	v_or_b32_e32 v5, v5, v23
	v_add_u32_e32 v20, 0x4400, v5
	v_mov_b32_e32 v21, v183
	v_or_b32_e32 v25, 0x400, v23
	v_mov_b32_e32 v27, v183

; template <int N> DI void wait_vm() { asm volatile("s_waitcnt vmcnt(%0)" ::"n"(N) : "memory"); }
; template <int BM, class Epi>
; DI void gemm_dma(const u16* __restrict__ X, long ldx, const u16* __restrict__ W, long ldw, int K, char* smem,
;                  int m0, int n0, const Epi& epi) {
;     ...
;   do {
;     if (kt + D - 2 < nk) wait_vm<PW * (D - 2)>(); else wait_vm<0>();
;     __syncthreads();
;     if (kt + D - 1 < nk) GD_ISSUE(nxt)
;     nxt = (nxt + 1 == D) ? 0 : nxt + 1;
;     const char* base = smem + cur * STG;
;     cur = (cur + 1 == D) ? 0 : cur + 1;
;     bf16x8 xf[MT];
; #pragma unroll
;     for (int i = 0; i < MT; ++i) xf[i] = *(const bf16x8*)(base + (xrow0 + i * 16) * 64 + rd);
; #pragma unroll
;     for (int nh = 0; nh < NT / 4; ++nh) {
;       bf16x8 wf[4];
; #pragma unroll
;       for (int i = 0; i < 4; ++i) wf[i] = *(const bf16x8*)(base + BM * 64 + (wrow0 + (nh * 4 + i) * 16) * 64 + rd);
; #pragma unroll
;       for (int i = 0; i < 4; ++i)
; #pragma unroll
;         for (int mt = 0; mt < MT; ++mt)
;           acc[nh * 4 + i][mt] = __builtin_amdgcn_mfma_f32_16x16x32_bf16(wf[i], xf[mt], acc[nh * 4 + i][mt], 0, 0, 0);
;     }
;   } while (++kt < nk);
.LBB0_1139:
	s_mul_i32 s12, s10, 0x6000
	v_lshl_add_u64 v[196:197], v[130:131], 0, s[42:43]
	s_waitcnt vmcnt(6)
	s_barrier
	s_mul_i32 s98, s11, 0x6000
	v_or_b32_e32 v137, s98, v134
	v_add_u32_e32 v150, v137, v136
	ds_read_b128 v[138:141], v150
	ds_read_b128 v[142:145], v150 offset:1024
	ds_read_b128 v[146:149], v150 offset:2048
	ds_read_b128 v[150:153], v150 offset:3072
	ds_read_b128 v[154:157], v137 offset:16384
	ds_read_b128 v[158:161], v137 offset:17408
	ds_read_b128 v[162:165], v137 offset:18432
	ds_read_b128 v[166:169], v137 offset:19456
	ds_read_b128 v[226:229], v137 offset:20480
	ds_read_b128 v[230:233], v137 offset:21504
	ds_read_b128 v[234:237], v137 offset:22528
	ds_read_b128 v[238:241], v137 offset:23552
	s_add_i32 s13, s12, s8
	s_mov_b32 s14, m0
	s_mov_b32 m0, s13
	s_nop 0
	global_load_lds_dwordx4 v[196:197], off
	s_mov_b32 m0, s14
	v_lshl_add_u64 v[224:225], v[196:197], 0, s[58:59]
	s_add_i32 s14, s13, 0x400
	s_mov_b32 s15, m0
	s_mov_b32 m0, s14
	s_nop 0
	global_load_lds_dwordx4 v[224:225], off
	s_mov_b32 m0, s15
	v_lshl_add_u64 v[224:225], v[196:197], 0, s[16:17]
	s_add_i32 s14, s13, 0x800
	s_mov_b32 s15, m0
	s_mov_b32 m0, s14
	s_nop 0
	global_load_lds_dwordx4 v[224:225], off
	s_mov_b32 m0, s15
	v_lshl_add_u64 v[196:197], v[196:197], 0, s[18:19]
	s_addk_i32 s13, 0xc00
	s_mov_b32 s14, m0
	s_mov_b32 m0, s13
	s_nop 0
	global_load_lds_dwordx4 v[196:197], off
	s_mov_b32 m0, s14
	s_add_i32 s12, s12, s9
	v_lshl_add_u64 v[194:195], v[128:129], 0, s[42:43]
	s_mov_b32 s13, m0
	s_mov_b32 m0, s12
	s_nop 0
	global_load_lds_dwordx4 v[194:195], off
	s_mov_b32 m0, s13
	s_addk_i32 s12, 0x400
	v_lshl_add_u64 v[194:195], v[194:195], 0, s[58:59]
	s_mov_b32 s13, m0
	s_mov_b32 m0, s12
	s_nop 0
	global_load_lds_dwordx4 v[194:195], off
	s_mov_b32 m0, s13
	s_waitcnt lgkmcnt(7)
	v_mfma_f32_16x16x32_bf16 v[124:127], v[154:157], v[138:141], v[124:127]
	s_add_i32 s10, s10, 1
	s_add_i32 s11, s11, 1
	s_cmp_lg_u32 s10, 3
	v_mfma_f32_16x16x32_bf16 v[120:123], v[154:157], v[142:145], v[120:123]
	s_cselect_b32 s10, s10, 0
	s_cmp_lg_u32 s11, 3
	s_cselect_b32 s11, s11, 0
	v_mfma_f32_16x16x32_bf16 v[116:119], v[154:157], v[146:149], v[116:119]
	s_add_u32 s42, s42, 64
	s_addc_u32 s43, s43, 0
	s_cmpk_lg_i32 s42, 0xf80
	v_mfma_f32_16x16x32_bf16 v[112:115], v[154:157], v[150:153], v[112:115]
	s_waitcnt lgkmcnt(6)
	v_mfma_f32_16x16x32_bf16 v[108:111], v[158:161], v[138:141], v[108:111]
	v_mfma_f32_16x16x32_bf16 v[104:107], v[158:161], v[142:145], v[104:107]
	v_mfma_f32_16x16x32_bf16 v[100:103], v[158:161], v[146:149], v[100:103]
	v_mfma_f32_16x16x32_bf16 v[96:99], v[158:161], v[150:153], v[96:99]
	s_waitcnt lgkmcnt(5)
	v_mfma_f32_16x16x32_bf16 v[92:95], v[162:165], v[138:141], v[92:95]
	v_mfma_f32_16x16x32_bf16 v[88:91], v[162:165], v[142:145], v[88:91]
	v_mfma_f32_16x16x32_bf16 v[84:87], v[162:165], v[146:149], v[84:87]
	v_mfma_f32_16x16x32_bf16 v[80:83], v[162:165], v[150:153], v[80:83]
	s_waitcnt lgkmcnt(4)
	v_mfma_f32_16x16x32_bf16 v[76:79], v[166:169], v[138:141], v[76:79]
	v_mfma_f32_16x16x32_bf16 v[72:75], v[166:169], v[142:145], v[72:75]
	v_mfma_f32_16x16x32_bf16 v[68:71], v[166:169], v[146:149], v[68:71]
	v_mfma_f32_16x16x32_bf16 v[64:67], v[166:169], v[150:153], v[64:67]
	s_waitcnt lgkmcnt(3)
	v_mfma_f32_16x16x32_bf16 v[60:63], v[226:229], v[138:141], v[60:63]
	v_mfma_f32_16x16x32_bf16 v[56:59], v[226:229], v[142:145], v[56:59]
	v_mfma_f32_16x16x32_bf16 v[52:55], v[226:229], v[146:149], v[52:55]
	v_mfma_f32_16x16x32_bf16 v[48:51], v[226:229], v[150:153], v[48:51]
	s_waitcnt lgkmcnt(2)
	v_mfma_f32_16x16x32_bf16 v[44:47], v[230:233], v[138:141], v[44:47]
	v_mfma_f32_16x16x32_bf16 v[40:43], v[230:233], v[142:145], v[40:43]
	v_mfma_f32_16x16x32_bf16 v[36:39], v[230:233], v[146:149], v[36:39]
	v_mfma_f32_16x16x32_bf16 v[32:35], v[230:233], v[150:153], v[32:35]
	s_waitcnt lgkmcnt(1)
	v_mfma_f32_16x16x32_bf16 v[28:31], v[234:237], v[138:141], v[28:31]
	v_mfma_f32_16x16x32_bf16 v[24:27], v[234:237], v[142:145], v[24:27]
	v_mfma_f32_16x16x32_bf16 v[20:23], v[234:237], v[146:149], v[20:23]
	v_mfma_f32_16x16x32_bf16 v[16:19], v[234:237], v[150:153], v[16:19]
	s_waitcnt lgkmcnt(0)
	v_mfma_f32_16x16x32_bf16 v[12:15], v[238:241], v[138:141], v[12:15]
	v_mfma_f32_16x16x32_bf16 v[8:11], v[238:241], v[142:145], v[8:11]
	v_mfma_f32_16x16x32_bf16 v[4:7], v[238:241], v[146:149], v[4:7]
	v_mfma_f32_16x16x32_bf16 v[0:3], v[238:241], v[150:153], v[0:3]
	s_cbranch_scc1 .LBB0_1139
	v_add_u32_e32 v180, v134, v136
	v_or_b32_e32 v148, 0x10000, v134
	v_or_b32_e32 v152, 0x10400, v134
	v_or_b32_e32 v156, 0x10800, v134
	v_or_b32_e32 v160, 0x10c00, v134
	s_waitcnt vmcnt(6)
	s_barrier
; DI void st_bf4(u16* p, float a, float b, float c, float d) { *(uint2*)p = make_uint2(pk2(a, b), pk2(c, d)); }
; template <int BM, class Epi>
; DI void gemm_dma(const u16* __restrict__ X, long ldx, const u16* __restrict__ W, long ldw, int K, char* smem,
;                  int m0, int n0, const Epi& epi) {
;     ...
;     for (int i = 0; i < MT; ++i) xf[i] = *(const bf16x8*)(base + (xrow0 + i * 16) * 64 + rd);
; #pragma unroll
;     for (int nh = 0; nh < NT / 4; ++nh) {
;       bf16x8 wf[4];
; #pragma unroll
;       for (int i = 0; i < 4; ++i) wf[i] = *(const bf16x8*)(base + BM * 64 + (wrow0 + (nh * 4 + i) * 16) * 64 + rd);
; #pragma unroll
;       for (int i = 0; i < 4; ++i)
; #pragma unroll
;         for (int mt = 0; mt < MT; ++mt)
;           acc[nh * 4 + i][mt] = __builtin_amdgcn_mfma_f32_16x16x32_bf16(wf[i], xf[mt], acc[nh * 4 + i][mt], 0, 0, 0);
;     }
;   } while (++kt < nk);
;     ...
;   epi.run(acc, m0 + xrow0 + lr, n0 + wrow0 + 4 * g);
;   template <int NT, int MT> DI void run(f32x4 (&acc)[NT][MT], int mb, int nb) const {
; #pragma unroll
;     for (int nt = 0; nt < NT; ++nt)
; #pragma unroll
;       for (int mt = 0; mt < MT; ++mt) {
;         f32x4 v = acc[nt][mt];
;         st_bf4(C + (size_t)(mb + mt * 16) * ldc + nb + nt * 16, v[0], v[1], v[2], v[3]);
;       }
;   }
	ds_read_b128 v[128:131], v180 offset:49152
	ds_read_b128 v[136:139], v180 offset:50176
	ds_read_b128 v[140:143], v180 offset:51200
	ds_read_b128 v[144:147], v180 offset:52224
	ds_read_b128 v[148:151], v148
	ds_read_b128 v[152:155], v152
	ds_read_b128 v[156:159], v156
	ds_read_b128 v[160:163], v160
	s_waitcnt lgkmcnt(3)
	v_mfma_f32_16x16x32_bf16 v[124:127], v[148:151], v[128:131], v[124:127]
	v_readlane_b32 s8, v252, 33
	v_readlane_b32 s9, v252, 34
	s_lshl_b32 s7, s7, 8
	v_mfma_f32_16x16x32_bf16 v[120:123], v[148:151], v[136:139], v[120:123]
	v_lshl_or_b32 v182, v132, 3, s7
	v_mfma_f32_16x16x32_bf16 v[116:119], v[148:151], v[140:143], v[116:119]
	v_mfma_f32_16x16x32_bf16 v[112:115], v[148:151], v[144:147], v[112:115]
	s_waitcnt lgkmcnt(2)
	v_mfma_f32_16x16x32_bf16 v[108:111], v[152:155], v[128:131], v[108:111]
	v_mfma_f32_16x16x32_bf16 v[104:107], v[152:155], v[136:139], v[104:107]
	v_mfma_f32_16x16x32_bf16 v[100:103], v[152:155], v[140:143], v[100:103]
	v_mfma_f32_16x16x32_bf16 v[96:99], v[152:155], v[144:147], v[96:99]
	s_waitcnt lgkmcnt(1)
	v_mfma_f32_16x16x32_bf16 v[92:95], v[156:159], v[128:131], v[92:95]
	v_mfma_f32_16x16x32_bf16 v[148:151], v[156:159], v[136:139], v[88:91]
	v_mfma_f32_16x16x32_bf16 v[84:87], v[156:159], v[140:143], v[84:87]
	s_nop 1
	v_or_b32_e32 v88, 0x11c00, v134
	ds_read_b128 v[88:91], v88
	v_mfma_f32_16x16x32_bf16 v[152:155], v[156:159], v[144:147], v[80:83]
	s_waitcnt lgkmcnt(1)
	v_mfma_f32_16x16x32_bf16 v[76:79], v[160:163], v[128:131], v[76:79]
	s_nop 0
	v_or_b32_e32 v80, 0x11800, v134
	ds_read_b128 v[80:83], v80
	v_mfma_f32_16x16x32_bf16 v[156:159], v[160:163], v[136:139], v[72:75]
	v_mfma_f32_16x16x32_bf16 v[68:71], v[160:163], v[140:143], v[68:71]
	s_nop 1
	v_or_b32_e32 v72, 0x11400, v134
	ds_read_b128 v[72:75], v72
	v_mfma_f32_16x16x32_bf16 v[160:163], v[160:163], v[144:147], v[64:67]
	s_nop 2
	v_or_b32_e32 v64, 0x11000, v134
	ds_read_b128 v[64:67], v64
	s_waitcnt lgkmcnt(1)
	v_mfma_f32_16x16x32_bf16 v[44:47], v[72:75], v[128:131], v[44:47]
	s_waitcnt vmcnt(0)
	s_waitcnt lgkmcnt(0)
	s_barrier
	v_mfma_f32_16x16x32_bf16 v[60:63], v[64:67], v[128:131], v[60:63]
	v_mfma_f32_16x16x32_bf16 v[164:167], v[64:67], v[136:139], v[56:59]
	v_mfma_f32_16x16x32_bf16 v[52:55], v[64:67], v[140:143], v[52:55]
	v_mfma_f32_16x16x32_bf16 v[168:171], v[64:67], v[144:147], v[48:51]
	v_mfma_f32_16x16x32_bf16 v[172:175], v[72:75], v[136:139], v[40:43]
	v_mfma_f32_16x16x32_bf16 v[36:39], v[72:75], v[140:143], v[36:39]
	v_mfma_f32_16x16x32_bf16 v[176:179], v[72:75], v[144:147], v[32:35]
	v_mfma_f32_16x16x32_bf16 v[28:31], v[80:83], v[128:131], v[28:31]
	v_mfma_f32_16x16x32_bf16 v[24:27], v[80:83], v[136:139], v[24:27]
	v_mfma_f32_16x16x32_bf16 v[20:23], v[80:83], v[140:143], v[20:23]
	v_mfma_f32_16x16x32_bf16 v[16:19], v[80:83], v[144:147], v[16:19]
	v_mfma_f32_16x16x32_bf16 v[12:15], v[88:91], v[128:131], v[12:15]
	v_mfma_f32_16x16x32_bf16 v[8:11], v[88:91], v[136:139], v[8:11]
	v_mfma_f32_16x16x32_bf16 v[4:7], v[88:91], v[140:143], v[4:7]
	v_mfma_f32_16x16x32_bf16 v[0:3], v[88:91], v[144:147], v[0:3]
	ds_read_b128 v[128:131], v180
	ds_read_b128 v[136:139], v180 offset:1024
	ds_read_b128 v[140:143], v180 offset:2048
	ds_read_b128 v[144:147], v180 offset:3072
	ds_read_b128 v[32:35], v134 offset:16384
	ds_read_b128 v[40:43], v134 offset:17408
	ds_read_b128 v[48:51], v134 offset:18432
	ds_read_b128 v[186:189], v134 offset:19456
	s_waitcnt lgkmcnt(2)
	v_mfma_f32_16x16x32_bf16 v[108:111], v[40:43], v[128:131], v[108:111]
	v_mfma_f32_16x16x32_bf16 v[104:107], v[40:43], v[136:139], v[104:107]
	v_mfma_f32_16x16x32_bf16 v[100:103], v[40:43], v[140:143], v[100:103]
	s_nop 5
	v_cvt_pk_bf16_f32 v108, v108, v109
	v_cvt_pk_bf16_f32 v109, v110, v111
	v_cvt_pk_bf16_f32 v104, v104, v105
	v_mfma_f32_16x16x32_bf16 v[190:193], v[40:43], v[144:147], v[96:99]
	v_cvt_pk_bf16_f32 v105, v106, v107
	v_cvt_pk_bf16_f32 v100, v100, v101
	v_cvt_pk_bf16_f32 v101, v102, v103
	s_waitcnt lgkmcnt(1)
	v_mfma_f32_16x16x32_bf16 v[80:83], v[48:51], v[136:139], v[148:151]
	v_mfma_f32_16x16x32_bf16 v[64:67], v[48:51], v[144:147], v[152:155]
	s_waitcnt lgkmcnt(0)
	v_mfma_f32_16x16x32_bf16 v[40:43], v[186:189], v[140:143], v[68:71]
	s_nop 2
	ds_read_b128 v[68:71], v134 offset:20480
	ds_read_b128 v[96:99], v134 offset:21504
	ds_read_b128 v[148:151], v134 offset:22528
	ds_read_b128 v[152:155], v134 offset:23552
	v_cvt_pk_bf16_f32 v80, v80, v81
	v_cvt_pk_bf16_f32 v81, v82, v83
	v_mfma_f32_16x16x32_bf16 v[88:91], v[48:51], v[128:131], v[92:95]
	v_cvt_pk_bf16_f32 v64, v64, v65
	v_cvt_pk_bf16_f32 v65, v66, v67
	v_cvt_pk_bf16_f32 v40, v40, v41
	v_mfma_f32_16x16x32_bf16 v[56:59], v[186:189], v[128:131], v[76:79]
	v_cvt_pk_bf16_f32 v41, v42, v43
	s_nop 2
	v_cvt_pk_bf16_f32 v88, v88, v89
	v_cvt_pk_bf16_f32 v89, v90, v91
	s_waitcnt lgkmcnt(3)
	v_mfma_f32_16x16x32_bf16 v[92:95], v[68:71], v[128:131], v[60:63]
	v_mfma_f32_16x16x32_bf16 v[76:79], v[68:71], v[140:143], v[52:55]
	v_cvt_pk_bf16_f32 v56, v56, v57
	v_cvt_pk_bf16_f32 v57, v58, v59
	s_waitcnt lgkmcnt(2)
	v_mfma_f32_16x16x32_bf16 v[60:63], v[96:99], v[128:131], v[44:47]
	v_mfma_f32_16x16x32_bf16 v[52:55], v[96:99], v[136:139], v[172:175]
	v_mfma_f32_16x16x32_bf16 v[44:47], v[96:99], v[140:143], v[36:39]
	v_mfma_f32_16x16x32_bf16 v[36:39], v[96:99], v[144:147], v[176:179]
	v_lshl_add_u32 v96, s40, 8, v135
	v_mfma_f32_16x16x32_bf16 v[124:127], v[32:35], v[128:131], v[124:127]
	s_waitcnt lgkmcnt(1)
; DI void st_bf4(u16* p, float a, float b, float c, float d) { *(uint2*)p = make_uint2(pk2(a, b), pk2(c, d)); }
; template <int BM, class Epi>
; DI void gemm_dma(const u16* __restrict__ X, long ldx, const u16* __restrict__ W, long ldw, int K, char* smem,
;                  int m0, int n0, const Epi& epi) {
;     ...
;       for (int i = 0; i < 4; ++i)
; #pragma unroll
;         for (int mt = 0; mt < MT; ++mt)
;           acc[nh * 4 + i][mt] = __builtin_amdgcn_mfma_f32_16x16x32_bf16(wf[i], xf[mt], acc[nh * 4 + i][mt], 0, 0, 0);
;   template <int NT, int MT> DI void run(f32x4 (&acc)[NT][MT], int mb, int nb) const {
; #pragma unroll
;     for (int nt = 0; nt < NT; ++nt)
; #pragma unroll
;       for (int mt = 0; mt < MT; ++mt) {
;         f32x4 v = acc[nt][mt];
;         st_bf4(C + (size_t)(mb + mt * 16) * ldc + nb + nt * 16, v[0], v[1], v[2], v[3]);
;       }
;   }
	v_mfma_f32_16x16x32_bf16 v[28:31], v[148:151], v[128:131], v[28:31]
	s_waitcnt lgkmcnt(0)
	v_mfma_f32_16x16x32_bf16 v[12:15], v[152:155], v[128:131], v[12:15]
	v_or_b32_e32 v128, v96, v133
	v_ashrrev_i32_e32 v129, 31, v128
	v_lshlrev_b64 v[96:97], 11, v[128:129]
	v_lshl_add_u64 v[96:97], s[8:9], 0, v[96:97]
	v_lshl_add_u64 v[96:97], v[96:97], 0, v[182:183]
	v_cvt_pk_bf16_f32 v98, v124, v125
	v_cvt_pk_bf16_f32 v99, v126, v127
	v_mfma_f32_16x16x32_bf16 v[120:123], v[32:35], v[136:139], v[120:123]
	global_store_dwordx2 v[96:97], v[98:99], off
	v_or_b32_e32 v98, 16, v128
	v_ashrrev_i32_e32 v99, 31, v98
	v_lshlrev_b64 v[98:99], 11, v[98:99]
	v_lshl_add_u64 v[98:99], s[8:9], 0, v[98:99]
	v_lshl_add_u64 v[98:99], v[98:99], 0, v[182:183]
	s_nop 1
	v_cvt_pk_bf16_f32 v120, v120, v121
	v_cvt_pk_bf16_f32 v121, v122, v123
	v_mfma_f32_16x16x32_bf16 v[116:119], v[32:35], v[140:143], v[116:119]
	global_store_dwordx2 v[98:99], v[120:121], off
	v_or_b32_e32 v120, 32, v128
	v_ashrrev_i32_e32 v121, 31, v120
	v_lshlrev_b64 v[120:121], 11, v[120:121]
	v_lshl_add_u64 v[120:121], s[8:9], 0, v[120:121]
	v_lshl_add_u64 v[120:121], v[120:121], 0, v[182:183]
	s_nop 1
	v_cvt_pk_bf16_f32 v116, v116, v117
	v_cvt_pk_bf16_f32 v117, v118, v119
	v_mfma_f32_16x16x32_bf16 v[112:115], v[32:35], v[144:147], v[112:115]
	global_store_dwordx2 v[120:121], v[116:117], off
	v_or_b32_e32 v116, 48, v128
	v_ashrrev_i32_e32 v117, 31, v116
	v_mfma_f32_16x16x32_bf16 v[32:35], v[186:189], v[144:147], v[160:163]
	v_lshlrev_b64 v[116:117], 11, v[116:117]
	v_lshl_add_u64 v[116:117], s[8:9], 0, v[116:117]
	v_lshl_add_u64 v[116:117], v[116:117], 0, v[182:183]
	v_mfma_f32_16x16x32_bf16 v[72:75], v[48:51], v[140:143], v[84:87]
	v_cvt_pk_bf16_f32 v112, v112, v113
	s_nop 2
	v_cvt_pk_bf16_f32 v32, v32, v33
	v_cvt_pk_bf16_f32 v33, v34, v35
	v_mfma_f32_16x16x32_bf16 v[84:87], v[68:71], v[136:139], v[164:167]
	global_store_dwordx2 v[116:117], v[32:33], off offset:96
	v_cvt_pk_bf16_f32 v32, v92, v93
	v_cvt_pk_bf16_f32 v33, v94, v95
	v_mfma_f32_16x16x32_bf16 v[68:71], v[68:71], v[144:147], v[168:171]
	global_store_dwordx2 v[96:97], v[32:33], off offset:128
	s_nop 2
	v_cvt_pk_bf16_f32 v32, v84, v85
	v_cvt_pk_bf16_f32 v33, v86, v87
	global_store_dwordx2 v[98:99], v[32:33], off offset:128
	v_cvt_pk_bf16_f32 v32, v76, v77
	v_cvt_pk_bf16_f32 v33, v78, v79
	v_mfma_f32_16x16x32_bf16 v[48:51], v[186:189], v[136:139], v[156:159]
	global_store_dwordx2 v[120:121], v[32:33], off offset:128
	v_cvt_pk_bf16_f32 v32, v68, v69
	v_cvt_pk_bf16_f32 v33, v70, v71
	v_mfma_f32_16x16x32_bf16 v[24:27], v[148:151], v[136:139], v[24:27]
	global_store_dwordx2 v[116:117], v[32:33], off offset:128
	v_cvt_pk_bf16_f32 v32, v60, v61
	v_cvt_pk_bf16_f32 v33, v62, v63
	v_mfma_f32_16x16x32_bf16 v[20:23], v[148:151], v[140:143], v[20:23]
	global_store_dwordx2 v[96:97], v[32:33], off offset:160
	v_cvt_pk_bf16_f32 v32, v52, v53
	v_cvt_pk_bf16_f32 v33, v54, v55
	v_mfma_f32_16x16x32_bf16 v[16:19], v[148:151], v[144:147], v[16:19]
	global_store_dwordx2 v[98:99], v[32:33], off offset:160
	v_cvt_pk_bf16_f32 v32, v44, v45
	v_cvt_pk_bf16_f32 v33, v46, v47
	v_mfma_f32_16x16x32_bf16 v[8:11], v[152:155], v[136:139], v[8:11]
	v_cvt_pk_bf16_f32 v113, v114, v115
	global_store_dwordx2 v[120:121], v[100:101], off offset:32
	v_cvt_pk_bf16_f32 v100, v190, v191
	v_mfma_f32_16x16x32_bf16 v[4:7], v[152:155], v[140:143], v[4:7]
	v_cvt_pk_bf16_f32 v101, v192, v193
	v_cvt_pk_bf16_f32 v72, v72, v73
	v_cvt_pk_bf16_f32 v73, v74, v75
	v_mfma_f32_16x16x32_bf16 v[0:3], v[152:155], v[144:147], v[0:3]
	v_cvt_pk_bf16_f32 v48, v48, v49
	v_cvt_pk_bf16_f32 v49, v50, v51
	global_store_dwordx2 v[120:121], v[32:33], off offset:160
	v_cvt_pk_bf16_f32 v32, v36, v37
	v_cvt_pk_bf16_f32 v33, v38, v39
	v_cvt_pk_bf16_f32 v28, v28, v29
	v_cvt_pk_bf16_f32 v29, v30, v31
	v_cvt_pk_bf16_f32 v24, v24, v25
	v_cvt_pk_bf16_f32 v25, v26, v27
	v_cvt_pk_bf16_f32 v20, v20, v21
	v_cvt_pk_bf16_f32 v21, v22, v23
	v_cvt_pk_bf16_f32 v16, v16, v17
	v_cvt_pk_bf16_f32 v17, v18, v19
	v_cvt_pk_bf16_f32 v12, v12, v13
	v_cvt_pk_bf16_f32 v13, v14, v15
	v_cvt_pk_bf16_f32 v8, v8, v9
	v_cvt_pk_bf16_f32 v9, v10, v11
	v_cvt_pk_bf16_f32 v4, v4, v5
	v_cvt_pk_bf16_f32 v5, v6, v7
	v_cvt_pk_bf16_f32 v0, v0, v1
	v_cvt_pk_bf16_f32 v1, v2, v3
	global_store_dwordx2 v[116:117], v[112:113], off
	global_store_dwordx2 v[96:97], v[108:109], off offset:32
	global_store_dwordx2 v[98:99], v[104:105], off offset:32
	global_store_dwordx2 v[116:117], v[100:101], off offset:32
	global_store_dwordx2 v[96:97], v[88:89], off offset:64
	global_store_dwordx2 v[98:99], v[80:81], off offset:64
	global_store_dwordx2 v[120:121], v[72:73], off offset:64
	global_store_dwordx2 v[116:117], v[64:65], off offset:64
	global_store_dwordx2 v[96:97], v[56:57], off offset:96
	global_store_dwordx2 v[98:99], v[48:49], off offset:96
	global_store_dwordx2 v[120:121], v[40:41], off offset:96
	global_store_dwordx2 v[116:117], v[32:33], off offset:160
	global_store_dwordx2 v[96:97], v[28:29], off offset:192
	global_store_dwordx2 v[98:99], v[24:25], off offset:192
	global_store_dwordx2 v[120:121], v[20:21], off offset:192
	global_store_dwordx2 v[116:117], v[16:17], off offset:192
	global_store_dwordx2 v[96:97], v[12:13], off offset:224
	global_store_dwordx2 v[98:99], v[8:9], off offset:224
	global_store_dwordx2 v[120:121], v[4:5], off offset:224
	global_store_dwordx2 v[116:117], v[0:1], off offset:224
	s_branch .LBB0_1132

; template <int MT, class Epi>
; DI void gemm_tile(const u16* __restrict__ X, long ldx, const u16* __restrict__ W, long ldw, int K, char* smem,
;                   int m0, int n0, const Epi& epi, bool pre = false, const u16* Xn = nullptr, const u16* Wn = nullptr) {
;     ...
;   const int r8 = lane >> 3, c0 = (lane & 7) ^ (r8 >> 1);
;   const long oxe = (long)(wu * MT * 8 + r8) * ldx + (c0 << 3), oxo = (long)(wu * MT * 8 + r8) * ldx + ((c0 ^ 4) << 3);
;   const long owe = (long)(wu * 32 + r8) * ldw + (c0 << 3), owo = (long)(wu * 32 + r8) * ldw + ((c0 ^ 4) << 3);
;   const u16 *xe = X + oxe, *xo = X + oxo, *we = W + owe, *wo = W + owo;
;   const long ldx8 = 8 * ldx, ldw8 = 8 * ldw;
;   const unsigned xdst = sbase + wu * MT * 1024, wdst = sbase + 16384 + wu * 4096;
;     ...
;   if (!pre) {
;     __syncthreads();
;     GT_DMA(0u)
;   } else {
;     xe += 64; xo += 64; we += 64; wo += 64;
;   }
;   const int nk = K >> 6;
;   int kt = 0;
;   do {
;     asm volatile("s_waitcnt vmcnt(0)" ::: "memory");
;     __syncthreads();
;     if (kt + 1 < nk) GT_DMA((unsigned)((kt + 1) & 1) * 32768u)
;     else if (Xn != nullptr) { xe = Xn + oxe; xo = Xn + oxo; we = Wn + owe; wo = Wn + owo; GT_DMA(0u) }
;     const char* cur = smem + (kt & 1) * 32768;
; #pragma unroll
;     for (int ks = 0; ks < 2; ++ks) {
;       bf16x8 xf[MT], wf[4];
;       const int ch = ((ks * 4 + g) ^ rsw) << 4;
; #pragma unroll
;       for (int i = 0; i < MT; ++i) xf[i] = *(const bf16x8*)(cur + (wm * 16 * MT + i * 16 + lr) * 128 + ch);
; #pragma unroll
;       for (int i = 0; i < 4; ++i) wf[i] = *(const bf16x8*)(cur + 16384 + (wn * 64 + i * 16 + lr) * 128 + ch);
; DI void phase_even(const Params& p, int e, int sub, char* smem) {
;     ...
;         const int u = t - 1056, c = u >> 3, g = (u >> 1) & 3, tn = u & 1;
;         EpiSgu epi{p.b_spatial + (e * 4 + g) * 128, uvbuf, gbuf, g, c < 128 ? c * 128 : M_PROMPT + (c - 128) * 32, c < 128 ? 128 : 32};
;         gemm_tile<4>(W + WE_WS + (size_t)g * 16384, 128, vT + ((size_t)c * 1024 + g * 256 + tn * 128) * 128, 128, 128, smem, 0, tn * 128, epi);
.LBB0_1147:
	s_cmpk_gt_i32 s4, 0x41f
	s_mov_b64 s[40:41], -1
	s_cbranch_scc0 .LBB0_1157
	s_add_i32 s7, s4, 0xfffffbe0
	s_bfe_u32 s9, s4, 0x20001
	v_readlane_b32 s56, v252, 8
	s_lshr_b32 s34, s7, 3
	s_lshl_b32 s8, s9, 9
	v_readlane_b32 s66, v252, 18
	v_readlane_b32 s67, v252, 19
	s_add_u32 s40, s66, s8
	s_addc_u32 s41, s67, 0
	s_lshl_b32 s8, s34, 5
	s_lshl_b32 s10, s34, 7
	s_add_i32 s11, s8, 0x3000
	s_cmpk_lt_u32 s7, 0x400
	s_cselect_b32 s8, 0x80, 32
	s_cselect_b32 s7, s10, s11
	s_lshl_b32 s10, s9, 15
	v_readlane_b32 s12, v252, 41
	v_readlane_b32 s13, v252, 42
	s_add_u32 s12, s12, s10
	s_addc_u32 s13, s13, 0
	s_lshl_b64 s[14:15], s[34:35], 10
	s_lshl_b32 s9, s9, 8
	v_mov_b32_e32 v72, v185
	s_or_b32 s11, s14, s9
	s_and_b32 s10, s5, 0x80
	s_or_b32 s14, s11, s10
	v_ashrrev_i32_e32 v1, 6, v72
	v_bfe_u32 v2, v72, 3, 3
	v_readfirstlane_b32 s11, v1
	s_waitcnt vmcnt(4)
	v_bfe_u32 v113, v72, 4, 2
	v_bitop3_b32 v6, v113, v72, 7 bitop3:0x78
	v_lshl_or_b32 v2, s11, 5, v2
	v_ashrrev_i32_e32 v3, 31, v2
	s_lshl_b64 s[14:15], s[14:15], 8
	v_readlane_b32 s16, v252, 37
	v_lshlrev_b64 v[2:3], 8, v[2:3]
	v_lshlrev_b32_e32 v182, 4, v6
	v_readlane_b32 s17, v252, 38
	s_add_u32 s14, s16, s14
	v_mov_b32_e32 v0, v183
	v_lshl_add_u64 v[4:5], s[12:13], 0, v[2:3]
	v_xor_b32_e32 v8, 64, v182
	v_mov_b32_e32 v9, v183
	s_addc_u32 s15, s17, s15
	v_lshl_add_u64 v[6:7], v[4:5], 0, v[182:183]
	v_lshl_add_u64 v[4:5], v[4:5], 0, v[8:9]
	s_lshl_b32 s11, s11, 12
	s_waitcnt lgkmcnt(0)
	s_barrier
	s_mov_b32 s12, m0
	s_mov_b32 m0, s11
	s_nop 0
	global_load_lds_dwordx4 v[6:7], off
	s_mov_b32 m0, s12
	s_mov_b64 s[18:19], 0x800
	v_lshl_add_u64 v[2:3], s[14:15], 0, v[2:3]
	v_lshl_add_u64 v[12:13], v[4:5], 0, s[18:19]
	s_or_b32 s12, s11, 0x400
	s_mov_b32 s13, m0
	s_mov_b32 m0, s12
	s_nop 0
	global_load_lds_dwordx4 v[12:13], off
	s_mov_b32 m0, s13
	s_mov_b64 s[14:15], 0x1000
	v_lshl_add_u64 v[12:13], v[6:7], 0, s[14:15]
	s_or_b32 s12, s11, 0x800
	s_mov_b32 s13, m0
	s_mov_b32 m0, s12
	s_nop 0
	global_load_lds_dwordx4 v[12:13], off
	s_mov_b32 m0, s13
	s_mov_b64 s[16:17], 0x1800
	v_lshl_add_u64 v[12:13], v[4:5], 0, s[16:17]
	s_or_b32 s12, s11, 0xc00
	s_mov_b32 s13, m0
	s_mov_b32 m0, s12
	s_nop 0
	global_load_lds_dwordx4 v[12:13], off
	s_mov_b32 m0, s13
	v_lshl_add_u64 v[10:11], v[2:3], 0, v[182:183]
	v_lshl_add_u64 v[2:3], v[2:3], 0, v[8:9]
	s_add_i32 s12, s11, 0x4000
	s_mov_b32 s13, m0
	s_mov_b32 m0, s12
	s_nop 0
	global_load_lds_dwordx4 v[10:11], off
	s_mov_b32 m0, s13
	v_lshl_add_u64 v[8:9], v[2:3], 0, s[18:19]
	s_add_i32 s12, s11, 0x4400
	s_mov_b32 s13, m0
	s_mov_b32 m0, s12
	s_nop 0
	global_load_lds_dwordx4 v[8:9], off
	s_mov_b32 m0, s13
	v_lshl_add_u64 v[8:9], v[10:11], 0, s[14:15]
	s_add_i32 s12, s11, 0x4800
	s_mov_b32 s13, m0
	s_mov_b32 m0, s12
	s_nop 0
	global_load_lds_dwordx4 v[8:9], off
	s_mov_b32 m0, s13
	v_lshl_add_u64 v[8:9], v[2:3], 0, s[16:17]
	s_add_i32 s12, s11, 0x4c00
	s_mov_b32 s13, m0
	s_mov_b32 m0, s12
	s_nop 0
	global_load_lds_dwordx4 v[8:9], off
	s_mov_b32 m0, s13
	s_waitcnt vmcnt(0)
	s_barrier
	s_add_i32 s13, s11, 0x8000
	v_lshl_add_u64 v[8:9], v[6:7], 0, s[28:29]
	s_mov_b32 s14, m0
	s_mov_b32 m0, s13
	s_nop 0
	global_load_lds_dwordx4 v[8:9], off
	s_mov_b32 m0, s14
	s_mov_b64 s[18:19], 0x880
	v_lshl_add_u64 v[8:9], v[4:5], 0, s[18:19]
	s_add_i32 s13, s11, 0x8400
	s_mov_b32 s14, m0
	s_mov_b32 m0, s13
	s_nop 0
	global_load_lds_dwordx4 v[8:9], off
	s_mov_b32 m0, s14
	s_mov_b64 s[20:21], 0x1080
	v_lshl_add_u64 v[6:7], v[6:7], 0, s[20:21]
	s_add_i32 s13, s11, 0x8800
	s_mov_b32 s14, m0
	s_mov_b32 m0, s13
	s_nop 0
	global_load_lds_dwordx4 v[6:7], off
	s_mov_b32 m0, s14
	s_mov_b64 s[16:17], 0x1880
	v_lshl_add_u64 v[4:5], v[4:5], 0, s[16:17]
	s_add_i32 s13, s11, 0x8c00
	s_mov_b32 s14, m0
	s_mov_b32 m0, s13
	s_nop 0
	global_load_lds_dwordx4 v[4:5], off
	s_mov_b32 m0, s14
	s_add_i32 s12, s11, 0xc000
	v_lshl_add_u64 v[12:13], v[10:11], 0, s[28:29]
	s_mov_b32 s13, m0
	s_mov_b32 m0, s12
	s_nop 0
	global_load_lds_dwordx4 v[12:13], off
	s_mov_b32 m0, s13
	v_lshl_add_u64 v[4:5], v[2:3], 0, s[18:19]
	s_add_i32 s12, s11, 0xc400
	s_mov_b32 s13, m0
	s_mov_b32 m0, s12
	s_nop 0
	global_load_lds_dwordx4 v[4:5], off
	s_mov_b32 m0, s13
	v_lshrrev_b32_e32 v14, 1, v72
	v_lshl_add_u64 v[4:5], v[10:11], 0, s[20:21]
	s_add_i32 s12, s11, 0xc800
	s_mov_b32 s13, m0
	s_mov_b32 m0, s12
	s_nop 0
	global_load_lds_dwordx4 v[4:5], off
	s_mov_b32 m0, s13
	v_lshl_add_u64 v[2:3], v[2:3], 0, s[16:17]
	v_and_b32_e32 v112, 15, v72
	v_ashrrev_i32_e32 v114, 7, v72
	s_add_i32 s11, s11, 0xcc00
	s_mov_b32 s12, m0
	s_mov_b32 m0, s11
	s_nop 0
	global_load_lds_dwordx4 v[2:3], off
	s_mov_b32 m0, s12
	v_bitop3_b32 v2, v113, v14, 7 bitop3:0x78
	v_lshlrev_b32_e32 v2, 4, v2
	v_lshlrev_b32_e32 v76, 7, v112
	v_lshlrev_b32_e32 v73, 13, v114
	s_waitcnt vmcnt(1)
	v_or3_b32 v100, v2, v73, v76
	ds_read_b128 v[4:7], v100 offset:16384
	ds_read_b128 v[36:39], v100 offset:18432
	ds_read_b128 v[52:55], v100 offset:20480
	ds_read_b128 v[68:71], v100 offset:22528
	v_and_b32_e32 v115, 1, v1
	v_lshlrev_b32_e32 v77, 13, v115
	v_bfe_u32 v72, v72, 1, 3
	v_or3_b32 v84, v2, v77, v76
	v_bitop3_b32 v72, v113, v72, 4 bitop3:0x36
	ds_read_b128 v[8:11], v84
	ds_read_b128 v[16:19], v84 offset:2048
	ds_read_b128 v[24:27], v84 offset:4096
	ds_read_b128 v[32:35], v84 offset:6144
	v_lshlrev_b32_e32 v78, 4, v72
	v_or_b32_e32 v72, v78, v73
	v_add_u32_e32 v116, v72, v76
	ds_read_b128 v[72:75], v116 offset:16384
	v_mov_b32_e32 v1, v0
	v_mov_b32_e32 v2, v0
	v_mov_b32_e32 v3, v0
	v_readlane_b32 s57, v252, 9
	v_readlane_b32 s58, v252, 10
	s_waitcnt lgkmcnt(4)
	v_mfma_f32_16x16x32_bf16 v[12:15], v[4:7], v[8:11], v[0:3]
	v_readlane_b32 s59, v252, 11
	v_readlane_b32 s60, v252, 12
	v_readlane_b32 s61, v252, 13
	s_waitcnt lgkmcnt(3)
; template <int MT, class Epi>
; DI void gemm_tile(const u16* __restrict__ X, long ldx, const u16* __restrict__ W, long ldw, int K, char* smem,
;                   int m0, int n0, const Epi& epi, bool pre = false, const u16* Xn = nullptr, const u16* Wn = nullptr) {
;     ...
; #pragma unroll
;     for (int ks = 0; ks < 2; ++ks) {
;       bf16x8 xf[MT], wf[4];
;       const int ch = ((ks * 4 + g) ^ rsw) << 4;
; #pragma unroll
;       for (int i = 0; i < MT; ++i) xf[i] = *(const bf16x8*)(cur + (wm * 16 * MT + i * 16 + lr) * 128 + ch);
; #pragma unroll
;       for (int i = 0; i < 4; ++i) wf[i] = *(const bf16x8*)(cur + 16384 + (wn * 64 + i * 16 + lr) * 128 + ch);
; #pragma unroll
;       for (int nt = 0; nt < 4; ++nt)
; #pragma unroll
;         for (int mt = 0; mt < MT; ++mt)
;           acc[nt][mt] = __builtin_amdgcn_mfma_f32_16x16x32_bf16(wf[nt], xf[mt], acc[nt][mt], 0, 0, 0);
;   template <int NT, int MT> DI void run(f32x4 (&acc)[NT][MT], int mb, int nb) const {
; #pragma unroll
;     for (int mt = 0; mt < MT; ++mt) {
;       const int i = mb + mt * 16;
;       if (i < nvalid) {
	v_mfma_f32_16x16x32_bf16 v[20:23], v[4:7], v[16:19], v[0:3]
	v_readlane_b32 s62, v252, 14
	v_readlane_b32 s63, v252, 15
	v_readlane_b32 s64, v252, 16
	s_waitcnt lgkmcnt(2)
	v_mfma_f32_16x16x32_bf16 v[28:31], v[4:7], v[24:27], v[0:3]
	v_readlane_b32 s65, v252, 17
	v_readlane_b32 s68, v252, 20
	v_readlane_b32 s69, v252, 21
	s_waitcnt lgkmcnt(1)
	v_mfma_f32_16x16x32_bf16 v[4:7], v[4:7], v[32:35], v[0:3]
	v_readlane_b32 s70, v252, 22
	v_readlane_b32 s71, v252, 23
	v_mfma_f32_16x16x32_bf16 v[40:43], v[36:39], v[8:11], v[0:3]
	v_mfma_f32_16x16x32_bf16 v[44:47], v[36:39], v[16:19], v[0:3]
	v_mfma_f32_16x16x32_bf16 v[48:51], v[36:39], v[24:27], v[0:3]
	v_mfma_f32_16x16x32_bf16 v[36:39], v[36:39], v[32:35], v[0:3]
	v_mfma_f32_16x16x32_bf16 v[56:59], v[52:55], v[8:11], v[0:3]
	v_mfma_f32_16x16x32_bf16 v[60:63], v[52:55], v[16:19], v[0:3]
	v_mfma_f32_16x16x32_bf16 v[64:67], v[52:55], v[24:27], v[0:3]
	v_mfma_f32_16x16x32_bf16 v[52:55], v[52:55], v[32:35], v[0:3]
	v_mfma_f32_16x16x32_bf16 v[8:11], v[68:71], v[8:11], v[0:3]
	v_mfma_f32_16x16x32_bf16 v[16:19], v[68:71], v[16:19], v[0:3]
	v_mfma_f32_16x16x32_bf16 v[24:27], v[68:71], v[24:27], v[0:3]
	v_mfma_f32_16x16x32_bf16 v[0:3], v[68:71], v[32:35], v[0:3]
	v_or_b32_e32 v32, v78, v77
	v_add_u32_e32 v108, v32, v76
	ds_read_b128 v[32:35], v108
	ds_read_b128 v[68:71], v108 offset:2048
	ds_read_b128 v[76:79], v108 offset:4096
	ds_read_b128 v[80:83], v108 offset:6144
	s_waitcnt lgkmcnt(3)
	v_mfma_f32_16x16x32_bf16 v[12:15], v[72:75], v[32:35], v[12:15]
	s_waitcnt lgkmcnt(2)
	v_mfma_f32_16x16x32_bf16 v[20:23], v[72:75], v[68:71], v[20:23]
	s_waitcnt lgkmcnt(1)
	v_mfma_f32_16x16x32_bf16 v[28:31], v[72:75], v[76:79], v[28:31]
	s_waitcnt lgkmcnt(0)
	v_mfma_f32_16x16x32_bf16 v[4:7], v[72:75], v[80:83], v[4:7]
	ds_read_b128 v[72:75], v116 offset:18432
	s_waitcnt lgkmcnt(0)
	v_mfma_f32_16x16x32_bf16 v[40:43], v[72:75], v[32:35], v[40:43]
	v_mfma_f32_16x16x32_bf16 v[44:47], v[72:75], v[68:71], v[44:47]
	v_mfma_f32_16x16x32_bf16 v[48:51], v[72:75], v[76:79], v[48:51]
	v_mfma_f32_16x16x32_bf16 v[36:39], v[72:75], v[80:83], v[36:39]
	ds_read_b128 v[72:75], v116 offset:20480
	s_waitcnt lgkmcnt(0)
	v_mfma_f32_16x16x32_bf16 v[56:59], v[72:75], v[32:35], v[56:59]
	v_mfma_f32_16x16x32_bf16 v[60:63], v[72:75], v[68:71], v[60:63]
	v_mfma_f32_16x16x32_bf16 v[64:67], v[72:75], v[76:79], v[64:67]
	v_mfma_f32_16x16x32_bf16 v[52:55], v[72:75], v[80:83], v[52:55]
	ds_read_b128 v[72:75], v116 offset:22528
	s_waitcnt vmcnt(0)
	s_waitcnt lgkmcnt(0)
	v_mfma_f32_16x16x32_bf16 v[8:11], v[72:75], v[32:35], v[8:11]
	s_barrier
	ds_read_b128 v[32:35], v100 offset:49152
	ds_read_b128 v[104:107], v108 offset:36864
	v_mfma_f32_16x16x32_bf16 v[16:19], v[72:75], v[68:71], v[16:19]
	ds_read_b128 v[68:71], v84 offset:32768
	v_mfma_f32_16x16x32_bf16 v[24:27], v[72:75], v[76:79], v[24:27]
	ds_read_b128 v[76:79], v84 offset:36864
	v_mfma_f32_16x16x32_bf16 v[0:3], v[72:75], v[80:83], v[0:3]
	ds_read_b128 v[72:75], v84 offset:34816
	ds_read_b128 v[80:83], v84 offset:38912
	s_waitcnt lgkmcnt(3)
	v_mfma_f32_16x16x32_bf16 v[12:15], v[32:35], v[68:71], v[12:15]
	s_waitcnt lgkmcnt(1)
	v_mfma_f32_16x16x32_bf16 v[20:23], v[32:35], v[72:75], v[20:23]
	v_mfma_f32_16x16x32_bf16 v[28:31], v[32:35], v[76:79], v[28:31]
	s_waitcnt lgkmcnt(0)
	v_mfma_f32_16x16x32_bf16 v[4:7], v[32:35], v[80:83], v[4:7]
	ds_read_b128 v[32:35], v100 offset:51200
	s_waitcnt lgkmcnt(0)
	v_mfma_f32_16x16x32_bf16 v[40:43], v[32:35], v[68:71], v[40:43]
	v_mfma_f32_16x16x32_bf16 v[84:87], v[32:35], v[72:75], v[44:47]
	v_mfma_f32_16x16x32_bf16 v[48:51], v[32:35], v[76:79], v[48:51]
	v_mfma_f32_16x16x32_bf16 v[32:35], v[32:35], v[80:83], v[36:39]
	s_nop 2
	ds_read_b128 v[36:39], v100 offset:53248
	s_waitcnt lgkmcnt(0)
	v_mfma_f32_16x16x32_bf16 v[88:91], v[36:39], v[68:71], v[56:59]
	v_mfma_f32_16x16x32_bf16 v[92:95], v[36:39], v[72:75], v[60:63]
	v_mfma_f32_16x16x32_bf16 v[64:67], v[36:39], v[76:79], v[64:67]
	s_waitcnt vmcnt(0)
	v_mfma_f32_16x16x32_bf16 v[96:99], v[36:39], v[80:83], v[52:55]
	ds_read_b128 v[36:39], v100 offset:55296
	ds_read_b128 v[100:103], v108 offset:34816
	s_waitcnt lgkmcnt(1)
	v_mfma_f32_16x16x32_bf16 v[68:71], v[36:39], v[68:71], v[8:11]
	s_nop 2
	ds_read_b128 v[8:11], v116 offset:49152
	v_mfma_f32_16x16x32_bf16 v[16:19], v[36:39], v[72:75], v[16:19]
	v_mfma_f32_16x16x32_bf16 v[74:77], v[36:39], v[76:79], v[24:27]
	v_mfma_f32_16x16x32_bf16 v[0:3], v[36:39], v[80:83], v[0:3]
	ds_read_b128 v[78:81], v108 offset:32768
	ds_read_b128 v[108:111], v108 offset:38912
	s_waitcnt lgkmcnt(1)
	v_mfma_f32_16x16x32_bf16 v[60:63], v[8:11], v[78:81], v[12:15]
	s_waitcnt lgkmcnt(0)
	v_mfma_f32_16x16x32_bf16 v[12:15], v[8:11], v[108:111], v[4:7]
	s_nop 2
	ds_read_b128 v[4:7], v116 offset:51200
	v_mfma_f32_16x16x32_bf16 v[44:47], v[8:11], v[100:103], v[20:23]
	v_mfma_f32_16x16x32_bf16 v[28:31], v[8:11], v[104:107], v[28:31]
	s_waitcnt lgkmcnt(0)
	v_mfma_f32_16x16x32_bf16 v[56:59], v[4:7], v[78:81], v[40:43]
	v_mfma_f32_16x16x32_bf16 v[40:43], v[4:7], v[100:103], v[84:87]
	v_mfma_f32_16x16x32_bf16 v[24:27], v[4:7], v[104:107], v[48:51]
	s_nop 1
	ds_read_b128 v[82:85], v116 offset:55296
	v_mfma_f32_16x16x32_bf16 v[8:11], v[4:7], v[108:111], v[32:35]
	ds_read_b128 v[4:7], v116 offset:53248
	s_nop 1
	v_lshl_add_u32 v32, v114, 6, s10
	s_waitcnt lgkmcnt(0)
	v_mfma_f32_16x16x32_bf16 v[52:55], v[4:7], v[78:81], v[88:91]
	v_mfma_f32_16x16x32_bf16 v[36:39], v[4:7], v[100:103], v[92:95]
	v_mfma_f32_16x16x32_bf16 v[20:23], v[4:7], v[104:107], v[64:67]
	v_mfma_f32_16x16x32_bf16 v[4:7], v[4:7], v[108:111], v[96:99]
	s_nop 1
	v_lshl_or_b32 v64, v113, 2, v32
	v_mfma_f32_16x16x32_bf16 v[48:51], v[82:85], v[78:81], v[68:71]
	v_lshl_or_b32 v78, v115, 6, v112
	v_cmp_gt_u32_e32 vcc, s8, v78
	v_lshlrev_b32_e32 v73, 2, v78
	v_mfma_f32_16x16x32_bf16 v[32:35], v[82:85], v[100:103], v[16:19]
	v_add_u32_e32 v70, s9, v64
	v_ashrrev_i32_e32 v71, 31, v70
	v_add_u32_e32 v68, 16, v70
	v_mfma_f32_16x16x32_bf16 v[16:19], v[82:85], v[104:107], v[74:77]
	v_add_u32_e32 v66, 32, v70
	v_add_u32_e32 v64, 48, v70
	v_mfma_f32_16x16x32_bf16 v[0:3], v[82:85], v[108:111], v[0:3]
	s_and_saveexec_b64 s[42:43], vcc
	s_cbranch_execz .LBB0_1150
; DI float bflo(unsigned u) { return __uint_as_float(u << 16); }
; DI float bfhi(unsigned u) { return __uint_as_float(u & 0xffff0000u); }
; DI void st_bf4(u16* p, float a, float b, float c, float d) { *(uint2*)p = make_uint2(pk2(a, b), pk2(c, d)); }
;   template <int NT, int MT> DI void run(f32x4 (&acc)[NT][MT], int mb, int nb) const {
; #pragma unroll
;     for (int mt = 0; mt < MT; ++mt) {
;       const int i = mb + mt * 16;
;       if (i < nvalid) {
;         const float bias = bs[i];
;         const size_t row = (size_t)(rowbase + i);
; #pragma unroll
;         for (int nt = 0; nt < NT; ++nt) {
;           const int ch = g * 256 + nb + nt * 16;
;           const uint2 uu = *(const uint2*)(uv + row * 2048 + ch);
;           u16* q = mix + row * 2048 + 1024 + ch;
;           const uint2 gt = *(const uint2*)q;
;           f32x4 v = acc[nt][mt];
;           st_bf4(q, (v[0] + bias) * bflo(uu.x) * bflo(gt.x), (v[1] + bias) * bfhi(uu.x) * bfhi(gt.x),
;                  (v[2] + bias) * bflo(uu.y) * bflo(gt.y), (v[3] + bias) * bfhi(uu.y) * bfhi(gt.y));
;         }
;       }
	v_mov_b32_e32 v135, v183
	v_add_u32_e32 v134, s7, v78
	v_readlane_b32 s10, v252, 33
	v_lshlrev_b64 v[136:137], 12, v[134:135]
	v_readlane_b32 s11, v252, 34
	v_lshlrev_b64 v[138:139], 1, v[70:71]
	global_load_dword v140, v73, s[40:41]
	v_lshl_add_u64 v[142:143], s[10:11], 0, v[136:137]
	v_readlane_b32 s10, v252, 35
	v_readlane_b32 s11, v252, 36
	v_lshl_add_u64 v[144:145], v[142:143], 0, v[138:139]
	global_load_dwordx2 v[146:147], v[144:145], off
	v_lshl_add_u64 v[148:149], s[10:11], 0, v[136:137]
	v_lshl_add_u64 v[150:151], v[148:149], 0, v[138:139]
	global_load_dwordx2 v[152:153], v[150:151], off offset:2048
	v_ashrrev_i32_e32 v141, 31, v68
	v_ashrrev_i32_e32 v154, 31, v66
	v_ashrrev_i32_e32 v155, 31, v64
	v_mov_b32_e32 v190, v68
	v_mov_b32_e32 v191, v141
	v_lshlrev_b64 v[156:157], 1, v[190:191]
	v_lshl_add_u64 v[158:159], v[142:143], 0, v[156:157]
	global_load_dwordx2 v[160:161], v[158:159], off
	v_lshl_add_u64 v[162:163], v[148:149], 0, v[156:157]
	global_load_dwordx2 v[164:165], v[162:163], off offset:2048
	v_mov_b32_e32 v192, v66
	v_mov_b32_e32 v193, v154
	v_lshlrev_b64 v[166:167], 1, v[192:193]
	v_lshl_add_u64 v[168:169], v[142:143], 0, v[166:167]
	global_load_dwordx2 v[170:171], v[168:169], off
	v_lshl_add_u64 v[172:173], v[148:149], 0, v[166:167]
	global_load_dwordx2 v[174:175], v[172:173], off offset:2048
	v_mov_b32_e32 v194, v64
	v_mov_b32_e32 v195, v155
	v_lshlrev_b64 v[176:177], 1, v[194:195]
	v_lshl_add_u64 v[178:179], v[142:143], 0, v[176:177]
	global_load_dwordx2 v[180:181], v[178:179], off
	v_lshl_add_u64 v[186:187], v[148:149], 0, v[176:177]
	global_load_dwordx2 v[188:189], v[186:187], off offset:2048
	s_nop 0
	s_nop 0
	s_nop 0
	s_nop 0
	s_nop 0
	s_nop 0
	s_nop 0
	s_nop 0
	s_nop 0
	s_nop 0
	s_nop 0
	s_nop 0
	s_nop 0
	s_nop 0
	s_nop 0
	s_nop 0
	s_nop 0
	s_waitcnt vmcnt(8)
	v_mov_b32_e32 v196, v140
	v_mov_b32_e32 v197, v73
	v_pk_add_f32 v[60:61], v[60:61], v[196:197] op_sel_hi:[1,0]
	v_mov_b32_e32 v224, v140
	v_mov_b32_e32 v225, v73
	v_pk_add_f32 v[62:63], v[62:63], v[224:225] op_sel_hi:[1,0]
	v_mov_b32_e32 v226, v140
	v_mov_b32_e32 v227, v73
	v_pk_add_f32 v[56:57], v[56:57], v[226:227] op_sel_hi:[1,0]
	v_mov_b32_e32 v228, v140
	v_mov_b32_e32 v229, v73
	v_pk_add_f32 v[58:59], v[58:59], v[228:229] op_sel_hi:[1,0]
	v_mov_b32_e32 v230, v140
	v_mov_b32_e32 v231, v73
	v_pk_add_f32 v[52:53], v[52:53], v[230:231] op_sel_hi:[1,0]
	s_waitcnt vmcnt(7)
	v_lshlrev_b32_e32 v86, 16, v146
	v_and_b32_e32 v87, 0xffff0000, v146
	v_lshlrev_b32_e32 v82, 16, v147
	v_and_b32_e32 v83, 0xffff0000, v147
	s_waitcnt vmcnt(6)
	v_lshlrev_b32_e32 v88, 16, v152
	v_and_b32_e32 v89, 0xffff0000, v152
	v_pk_mul_f32 v[60:61], v[60:61], v[86:87]
	v_lshlrev_b32_e32 v84, 16, v153
	v_and_b32_e32 v85, 0xffff0000, v153
	v_pk_mul_f32 v[62:63], v[62:63], v[82:83]
	v_pk_mul_f32 v[60:61], v[60:61], v[88:89]
	v_pk_mul_f32 v[62:63], v[62:63], v[84:85]
	v_cvt_pk_bf16_f32 v60, v60, v61
	v_cvt_pk_bf16_f32 v61, v62, v63
	global_store_dwordx2 v[150:151], v[60:61], off offset:2048
	s_nop 0
	s_nop 0
	s_nop 0
	s_nop 0
	s_nop 0
	v_mov_b32_e32 v232, v140
	v_mov_b32_e32 v233, v73
	v_pk_add_f32 v[54:55], v[54:55], v[232:233] op_sel_hi:[1,0]
	v_mov_b32_e32 v234, v140
	v_mov_b32_e32 v235, v73
	v_pk_add_f32 v[48:49], v[48:49], v[234:235] op_sel_hi:[1,0]
	v_mov_b32_e32 v236, v140
	v_mov_b32_e32 v237, v73
	v_pk_add_f32 v[50:51], v[50:51], v[236:237] op_sel_hi:[1,0]
	s_waitcnt vmcnt(5)
	v_lshlrev_b32_e32 v82, 16, v160
	v_and_b32_e32 v83, 0xffff0000, v160
	v_lshlrev_b32_e32 v62, 16, v161
	v_and_b32_e32 v63, 0xffff0000, v161
	s_waitcnt vmcnt(4)
	v_lshlrev_b32_e32 v84, 16, v164
	v_and_b32_e32 v85, 0xffff0000, v164
	v_pk_mul_f32 v[56:57], v[56:57], v[82:83]
	v_lshlrev_b32_e32 v80, 16, v165
	v_and_b32_e32 v81, 0xffff0000, v165
	v_pk_mul_f32 v[58:59], v[58:59], v[62:63]
	v_pk_mul_f32 v[56:57], v[56:57], v[84:85]
	v_pk_mul_f32 v[58:59], v[58:59], v[80:81]
	v_cvt_pk_bf16_f32 v56, v56, v57
	v_cvt_pk_bf16_f32 v57, v58, v59
	global_store_dwordx2 v[162:163], v[56:57], off offset:2048
	s_nop 0
	s_nop 0
	s_nop 0
	s_nop 0
	s_nop 0
	s_waitcnt vmcnt(3)
	v_lshlrev_b32_e32 v62, 16, v170
	v_and_b32_e32 v63, 0xffff0000, v170
	v_lshlrev_b32_e32 v58, 16, v171
	v_and_b32_e32 v59, 0xffff0000, v171
	s_waitcnt vmcnt(2)
	v_lshlrev_b32_e32 v80, 16, v174
	v_and_b32_e32 v81, 0xffff0000, v174
	v_pk_mul_f32 v[52:53], v[52:53], v[62:63]
	v_lshlrev_b32_e32 v60, 16, v175
	v_and_b32_e32 v61, 0xffff0000, v175
	v_pk_mul_f32 v[54:55], v[54:55], v[58:59]
	v_pk_mul_f32 v[52:53], v[52:53], v[80:81]
	v_pk_mul_f32 v[54:55], v[54:55], v[60:61]
	v_cvt_pk_bf16_f32 v52, v52, v53
	v_cvt_pk_bf16_f32 v53, v54, v55
	global_store_dwordx2 v[172:173], v[52:53], off offset:2048
	s_nop 0
	s_nop 0
	s_nop 0
	s_nop 0
	s_nop 0
	s_waitcnt vmcnt(1)
	v_lshlrev_b32_e32 v58, 16, v180
	v_and_b32_e32 v59, 0xffff0000, v180
	v_lshlrev_b32_e32 v54, 16, v181
	v_and_b32_e32 v55, 0xffff0000, v181
	s_waitcnt vmcnt(0)
	v_lshlrev_b32_e32 v60, 16, v188
	v_and_b32_e32 v61, 0xffff0000, v188
	v_pk_mul_f32 v[48:49], v[48:49], v[58:59]
	v_lshlrev_b32_e32 v56, 16, v189
	v_and_b32_e32 v57, 0xffff0000, v189
	v_pk_mul_f32 v[50:51], v[50:51], v[54:55]
	v_pk_mul_f32 v[48:49], v[48:49], v[60:61]
	v_pk_mul_f32 v[50:51], v[50:51], v[56:57]
	v_cvt_pk_bf16_f32 v48, v48, v49
	v_cvt_pk_bf16_f32 v49, v50, v51
	global_store_dwordx2 v[186:187], v[48:49], off offset:2048
	v_mov_b32_e32 v52, v186
	v_mov_b32_e32 v53, v187
	v_mov_b32_e32 v65, v155
	v_mov_b32_e32 v67, v154
	v_mov_b32_e32 v69, v141
	v_mov_b32_e32 v72, v140
	v_mov_b32_e32 v74, v142
	v_mov_b32_e32 v75, v143
	v_mov_b32_e32 v76, v148
	v_mov_b32_e32 v77, v149
	v_mov_b32_e32 v182, v134
; DI float bflo(unsigned u) { return __uint_as_float(u << 16); }
; DI float bfhi(unsigned u) { return __uint_as_float(u & 0xffff0000u); }
; DI void st_bf4(u16* p, float a, float b, float c, float d) { *(uint2*)p = make_uint2(pk2(a, b), pk2(c, d)); }
;   template <int NT, int MT> DI void run(f32x4 (&acc)[NT][MT], int mb, int nb) const {
; #pragma unroll
;     for (int mt = 0; mt < MT; ++mt) {
;       const int i = mb + mt * 16;
;       if (i < nvalid) {
;         const float bias = bs[i];
;         const size_t row = (size_t)(rowbase + i);
; #pragma unroll
;         for (int nt = 0; nt < NT; ++nt) {
;           const int ch = g * 256 + nb + nt * 16;
;           const uint2 uu = *(const uint2*)(uv + row * 2048 + ch);
;           u16* q = mix + row * 2048 + 1024 + ch;
;           const uint2 gt = *(const uint2*)q;
;           f32x4 v = acc[nt][mt];
;           st_bf4(q, (v[0] + bias) * bflo(uu.x) * bflo(gt.x), (v[1] + bias) * bfhi(uu.x) * bfhi(gt.x),
;                  (v[2] + bias) * bflo(uu.y) * bflo(gt.y), (v[3] + bias) * bfhi(uu.y) * bfhi(gt.y));
;         }
;       }
.LBB0_1150:
	s_or_b64 exec, exec, s[42:43]
	v_or_b32_e32 v49, 16, v78
	v_cmp_gt_u32_e32 vcc, s8, v49
	s_and_saveexec_b64 s[42:43], vcc
	s_cbranch_execz .LBB0_1152
	v_mov_b32_e32 v135, v183
	v_add_u32_e32 v134, s7, v49
	v_readlane_b32 s10, v252, 33
	v_lshlrev_b64 v[136:137], 12, v[134:135]
	v_readlane_b32 s11, v252, 34
	v_lshlrev_b64 v[138:139], 1, v[70:71]
	global_load_dword v140, v73, s[40:41] offset:64
	v_lshl_add_u64 v[142:143], s[10:11], 0, v[136:137]
	v_readlane_b32 s10, v252, 35
	v_readlane_b32 s11, v252, 36
	v_lshl_add_u64 v[144:145], v[142:143], 0, v[138:139]
	global_load_dwordx2 v[146:147], v[144:145], off
	v_lshl_add_u64 v[148:149], s[10:11], 0, v[136:137]
	v_lshl_add_u64 v[150:151], v[148:149], 0, v[138:139]
	global_load_dwordx2 v[152:153], v[150:151], off offset:2048
	v_ashrrev_i32_e32 v141, 31, v68
	v_ashrrev_i32_e32 v154, 31, v66
	v_ashrrev_i32_e32 v155, 31, v64
	v_mov_b32_e32 v190, v68
	v_mov_b32_e32 v191, v141
	v_lshlrev_b64 v[156:157], 1, v[190:191]
	v_lshl_add_u64 v[158:159], v[142:143], 0, v[156:157]
	global_load_dwordx2 v[160:161], v[158:159], off
	v_lshl_add_u64 v[162:163], v[148:149], 0, v[156:157]
	global_load_dwordx2 v[164:165], v[162:163], off offset:2048
	v_mov_b32_e32 v192, v66
	v_mov_b32_e32 v193, v154
	v_lshlrev_b64 v[166:167], 1, v[192:193]
	v_lshl_add_u64 v[168:169], v[142:143], 0, v[166:167]
	global_load_dwordx2 v[170:171], v[168:169], off
	v_lshl_add_u64 v[172:173], v[148:149], 0, v[166:167]
	global_load_dwordx2 v[174:175], v[172:173], off offset:2048
	v_mov_b32_e32 v194, v64
	v_mov_b32_e32 v195, v155
	v_lshlrev_b64 v[176:177], 1, v[194:195]
	v_lshl_add_u64 v[178:179], v[142:143], 0, v[176:177]
	global_load_dwordx2 v[180:181], v[178:179], off
	v_lshl_add_u64 v[186:187], v[148:149], 0, v[176:177]
	global_load_dwordx2 v[188:189], v[186:187], off offset:2048
	s_nop 0
	s_nop 0
	s_nop 0
	s_nop 0
	s_nop 0
	s_nop 0
	s_nop 0
	s_nop 0
	s_nop 0
	s_nop 0
	s_nop 0
	s_nop 0
	s_nop 0
	s_nop 0
	s_nop 0
	s_nop 0
	s_nop 0
	s_waitcnt vmcnt(8)
	v_mov_b32_e32 v196, v140
	v_mov_b32_e32 v197, v49
	v_pk_add_f32 v[44:45], v[44:45], v[196:197] op_sel_hi:[1,0]
	v_mov_b32_e32 v224, v140
	v_mov_b32_e32 v225, v49
	v_pk_add_f32 v[46:47], v[46:47], v[224:225] op_sel_hi:[1,0]
	v_mov_b32_e32 v226, v140
	v_mov_b32_e32 v227, v49
	v_pk_add_f32 v[40:41], v[40:41], v[226:227] op_sel_hi:[1,0]
	v_mov_b32_e32 v228, v140
	v_mov_b32_e32 v229, v49
	v_pk_add_f32 v[42:43], v[42:43], v[228:229] op_sel_hi:[1,0]
	v_mov_b32_e32 v230, v140
	v_mov_b32_e32 v231, v49
	v_pk_add_f32 v[36:37], v[36:37], v[230:231] op_sel_hi:[1,0]
	s_waitcnt vmcnt(7)
	v_lshlrev_b32_e32 v60, 16, v146
	v_and_b32_e32 v61, 0xffff0000, v146
	v_lshlrev_b32_e32 v56, 16, v147
	v_and_b32_e32 v57, 0xffff0000, v147
	s_waitcnt vmcnt(6)
	v_lshlrev_b32_e32 v62, 16, v152
	v_and_b32_e32 v63, 0xffff0000, v152
	v_pk_mul_f32 v[44:45], v[44:45], v[60:61]
	v_lshlrev_b32_e32 v58, 16, v153
	v_and_b32_e32 v59, 0xffff0000, v153
	v_pk_mul_f32 v[46:47], v[46:47], v[56:57]
	v_pk_mul_f32 v[44:45], v[44:45], v[62:63]
	v_pk_mul_f32 v[46:47], v[46:47], v[58:59]
	v_cvt_pk_bf16_f32 v44, v44, v45
	v_cvt_pk_bf16_f32 v45, v46, v47
	global_store_dwordx2 v[150:151], v[44:45], off offset:2048
	s_nop 0
	s_nop 0
	s_nop 0
	s_nop 0
	s_nop 0
	v_mov_b32_e32 v232, v140
	v_mov_b32_e32 v233, v49
	v_pk_add_f32 v[38:39], v[38:39], v[232:233] op_sel_hi:[1,0]
	v_mov_b32_e32 v234, v140
	v_mov_b32_e32 v235, v49
	v_pk_add_f32 v[32:33], v[32:33], v[234:235] op_sel_hi:[1,0]
	v_mov_b32_e32 v236, v140
	v_mov_b32_e32 v237, v49
	v_pk_add_f32 v[34:35], v[34:35], v[236:237] op_sel_hi:[1,0]
	s_waitcnt vmcnt(5)
	v_lshlrev_b32_e32 v56, 16, v160
	v_and_b32_e32 v57, 0xffff0000, v160
	v_lshlrev_b32_e32 v46, 16, v161
	v_and_b32_e32 v47, 0xffff0000, v161
	s_waitcnt vmcnt(4)
	v_lshlrev_b32_e32 v58, 16, v164
	v_and_b32_e32 v59, 0xffff0000, v164
	v_pk_mul_f32 v[40:41], v[40:41], v[56:57]
	v_lshlrev_b32_e32 v54, 16, v165
	v_and_b32_e32 v55, 0xffff0000, v165
	v_pk_mul_f32 v[42:43], v[42:43], v[46:47]
	v_pk_mul_f32 v[40:41], v[40:41], v[58:59]
	v_pk_mul_f32 v[42:43], v[42:43], v[54:55]
	v_cvt_pk_bf16_f32 v40, v40, v41
	v_cvt_pk_bf16_f32 v41, v42, v43
	global_store_dwordx2 v[162:163], v[40:41], off offset:2048
	s_nop 0
	s_nop 0
	s_nop 0
	s_nop 0
	s_nop 0
	s_waitcnt vmcnt(3)
	v_lshlrev_b32_e32 v46, 16, v170
	v_and_b32_e32 v47, 0xffff0000, v170
	v_lshlrev_b32_e32 v42, 16, v171
	v_and_b32_e32 v43, 0xffff0000, v171
	s_waitcnt vmcnt(2)
	v_lshlrev_b32_e32 v54, 16, v174
	v_and_b32_e32 v55, 0xffff0000, v174
	v_pk_mul_f32 v[36:37], v[36:37], v[46:47]
	v_lshlrev_b32_e32 v44, 16, v175
	v_and_b32_e32 v45, 0xffff0000, v175
	v_pk_mul_f32 v[38:39], v[38:39], v[42:43]
	v_pk_mul_f32 v[36:37], v[36:37], v[54:55]
	v_pk_mul_f32 v[38:39], v[38:39], v[44:45]
	v_cvt_pk_bf16_f32 v36, v36, v37
	v_cvt_pk_bf16_f32 v37, v38, v39
	global_store_dwordx2 v[172:173], v[36:37], off offset:2048
	s_nop 0
	s_nop 0
	s_nop 0
	s_nop 0
	s_nop 0
	s_waitcnt vmcnt(1)
	v_lshlrev_b32_e32 v42, 16, v180
	v_and_b32_e32 v43, 0xffff0000, v180
	v_lshlrev_b32_e32 v38, 16, v181
	v_and_b32_e32 v39, 0xffff0000, v181
	s_waitcnt vmcnt(0)
	v_lshlrev_b32_e32 v44, 16, v188
	v_and_b32_e32 v45, 0xffff0000, v188
	v_pk_mul_f32 v[32:33], v[32:33], v[42:43]
	v_lshlrev_b32_e32 v40, 16, v189
	v_and_b32_e32 v41, 0xffff0000, v189
	v_pk_mul_f32 v[34:35], v[34:35], v[38:39]
	v_pk_mul_f32 v[32:33], v[32:33], v[44:45]
	v_pk_mul_f32 v[34:35], v[34:35], v[40:41]
	v_cvt_pk_bf16_f32 v32, v32, v33
	v_cvt_pk_bf16_f32 v33, v34, v35
	global_store_dwordx2 v[186:187], v[32:33], off offset:2048
	v_mov_b32_e32 v36, v186
	v_mov_b32_e32 v37, v187
	v_mov_b32_e32 v48, v140
	v_mov_b32_e32 v50, v142
	v_mov_b32_e32 v51, v143
	v_mov_b32_e32 v52, v148
	v_mov_b32_e32 v53, v149
	v_mov_b32_e32 v65, v155
	v_mov_b32_e32 v67, v154
	v_mov_b32_e32 v69, v141
	v_mov_b32_e32 v182, v134
; DI float bflo(unsigned u) { return __uint_as_float(u << 16); }
; DI float bfhi(unsigned u) { return __uint_as_float(u & 0xffff0000u); }
; DI void st_bf4(u16* p, float a, float b, float c, float d) { *(uint2*)p = make_uint2(pk2(a, b), pk2(c, d)); }
;   template <int NT, int MT> DI void run(f32x4 (&acc)[NT][MT], int mb, int nb) const {
; #pragma unroll
;     for (int mt = 0; mt < MT; ++mt) {
;       const int i = mb + mt * 16;
;       if (i < nvalid) {
;         const float bias = bs[i];
;         const size_t row = (size_t)(rowbase + i);
; #pragma unroll
;         for (int nt = 0; nt < NT; ++nt) {
;           const int ch = g * 256 + nb + nt * 16;
;           const uint2 uu = *(const uint2*)(uv + row * 2048 + ch);
;           u16* q = mix + row * 2048 + 1024 + ch;
;           const uint2 gt = *(const uint2*)q;
;           f32x4 v = acc[nt][mt];
;           st_bf4(q, (v[0] + bias) * bflo(uu.x) * bflo(gt.x), (v[1] + bias) * bfhi(uu.x) * bfhi(gt.x),
;                  (v[2] + bias) * bflo(uu.y) * bflo(gt.y), (v[3] + bias) * bfhi(uu.y) * bfhi(gt.y));
;         }
;       }
.LBB0_1152:
	s_or_b64 exec, exec, s[42:43]
	v_or_b32_e32 v33, 32, v78
	v_cmp_gt_u32_e32 vcc, s8, v33
	s_and_saveexec_b64 s[42:43], vcc
	s_mov_b64 s[68:69], s[24:25]
	s_mov_b64 s[70:71], s[26:27]
	s_movk_i32 s64, 0x41ff
	s_mov_b64 s[66:67], 0x5a8080
	s_mov_b32 s65, 0x2aaaaaab
	s_cbranch_execz .LBB0_1154
	v_mov_b32_e32 v135, v183
	v_add_u32_e32 v134, s7, v33
	v_readlane_b32 s10, v252, 33
	v_lshlrev_b64 v[136:137], 12, v[134:135]
	v_readlane_b32 s11, v252, 34
	v_lshlrev_b64 v[138:139], 1, v[70:71]
	global_load_dword v140, v73, s[40:41] offset:128
	v_lshl_add_u64 v[142:143], s[10:11], 0, v[136:137]
	v_readlane_b32 s10, v252, 35
	v_readlane_b32 s11, v252, 36
	v_lshl_add_u64 v[144:145], v[142:143], 0, v[138:139]
	global_load_dwordx2 v[146:147], v[144:145], off
	v_lshl_add_u64 v[148:149], s[10:11], 0, v[136:137]
	v_lshl_add_u64 v[150:151], v[148:149], 0, v[138:139]
	global_load_dwordx2 v[152:153], v[150:151], off offset:2048
	v_ashrrev_i32_e32 v141, 31, v68
	v_ashrrev_i32_e32 v154, 31, v66
	v_ashrrev_i32_e32 v155, 31, v64
	v_mov_b32_e32 v190, v68
	v_mov_b32_e32 v191, v141
	v_lshlrev_b64 v[156:157], 1, v[190:191]
	v_lshl_add_u64 v[158:159], v[142:143], 0, v[156:157]
	global_load_dwordx2 v[160:161], v[158:159], off
	v_lshl_add_u64 v[162:163], v[148:149], 0, v[156:157]
	global_load_dwordx2 v[164:165], v[162:163], off offset:2048
	v_mov_b32_e32 v192, v66
	v_mov_b32_e32 v193, v154
	v_lshlrev_b64 v[166:167], 1, v[192:193]
	v_lshl_add_u64 v[168:169], v[142:143], 0, v[166:167]
	global_load_dwordx2 v[170:171], v[168:169], off
	v_lshl_add_u64 v[172:173], v[148:149], 0, v[166:167]
	global_load_dwordx2 v[174:175], v[172:173], off offset:2048
	v_mov_b32_e32 v194, v64
	v_mov_b32_e32 v195, v155
	v_lshlrev_b64 v[176:177], 1, v[194:195]
	v_lshl_add_u64 v[178:179], v[142:143], 0, v[176:177]
	global_load_dwordx2 v[180:181], v[178:179], off
	v_lshl_add_u64 v[186:187], v[148:149], 0, v[176:177]
	global_load_dwordx2 v[188:189], v[186:187], off offset:2048
	s_nop 0
	s_nop 0
	s_nop 0
	s_nop 0
	s_nop 0
	s_nop 0
	s_nop 0
	s_nop 0
	s_nop 0
	s_nop 0
	s_nop 0
	s_nop 0
	s_nop 0
	s_nop 0
	s_nop 0
	s_nop 0
	s_nop 0
	s_waitcnt vmcnt(8)
	v_mov_b32_e32 v196, v140
	v_mov_b32_e32 v197, v33
	v_pk_add_f32 v[28:29], v[28:29], v[196:197] op_sel_hi:[1,0]
	v_mov_b32_e32 v224, v140
	v_mov_b32_e32 v225, v33
	v_pk_add_f32 v[30:31], v[30:31], v[224:225] op_sel_hi:[1,0]
	v_mov_b32_e32 v226, v140
	v_mov_b32_e32 v227, v33
	v_pk_add_f32 v[24:25], v[24:25], v[226:227] op_sel_hi:[1,0]
	v_mov_b32_e32 v228, v140
	v_mov_b32_e32 v229, v33
	v_pk_add_f32 v[26:27], v[26:27], v[228:229] op_sel_hi:[1,0]
	v_mov_b32_e32 v230, v140
	v_mov_b32_e32 v231, v33
	v_pk_add_f32 v[20:21], v[20:21], v[230:231] op_sel_hi:[1,0]
	s_waitcnt vmcnt(7)
	v_lshlrev_b32_e32 v44, 16, v146
	v_and_b32_e32 v45, 0xffff0000, v146
	v_lshlrev_b32_e32 v40, 16, v147
	v_and_b32_e32 v41, 0xffff0000, v147
	s_waitcnt vmcnt(6)
	v_lshlrev_b32_e32 v46, 16, v152
	v_and_b32_e32 v47, 0xffff0000, v152
	v_pk_mul_f32 v[28:29], v[28:29], v[44:45]
	v_lshlrev_b32_e32 v42, 16, v153
	v_and_b32_e32 v43, 0xffff0000, v153
	v_pk_mul_f32 v[30:31], v[30:31], v[40:41]
	v_pk_mul_f32 v[28:29], v[28:29], v[46:47]
	v_pk_mul_f32 v[30:31], v[30:31], v[42:43]
	v_cvt_pk_bf16_f32 v28, v28, v29
	v_cvt_pk_bf16_f32 v29, v30, v31
	global_store_dwordx2 v[150:151], v[28:29], off offset:2048
	s_nop 0
	s_nop 0
	s_nop 0
	s_nop 0
	s_nop 0
	v_mov_b32_e32 v232, v140
	v_mov_b32_e32 v233, v33
	v_pk_add_f32 v[22:23], v[22:23], v[232:233] op_sel_hi:[1,0]
	v_mov_b32_e32 v234, v140
	v_mov_b32_e32 v235, v33
	v_pk_add_f32 v[16:17], v[16:17], v[234:235] op_sel_hi:[1,0]
	v_mov_b32_e32 v236, v140
	v_mov_b32_e32 v237, v33
	v_pk_add_f32 v[18:19], v[18:19], v[236:237] op_sel_hi:[1,0]
	s_waitcnt vmcnt(5)
	v_lshlrev_b32_e32 v40, 16, v160
	v_and_b32_e32 v41, 0xffff0000, v160
	v_lshlrev_b32_e32 v30, 16, v161
	v_and_b32_e32 v31, 0xffff0000, v161
	s_waitcnt vmcnt(4)
	v_lshlrev_b32_e32 v42, 16, v164
	v_and_b32_e32 v43, 0xffff0000, v164
	v_pk_mul_f32 v[24:25], v[24:25], v[40:41]
	v_lshlrev_b32_e32 v38, 16, v165
	v_and_b32_e32 v39, 0xffff0000, v165
	v_pk_mul_f32 v[26:27], v[26:27], v[30:31]
	v_pk_mul_f32 v[24:25], v[24:25], v[42:43]
	v_pk_mul_f32 v[26:27], v[26:27], v[38:39]
	v_cvt_pk_bf16_f32 v24, v24, v25
	v_cvt_pk_bf16_f32 v25, v26, v27
	global_store_dwordx2 v[162:163], v[24:25], off offset:2048
	s_nop 0
	s_nop 0
	s_nop 0
	s_nop 0
	s_nop 0
	s_waitcnt vmcnt(3)
	v_lshlrev_b32_e32 v30, 16, v170
	v_and_b32_e32 v31, 0xffff0000, v170
	v_lshlrev_b32_e32 v26, 16, v171
	v_and_b32_e32 v27, 0xffff0000, v171
	s_waitcnt vmcnt(2)
	v_lshlrev_b32_e32 v38, 16, v174
	v_and_b32_e32 v39, 0xffff0000, v174
	v_pk_mul_f32 v[20:21], v[20:21], v[30:31]
	v_lshlrev_b32_e32 v28, 16, v175
	v_and_b32_e32 v29, 0xffff0000, v175
	v_pk_mul_f32 v[22:23], v[22:23], v[26:27]
	v_pk_mul_f32 v[20:21], v[20:21], v[38:39]
	v_pk_mul_f32 v[22:23], v[22:23], v[28:29]
	v_cvt_pk_bf16_f32 v20, v20, v21
	v_cvt_pk_bf16_f32 v21, v22, v23
	global_store_dwordx2 v[172:173], v[20:21], off offset:2048
	s_nop 0
	s_nop 0
	s_nop 0
	s_nop 0
	s_nop 0
	s_waitcnt vmcnt(1)
	v_lshlrev_b32_e32 v26, 16, v180
	v_and_b32_e32 v27, 0xffff0000, v180
	v_lshlrev_b32_e32 v22, 16, v181
	v_and_b32_e32 v23, 0xffff0000, v181
	s_waitcnt vmcnt(0)
	v_lshlrev_b32_e32 v28, 16, v188
	v_and_b32_e32 v29, 0xffff0000, v188
	v_pk_mul_f32 v[16:17], v[16:17], v[26:27]
	v_lshlrev_b32_e32 v24, 16, v189
	v_and_b32_e32 v25, 0xffff0000, v189
	v_pk_mul_f32 v[18:19], v[18:19], v[22:23]
	v_pk_mul_f32 v[16:17], v[16:17], v[28:29]
	v_pk_mul_f32 v[18:19], v[18:19], v[24:25]
	v_cvt_pk_bf16_f32 v16, v16, v17
	v_cvt_pk_bf16_f32 v17, v18, v19
	global_store_dwordx2 v[186:187], v[16:17], off offset:2048
	v_mov_b32_e32 v20, v186
	v_mov_b32_e32 v21, v187
	v_mov_b32_e32 v32, v140
	v_mov_b32_e32 v34, v142
	v_mov_b32_e32 v35, v143
	v_mov_b32_e32 v36, v148
	v_mov_b32_e32 v37, v149
	v_mov_b32_e32 v65, v155
	v_mov_b32_e32 v67, v154
	v_mov_b32_e32 v69, v141
	v_mov_b32_e32 v182, v134
; DI float bflo(unsigned u) { return __uint_as_float(u << 16); }
; DI float bfhi(unsigned u) { return __uint_as_float(u & 0xffff0000u); }
; DI void st_bf4(u16* p, float a, float b, float c, float d) { *(uint2*)p = make_uint2(pk2(a, b), pk2(c, d)); }
;   template <int NT, int MT> DI void run(f32x4 (&acc)[NT][MT], int mb, int nb) const {
; #pragma unroll
;     for (int mt = 0; mt < MT; ++mt) {
;       const int i = mb + mt * 16;
;       if (i < nvalid) {
;         const float bias = bs[i];
;         const size_t row = (size_t)(rowbase + i);
; #pragma unroll
;         for (int nt = 0; nt < NT; ++nt) {
;           const int ch = g * 256 + nb + nt * 16;
;           const uint2 uu = *(const uint2*)(uv + row * 2048 + ch);
;           u16* q = mix + row * 2048 + 1024 + ch;
;           const uint2 gt = *(const uint2*)q;
;           f32x4 v = acc[nt][mt];
;           st_bf4(q, (v[0] + bias) * bflo(uu.x) * bflo(gt.x), (v[1] + bias) * bfhi(uu.x) * bfhi(gt.x),
;                  (v[2] + bias) * bflo(uu.y) * bflo(gt.y), (v[3] + bias) * bfhi(uu.y) * bfhi(gt.y));
;         }
;       }
.LBB0_1154:
	s_or_b64 exec, exec, s[42:43]
	v_or_b32_e32 v17, 48, v78
	v_cmp_gt_u32_e32 vcc, s8, v17
	s_and_saveexec_b64 s[42:43], vcc
	s_cbranch_execz .LBB0_1156
	v_mov_b32_e32 v135, v183
	v_add_u32_e32 v134, s7, v17
	v_readlane_b32 s8, v252, 33
	v_lshlrev_b64 v[136:137], 12, v[134:135]
	v_readlane_b32 s9, v252, 34
	v_lshlrev_b64 v[138:139], 1, v[70:71]
	global_load_dword v140, v73, s[40:41] offset:192
	v_lshl_add_u64 v[142:143], s[8:9], 0, v[136:137]
	v_readlane_b32 s8, v252, 35
	v_readlane_b32 s9, v252, 36
	v_lshl_add_u64 v[144:145], v[142:143], 0, v[138:139]
	global_load_dwordx2 v[146:147], v[144:145], off
	v_lshl_add_u64 v[148:149], s[8:9], 0, v[136:137]
	v_lshl_add_u64 v[150:151], v[148:149], 0, v[138:139]
	global_load_dwordx2 v[152:153], v[150:151], off offset:2048
	v_ashrrev_i32_e32 v141, 31, v68
	v_ashrrev_i32_e32 v154, 31, v66
	v_ashrrev_i32_e32 v155, 31, v64
	v_mov_b32_e32 v190, v68
	v_mov_b32_e32 v191, v141
	v_lshlrev_b64 v[156:157], 1, v[190:191]
	v_lshl_add_u64 v[158:159], v[142:143], 0, v[156:157]
	global_load_dwordx2 v[160:161], v[158:159], off
	v_lshl_add_u64 v[162:163], v[148:149], 0, v[156:157]
	global_load_dwordx2 v[164:165], v[162:163], off offset:2048
	v_mov_b32_e32 v192, v66
	v_mov_b32_e32 v193, v154
	v_lshlrev_b64 v[166:167], 1, v[192:193]
	v_lshl_add_u64 v[168:169], v[142:143], 0, v[166:167]
	global_load_dwordx2 v[170:171], v[168:169], off
	v_lshl_add_u64 v[172:173], v[148:149], 0, v[166:167]
	global_load_dwordx2 v[174:175], v[172:173], off offset:2048
	v_mov_b32_e32 v194, v64
	v_mov_b32_e32 v195, v155
	v_lshlrev_b64 v[176:177], 1, v[194:195]
	v_lshl_add_u64 v[178:179], v[142:143], 0, v[176:177]
	global_load_dwordx2 v[180:181], v[178:179], off
	v_lshl_add_u64 v[186:187], v[148:149], 0, v[176:177]
	global_load_dwordx2 v[188:189], v[186:187], off offset:2048
	s_nop 0
	s_nop 0
	s_nop 0
	s_nop 0
	s_nop 0
	s_nop 0
	s_nop 0
	s_nop 0
	s_nop 0
	s_nop 0
	s_nop 0
	s_nop 0
	s_nop 0
	s_nop 0
	s_nop 0
	s_nop 0
	s_nop 0
	s_waitcnt vmcnt(8)
	v_mov_b32_e32 v196, v140
	v_mov_b32_e32 v197, v17
	v_pk_add_f32 v[12:13], v[12:13], v[196:197] op_sel_hi:[1,0]
	v_mov_b32_e32 v224, v140
	v_mov_b32_e32 v225, v17
	v_pk_add_f32 v[14:15], v[14:15], v[224:225] op_sel_hi:[1,0]
	v_mov_b32_e32 v226, v140
	v_mov_b32_e32 v227, v17
	v_pk_add_f32 v[8:9], v[8:9], v[226:227] op_sel_hi:[1,0]
	v_mov_b32_e32 v228, v140
	v_mov_b32_e32 v229, v17
	v_pk_add_f32 v[10:11], v[10:11], v[228:229] op_sel_hi:[1,0]
	v_mov_b32_e32 v230, v140
	v_mov_b32_e32 v231, v17
	v_pk_add_f32 v[4:5], v[4:5], v[230:231] op_sel_hi:[1,0]
	s_waitcnt vmcnt(7)
	v_lshlrev_b32_e32 v28, 16, v146
	v_and_b32_e32 v29, 0xffff0000, v146
	v_lshlrev_b32_e32 v24, 16, v147
	v_and_b32_e32 v25, 0xffff0000, v147
	s_waitcnt vmcnt(6)
	v_lshlrev_b32_e32 v30, 16, v152
	v_and_b32_e32 v31, 0xffff0000, v152
	v_pk_mul_f32 v[12:13], v[12:13], v[28:29]
	v_lshlrev_b32_e32 v26, 16, v153
	v_and_b32_e32 v27, 0xffff0000, v153
	v_pk_mul_f32 v[14:15], v[14:15], v[24:25]
	v_pk_mul_f32 v[12:13], v[12:13], v[30:31]
	v_pk_mul_f32 v[14:15], v[14:15], v[26:27]
	v_cvt_pk_bf16_f32 v12, v12, v13
	v_cvt_pk_bf16_f32 v13, v14, v15
	global_store_dwordx2 v[150:151], v[12:13], off offset:2048
	s_nop 0
	s_nop 0
	s_nop 0
	s_nop 0
	s_nop 0
	v_mov_b32_e32 v232, v140
	v_mov_b32_e32 v233, v17
	v_pk_add_f32 v[6:7], v[6:7], v[232:233] op_sel_hi:[1,0]
	v_mov_b32_e32 v234, v140
	v_mov_b32_e32 v235, v17
	v_pk_add_f32 v[0:1], v[0:1], v[234:235] op_sel_hi:[1,0]
	v_mov_b32_e32 v236, v140
	v_mov_b32_e32 v237, v17
	v_pk_add_f32 v[2:3], v[2:3], v[236:237] op_sel_hi:[1,0]
	s_waitcnt vmcnt(5)
	v_lshlrev_b32_e32 v24, 16, v160
	v_and_b32_e32 v25, 0xffff0000, v160
	v_lshlrev_b32_e32 v14, 16, v161
	v_and_b32_e32 v15, 0xffff0000, v161
	s_waitcnt vmcnt(4)
	v_lshlrev_b32_e32 v26, 16, v164
	v_and_b32_e32 v27, 0xffff0000, v164
	v_pk_mul_f32 v[8:9], v[8:9], v[24:25]
	v_lshlrev_b32_e32 v22, 16, v165
	v_and_b32_e32 v23, 0xffff0000, v165
	v_pk_mul_f32 v[10:11], v[10:11], v[14:15]
	v_pk_mul_f32 v[8:9], v[8:9], v[26:27]
	v_pk_mul_f32 v[10:11], v[10:11], v[22:23]
	v_cvt_pk_bf16_f32 v8, v8, v9
	v_cvt_pk_bf16_f32 v9, v10, v11
	global_store_dwordx2 v[162:163], v[8:9], off offset:2048
	s_nop 0
	s_nop 0
	s_nop 0
	s_nop 0
	s_nop 0
	s_waitcnt vmcnt(3)
	v_lshlrev_b32_e32 v14, 16, v170
	v_and_b32_e32 v15, 0xffff0000, v170
	v_lshlrev_b32_e32 v10, 16, v171
	v_and_b32_e32 v11, 0xffff0000, v171
	s_waitcnt vmcnt(2)
	v_lshlrev_b32_e32 v22, 16, v174
	v_and_b32_e32 v23, 0xffff0000, v174
	v_pk_mul_f32 v[4:5], v[4:5], v[14:15]
	v_lshlrev_b32_e32 v12, 16, v175
	v_and_b32_e32 v13, 0xffff0000, v175
	v_pk_mul_f32 v[6:7], v[6:7], v[10:11]
	v_pk_mul_f32 v[4:5], v[4:5], v[22:23]
	v_pk_mul_f32 v[6:7], v[6:7], v[12:13]
	v_cvt_pk_bf16_f32 v4, v4, v5
	v_cvt_pk_bf16_f32 v5, v6, v7
	global_store_dwordx2 v[172:173], v[4:5], off offset:2048
	s_nop 0
	s_nop 0
	s_nop 0
	s_nop 0
	s_nop 0
	s_waitcnt vmcnt(1)
	v_lshlrev_b32_e32 v10, 16, v180
	v_and_b32_e32 v11, 0xffff0000, v180
	v_lshlrev_b32_e32 v6, 16, v181
	v_and_b32_e32 v7, 0xffff0000, v181
	s_waitcnt vmcnt(0)
	v_lshlrev_b32_e32 v12, 16, v188
	v_and_b32_e32 v13, 0xffff0000, v188
	v_pk_mul_f32 v[0:1], v[0:1], v[10:11]
	v_lshlrev_b32_e32 v8, 16, v189
	v_and_b32_e32 v9, 0xffff0000, v189
	v_pk_mul_f32 v[2:3], v[2:3], v[6:7]
	v_pk_mul_f32 v[0:1], v[0:1], v[12:13]
	v_pk_mul_f32 v[2:3], v[2:3], v[8:9]
	v_cvt_pk_bf16_f32 v0, v0, v1
	v_cvt_pk_bf16_f32 v1, v2, v3
	global_store_dwordx2 v[186:187], v[0:1], off offset:2048
	v_mov_b32_e32 v4, v186
	v_mov_b32_e32 v5, v187
	v_mov_b32_e32 v16, v140
	v_mov_b32_e32 v18, v142
	v_mov_b32_e32 v19, v143
	v_mov_b32_e32 v20, v148
	v_mov_b32_e32 v21, v149
	v_mov_b32_e32 v65, v155
	v_mov_b32_e32 v67, v154
	v_mov_b32_e32 v69, v141
	v_mov_b32_e32 v182, v134

; template <int MT, class Epi>
; DI void gemm_tile(const u16* __restrict__ X, long ldx, const u16* __restrict__ W, long ldw, int K, char* smem,
;                   int m0, int n0, const Epi& epi, bool pre = false, const u16* Xn = nullptr, const u16* Wn = nullptr) {
;     ...
;   const int r8 = lane >> 3, c0 = (lane & 7) ^ (r8 >> 1);
;   const long oxe = (long)(wu * MT * 8 + r8) * ldx + (c0 << 3), oxo = (long)(wu * MT * 8 + r8) * ldx + ((c0 ^ 4) << 3);
;   const long owe = (long)(wu * 32 + r8) * ldw + (c0 << 3), owo = (long)(wu * 32 + r8) * ldw + ((c0 ^ 4) << 3);
;   const u16 *xe = X + oxe, *xo = X + oxo, *we = W + owe, *wo = W + owo;
;   const long ldx8 = 8 * ldx, ldw8 = 8 * ldw;
;   const unsigned xdst = sbase + wu * MT * 1024, wdst = sbase + 16384 + wu * 4096;
;     ...
;   if (!pre) {
;     __syncthreads();
;     GT_DMA(0u)
;   } else {
;     xe += 64; xo += 64; we += 64; wo += 64;
;   }
;   const int nk = K >> 6;
;   int kt = 0;
;   do {
;     asm volatile("s_waitcnt vmcnt(0)" ::: "memory");
;     __syncthreads();
;     if (kt + 1 < nk) GT_DMA((unsigned)((kt + 1) & 1) * 32768u)
;     else if (Xn != nullptr) { xe = Xn + oxe; xo = Xn + oxo; we = Wn + owe; wo = Wn + owo; GT_DMA(0u) }
;     const char* cur = smem + (kt & 1) * 32768;
; #pragma unroll
;     for (int ks = 0; ks < 2; ++ks) {
;       bf16x8 xf[MT], wf[4];
;       const int ch = ((ks * 4 + g) ^ rsw) << 4;
; #pragma unroll
;       for (int i = 0; i < MT; ++i) xf[i] = *(const bf16x8*)(cur + (wm * 16 * MT + i * 16 + lr) * 128 + ch);
; #pragma unroll
;       for (int i = 0; i < 4; ++i) wf[i] = *(const bf16x8*)(cur + 16384 + (wn * 64 + i * 16 + lr) * 128 + ch);
; DI void phase_even(const Params& p, int e, int sub, char* smem) {
;     ...
;       if (t < 1056) {
;         const int g = t / 264, r = t % 264, tm = r >> 1, tn = r & 1;
;         EpiPool epi{p.pool_scale + e * 1024, gbuf, g};
;         gemm_tile<4>(hbuf + (size_t)tm * 128 * 1024 + g * 256, 1024, W + WE_POOL + (size_t)g * 65536 + (size_t)tn * 128 * 256, 256, 256, smem,
;                      tm * 128, tn * 128, epi);
.LBB0_1157:
	s_and_b64 vcc, exec, s[40:41]
	s_cbranch_vccz .LBB0_1146
	s_mul_hi_i32 s7, s4, 0x3e0f83e1
	s_lshr_b32 s8, s7, 31
	s_ashr_i32 s7, s7, 6
	s_add_i32 s8, s7, s8
	s_mul_i32 s7, s8, 0xfffffef8
	s_add_i32 s7, s4, s7
	s_ashr_i32 s10, s7, 1
	s_ashr_i32 s11, s10, 31
	s_and_b32 s16, s7, 1
	s_lshl_b64 s[12:13], s[10:11], 18
	s_add_u32 s7, s0, s12
	s_addc_u32 s9, s1, s13
	s_lshl_b32 s40, s8, 8
	s_ashr_i32 s41, s40, 31
	s_lshl_b64 s[12:13], s[40:41], 1
	s_add_u32 s12, s7, s12
	s_addc_u32 s13, s9, s13
	s_ashr_i32 s9, s8, 31
	s_lshl_b64 s[8:9], s[8:9], 17
	v_readlane_b32 s7, v252, 43
	s_add_u32 s7, s7, s8
	v_readlane_b32 s8, v252, 44
	s_waitcnt vmcnt(7)
	v_mov_b32_e32 v16, v185
	s_addc_u32 s8, s8, s9
	s_lshl_b32 s9, s16, 16
	s_add_u32 s14, s7, s9
	v_ashrrev_i32_e32 v0, 6, v16
	v_and_b32_e32 v53, 1, v0
	v_readfirstlane_b32 s9, v0
	v_bfe_u32 v0, v16, 3, 3
	v_bfe_u32 v54, v16, 4, 2
	v_lshl_or_b32 v0, s9, 5, v0
	v_bitop3_b32 v4, v54, v16, 7 bitop3:0x78
	v_ashrrev_i32_e32 v1, 31, v0
	v_lshlrev_b64 v[2:3], 11, v[0:1]
	v_lshlrev_b32_e32 v182, 4, v4
	v_mov_b32_e32 v10, v183
	v_lshl_add_u64 v[2:3], s[12:13], 0, v[2:3]
	v_xor_b32_e32 v6, 64, v182
	v_mov_b32_e32 v7, v183
	s_addc_u32 s15, s8, 0
	s_lshl_b32 s7, s10, 7
	v_lshl_add_u64 v[4:5], v[2:3], 0, v[182:183]
	v_lshl_add_u64 v[2:3], v[2:3], 0, v[6:7]
	s_lshl_b32 s41, s9, 12
	s_waitcnt lgkmcnt(0)
	s_barrier
	s_mov_b32 s9, m0
	s_mov_b32 m0, s41
	s_nop 0
	global_load_lds_dwordx4 v[4:5], off
	s_mov_b32 m0, s9
	s_mov_b64 s[10:11], 0x4000
	v_lshl_add_u64 v[14:15], v[2:3], 0, s[10:11]
	s_or_b32 s44, s41, 0x400
	s_mov_b32 s9, m0
	s_mov_b32 m0, s44
	s_nop 0
	global_load_lds_dwordx4 v[14:15], off
	s_mov_b32 m0, s9
	s_mov_b64 s[10:11], 0x8000
	v_lshlrev_b64 v[0:1], 9, v[0:1]
	v_lshl_add_u64 v[14:15], v[4:5], 0, s[10:11]
	s_or_b32 s42, s41, 0x800
	s_mov_b32 s9, m0
	s_mov_b32 m0, s42
	s_nop 0
	global_load_lds_dwordx4 v[14:15], off
	s_mov_b32 m0, s9
	s_mov_b64 s[10:11], 0xc000
	v_lshl_add_u64 v[8:9], s[14:15], 0, v[0:1]
	v_lshl_add_u64 v[14:15], v[2:3], 0, s[10:11]
	s_or_b32 s17, s41, 0xc00
	s_mov_b32 s9, m0
	s_mov_b32 m0, s17
	s_nop 0
	global_load_lds_dwordx4 v[14:15], off
	s_mov_b32 m0, s9
	v_lshl_add_u64 v[0:1], v[8:9], 0, v[182:183]
	v_lshl_add_u64 v[6:7], v[8:9], 0, v[6:7]
	s_add_i32 s18, s41, 0x4000
	s_mov_b32 s9, m0
	s_mov_b32 m0, s18
	s_nop 0
	global_load_lds_dwordx4 v[0:1], off
	s_mov_b32 m0, s9
	s_mov_b64 s[10:11], 0x1000
	v_lshl_add_u64 v[8:9], v[6:7], 0, s[10:11]
	s_add_i32 s19, s41, 0x4400
	s_mov_b32 s9, m0
	s_mov_b32 m0, s19
	s_nop 0
	global_load_lds_dwordx4 v[8:9], off
	s_mov_b32 m0, s9
	s_mov_b64 s[10:11], 0x2000
	v_lshl_add_u64 v[8:9], v[0:1], 0, s[10:11]
	s_add_i32 s34, s41, 0x4800
	s_mov_b32 s9, m0
	s_mov_b32 m0, s34
	s_nop 0
	global_load_lds_dwordx4 v[8:9], off
	s_mov_b32 m0, s9
	s_mov_b64 s[10:11], 0x3000
	v_lshl_add_u64 v[8:9], v[6:7], 0, s[10:11]
	s_add_i32 s43, s41, 0x4c00
	s_mov_b32 s9, m0
	s_mov_b32 m0, s43
	s_nop 0
	global_load_lds_dwordx4 v[8:9], off
	s_mov_b32 m0, s9
	s_waitcnt vmcnt(0)
	s_barrier
	v_lshl_add_u64 v[8:9], v[4:5], 0, s[28:29]
	s_add_i32 s14, s41, 0x8000
	s_mov_b32 s9, m0
	s_mov_b32 m0, s14
	s_nop 0
	global_load_lds_dwordx4 v[8:9], off
	s_mov_b32 m0, s9
	v_lshl_add_u64 v[8:9], v[2:3], 0, s[94:95]
	s_add_i32 s11, s41, 0x8400
	s_mov_b32 s9, m0
	s_mov_b32 m0, s11
	s_nop 0
	global_load_lds_dwordx4 v[8:9], off
	s_mov_b32 m0, s9
	v_lshl_add_u64 v[8:9], v[4:5], 0, s[78:79]
	s_add_i32 s9, s41, 0x8800
	s_mov_b32 s10, m0
	s_mov_b32 m0, s9
	s_nop 0
	global_load_lds_dwordx4 v[8:9], off
	s_mov_b32 m0, s10
	v_lshl_add_u64 v[8:9], v[2:3], 0, s[54:55]
	s_add_i32 s12, s41, 0x8c00
	s_mov_b32 s10, m0
	s_mov_b32 m0, s12
	s_nop 0
	global_load_lds_dwordx4 v[8:9], off
	s_mov_b32 m0, s10
	s_mov_b64 s[20:21], 0x1080
	v_lshl_add_u64 v[14:15], v[0:1], 0, s[28:29]
	s_add_i32 s10, s41, 0xc000
	s_mov_b32 s13, m0
	s_mov_b32 m0, s10
	s_nop 0
	global_load_lds_dwordx4 v[14:15], off
	s_mov_b32 m0, s13
	v_lshl_add_u64 v[8:9], v[6:7], 0, s[20:21]
	s_mov_b64 s[20:21], 0x2080
	s_add_i32 s15, s41, 0xc400
	s_mov_b32 s13, m0
	s_mov_b32 m0, s15
	s_nop 0
	global_load_lds_dwordx4 v[8:9], off
	s_mov_b32 m0, s13
	v_lshl_add_u64 v[8:9], v[0:1], 0, s[20:21]
	s_mov_b64 s[20:21], 0x3080
	s_lshl_b32 s8, s16, 7
	v_lshrrev_b32_e32 v17, 1, v16
	s_add_i32 s13, s41, 0xc800
	s_mov_b32 s16, m0
	s_mov_b32 m0, s13
	s_nop 0
	global_load_lds_dwordx4 v[8:9], off
	s_mov_b32 m0, s16
	v_lshl_add_u64 v[8:9], v[6:7], 0, s[20:21]
	v_and_b32_e32 v52, 15, v16
	v_ashrrev_i32_e32 v55, 7, v16
	s_add_i32 s16, s41, 0xcc00
	s_mov_b32 s45, m0
	s_mov_b32 m0, s16
	s_nop 0
	global_load_lds_dwordx4 v[8:9], off
	s_mov_b32 m0, s45
	v_bitop3_b32 v8, v54, v17, 7 bitop3:0x78
	v_lshlrev_b32_e32 v9, 4, v8
	v_lshlrev_b32_e32 v89, 13, v53
	s_waitcnt vmcnt(1)
	v_lshlrev_b32_e32 v100, 7, v52
	v_lshlrev_b32_e32 v101, 13, v55
	v_or3_b32 v8, v9, v89, v100
	v_or3_b32 v9, v9, v101, v100
	v_bfe_u32 v88, v16, 1, 3
	ds_read_b128 v[14:17], v8
	ds_read_b128 v[18:21], v8 offset:2048
	ds_read_b128 v[22:25], v8 offset:4096
	ds_read_b128 v[26:29], v8 offset:6144
	ds_read_b128 v[30:33], v9 offset:16384
	ds_read_b128 v[34:37], v9 offset:18432
	ds_read_b128 v[38:41], v9 offset:20480
	ds_read_b128 v[42:45], v9 offset:22528
	v_mov_b32_e32 v11, v10
	v_mov_b32_e32 v12, v10
	v_mov_b32_e32 v13, v10
	s_mov_b64 s[20:21], 0x100
	v_lshl_add_u64 v[50:51], v[4:5], 0, s[20:21]
	s_waitcnt lgkmcnt(3)
; template <int MT, class Epi>
; DI void gemm_tile(const u16* __restrict__ X, long ldx, const u16* __restrict__ W, long ldw, int K, char* smem,
;                   int m0, int n0, const Epi& epi, bool pre = false, const u16* Xn = nullptr, const u16* Wn = nullptr) {
;     ...
;   do {
;     asm volatile("s_waitcnt vmcnt(0)" ::: "memory");
;     __syncthreads();
;     if (kt + 1 < nk) GT_DMA((unsigned)((kt + 1) & 1) * 32768u)
;     else if (Xn != nullptr) { xe = Xn + oxe; xo = Xn + oxo; we = Wn + owe; wo = Wn + owo; GT_DMA(0u) }
;     const char* cur = smem + (kt & 1) * 32768;
; #pragma unroll
;     for (int ks = 0; ks < 2; ++ks) {
;       bf16x8 xf[MT], wf[4];
;       const int ch = ((ks * 4 + g) ^ rsw) << 4;
; #pragma unroll
;       for (int i = 0; i < MT; ++i) xf[i] = *(const bf16x8*)(cur + (wm * 16 * MT + i * 16 + lr) * 128 + ch);
; #pragma unroll
;       for (int i = 0; i < 4; ++i) wf[i] = *(const bf16x8*)(cur + 16384 + (wn * 64 + i * 16 + lr) * 128 + ch);
; #pragma unroll
;       for (int nt = 0; nt < 4; ++nt)
; #pragma unroll
;         for (int mt = 0; mt < MT; ++mt)
;           acc[nt][mt] = __builtin_amdgcn_mfma_f32_16x16x32_bf16(wf[nt], xf[mt], acc[nt][mt], 0, 0, 0);
;     }
;   } while (++kt < nk);
	v_mfma_f32_16x16x32_bf16 v[46:49], v[30:33], v[14:17], v[10:13]
	v_lshl_add_u64 v[116:117], v[0:1], 0, s[20:21]
	s_mov_b64 s[20:21], 0x4100
	v_lshlrev_b32_e32 v53, 6, v53
	v_mfma_f32_16x16x32_bf16 v[56:59], v[30:33], v[18:21], v[10:13]
	v_readlane_b32 s56, v252, 8
	v_readlane_b32 s58, v252, 10
	v_readlane_b32 s59, v252, 11
	v_mfma_f32_16x16x32_bf16 v[60:63], v[30:33], v[22:25], v[10:13]
	v_readlane_b32 s64, v252, 16
	v_readlane_b32 s65, v252, 17
	v_readlane_b32 s66, v252, 18
	v_mfma_f32_16x16x32_bf16 v[30:33], v[30:33], v[26:29], v[10:13]
	v_readlane_b32 s67, v252, 19
	v_readlane_b32 s68, v252, 20
	v_readlane_b32 s69, v252, 21
	s_waitcnt lgkmcnt(2)
	v_mfma_f32_16x16x32_bf16 v[64:67], v[34:37], v[14:17], v[10:13]
	v_readlane_b32 s70, v252, 22
	v_readlane_b32 s71, v252, 23
	s_mov_b32 s65, 0x2aaaaaab
	v_mfma_f32_16x16x32_bf16 v[68:71], v[34:37], v[18:21], v[10:13]
	s_mov_b64 s[66:67], 0x5a8080
	s_movk_i32 s64, 0x41ff
	s_mov_b64 s[70:71], s[26:27]
	v_mfma_f32_16x16x32_bf16 v[72:75], v[34:37], v[22:25], v[10:13]
	s_mov_b64 s[68:69], s[24:25]
	v_readlane_b32 s57, v252, 9
	v_readlane_b32 s60, v252, 12
	v_mfma_f32_16x16x32_bf16 v[34:37], v[34:37], v[26:29], v[10:13]
	v_readlane_b32 s61, v252, 13
	v_readlane_b32 s62, v252, 14
	v_readlane_b32 s63, v252, 15
	s_waitcnt lgkmcnt(1)
	v_mfma_f32_16x16x32_bf16 v[76:79], v[38:41], v[14:17], v[10:13]
	v_mfma_f32_16x16x32_bf16 v[80:83], v[38:41], v[18:21], v[10:13]
	v_mfma_f32_16x16x32_bf16 v[84:87], v[38:41], v[22:25], v[10:13]
	v_mfma_f32_16x16x32_bf16 v[38:41], v[38:41], v[26:29], v[10:13]
	s_waitcnt lgkmcnt(0)
	v_mfma_f32_16x16x32_bf16 v[14:17], v[42:45], v[14:17], v[10:13]
	v_mfma_f32_16x16x32_bf16 v[18:21], v[42:45], v[18:21], v[10:13]
	v_mfma_f32_16x16x32_bf16 v[22:25], v[42:45], v[22:25], v[10:13]
	v_mfma_f32_16x16x32_bf16 v[26:29], v[42:45], v[26:29], v[10:13]
	s_nop 2
	v_bitop3_b32 v10, v54, v88, 4 bitop3:0x36
	v_lshlrev_b32_e32 v11, 4, v10
	v_or_b32_e32 v10, v11, v89
	v_or_b32_e32 v11, v11, v101
	v_add_u32_e32 v10, v10, v100
	v_add_u32_e32 v11, v11, v100
	ds_read_b128 v[42:45], v10
	ds_read_b128 v[88:91], v10 offset:2048
	ds_read_b128 v[92:95], v10 offset:4096
	s_waitcnt vmcnt(0)
	ds_read_b128 v[96:99], v10 offset:6144
	ds_read_b128 v[100:103], v11 offset:16384
	ds_read_b128 v[104:107], v11 offset:18432
	ds_read_b128 v[108:111], v11 offset:20480
	ds_read_b128 v[112:115], v11 offset:22528
	s_waitcnt vmcnt(0)
	s_waitcnt lgkmcnt(0)
	s_barrier
	s_mov_b32 s45, m0
	s_mov_b32 m0, s41
	s_nop 0
	global_load_lds_dwordx4 v[50:51], off
	s_mov_b32 m0, s45
	v_mfma_f32_16x16x32_bf16 v[12:15], v[112:115], v[42:45], v[14:17]
	v_mfma_f32_16x16x32_bf16 v[16:19], v[112:115], v[88:91], v[18:21]
	v_mfma_f32_16x16x32_bf16 v[20:23], v[112:115], v[92:95], v[22:25]
	v_mfma_f32_16x16x32_bf16 v[24:27], v[112:115], v[96:99], v[26:29]
	s_nop 2
	v_lshl_add_u64 v[28:29], v[2:3], 0, s[20:21]
	s_mov_b32 s41, m0
	s_mov_b32 m0, s44
	s_nop 0
	global_load_lds_dwordx4 v[28:29], off
	s_mov_b32 m0, s41
	s_mov_b64 s[20:21], 0x8100
	v_lshl_add_u64 v[28:29], v[4:5], 0, s[20:21]
	s_mov_b32 s41, m0
	s_mov_b32 m0, s42
	s_nop 0
	global_load_lds_dwordx4 v[28:29], off
	s_mov_b32 m0, s41
	s_mov_b64 s[20:21], 0xc100
	v_lshl_add_u64 v[28:29], v[2:3], 0, s[20:21]
	s_mov_b32 s41, m0
	s_mov_b32 m0, s17
	s_nop 0
	global_load_lds_dwordx4 v[28:29], off
	s_mov_b32 m0, s41
	s_mov_b32 s17, m0
	s_mov_b32 m0, s18
	s_nop 0
	global_load_lds_dwordx4 v[116:117], off
	s_mov_b32 m0, s17
	s_mov_b64 s[20:21], 0x1100
	v_lshl_add_u64 v[28:29], v[6:7], 0, s[20:21]
	s_mov_b32 s17, m0
	s_mov_b32 m0, s19
	s_nop 0
	global_load_lds_dwordx4 v[28:29], off
	s_mov_b32 m0, s17
	s_mov_b64 s[18:19], 0x2100
	v_lshl_add_u64 v[28:29], v[0:1], 0, s[18:19]
	s_mov_b32 s17, m0
	s_mov_b32 m0, s34
	s_nop 0
	global_load_lds_dwordx4 v[28:29], off
	s_mov_b32 m0, s17
	s_mov_b64 s[18:19], 0x3100
	v_lshl_add_u64 v[28:29], v[6:7], 0, s[18:19]
	s_mov_b32 s17, m0
	s_mov_b32 m0, s43
	s_nop 0
	global_load_lds_dwordx4 v[28:29], off
	s_mov_b32 m0, s17
	v_mfma_f32_16x16x32_bf16 v[46:49], v[100:103], v[42:45], v[46:49]
	s_mov_b64 s[18:19], 0x180
	v_lshl_add_u64 v[116:117], v[4:5], 0, s[18:19]
	v_lshl_add_u64 v[118:119], v[0:1], 0, s[18:19]
	v_mfma_f32_16x16x32_bf16 v[56:59], v[100:103], v[88:91], v[56:59]
	s_mov_b64 s[18:19], 0x4180
	v_mfma_f32_16x16x32_bf16 v[60:63], v[100:103], v[92:95], v[60:63]
	v_mfma_f32_16x16x32_bf16 v[30:33], v[100:103], v[96:99], v[30:33]
	v_mfma_f32_16x16x32_bf16 v[64:67], v[104:107], v[42:45], v[64:67]
	v_mfma_f32_16x16x32_bf16 v[68:71], v[104:107], v[88:91], v[68:71]
	v_mfma_f32_16x16x32_bf16 v[72:75], v[104:107], v[92:95], v[72:75]
	v_mfma_f32_16x16x32_bf16 v[34:37], v[104:107], v[96:99], v[34:37]
	v_mfma_f32_16x16x32_bf16 v[76:79], v[108:111], v[42:45], v[76:79]
	v_mfma_f32_16x16x32_bf16 v[80:83], v[108:111], v[88:91], v[80:83]
	v_mfma_f32_16x16x32_bf16 v[84:87], v[108:111], v[92:95], v[84:87]
	v_mfma_f32_16x16x32_bf16 v[38:41], v[108:111], v[96:99], v[38:41]
	ds_read_b128 v[42:45], v8 offset:32768
	ds_read_b128 v[88:91], v8 offset:34816
	ds_read_b128 v[92:95], v8 offset:36864
	ds_read_b128 v[96:99], v8 offset:38912
	ds_read_b128 v[100:103], v9 offset:49152
	ds_read_b128 v[104:107], v9 offset:51200
	ds_read_b128 v[108:111], v9 offset:53248
	ds_read_b128 v[112:115], v9 offset:55296
	s_waitcnt lgkmcnt(3)
	v_mfma_f32_16x16x32_bf16 v[46:49], v[100:103], v[42:45], v[46:49]
	v_mfma_f32_16x16x32_bf16 v[56:59], v[100:103], v[88:91], v[56:59]
	v_mfma_f32_16x16x32_bf16 v[60:63], v[100:103], v[92:95], v[60:63]
	v_mfma_f32_16x16x32_bf16 v[28:31], v[100:103], v[96:99], v[30:33]
	s_waitcnt lgkmcnt(2)
	v_mfma_f32_16x16x32_bf16 v[64:67], v[104:107], v[42:45], v[64:67]
	v_mfma_f32_16x16x32_bf16 v[68:71], v[104:107], v[88:91], v[68:71]
	v_mfma_f32_16x16x32_bf16 v[72:75], v[104:107], v[92:95], v[72:75]
	v_mfma_f32_16x16x32_bf16 v[32:35], v[104:107], v[96:99], v[34:37]
	s_waitcnt lgkmcnt(1)
	v_mfma_f32_16x16x32_bf16 v[76:79], v[108:111], v[42:45], v[76:79]
	v_mfma_f32_16x16x32_bf16 v[80:83], v[108:111], v[88:91], v[80:83]
	v_mfma_f32_16x16x32_bf16 v[84:87], v[108:111], v[92:95], v[84:87]
	v_mfma_f32_16x16x32_bf16 v[36:39], v[108:111], v[96:99], v[38:41]
	s_waitcnt lgkmcnt(0)
	v_mfma_f32_16x16x32_bf16 v[12:15], v[112:115], v[42:45], v[12:15]
	v_mfma_f32_16x16x32_bf16 v[16:19], v[112:115], v[88:91], v[16:19]
	v_mfma_f32_16x16x32_bf16 v[20:23], v[112:115], v[92:95], v[20:23]
	v_mfma_f32_16x16x32_bf16 v[24:27], v[112:115], v[96:99], v[24:27]
	ds_read_b128 v[40:43], v10 offset:32768
	ds_read_b128 v[88:91], v10 offset:34816
	ds_read_b128 v[92:95], v10 offset:36864
	ds_read_b128 v[96:99], v10 offset:38912
	ds_read_b128 v[100:103], v11 offset:49152
	ds_read_b128 v[104:107], v11 offset:51200
	ds_read_b128 v[108:111], v11 offset:53248
	ds_read_b128 v[112:115], v11 offset:55296
	s_waitcnt vmcnt(0)
	s_waitcnt lgkmcnt(0)
	s_barrier
; DI float bflo(unsigned u) { return __uint_as_float(u << 16); }
; DI float bfhi(unsigned u) { return __uint_as_float(u & 0xffff0000u); }
; DI void st_bf4(u16* p, float a, float b, float c, float d) { *(uint2*)p = make_uint2(pk2(a, b), pk2(c, d)); }
; template <int MT, class Epi>
; DI void gemm_tile(const u16* __restrict__ X, long ldx, const u16* __restrict__ W, long ldw, int K, char* smem,
;                   int m0, int n0, const Epi& epi, bool pre = false, const u16* Xn = nullptr, const u16* Wn = nullptr) {
;     ...
;   do {
;     asm volatile("s_waitcnt vmcnt(0)" ::: "memory");
;     __syncthreads();
;     if (kt + 1 < nk) GT_DMA((unsigned)((kt + 1) & 1) * 32768u)
;     else if (Xn != nullptr) { xe = Xn + oxe; xo = Xn + oxo; we = Wn + owe; wo = Wn + owo; GT_DMA(0u) }
;     const char* cur = smem + (kt & 1) * 32768;
; #pragma unroll
;     for (int ks = 0; ks < 2; ++ks) {
;       bf16x8 xf[MT], wf[4];
;       const int ch = ((ks * 4 + g) ^ rsw) << 4;
; #pragma unroll
;       for (int i = 0; i < MT; ++i) xf[i] = *(const bf16x8*)(cur + (wm * 16 * MT + i * 16 + lr) * 128 + ch);
; #pragma unroll
;       for (int i = 0; i < 4; ++i) wf[i] = *(const bf16x8*)(cur + 16384 + (wn * 64 + i * 16 + lr) * 128 + ch);
; #pragma unroll
;       for (int nt = 0; nt < 4; ++nt)
; #pragma unroll
;         for (int mt = 0; mt < MT; ++mt)
;           acc[nt][mt] = __builtin_amdgcn_mfma_f32_16x16x32_bf16(wf[nt], xf[mt], acc[nt][mt], 0, 0, 0);
;   template <int NT, int MT> DI void run(f32x4 (&acc)[NT][MT], int mb, int nb) const {
; #pragma unroll
;     for (int nt = 0; nt < NT; ++nt) {
;       const int ch = g * 256 + nb + nt * 16;
;       const float4 sc = *(const float4*)(scale + ch);
; #pragma unroll
;       for (int mt = 0; mt < MT; ++mt) {
;         const int m = mb + mt * 16;
;         u16* q = mix + (size_t)m * 2048 + ch;
;         const uint2 gt = *(const uint2*)q;
;         f32x4 v = acc[nt][mt];
;         st_bf4(q, v[0] * sc.x * bflo(gt.x), v[1] * sc.y * bfhi(gt.x), v[2] * sc.z * bflo(gt.y), v[3] * sc.w * bfhi(gt.y));
	s_mov_b32 s17, m0
	s_mov_b32 m0, s14
	s_nop 0
	global_load_lds_dwordx4 v[116:117], off
	s_mov_b32 m0, s17
	v_mfma_f32_16x16x32_bf16 v[44:47], v[100:103], v[40:43], v[46:49]
	v_mfma_f32_16x16x32_bf16 v[48:51], v[100:103], v[88:91], v[56:59]
	v_mfma_f32_16x16x32_bf16 v[56:59], v[100:103], v[92:95], v[60:63]
	v_mfma_f32_16x16x32_bf16 v[60:63], v[104:107], v[40:43], v[64:67]
	v_mfma_f32_16x16x32_bf16 v[64:67], v[104:107], v[88:91], v[68:71]
	v_mfma_f32_16x16x32_bf16 v[68:71], v[104:107], v[92:95], v[72:75]
	v_mfma_f32_16x16x32_bf16 v[72:75], v[108:111], v[40:43], v[76:79]
	v_mfma_f32_16x16x32_bf16 v[12:15], v[112:115], v[40:43], v[12:15]
	v_lshl_add_u64 v[40:41], v[2:3], 0, s[18:19]
	s_mov_b32 s14, m0
	s_mov_b32 m0, s11
	s_nop 0
	global_load_lds_dwordx4 v[40:41], off
	s_mov_b32 m0, s14
	s_mov_b64 s[18:19], 0x8180
	v_lshl_add_u64 v[4:5], v[4:5], 0, s[18:19]
	s_mov_b32 s11, m0
	s_mov_b32 m0, s9
	s_nop 0
	global_load_lds_dwordx4 v[4:5], off
	s_mov_b32 m0, s11
	s_mov_b64 s[18:19], 0xc180
	v_lshl_add_u64 v[2:3], v[2:3], 0, s[18:19]
	s_mov_b32 s9, m0
	s_mov_b32 m0, s12
	s_nop 0
	global_load_lds_dwordx4 v[2:3], off
	s_mov_b32 m0, s9
	v_mfma_f32_16x16x32_bf16 v[28:31], v[100:103], v[96:99], v[28:31]
	s_mov_b32 s9, m0
	s_mov_b32 m0, s10
	s_nop 0
	global_load_lds_dwordx4 v[118:119], off
	s_mov_b32 m0, s9
	s_mov_b64 s[10:11], 0x1180
	v_lshl_add_u64 v[2:3], v[6:7], 0, s[10:11]
	s_mov_b32 s9, m0
	s_mov_b32 m0, s15
	s_nop 0
	global_load_lds_dwordx4 v[2:3], off
	s_mov_b32 m0, s9
	s_mov_b64 s[10:11], 0x2180
	v_lshl_add_u64 v[0:1], v[0:1], 0, s[10:11]
	s_mov_b32 s9, m0
	s_mov_b32 m0, s13
	s_nop 0
	global_load_lds_dwordx4 v[0:1], off
	s_mov_b32 m0, s9
	s_mov_b64 s[10:11], 0x3180
	v_lshl_add_u64 v[0:1], v[6:7], 0, s[10:11]
	s_mov_b32 s9, m0
	s_mov_b32 m0, s16
	s_nop 0
	global_load_lds_dwordx4 v[0:1], off
	s_mov_b32 m0, s9
	v_mfma_f32_16x16x32_bf16 v[32:35], v[104:107], v[96:99], v[32:35]
	v_mfma_f32_16x16x32_bf16 v[76:79], v[108:111], v[88:91], v[80:83]
	v_mfma_f32_16x16x32_bf16 v[80:83], v[108:111], v[92:95], v[84:87]
	v_mfma_f32_16x16x32_bf16 v[36:39], v[108:111], v[96:99], v[36:39]
	v_mfma_f32_16x16x32_bf16 v[16:19], v[112:115], v[88:91], v[16:19]
	v_mfma_f32_16x16x32_bf16 v[20:23], v[112:115], v[92:95], v[20:23]
	v_mfma_f32_16x16x32_bf16 v[24:27], v[112:115], v[96:99], v[24:27]
	ds_read_b128 v[0:3], v8
	ds_read_b128 v[4:7], v8 offset:2048
	ds_read_b128 v[40:43], v8 offset:4096
	ds_read_b128 v[84:87], v8 offset:6144
	ds_read_b128 v[88:91], v9 offset:16384
	ds_read_b128 v[92:95], v9 offset:18432
	ds_read_b128 v[96:99], v9 offset:20480
	ds_read_b128 v[100:103], v9 offset:22528
	s_waitcnt lgkmcnt(3)
	v_mfma_f32_16x16x32_bf16 v[44:47], v[88:91], v[0:3], v[44:47]
	v_mfma_f32_16x16x32_bf16 v[48:51], v[88:91], v[4:7], v[48:51]
	v_mfma_f32_16x16x32_bf16 v[56:59], v[88:91], v[40:43], v[56:59]
	v_mfma_f32_16x16x32_bf16 v[28:31], v[88:91], v[84:87], v[28:31]
	s_waitcnt lgkmcnt(2)
	v_mfma_f32_16x16x32_bf16 v[60:63], v[92:95], v[0:3], v[60:63]
	v_mfma_f32_16x16x32_bf16 v[64:67], v[92:95], v[4:7], v[64:67]
	v_mfma_f32_16x16x32_bf16 v[68:71], v[92:95], v[40:43], v[68:71]
	v_mfma_f32_16x16x32_bf16 v[32:35], v[92:95], v[84:87], v[32:35]
	s_waitcnt lgkmcnt(1)
	v_mfma_f32_16x16x32_bf16 v[72:75], v[96:99], v[0:3], v[72:75]
	v_mfma_f32_16x16x32_bf16 v[76:79], v[96:99], v[4:7], v[76:79]
	v_mfma_f32_16x16x32_bf16 v[80:83], v[96:99], v[40:43], v[80:83]
	v_mfma_f32_16x16x32_bf16 v[36:39], v[96:99], v[84:87], v[36:39]
	s_waitcnt lgkmcnt(0)
	v_mfma_f32_16x16x32_bf16 v[0:3], v[100:103], v[0:3], v[12:15]
	v_mfma_f32_16x16x32_bf16 v[4:7], v[100:103], v[4:7], v[16:19]
	v_mfma_f32_16x16x32_bf16 v[12:15], v[100:103], v[40:43], v[20:23]
	v_mfma_f32_16x16x32_bf16 v[16:19], v[100:103], v[84:87], v[24:27]
	s_nop 1
	ds_read_b128 v[20:23], v10
	ds_read_b128 v[24:27], v10 offset:2048
	ds_read_b128 v[40:43], v10 offset:4096
	ds_read_b128 v[84:87], v10 offset:6144
	ds_read_b128 v[88:91], v11 offset:16384
	ds_read_b128 v[92:95], v11 offset:18432
	ds_read_b128 v[96:99], v11 offset:20480
	ds_read_b128 v[100:103], v11 offset:22528
	s_waitcnt vmcnt(0)
	s_waitcnt lgkmcnt(0)
	v_mfma_f32_16x16x32_bf16 v[68:71], v[92:95], v[40:43], v[68:71]
	s_barrier
	v_or3_b32 v134, v53, s7, v52
	v_lshl_add_u32 v135, v55, 6, s8
	v_lshl_or_b32 v136, v54, 2, v135
	v_ashrrev_i32_e32 v137, 31, v134
	v_readlane_b32 s8, v252, 35
	v_mov_b32_e32 v230, v134
	v_mov_b32_e32 v231, v137
	v_lshlrev_b64 v[138:139], 12, v[230:231]
	v_readlane_b32 s9, v252, 36
	v_add_u32_e32 v140, s40, v136
	v_ashrrev_i32_e32 v141, 31, v140
	v_lshl_add_u64 v[142:143], s[8:9], 0, v[138:139]
	v_lshl_add_u64 v[144:145], v[140:141], 2, s[58:59]
	global_load_dwordx4 v[146:149], v[144:145], off
	v_lshlrev_b64 v[150:151], 1, v[140:141]
	v_lshl_add_u64 v[152:153], v[142:143], 0, v[150:151]
	global_load_dwordx2 v[154:155], v[152:153], off
	v_or_b32_e32 v156, 16, v134
	v_ashrrev_i32_e32 v157, 31, v156
	v_lshlrev_b64 v[158:159], 12, v[156:157]
	v_lshl_add_u64 v[160:161], s[8:9], 0, v[158:159]
	v_lshl_add_u64 v[162:163], v[160:161], 0, v[150:151]
	global_load_dwordx2 v[164:165], v[162:163], off
	v_or_b32_e32 v166, 32, v134
	v_ashrrev_i32_e32 v167, 31, v166
	v_lshlrev_b64 v[168:169], 12, v[166:167]
	v_lshl_add_u64 v[170:171], s[8:9], 0, v[168:169]
	v_lshl_add_u64 v[172:173], v[170:171], 0, v[150:151]
	global_load_dwordx2 v[174:175], v[172:173], off
	v_or_b32_e32 v176, 48, v134
	v_ashrrev_i32_e32 v177, 31, v176
	v_lshlrev_b64 v[178:179], 12, v[176:177]
	v_lshl_add_u64 v[180:181], s[8:9], 0, v[178:179]
	v_lshl_add_u64 v[186:187], v[180:181], 0, v[150:151]
	global_load_dwordx2 v[188:189], v[186:187], off
	v_or_b32_e32 v190, 16, v140
	v_ashrrev_i32_e32 v191, 31, v190
; DI float bflo(unsigned u) { return __uint_as_float(u << 16); }
; DI float bfhi(unsigned u) { return __uint_as_float(u & 0xffff0000u); }
; DI void st_bf4(u16* p, float a, float b, float c, float d) { *(uint2*)p = make_uint2(pk2(a, b), pk2(c, d)); }
; template <int MT, class Epi>
; DI void gemm_tile(const u16* __restrict__ X, long ldx, const u16* __restrict__ W, long ldw, int K, char* smem,
;                   int m0, int n0, const Epi& epi, bool pre = false, const u16* Xn = nullptr, const u16* Wn = nullptr) {
;     ...
;       for (int nt = 0; nt < 4; ++nt)
; #pragma unroll
;         for (int mt = 0; mt < MT; ++mt)
;           acc[nt][mt] = __builtin_amdgcn_mfma_f32_16x16x32_bf16(wf[nt], xf[mt], acc[nt][mt], 0, 0, 0);
;   template <int NT, int MT> DI void run(f32x4 (&acc)[NT][MT], int mb, int nb) const {
; #pragma unroll
;     for (int nt = 0; nt < NT; ++nt) {
;       const int ch = g * 256 + nb + nt * 16;
;       const float4 sc = *(const float4*)(scale + ch);
; #pragma unroll
;       for (int mt = 0; mt < MT; ++mt) {
;         const int m = mb + mt * 16;
;         u16* q = mix + (size_t)m * 2048 + ch;
;         const uint2 gt = *(const uint2*)q;
;         f32x4 v = acc[nt][mt];
;         st_bf4(q, v[0] * sc.x * bflo(gt.x), v[1] * sc.y * bfhi(gt.x), v[2] * sc.z * bflo(gt.y), v[3] * sc.w * bfhi(gt.y));
;       }
	v_lshlrev_b64 v[192:193], 1, v[190:191]
	v_lshl_add_u64 v[194:195], v[190:191], 2, s[58:59]
	v_lshl_add_u64 v[196:197], v[142:143], 0, v[192:193]
	global_load_dwordx2 v[224:225], v[196:197], off
	global_load_dwordx4 v[226:229], v[194:195], off
	v_mfma_f32_16x16x32_bf16 v[44:47], v[88:91], v[20:23], v[44:47]
	v_mfma_f32_16x16x32_bf16 v[48:51], v[88:91], v[24:27], v[48:51]
	v_mfma_f32_16x16x32_bf16 v[56:59], v[88:91], v[40:43], v[56:59]
	v_mfma_f32_16x16x32_bf16 v[28:31], v[88:91], v[84:87], v[28:31]
	v_mfma_f32_16x16x32_bf16 v[60:63], v[92:95], v[20:23], v[60:63]
	v_mfma_f32_16x16x32_bf16 v[64:67], v[92:95], v[24:27], v[64:67]
	v_mfma_f32_16x16x32_bf16 v[32:35], v[92:95], v[84:87], v[32:35]
	v_mfma_f32_16x16x32_bf16 v[72:75], v[96:99], v[20:23], v[72:75]
	v_mfma_f32_16x16x32_bf16 v[76:79], v[96:99], v[24:27], v[76:79]
	v_mfma_f32_16x16x32_bf16 v[80:83], v[96:99], v[40:43], v[80:83]
	v_mfma_f32_16x16x32_bf16 v[36:39], v[96:99], v[84:87], v[36:39]
	v_mfma_f32_16x16x32_bf16 v[0:3], v[100:103], v[20:23], v[0:3]
	v_mfma_f32_16x16x32_bf16 v[4:7], v[100:103], v[24:27], v[4:7]
	v_mfma_f32_16x16x32_bf16 v[12:15], v[100:103], v[40:43], v[12:15]
	v_mfma_f32_16x16x32_bf16 v[16:19], v[100:103], v[84:87], v[16:19]
	ds_read_b128 v[84:87], v11 offset:55296
	ds_read_b128 v[88:91], v11 offset:53248
	ds_read_b128 v[20:23], v11 offset:51200
	ds_read_b128 v[24:27], v11 offset:49152
	ds_read_b128 v[92:95], v10 offset:38912
	ds_read_b128 v[96:99], v10 offset:36864
	ds_read_b128 v[100:103], v10 offset:34816
	ds_read_b128 v[104:107], v10 offset:32768
	ds_read_b128 v[40:43], v9 offset:55296
	ds_read_b128 v[108:111], v9 offset:53248
	ds_read_b128 v[112:115], v9 offset:51200
	ds_read_b128 v[116:119], v9 offset:49152
	ds_read_b128 v[120:123], v8 offset:38912
	ds_read_b128 v[124:127], v8 offset:36864
	ds_read_b128 v[128:131], v8 offset:34816
	ds_read_b128 v[8:11], v8 offset:32768
	s_waitcnt lgkmcnt(2)
	v_mfma_f32_16x16x32_bf16 v[68:71], v[112:115], v[124:127], v[68:71]
	s_waitcnt lgkmcnt(1)
	v_mfma_f32_16x16x32_bf16 v[64:67], v[112:115], v[128:131], v[64:67]
	v_mfma_f32_16x16x32_bf16 v[48:51], v[116:119], v[128:131], v[48:51]
	v_mfma_f32_16x16x32_bf16 v[28:31], v[116:119], v[120:123], v[28:31]
	s_waitcnt lgkmcnt(0)
	v_mfma_f32_16x16x32_bf16 v[72:75], v[108:111], v[8:11], v[72:75]
	v_mfma_f32_16x16x32_bf16 v[76:79], v[108:111], v[128:131], v[76:79]
	v_mfma_f32_16x16x32_bf16 v[80:83], v[108:111], v[124:127], v[80:83]
	v_mfma_f32_16x16x32_bf16 v[108:111], v[108:111], v[120:123], v[36:39]
	v_mfma_f32_16x16x32_bf16 v[36:39], v[20:23], v[96:99], v[68:71]
	s_nop 2
	s_nop 0
	s_nop 0
	s_nop 0
	v_mfma_f32_16x16x32_bf16 v[44:47], v[116:119], v[8:11], v[44:47]
	s_nop 0
	s_nop 0
	s_nop 0
	v_mfma_f32_16x16x32_bf16 v[56:59], v[116:119], v[124:127], v[56:59]
	s_nop 0
	v_mfma_f32_16x16x32_bf16 v[116:119], v[112:115], v[8:11], v[60:63]
	v_mfma_f32_16x16x32_bf16 v[32:35], v[112:115], v[120:123], v[32:35]
	v_mfma_f32_16x16x32_bf16 v[0:3], v[40:43], v[8:11], v[0:3]
	v_mfma_f32_16x16x32_bf16 v[4:7], v[40:43], v[128:131], v[4:7]
	v_mfma_f32_16x16x32_bf16 v[112:115], v[40:43], v[124:127], v[12:15]
	v_mfma_f32_16x16x32_bf16 v[120:123], v[40:43], v[120:123], v[16:19]
	v_mfma_f32_16x16x32_bf16 v[40:43], v[20:23], v[100:103], v[64:67]
	s_nop 2
	s_nop 0
	s_nop 0
	v_mfma_f32_16x16x32_bf16 v[60:63], v[24:27], v[100:103], v[48:51]
	s_nop 0
	s_nop 0
	s_nop 0
	v_mfma_f32_16x16x32_bf16 v[48:51], v[24:27], v[92:95], v[28:31]
	v_mfma_f32_16x16x32_bf16 v[28:31], v[88:91], v[104:107], v[72:75]
	s_waitcnt vmcnt(6)
	s_nop 1
	v_pk_mul_f32 v[60:61], v[60:61], v[146:147]
	s_nop 0
	s_nop 0
	s_nop 0
	v_mfma_f32_16x16x32_bf16 v[124:127], v[24:27], v[104:107], v[44:47]
	v_mul_f32_e64 v62, v62, v148
	v_mul_f32_e64 v63, v63, v149
	v_pk_mul_f32 v[48:49], v[48:49], v[146:147]
	v_pk_mul_f32 v[50:51], v[50:51], v[148:149]
	v_mfma_f32_16x16x32_bf16 v[56:59], v[24:27], v[96:99], v[56:59]
	v_mfma_f32_16x16x32_bf16 v[24:27], v[88:91], v[100:103], v[76:79]
	s_nop 2
	v_mul_f32_e64 v78, v124, v146
	v_mul_f32_e64 v79, v125, v147
	s_nop 1
	v_pk_mul_f32 v[56:57], v[56:57], v[146:147]
	v_pk_mul_f32 v[58:59], v[58:59], v[148:149]
	v_mfma_f32_16x16x32_bf16 v[44:47], v[20:23], v[104:107], v[116:119]
	s_waitcnt vmcnt(5)
	v_lshlrev_b32_e32 v76, 16, v154
	v_and_b32_e32 v77, 0xffff0000, v154
	v_pk_mul_f32 v[76:77], v[78:79], v[76:77]
	v_lshlrev_b32_e32 v74, 16, v155
	v_and_b32_e32 v75, 0xffff0000, v155
	v_pk_mul_f32 v[78:79], v[126:127], v[148:149]
	v_cvt_pk_bf16_f32 v76, v76, v77
	v_pk_mul_f32 v[74:75], v[78:79], v[74:75]
	v_mfma_f32_16x16x32_bf16 v[32:35], v[20:23], v[92:95], v[32:35]
	v_cvt_pk_bf16_f32 v77, v74, v75
	global_store_dwordx2 v[152:153], v[76:77], off
	s_nop 0
	s_nop 0
	s_nop 0
	s_nop 0
	s_nop 0
	s_nop 0
	v_mfma_f32_16x16x32_bf16 v[20:23], v[88:91], v[96:99], v[80:83]
	s_waitcnt vmcnt(4)
	v_lshlrev_b32_e32 v78, 16, v164
	v_and_b32_e32 v79, 0xffff0000, v164
	v_lshlrev_b32_e32 v76, 16, v165
	v_and_b32_e32 v77, 0xffff0000, v165
	v_pk_mul_f32 v[60:61], v[60:61], v[78:79]
	v_pk_mul_f32 v[62:63], v[62:63], v[76:77]
	v_cvt_pk_bf16_f32 v60, v60, v61
	v_cvt_pk_bf16_f32 v61, v62, v63
	global_store_dwordx2 v[162:163], v[60:61], off
	s_nop 0
	s_nop 0
	s_nop 0
	s_nop 0
	s_nop 0
	s_nop 0
	v_mfma_f32_16x16x32_bf16 v[16:19], v[88:91], v[92:95], v[108:111]
	s_waitcnt vmcnt(3)
	v_lshlrev_b32_e32 v76, 16, v174
	v_and_b32_e32 v77, 0xffff0000, v174
	v_lshlrev_b32_e32 v74, 16, v175
	v_and_b32_e32 v75, 0xffff0000, v175
	v_pk_mul_f32 v[56:57], v[56:57], v[76:77]
	v_pk_mul_f32 v[58:59], v[58:59], v[74:75]
	v_cvt_pk_bf16_f32 v56, v56, v57
	v_cvt_pk_bf16_f32 v57, v58, v59
	global_store_dwordx2 v[172:173], v[56:57], off
	s_nop 0
	s_nop 0
	s_nop 0
	s_nop 0
	s_nop 0
	s_nop 0
	v_mfma_f32_16x16x32_bf16 v[12:15], v[84:87], v[104:107], v[0:3]
	s_waitcnt vmcnt(2)
; DI float bflo(unsigned u) { return __uint_as_float(u << 16); }
; DI float bfhi(unsigned u) { return __uint_as_float(u & 0xffff0000u); }
; DI void st_bf4(u16* p, float a, float b, float c, float d) { *(uint2*)p = make_uint2(pk2(a, b), pk2(c, d)); }
;   template <int NT, int MT> DI void run(f32x4 (&acc)[NT][MT], int mb, int nb) const {
; #pragma unroll
;     for (int nt = 0; nt < NT; ++nt) {
;       const int ch = g * 256 + nb + nt * 16;
;       const float4 sc = *(const float4*)(scale + ch);
; #pragma unroll
;       for (int mt = 0; mt < MT; ++mt) {
;         const int m = mb + mt * 16;
;         u16* q = mix + (size_t)m * 2048 + ch;
;         const uint2 gt = *(const uint2*)q;
;         f32x4 v = acc[nt][mt];
;         st_bf4(q, v[0] * sc.x * bflo(gt.x), v[1] * sc.y * bfhi(gt.x), v[2] * sc.z * bflo(gt.y), v[3] * sc.w * bfhi(gt.y));
;       }
;     }
	v_lshlrev_b32_e32 v70, 16, v188
	v_and_b32_e32 v71, 0xffff0000, v188
	v_lshlrev_b32_e32 v52, 16, v189
	v_and_b32_e32 v53, 0xffff0000, v189
	v_pk_mul_f32 v[48:49], v[48:49], v[70:71]
	v_pk_mul_f32 v[50:51], v[50:51], v[52:53]
	v_cvt_pk_bf16_f32 v48, v48, v49
	v_cvt_pk_bf16_f32 v49, v50, v51
	global_store_dwordx2 v[186:187], v[48:49], off
	s_nop 0
	s_nop 0
	s_nop 0
	s_nop 0
	s_nop 0
	s_nop 0
	v_mfma_f32_16x16x32_bf16 v[8:11], v[84:87], v[100:103], v[4:7]
	s_nop 0
	s_waitcnt vmcnt(1)
	v_lshlrev_b32_e32 v62, 16, v224
	v_and_b32_e32 v63, 0xffff0000, v224
	s_waitcnt vmcnt(0)
	v_pk_mul_f32 v[44:45], v[44:45], v[226:227]
	v_lshlrev_b32_e32 v58, 16, v225
	v_and_b32_e32 v59, 0xffff0000, v225
	v_pk_mul_f32 v[46:47], v[46:47], v[228:229]
	v_pk_mul_f32 v[44:45], v[44:45], v[62:63]
	v_pk_mul_f32 v[46:47], v[46:47], v[58:59]
	v_cvt_pk_bf16_f32 v44, v44, v45
	v_cvt_pk_bf16_f32 v45, v46, v47
	global_store_dwordx2 v[196:197], v[44:45], off
	v_mov_b32_e32 v48, v226
	v_mov_b32_e32 v49, v227
	v_mov_b32_e32 v50, v228
	v_mov_b32_e32 v51, v229
	v_mov_b32_e32 v52, v192
	v_mov_b32_e32 v53, v193
	v_mov_b32_e32 v54, v196
	v_mov_b32_e32 v55, v197
	v_mov_b32_e32 v56, v180
	v_mov_b32_e32 v57, v181
	v_mov_b32_e32 v60, v170
	v_mov_b32_e32 v61, v171
	v_mov_b32_e32 v64, v140
	v_mov_b32_e32 v65, v141
	v_mov_b32_e32 v66, v142
	v_mov_b32_e32 v67, v143
	v_mov_b32_e32 v68, v160
	v_mov_b32_e32 v69, v161
	v_mov_b32_e32 v72, v150
	v_mov_b32_e32 v73, v151
	v_lshl_add_u64 v[134:135], v[68:69], 0, v[52:53]
	global_load_dwordx2 v[136:137], v[134:135], off
	v_lshl_add_u64 v[138:139], v[60:61], 0, v[52:53]
	global_load_dwordx2 v[140:141], v[138:139], off
	v_lshl_add_u64 v[142:143], v[56:57], 0, v[52:53]
	global_load_dwordx2 v[144:145], v[142:143], off
	v_or_b32_e32 v146, 32, v64
	v_ashrrev_i32_e32 v147, 31, v146
	v_lshl_add_u64 v[148:149], v[146:147], 2, s[58:59]
	v_lshlrev_b64 v[150:151], 1, v[146:147]
	v_lshl_add_u64 v[152:153], v[66:67], 0, v[150:151]
	global_load_dwordx4 v[154:157], v[148:149], off
	global_load_dwordx2 v[158:159], v[152:153], off
	v_lshl_add_u64 v[160:161], v[68:69], 0, v[150:151]
	global_load_dwordx2 v[162:163], v[160:161], off
	v_lshl_add_u64 v[164:165], v[60:61], 0, v[150:151]
	global_load_dwordx2 v[166:167], v[164:165], off
	v_lshl_add_u64 v[168:169], v[56:57], 0, v[150:151]
	global_load_dwordx2 v[170:171], v[168:169], off
	v_or_b32_e32 v172, 48, v64
	v_ashrrev_i32_e32 v173, 31, v172
	v_lshl_add_u64 v[174:175], v[172:173], 2, s[58:59]
	v_lshlrev_b64 v[176:177], 1, v[172:173]
	v_lshl_add_u64 v[178:179], v[66:67], 0, v[176:177]
	global_load_dwordx4 v[186:189], v[174:175], off
	global_load_dwordx2 v[180:181], v[178:179], off
	v_lshl_add_u64 v[190:191], v[68:69], 0, v[176:177]
	global_load_dwordx2 v[192:193], v[190:191], off
	v_lshl_add_u64 v[194:195], v[60:61], 0, v[176:177]
	global_load_dwordx2 v[196:197], v[194:195], off
	v_lshl_add_u64 v[224:225], v[56:57], 0, v[176:177]
	global_load_dwordx2 v[226:227], v[224:225], off
	s_nop 0
	s_nop 0
	v_pk_mul_f32 v[40:41], v[40:41], v[48:49]
	v_pk_mul_f32 v[42:43], v[42:43], v[50:51]
	v_pk_mul_f32 v[36:37], v[36:37], v[48:49]
	v_pk_mul_f32 v[38:39], v[38:39], v[50:51]
	v_pk_mul_f32 v[32:33], v[32:33], v[48:49]
	v_pk_mul_f32 v[34:35], v[34:35], v[50:51]
	v_mfma_f32_16x16x32_bf16 v[4:7], v[84:87], v[96:99], v[112:115]
	s_waitcnt vmcnt(12)
	v_lshlrev_b32_e32 v54, 16, v136
	v_and_b32_e32 v55, 0xffff0000, v136
	v_lshlrev_b32_e32 v46, 16, v137
	v_and_b32_e32 v47, 0xffff0000, v137
	v_pk_mul_f32 v[40:41], v[40:41], v[54:55]
	v_pk_mul_f32 v[42:43], v[42:43], v[46:47]
	v_cvt_pk_bf16_f32 v40, v40, v41
	v_cvt_pk_bf16_f32 v41, v42, v43
	global_store_dwordx2 v[134:135], v[40:41], off
	s_nop 0
	s_nop 0
	v_mfma_f32_16x16x32_bf16 v[0:3], v[84:87], v[92:95], v[120:123]
	s_waitcnt vmcnt(11)
	v_lshlrev_b32_e32 v44, 16, v140
	v_and_b32_e32 v45, 0xffff0000, v140
	v_lshlrev_b32_e32 v42, 16, v141
	v_and_b32_e32 v43, 0xffff0000, v141
	v_pk_mul_f32 v[36:37], v[36:37], v[44:45]
	v_pk_mul_f32 v[38:39], v[38:39], v[42:43]
	v_cvt_pk_bf16_f32 v36, v36, v37
	v_cvt_pk_bf16_f32 v37, v38, v39
	global_store_dwordx2 v[138:139], v[36:37], off
	s_nop 0
	s_nop 0
	s_waitcnt vmcnt(10)
; DI float bflo(unsigned u) { return __uint_as_float(u << 16); }
; DI float bfhi(unsigned u) { return __uint_as_float(u & 0xffff0000u); }
; DI void st_bf4(u16* p, float a, float b, float c, float d) { *(uint2*)p = make_uint2(pk2(a, b), pk2(c, d)); }
;   template <int NT, int MT> DI void run(f32x4 (&acc)[NT][MT], int mb, int nb) const {
; #pragma unroll
;     for (int nt = 0; nt < NT; ++nt) {
;       const int ch = g * 256 + nb + nt * 16;
;       const float4 sc = *(const float4*)(scale + ch);
; #pragma unroll
;       for (int mt = 0; mt < MT; ++mt) {
;         const int m = mb + mt * 16;
;         u16* q = mix + (size_t)m * 2048 + ch;
;         const uint2 gt = *(const uint2*)q;
;         f32x4 v = acc[nt][mt];
;         st_bf4(q, v[0] * sc.x * bflo(gt.x), v[1] * sc.y * bfhi(gt.x), v[2] * sc.z * bflo(gt.y), v[3] * sc.w * bfhi(gt.y));
;       }
;     }
	v_lshlrev_b32_e32 v40, 16, v144
	v_and_b32_e32 v41, 0xffff0000, v144
	v_lshlrev_b32_e32 v38, 16, v145
	v_and_b32_e32 v39, 0xffff0000, v145
	v_pk_mul_f32 v[32:33], v[32:33], v[40:41]
	v_pk_mul_f32 v[34:35], v[34:35], v[38:39]
	v_cvt_pk_bf16_f32 v32, v32, v33
	v_cvt_pk_bf16_f32 v33, v34, v35
	global_store_dwordx2 v[142:143], v[32:33], off
	s_nop 0
	s_nop 0
	s_nop 0
	s_nop 0
	s_nop 0
	s_nop 0
	s_waitcnt vmcnt(9)
	v_pk_mul_f32 v[28:29], v[28:29], v[154:155]
	s_nop 0
	v_pk_mul_f32 v[30:31], v[30:31], v[156:157]
	v_pk_mul_f32 v[24:25], v[24:25], v[154:155]
	v_pk_mul_f32 v[26:27], v[26:27], v[156:157]
	v_pk_mul_f32 v[20:21], v[20:21], v[154:155]
	v_pk_mul_f32 v[22:23], v[22:23], v[156:157]
	v_pk_mul_f32 v[16:17], v[16:17], v[154:155]
	v_pk_mul_f32 v[18:19], v[18:19], v[156:157]
	s_waitcnt vmcnt(8)
	v_lshlrev_b32_e32 v42, 16, v158
	v_and_b32_e32 v43, 0xffff0000, v158
	v_lshlrev_b32_e32 v40, 16, v159
	v_and_b32_e32 v41, 0xffff0000, v159
	v_pk_mul_f32 v[28:29], v[28:29], v[42:43]
	v_pk_mul_f32 v[30:31], v[30:31], v[40:41]
	v_cvt_pk_bf16_f32 v28, v28, v29
	v_cvt_pk_bf16_f32 v29, v30, v31
	global_store_dwordx2 v[152:153], v[28:29], off
	s_nop 0
	s_nop 0
	s_waitcnt vmcnt(7)
	v_lshlrev_b32_e32 v38, 16, v162
	v_and_b32_e32 v39, 0xffff0000, v162
	v_lshlrev_b32_e32 v30, 16, v163
	v_and_b32_e32 v31, 0xffff0000, v163
	v_pk_mul_f32 v[24:25], v[24:25], v[38:39]
	v_pk_mul_f32 v[26:27], v[26:27], v[30:31]
	v_cvt_pk_bf16_f32 v24, v24, v25
	v_cvt_pk_bf16_f32 v25, v26, v27
	global_store_dwordx2 v[160:161], v[24:25], off
	s_nop 0
	s_nop 0
	s_waitcnt vmcnt(6)
	v_lshlrev_b32_e32 v28, 16, v166
	v_and_b32_e32 v29, 0xffff0000, v166
	v_lshlrev_b32_e32 v26, 16, v167
	v_and_b32_e32 v27, 0xffff0000, v167
	v_pk_mul_f32 v[20:21], v[20:21], v[28:29]
	v_pk_mul_f32 v[22:23], v[22:23], v[26:27]
	v_cvt_pk_bf16_f32 v20, v20, v21
	v_cvt_pk_bf16_f32 v21, v22, v23
	global_store_dwordx2 v[164:165], v[20:21], off
	s_nop 0
	s_nop 0
	s_waitcnt vmcnt(5)
	v_lshlrev_b32_e32 v24, 16, v170
	v_and_b32_e32 v25, 0xffff0000, v170
	v_lshlrev_b32_e32 v22, 16, v171
	v_and_b32_e32 v23, 0xffff0000, v171
	v_pk_mul_f32 v[16:17], v[16:17], v[24:25]
	v_pk_mul_f32 v[18:19], v[18:19], v[22:23]
	v_cvt_pk_bf16_f32 v16, v16, v17
	v_cvt_pk_bf16_f32 v17, v18, v19
	global_store_dwordx2 v[168:169], v[16:17], off
	s_nop 0
	s_nop 0
	s_nop 0
	s_nop 0
	s_nop 0
	s_nop 0
	s_waitcnt vmcnt(4)
	v_pk_mul_f32 v[12:13], v[12:13], v[186:187]
	s_nop 0
	v_pk_mul_f32 v[14:15], v[14:15], v[188:189]
	v_pk_mul_f32 v[8:9], v[8:9], v[186:187]
	v_pk_mul_f32 v[10:11], v[10:11], v[188:189]
	v_pk_mul_f32 v[4:5], v[4:5], v[186:187]
	v_pk_mul_f32 v[6:7], v[6:7], v[188:189]
	v_pk_mul_f32 v[0:1], v[0:1], v[186:187]
	v_pk_mul_f32 v[2:3], v[2:3], v[188:189]
	s_waitcnt vmcnt(3)
	v_lshlrev_b32_e32 v26, 16, v180
	v_and_b32_e32 v27, 0xffff0000, v180
	v_lshlrev_b32_e32 v24, 16, v181
	v_and_b32_e32 v25, 0xffff0000, v181
	v_pk_mul_f32 v[12:13], v[12:13], v[26:27]
	v_pk_mul_f32 v[14:15], v[14:15], v[24:25]
	v_cvt_pk_bf16_f32 v12, v12, v13
	v_cvt_pk_bf16_f32 v13, v14, v15
	global_store_dwordx2 v[178:179], v[12:13], off
	s_nop 0
	s_nop 0
	s_waitcnt vmcnt(2)
	v_lshlrev_b32_e32 v22, 16, v192
	v_and_b32_e32 v23, 0xffff0000, v192
	v_lshlrev_b32_e32 v14, 16, v193
	v_and_b32_e32 v15, 0xffff0000, v193
	v_pk_mul_f32 v[8:9], v[8:9], v[22:23]
	v_pk_mul_f32 v[10:11], v[10:11], v[14:15]
	v_cvt_pk_bf16_f32 v8, v8, v9
	v_cvt_pk_bf16_f32 v9, v10, v11
	global_store_dwordx2 v[190:191], v[8:9], off
	s_nop 0
	s_nop 0
	s_waitcnt vmcnt(1)
	v_lshlrev_b32_e32 v12, 16, v196
	v_and_b32_e32 v13, 0xffff0000, v196
	v_lshlrev_b32_e32 v10, 16, v197
	v_and_b32_e32 v11, 0xffff0000, v197
	v_pk_mul_f32 v[4:5], v[4:5], v[12:13]
	v_pk_mul_f32 v[6:7], v[6:7], v[10:11]
	v_cvt_pk_bf16_f32 v4, v4, v5
	v_cvt_pk_bf16_f32 v5, v6, v7
	global_store_dwordx2 v[194:195], v[4:5], off
	s_nop 0
	s_nop 0
	s_waitcnt vmcnt(0)
	v_lshlrev_b32_e32 v8, 16, v226
	v_and_b32_e32 v9, 0xffff0000, v226
	v_lshlrev_b32_e32 v6, 16, v227
	v_and_b32_e32 v7, 0xffff0000, v227
	v_pk_mul_f32 v[0:1], v[0:1], v[8:9]
	v_pk_mul_f32 v[2:3], v[2:3], v[6:7]
	v_cvt_pk_bf16_f32 v0, v0, v1
	v_cvt_pk_bf16_f32 v1, v2, v3
	global_store_dwordx2 v[224:225], v[0:1], off
	v_mov_b32_e32 v4, v224
	v_mov_b32_e32 v5, v225
	v_mov_b32_e32 v16, v186
	v_mov_b32_e32 v17, v187
	v_mov_b32_e32 v18, v188
	v_mov_b32_e32 v19, v189
	v_mov_b32_e32 v20, v176
	v_mov_b32_e32 v21, v177
	v_mov_b32_e32 v32, v154
	v_mov_b32_e32 v33, v155
	v_mov_b32_e32 v34, v156
	v_mov_b32_e32 v35, v157
	v_mov_b32_e32 v36, v150
	v_mov_b32_e32 v37, v151
	s_branch .LBB0_1146

; DI float bflo(unsigned u) { return __uint_as_float(u << 16); }
; DI float bfhi(unsigned u) { return __uint_as_float(u & 0xffff0000u); }
; DI float wave_sum(float v) {
; #pragma unroll
;   for (int o = 32; o; o >>= 1) v += __shfl_xor(v, o, 64);
;   return v;
; DI void sgu_ln_items(const Params& p, int e, char* smem) {
;     ...
;     for (int b8 = 0; b8 < 32; b8 += 8) {
;       u32x4 q[8][2];
; #pragma unroll
;       for (int k = 0; k < 8; ++k) {
;         const int i = wave * 32 + b8 + k;
;         const int ic = i < nvalid ? i : 0;
;         const u16* src = uv + (size_t)(rowbase + ic) * 2048 + 1024 + lane * 8;
;         q[k][0] = *(const u32x4*)src;
;         q[k][1] = *(const u32x4*)(src + 512);
;       }
; #pragma unroll
;       for (int k = 0; k < 8; ++k) {
;         const int i = wave * 32 + b8 + k;
;         float s = 0.f, s2 = 0.f;
; #pragma unroll
;         for (int j = 0; j < 2; ++j)
; #pragma unroll
;           for (int w4 = 0; w4 < 4; ++w4) {
;             const float lo = bflo(q[k][j][w4]), hi = bfhi(q[k][j][w4]);
;             s += lo + hi; s2 += lo * lo + hi * hi;
;           }
;         s = wave_sum(s); s2 = wave_sum(s2);
;         const float mu = s * (1.f / 1024.f);
;         const float var = fmaxf(s2 * (1.f / 1024.f) - mu * mu, 0.f);
;         const float rstd = rsqrtf(var + 1e-6f);
;         if (lane == 0) st[i] = i < nvalid ? make_float2(mu, rstd) : make_float2(0.f, 0.f);
;       }
.LBB0_1167:
	s_waitcnt lgkmcnt(0)
	v_add_u32_e32 v2, s7, v89
	v_add_u32_e32 v0, 8, v2
	v_cmp_gt_i32_e64 s[52:53], s6, v0
	v_add_u32_e32 v3, 9, v2
	v_add_u32_e32 v4, 10, v2
	v_cndmask_b32_e64 v0, 0, v0, s[52:53]
	v_add_u32_e32 v0, s5, v0
	v_ashrrev_i32_e32 v1, 31, v0
	v_lshlrev_b64 v[0:1], 12, v[0:1]
	v_lshl_add_u64 v[0:1], v[114:115], 0, v[0:1]
	global_load_dwordx4 v[56:59], v[0:1], off offset:2048
	global_load_dwordx4 v[62:65], v[0:1], off offset:3072
	v_add_u32_e32 v5, 11, v2
	v_add_u32_e32 v6, 12, v2
	v_add_u32_e32 v7, 13, v2
	v_add_u32_e32 v8, 14, v2
	v_add_u32_e32 v2, 15, v2
	v_cmp_gt_i32_e64 s[50:51], s6, v3
	v_cmp_gt_i32_e64 s[48:49], s6, v4
	v_cmp_gt_i32_e64 s[46:47], s6, v5
	v_cmp_gt_i32_e64 s[44:45], s6, v6
	v_cmp_gt_i32_e64 s[42:43], s6, v7
	v_cmp_gt_i32_e64 s[40:41], s6, v8
	v_cndmask_b32_e64 v3, 0, v3, s[50:51]
	v_cndmask_b32_e64 v1, 0, v4, s[48:49]
	v_cndmask_b32_e64 v4, 0, v5, s[46:47]
	v_cndmask_b32_e64 v5, 0, v6, s[44:45]
	v_cndmask_b32_e64 v7, 0, v7, s[42:43]
	v_cndmask_b32_e64 v9, 0, v8, s[40:41]
	v_cmp_gt_i32_e32 vcc, s6, v2
	v_add_u32_e32 v0, s5, v3
	v_add_u32_e32 v4, s5, v4
	v_cndmask_b32_e32 v11, 0, v2, vcc
	v_add_u32_e32 v2, s5, v1
	v_add_u32_e32 v6, s5, v5
	v_add_u32_e32 v8, s5, v7
	v_add_u32_e32 v10, s5, v9
	v_add_u32_e32 v12, s5, v11
	v_ashrrev_i32_e32 v1, 31, v0
	v_ashrrev_i32_e32 v3, 31, v2
	v_ashrrev_i32_e32 v5, 31, v4
	v_ashrrev_i32_e32 v7, 31, v6
	v_ashrrev_i32_e32 v9, 31, v8
	v_ashrrev_i32_e32 v11, 31, v10
	v_ashrrev_i32_e32 v13, 31, v12
	v_lshlrev_b64 v[0:1], 12, v[0:1]
	v_lshlrev_b64 v[2:3], 12, v[2:3]
	v_lshlrev_b64 v[4:5], 12, v[4:5]
	v_lshlrev_b64 v[6:7], 12, v[6:7]
	v_lshlrev_b64 v[8:9], 12, v[8:9]
	v_lshlrev_b64 v[10:11], 12, v[10:11]
	v_lshlrev_b64 v[12:13], 12, v[12:13]
	v_lshl_add_u64 v[0:1], v[114:115], 0, v[0:1]
	v_lshl_add_u64 v[2:3], v[114:115], 0, v[2:3]
	v_lshl_add_u64 v[4:5], v[114:115], 0, v[4:5]
	v_lshl_add_u64 v[6:7], v[114:115], 0, v[6:7]
	v_lshl_add_u64 v[8:9], v[114:115], 0, v[8:9]
	v_lshl_add_u64 v[10:11], v[114:115], 0, v[10:11]
	v_lshl_add_u64 v[66:67], v[114:115], 0, v[12:13]
	global_load_dwordx4 v[52:55], v[0:1], off offset:2048
	global_load_dwordx4 v[48:51], v[0:1], off offset:3072
	global_load_dwordx4 v[44:47], v[2:3], off offset:2048
	global_load_dwordx4 v[40:43], v[2:3], off offset:3072
	global_load_dwordx4 v[36:39], v[4:5], off offset:2048
	global_load_dwordx4 v[32:35], v[4:5], off offset:3072
	global_load_dwordx4 v[28:31], v[6:7], off offset:2048
	global_load_dwordx4 v[24:27], v[6:7], off offset:3072
	global_load_dwordx4 v[20:23], v[8:9], off offset:2048
	global_load_dwordx4 v[16:19], v[8:9], off offset:3072
	global_load_dwordx4 v[12:15], v[10:11], off offset:2048
	s_nop 0
	global_load_dwordx4 v[8:11], v[10:11], off offset:3072
	s_nop 0
	global_load_dwordx4 v[4:7], v[66:67], off offset:2048
	global_load_dwordx4 v[0:3], v[66:67], off offset:3072
	s_waitcnt vmcnt(15)
	v_and_b32_e32 v67, 0xffff0000, v57
	v_lshlrev_b32_e32 v57, 16, v57
	v_and_b32_e32 v61, 0xffff0000, v56
	v_lshlrev_b32_e32 v69, 16, v58
	v_and_b32_e32 v71, 0xffff0000, v58
	v_lshlrev_b32_e32 v56, 16, v56
	v_mov_b32_e32 v58, v57
	v_mul_f32_e32 v72, v56, v56
	v_mov_b32_e32 v73, v57
	v_pk_add_f32 v[74:75], v[56:57], v[60:61] op_sel:[1,0] op_sel_hi:[0,1]
	v_pk_mul_f32 v[56:57], v[56:57], v[58:59] op_sel:[1,0] op_sel_hi:[0,1]
	v_mul_f32_e32 v182, v67, v67
	v_mul_f32_e32 v66, v61, v61
	v_mov_b32_e32 v57, v75
	v_pk_add_f32 v[66:67], v[72:73], v[66:67]
	v_pk_add_f32 v[56:57], v[56:57], v[182:183]
	v_mul_f32_e32 v68, v69, v69
	v_mul_f32_e32 v70, v71, v71
	v_pk_add_f32 v[56:57], v[66:67], v[56:57]
	v_lshlrev_b32_e32 v67, 16, v59
	v_and_b32_e32 v59, 0xffff0000, v59
	v_pk_add_f32 v[68:69], v[68:69], v[70:71]
	v_mul_f32_e32 v66, v67, v67
	v_mul_f32_e32 v58, v59, v59
	v_pk_add_f32 v[56:57], v[68:69], v[56:57]
	v_pk_add_f32 v[58:59], v[66:67], v[58:59]
	s_waitcnt vmcnt(14)
	v_lshlrev_b32_e32 v67, 16, v62
	v_and_b32_e32 v69, 0xffff0000, v62
	v_mul_f32_e32 v66, v67, v67
	v_mul_f32_e32 v68, v69, v69
	v_lshlrev_b32_e32 v71, 16, v63
	v_and_b32_e32 v63, 0xffff0000, v63
	v_mul_f32_e32 v70, v71, v71
	v_mul_f32_e32 v62, v63, v63
	v_lshlrev_b32_e32 v73, 16, v64
	v_and_b32_e32 v75, 0xffff0000, v64
	v_pk_add_f32 v[56:57], v[58:59], v[56:57]
	v_pk_add_f32 v[58:59], v[66:67], v[68:69]
	v_mul_f32_e32 v72, v73, v73
	v_mul_f32_e32 v74, v75, v75
	v_lshlrev_b32_e32 v77, 16, v65
	v_and_b32_e32 v65, 0xffff0000, v65
	v_pk_add_f32 v[56:57], v[58:59], v[56:57]
	v_pk_add_f32 v[58:59], v[70:71], v[62:63]
	v_mul_f32_e32 v76, v77, v77
	v_mul_f32_e32 v64, v65, v65
	v_pk_add_f32 v[56:57], v[58:59], v[56:57]
	v_pk_add_f32 v[58:59], v[72:73], v[74:75]
	s_nop 0
	v_pk_add_f32 v[56:57], v[58:59], v[56:57]
	v_pk_add_f32 v[58:59], v[76:77], v[64:65]
	s_nop 0
	v_pk_add_f32 v[56:57], v[58:59], v[56:57]
	v_mov_b32_e32 v59, v57
	v_mov_b32_e32 v58, v56
	s_nop 1
	v_permlane32_swap_b32_e32 v57, v59
	v_permlane32_swap_b32_e32 v56, v58
	s_waitcnt lgkmcnt(0)
	v_pk_add_f32 v[56:57], v[56:57], v[58:59]
	v_mov_b32_e32 v59, v57
	v_mov_b32_e32 v58, v56
	s_nop 1
	v_permlane16_swap_b32_e32 v57, v59
	v_permlane16_swap_b32_e32 v56, v58
	s_waitcnt lgkmcnt(0)
	v_pk_add_f32 v[56:57], v[56:57], v[58:59]
	s_nop 1
	v_mov_b32_dpp v59, v57 row_ror:8 row_mask:0xf bank_mask:0xf
	v_mov_b32_dpp v58, v56 row_ror:8 row_mask:0xf bank_mask:0xf
	s_waitcnt lgkmcnt(0)
	v_pk_add_f32 v[56:57], v[56:57], v[58:59]
	s_nop 1
	v_mov_b32_dpp v59, v57 row_ror:4 row_mask:0xf bank_mask:0xf
	v_mov_b32_dpp v58, v56 row_ror:4 row_mask:0xf bank_mask:0xf
	s_waitcnt lgkmcnt(0)
	v_pk_add_f32 v[56:57], v[56:57], v[58:59]
	s_nop 1
	v_mov_b32_dpp v59, v57 quad_perm:[2,3,0,1] row_mask:0xf bank_mask:0xf
	v_mov_b32_dpp v58, v56 quad_perm:[2,3,0,1] row_mask:0xf bank_mask:0xf
	s_waitcnt lgkmcnt(0)
	v_pk_add_f32 v[56:57], v[56:57], v[58:59]
	ds_bpermute_b32 v59, v123, v57
	ds_bpermute_b32 v58, v123, v56
	s_and_saveexec_b64 s[62:63], s[38:39]
	s_cbranch_execz .LBB0_1169
	s_waitcnt lgkmcnt(0)
	v_pk_add_f32 v[56:57], v[56:57], v[58:59]
	s_nop 0
	v_pk_mul_f32 v[56:57], v[56:57], s[36:37] op_sel_hi:[1,0]
	s_nop 0
	v_fma_f32 v56, -v57, v57, v56
	v_max_f32_e32 v56, 0, v56
	v_add_f32_e32 v56, 0x358637bd, v56
	v_mul_f32_e32 v58, 0x4b800000, v56
	v_cmp_gt_f32_e64 s[56:57], s33, v56
	s_nop 1
	v_cndmask_b32_e64 v56, v56, v58, s[56:57]
	v_rsq_f32_e32 v56, v56
	s_nop 0
	v_mul_f32_e32 v58, 0x45800000, v56
	v_cndmask_b32_e64 v56, v56, v58, s[56:57]
	v_cndmask_b32_e64 v59, 0, v56, s[52:53]
	v_cndmask_b32_e64 v58, 0, v57, s[52:53]
	ds_write_b64 v60, v[58:59]
; DI float bflo(unsigned u) { return __uint_as_float(u << 16); }
; DI float bfhi(unsigned u) { return __uint_as_float(u & 0xffff0000u); }
; DI float wave_sum(float v) {
; #pragma unroll
;   for (int o = 32; o; o >>= 1) v += __shfl_xor(v, o, 64);
;   return v;
; DI void sgu_ln_items(const Params& p, int e, char* smem) {
;     ...
;     for (int b8 = 0; b8 < 32; b8 += 8) {
;       u32x4 q[8][2];
; #pragma unroll
;       for (int k = 0; k < 8; ++k) {
;         const int i = wave * 32 + b8 + k;
;         const int ic = i < nvalid ? i : 0;
;         const u16* src = uv + (size_t)(rowbase + ic) * 2048 + 1024 + lane * 8;
;         q[k][0] = *(const u32x4*)src;
;         q[k][1] = *(const u32x4*)(src + 512);
;       }
; #pragma unroll
;       for (int k = 0; k < 8; ++k) {
;         const int i = wave * 32 + b8 + k;
;         float s = 0.f, s2 = 0.f;
; #pragma unroll
;         for (int j = 0; j < 2; ++j)
; #pragma unroll
;           for (int w4 = 0; w4 < 4; ++w4) {
;             const float lo = bflo(q[k][j][w4]), hi = bfhi(q[k][j][w4]);
;             s += lo + hi; s2 += lo * lo + hi * hi;
;           }
;         s = wave_sum(s); s2 = wave_sum(s2);
;         const float mu = s * (1.f / 1024.f);
;         const float var = fmaxf(s2 * (1.f / 1024.f) - mu * mu, 0.f);
;         const float rstd = rsqrtf(var + 1e-6f);
;         if (lane == 0) st[i] = i < nvalid ? make_float2(mu, rstd) : make_float2(0.f, 0.f);
;       }
.LBB0_1169:
	s_or_b64 exec, exec, s[62:63]
	s_waitcnt vmcnt(13)
	v_and_b32_e32 v57, 0xffff0000, v52
	s_waitcnt lgkmcnt(1)
	v_and_b32_e32 v59, 0xffff0000, v53
	v_lshlrev_b32_e32 v53, 16, v53
	v_lshlrev_b32_e32 v52, 16, v52
	v_lshlrev_b32_e32 v63, 16, v54
	v_and_b32_e32 v65, 0xffff0000, v54
	v_mul_f32_e32 v66, v52, v52
	v_mov_b32_e32 v54, v53
	v_mov_b32_e32 v67, v53
	s_waitcnt lgkmcnt(0)
	v_mul_f32_e32 v58, v57, v57
	v_mul_f32_e32 v182, v59, v59
	v_pk_add_f32 v[58:59], v[66:67], v[58:59]
	v_pk_mul_f32 v[66:67], v[52:53], v[54:55] op_sel:[1,0] op_sel_hi:[0,1]
	v_pk_add_f32 v[52:53], v[52:53], v[56:57] op_sel:[1,0] op_sel_hi:[0,1]
	v_mov_b32_e32 v67, v53
	v_mul_f32_e32 v62, v63, v63
	v_mul_f32_e32 v64, v65, v65
	v_pk_add_f32 v[52:53], v[66:67], v[182:183]
	v_pk_add_f32 v[56:57], v[62:63], v[64:65]
	v_pk_add_f32 v[52:53], v[58:59], v[52:53]
	s_waitcnt vmcnt(12)
	v_and_b32_e32 v59, 0xffff0000, v48
	v_pk_add_f32 v[52:53], v[56:57], v[52:53]
	v_lshlrev_b32_e32 v57, 16, v55
	v_and_b32_e32 v55, 0xffff0000, v55
	v_mul_f32_e32 v56, v57, v57
	v_mul_f32_e32 v54, v55, v55
	v_pk_add_f32 v[54:55], v[56:57], v[54:55]
	v_lshlrev_b32_e32 v57, 16, v48
	v_mul_f32_e32 v56, v57, v57
	v_mul_f32_e32 v58, v59, v59
	v_lshlrev_b32_e32 v63, 16, v49
	v_and_b32_e32 v49, 0xffff0000, v49
	v_mul_f32_e32 v62, v63, v63
	v_mul_f32_e32 v48, v49, v49
	v_lshlrev_b32_e32 v65, 16, v50
	v_and_b32_e32 v67, 0xffff0000, v50
	v_pk_add_f32 v[52:53], v[54:55], v[52:53]
	v_pk_add_f32 v[54:55], v[56:57], v[58:59]
	v_mul_f32_e32 v64, v65, v65
	v_mul_f32_e32 v66, v67, v67
	v_lshlrev_b32_e32 v69, 16, v51
	v_and_b32_e32 v51, 0xffff0000, v51
	v_pk_add_f32 v[52:53], v[54:55], v[52:53]
	v_pk_add_f32 v[48:49], v[62:63], v[48:49]
	v_mul_f32_e32 v68, v69, v69
	v_mul_f32_e32 v50, v51, v51
	v_pk_add_f32 v[48:49], v[48:49], v[52:53]
	v_pk_add_f32 v[52:53], v[64:65], v[66:67]
	v_pk_add_f32 v[50:51], v[68:69], v[50:51]
	v_pk_add_f32 v[48:49], v[52:53], v[48:49]
	s_nop 0
	v_pk_add_f32 v[48:49], v[50:51], v[48:49]
	v_mov_b32_e32 v51, v49
	v_mov_b32_e32 v50, v48
	s_nop 1
	v_permlane32_swap_b32_e32 v49, v51
	v_permlane32_swap_b32_e32 v48, v50
	s_waitcnt lgkmcnt(0)
	v_pk_add_f32 v[48:49], v[48:49], v[50:51]
	v_mov_b32_e32 v51, v49
	v_mov_b32_e32 v50, v48
	s_nop 1
	v_permlane16_swap_b32_e32 v49, v51
	v_permlane16_swap_b32_e32 v48, v50
	s_waitcnt lgkmcnt(0)
	v_pk_add_f32 v[48:49], v[48:49], v[50:51]
	s_nop 1
	v_mov_b32_dpp v51, v49 row_ror:8 row_mask:0xf bank_mask:0xf
	v_mov_b32_dpp v50, v48 row_ror:8 row_mask:0xf bank_mask:0xf
	s_waitcnt lgkmcnt(0)
	v_pk_add_f32 v[48:49], v[48:49], v[50:51]
	s_nop 1
	v_mov_b32_dpp v51, v49 row_ror:4 row_mask:0xf bank_mask:0xf
	v_mov_b32_dpp v50, v48 row_ror:4 row_mask:0xf bank_mask:0xf
	s_waitcnt lgkmcnt(0)
	v_pk_add_f32 v[48:49], v[48:49], v[50:51]
	s_nop 1
	v_mov_b32_dpp v51, v49 quad_perm:[2,3,0,1] row_mask:0xf bank_mask:0xf
	v_mov_b32_dpp v50, v48 quad_perm:[2,3,0,1] row_mask:0xf bank_mask:0xf
	s_waitcnt lgkmcnt(0)
	v_pk_add_f32 v[48:49], v[48:49], v[50:51]
	ds_bpermute_b32 v51, v123, v49
	ds_bpermute_b32 v50, v123, v48
	s_and_saveexec_b64 s[56:57], s[38:39]
	s_cbranch_execz .LBB0_1171
	s_waitcnt lgkmcnt(0)
	v_pk_add_f32 v[48:49], v[48:49], v[50:51]
	s_nop 0
	v_pk_mul_f32 v[48:49], v[48:49], s[36:37] op_sel_hi:[1,0]
	s_nop 0
	v_fma_f32 v48, -v49, v49, v48
	v_max_f32_e32 v48, 0, v48
	v_add_f32_e32 v48, 0x358637bd, v48
	v_mul_f32_e32 v50, 0x4b800000, v48
	v_cmp_gt_f32_e64 s[52:53], s33, v48
	s_nop 1
	v_cndmask_b32_e64 v48, v48, v50, s[52:53]
	v_rsq_f32_e32 v48, v48
	s_nop 0
	v_mul_f32_e32 v50, 0x45800000, v48
	v_cndmask_b32_e64 v48, v48, v50, s[52:53]
	v_cndmask_b32_e64 v51, 0, v48, s[50:51]
	v_cndmask_b32_e64 v50, 0, v49, s[50:51]
	ds_write_b64 v60, v[50:51] offset:8
.LBB0_1171:
	s_or_b64 exec, exec, s[56:57]
	s_waitcnt vmcnt(11)
	v_and_b32_e32 v49, 0xffff0000, v44
	s_waitcnt lgkmcnt(1)
	v_and_b32_e32 v51, 0xffff0000, v45
	v_lshlrev_b32_e32 v45, 16, v45
	v_lshlrev_b32_e32 v44, 16, v44
	v_lshlrev_b32_e32 v53, 16, v46
	v_and_b32_e32 v55, 0xffff0000, v46
	v_mul_f32_e32 v56, v44, v44
	v_mov_b32_e32 v46, v45
	v_mov_b32_e32 v57, v45
	s_waitcnt lgkmcnt(0)
	v_mul_f32_e32 v50, v49, v49
	v_mul_f32_e32 v182, v51, v51
	v_pk_add_f32 v[50:51], v[56:57], v[50:51]
	v_pk_mul_f32 v[56:57], v[44:45], v[46:47] op_sel:[1,0] op_sel_hi:[0,1]
	v_pk_add_f32 v[44:45], v[44:45], v[48:49] op_sel:[1,0] op_sel_hi:[0,1]
	v_mov_b32_e32 v57, v45
	v_mul_f32_e32 v52, v53, v53
	v_mul_f32_e32 v54, v55, v55
	v_pk_add_f32 v[44:45], v[56:57], v[182:183]
	v_pk_add_f32 v[48:49], v[52:53], v[54:55]
	v_pk_add_f32 v[44:45], v[50:51], v[44:45]
	s_waitcnt vmcnt(10)
	v_and_b32_e32 v51, 0xffff0000, v40
	v_pk_add_f32 v[44:45], v[48:49], v[44:45]
	v_lshlrev_b32_e32 v49, 16, v47
	v_and_b32_e32 v47, 0xffff0000, v47
	v_mul_f32_e32 v48, v49, v49
	v_mul_f32_e32 v46, v47, v47
	v_pk_add_f32 v[46:47], v[48:49], v[46:47]
	v_lshlrev_b32_e32 v49, 16, v40
	v_mul_f32_e32 v48, v49, v49
	v_mul_f32_e32 v50, v51, v51
	v_lshlrev_b32_e32 v53, 16, v41
	v_and_b32_e32 v41, 0xffff0000, v41
	v_mul_f32_e32 v52, v53, v53
	v_mul_f32_e32 v40, v41, v41
	v_lshlrev_b32_e32 v55, 16, v42
	v_and_b32_e32 v57, 0xffff0000, v42
	v_pk_add_f32 v[44:45], v[46:47], v[44:45]
	v_pk_add_f32 v[46:47], v[48:49], v[50:51]
	v_mul_f32_e32 v54, v55, v55
	v_mul_f32_e32 v56, v57, v57
	v_lshlrev_b32_e32 v59, 16, v43
	v_and_b32_e32 v43, 0xffff0000, v43
	v_pk_add_f32 v[44:45], v[46:47], v[44:45]
	v_pk_add_f32 v[40:41], v[52:53], v[40:41]
	v_mul_f32_e32 v58, v59, v59
	v_mul_f32_e32 v42, v43, v43
	v_pk_add_f32 v[40:41], v[40:41], v[44:45]
	v_pk_add_f32 v[44:45], v[54:55], v[56:57]
	v_pk_add_f32 v[42:43], v[58:59], v[42:43]
	v_pk_add_f32 v[40:41], v[44:45], v[40:41]
	s_nop 0
	v_pk_add_f32 v[40:41], v[42:43], v[40:41]
	v_mov_b32_e32 v43, v41
	v_mov_b32_e32 v42, v40
	s_nop 1
	v_permlane32_swap_b32_e32 v41, v43
	v_permlane32_swap_b32_e32 v40, v42
	s_waitcnt lgkmcnt(0)
	v_pk_add_f32 v[40:41], v[40:41], v[42:43]
	v_mov_b32_e32 v43, v41
	v_mov_b32_e32 v42, v40
	s_nop 1
	v_permlane16_swap_b32_e32 v41, v43
	v_permlane16_swap_b32_e32 v40, v42
	s_waitcnt lgkmcnt(0)
	v_pk_add_f32 v[40:41], v[40:41], v[42:43]
	s_nop 1
	v_mov_b32_dpp v43, v41 row_ror:8 row_mask:0xf bank_mask:0xf
	v_mov_b32_dpp v42, v40 row_ror:8 row_mask:0xf bank_mask:0xf
	s_waitcnt lgkmcnt(0)
	v_pk_add_f32 v[40:41], v[40:41], v[42:43]
	s_nop 1
	v_mov_b32_dpp v43, v41 row_ror:4 row_mask:0xf bank_mask:0xf
	v_mov_b32_dpp v42, v40 row_ror:4 row_mask:0xf bank_mask:0xf
	s_waitcnt lgkmcnt(0)
	v_pk_add_f32 v[40:41], v[40:41], v[42:43]
	s_nop 1
	v_mov_b32_dpp v43, v41 quad_perm:[2,3,0,1] row_mask:0xf bank_mask:0xf
	v_mov_b32_dpp v42, v40 quad_perm:[2,3,0,1] row_mask:0xf bank_mask:0xf
	s_waitcnt lgkmcnt(0)
	v_pk_add_f32 v[40:41], v[40:41], v[42:43]
	ds_bpermute_b32 v43, v123, v41
	ds_bpermute_b32 v42, v123, v40
	s_and_saveexec_b64 s[52:53], s[38:39]
	s_cbranch_execz .LBB0_1173
; DI float bflo(unsigned u) { return __uint_as_float(u << 16); }
; DI float bfhi(unsigned u) { return __uint_as_float(u & 0xffff0000u); }
; DI float wave_sum(float v) {
; #pragma unroll
;   for (int o = 32; o; o >>= 1) v += __shfl_xor(v, o, 64);
;   return v;
; DI void sgu_ln_items(const Params& p, int e, char* smem) {
;     ...
;     for (int b8 = 0; b8 < 32; b8 += 8) {
;       u32x4 q[8][2];
; #pragma unroll
;       for (int k = 0; k < 8; ++k) {
;         const int i = wave * 32 + b8 + k;
;         const int ic = i < nvalid ? i : 0;
;         const u16* src = uv + (size_t)(rowbase + ic) * 2048 + 1024 + lane * 8;
;         q[k][0] = *(const u32x4*)src;
;         q[k][1] = *(const u32x4*)(src + 512);
;       }
; #pragma unroll
;       for (int k = 0; k < 8; ++k) {
;         const int i = wave * 32 + b8 + k;
;         float s = 0.f, s2 = 0.f;
; #pragma unroll
;         for (int j = 0; j < 2; ++j)
; #pragma unroll
;           for (int w4 = 0; w4 < 4; ++w4) {
;             const float lo = bflo(q[k][j][w4]), hi = bfhi(q[k][j][w4]);
;             s += lo + hi; s2 += lo * lo + hi * hi;
;           }
;         s = wave_sum(s); s2 = wave_sum(s2);
;         const float mu = s * (1.f / 1024.f);
;         const float var = fmaxf(s2 * (1.f / 1024.f) - mu * mu, 0.f);
;         const float rstd = rsqrtf(var + 1e-6f);
;         if (lane == 0) st[i] = i < nvalid ? make_float2(mu, rstd) : make_float2(0.f, 0.f);
;       }
	s_waitcnt lgkmcnt(0)
	v_pk_add_f32 v[40:41], v[40:41], v[42:43]
	s_nop 0
	v_pk_mul_f32 v[40:41], v[40:41], s[36:37] op_sel_hi:[1,0]
	s_nop 0
	v_fma_f32 v40, -v41, v41, v40
	v_max_f32_e32 v40, 0, v40
	v_add_f32_e32 v40, 0x358637bd, v40
	v_mul_f32_e32 v42, 0x4b800000, v40
	v_cmp_gt_f32_e64 s[50:51], s33, v40
	s_nop 1
	v_cndmask_b32_e64 v40, v40, v42, s[50:51]
	v_rsq_f32_e32 v40, v40
	s_nop 0
	v_mul_f32_e32 v42, 0x45800000, v40
	v_cndmask_b32_e64 v40, v40, v42, s[50:51]
	v_cndmask_b32_e64 v43, 0, v40, s[48:49]
	v_cndmask_b32_e64 v42, 0, v41, s[48:49]
	ds_write_b64 v60, v[42:43] offset:16
.LBB0_1173:
	s_or_b64 exec, exec, s[52:53]
	s_waitcnt vmcnt(9)
	v_and_b32_e32 v41, 0xffff0000, v36
	s_waitcnt lgkmcnt(1)
	v_and_b32_e32 v43, 0xffff0000, v37
	v_lshlrev_b32_e32 v37, 16, v37
	v_lshlrev_b32_e32 v36, 16, v36
	v_lshlrev_b32_e32 v45, 16, v38
	v_and_b32_e32 v47, 0xffff0000, v38
	v_mul_f32_e32 v48, v36, v36
	v_mov_b32_e32 v38, v37
	v_mov_b32_e32 v49, v37
	s_waitcnt lgkmcnt(0)
	v_mul_f32_e32 v42, v41, v41
	v_mul_f32_e32 v182, v43, v43
	v_pk_add_f32 v[42:43], v[48:49], v[42:43]
	v_pk_mul_f32 v[48:49], v[36:37], v[38:39] op_sel:[1,0] op_sel_hi:[0,1]
	v_pk_add_f32 v[36:37], v[36:37], v[40:41] op_sel:[1,0] op_sel_hi:[0,1]
	v_mov_b32_e32 v49, v37
	v_mul_f32_e32 v44, v45, v45
	v_mul_f32_e32 v46, v47, v47
	v_pk_add_f32 v[36:37], v[48:49], v[182:183]
	v_pk_add_f32 v[40:41], v[44:45], v[46:47]
	v_pk_add_f32 v[36:37], v[42:43], v[36:37]
	s_waitcnt vmcnt(8)
	v_and_b32_e32 v43, 0xffff0000, v32
	v_pk_add_f32 v[36:37], v[40:41], v[36:37]
	v_lshlrev_b32_e32 v41, 16, v39
	v_and_b32_e32 v39, 0xffff0000, v39
	v_mul_f32_e32 v40, v41, v41
	v_mul_f32_e32 v38, v39, v39
	v_pk_add_f32 v[38:39], v[40:41], v[38:39]
	v_lshlrev_b32_e32 v41, 16, v32
	v_mul_f32_e32 v40, v41, v41
	v_mul_f32_e32 v42, v43, v43
	v_lshlrev_b32_e32 v45, 16, v33
	v_and_b32_e32 v33, 0xffff0000, v33
	v_mul_f32_e32 v44, v45, v45
	v_mul_f32_e32 v32, v33, v33
	v_lshlrev_b32_e32 v47, 16, v34
	v_and_b32_e32 v49, 0xffff0000, v34
	v_pk_add_f32 v[36:37], v[38:39], v[36:37]
	v_pk_add_f32 v[38:39], v[40:41], v[42:43]
	v_mul_f32_e32 v46, v47, v47
	v_mul_f32_e32 v48, v49, v49
	v_lshlrev_b32_e32 v51, 16, v35
	v_and_b32_e32 v35, 0xffff0000, v35
	v_pk_add_f32 v[36:37], v[38:39], v[36:37]
	v_pk_add_f32 v[32:33], v[44:45], v[32:33]
	v_mul_f32_e32 v50, v51, v51
	v_mul_f32_e32 v34, v35, v35
	v_pk_add_f32 v[32:33], v[32:33], v[36:37]
	v_pk_add_f32 v[36:37], v[46:47], v[48:49]
	v_pk_add_f32 v[34:35], v[50:51], v[34:35]
	v_pk_add_f32 v[32:33], v[36:37], v[32:33]
	s_nop 0
	v_pk_add_f32 v[32:33], v[34:35], v[32:33]
	v_mov_b32_e32 v35, v33
	v_mov_b32_e32 v34, v32
	s_nop 1
	v_permlane32_swap_b32_e32 v33, v35
	v_permlane32_swap_b32_e32 v32, v34
	s_waitcnt lgkmcnt(0)
	v_pk_add_f32 v[32:33], v[32:33], v[34:35]
	v_mov_b32_e32 v35, v33
	v_mov_b32_e32 v34, v32
	s_nop 1
	v_permlane16_swap_b32_e32 v33, v35
	v_permlane16_swap_b32_e32 v32, v34
	s_waitcnt lgkmcnt(0)
	v_pk_add_f32 v[32:33], v[32:33], v[34:35]
	s_nop 1
	v_mov_b32_dpp v35, v33 row_ror:8 row_mask:0xf bank_mask:0xf
	v_mov_b32_dpp v34, v32 row_ror:8 row_mask:0xf bank_mask:0xf
	s_waitcnt lgkmcnt(0)
	v_pk_add_f32 v[32:33], v[32:33], v[34:35]
	s_nop 1
	v_mov_b32_dpp v35, v33 row_ror:4 row_mask:0xf bank_mask:0xf
	v_mov_b32_dpp v34, v32 row_ror:4 row_mask:0xf bank_mask:0xf
	s_waitcnt lgkmcnt(0)
	v_pk_add_f32 v[32:33], v[32:33], v[34:35]
	s_nop 1
	v_mov_b32_dpp v35, v33 quad_perm:[2,3,0,1] row_mask:0xf bank_mask:0xf
	v_mov_b32_dpp v34, v32 quad_perm:[2,3,0,1] row_mask:0xf bank_mask:0xf
	s_waitcnt lgkmcnt(0)
	v_pk_add_f32 v[32:33], v[32:33], v[34:35]
	ds_bpermute_b32 v35, v123, v33
	ds_bpermute_b32 v34, v123, v32
	s_and_saveexec_b64 s[50:51], s[38:39]
	s_cbranch_execz .LBB0_1175
	s_waitcnt lgkmcnt(0)
	v_pk_add_f32 v[32:33], v[32:33], v[34:35]
	s_nop 0
	v_pk_mul_f32 v[32:33], v[32:33], s[36:37] op_sel_hi:[1,0]
	s_nop 0
	v_fma_f32 v32, -v33, v33, v32
	v_max_f32_e32 v32, 0, v32
	v_add_f32_e32 v32, 0x358637bd, v32
	v_mul_f32_e32 v34, 0x4b800000, v32
	v_cmp_gt_f32_e64 s[48:49], s33, v32
	s_nop 1
	v_cndmask_b32_e64 v32, v32, v34, s[48:49]
	v_rsq_f32_e32 v32, v32
	s_nop 0
	v_mul_f32_e32 v34, 0x45800000, v32
	v_cndmask_b32_e64 v32, v32, v34, s[48:49]
	v_cndmask_b32_e64 v35, 0, v32, s[46:47]
	v_cndmask_b32_e64 v34, 0, v33, s[46:47]
	ds_write_b64 v60, v[34:35] offset:24
; DI float bflo(unsigned u) { return __uint_as_float(u << 16); }
; DI float bfhi(unsigned u) { return __uint_as_float(u & 0xffff0000u); }
; DI float wave_sum(float v) {
; #pragma unroll
;   for (int o = 32; o; o >>= 1) v += __shfl_xor(v, o, 64);
;   return v;
; DI void sgu_ln_items(const Params& p, int e, char* smem) {
;     ...
;     for (int b8 = 0; b8 < 32; b8 += 8) {
;       u32x4 q[8][2];
; #pragma unroll
;       for (int k = 0; k < 8; ++k) {
;         const int i = wave * 32 + b8 + k;
;         const int ic = i < nvalid ? i : 0;
;         const u16* src = uv + (size_t)(rowbase + ic) * 2048 + 1024 + lane * 8;
;         q[k][0] = *(const u32x4*)src;
;         q[k][1] = *(const u32x4*)(src + 512);
;       }
; #pragma unroll
;       for (int k = 0; k < 8; ++k) {
;         const int i = wave * 32 + b8 + k;
;         float s = 0.f, s2 = 0.f;
; #pragma unroll
;         for (int j = 0; j < 2; ++j)
; #pragma unroll
;           for (int w4 = 0; w4 < 4; ++w4) {
;             const float lo = bflo(q[k][j][w4]), hi = bfhi(q[k][j][w4]);
;             s += lo + hi; s2 += lo * lo + hi * hi;
;           }
;         s = wave_sum(s); s2 = wave_sum(s2);
;         const float mu = s * (1.f / 1024.f);
;         const float var = fmaxf(s2 * (1.f / 1024.f) - mu * mu, 0.f);
;         const float rstd = rsqrtf(var + 1e-6f);
;         if (lane == 0) st[i] = i < nvalid ? make_float2(mu, rstd) : make_float2(0.f, 0.f);
;       }
.LBB0_1175:
	s_or_b64 exec, exec, s[50:51]
	s_waitcnt vmcnt(7)
	v_and_b32_e32 v33, 0xffff0000, v28
	s_waitcnt lgkmcnt(1)
	v_and_b32_e32 v35, 0xffff0000, v29
	v_lshlrev_b32_e32 v29, 16, v29
	v_lshlrev_b32_e32 v28, 16, v28
	v_lshlrev_b32_e32 v37, 16, v30
	v_and_b32_e32 v39, 0xffff0000, v30
	v_mul_f32_e32 v40, v28, v28
	v_mov_b32_e32 v30, v29
	v_mov_b32_e32 v41, v29
	s_waitcnt lgkmcnt(0)
	v_mul_f32_e32 v34, v33, v33
	v_mul_f32_e32 v182, v35, v35
	v_pk_add_f32 v[34:35], v[40:41], v[34:35]
	v_pk_mul_f32 v[40:41], v[28:29], v[30:31] op_sel:[1,0] op_sel_hi:[0,1]
	v_pk_add_f32 v[28:29], v[28:29], v[32:33] op_sel:[1,0] op_sel_hi:[0,1]
	v_mov_b32_e32 v41, v29
	v_mul_f32_e32 v36, v37, v37
	v_mul_f32_e32 v38, v39, v39
	v_pk_add_f32 v[28:29], v[40:41], v[182:183]
	v_pk_add_f32 v[32:33], v[36:37], v[38:39]
	v_pk_add_f32 v[28:29], v[34:35], v[28:29]
	s_waitcnt vmcnt(6)
	v_and_b32_e32 v35, 0xffff0000, v24
	v_pk_add_f32 v[28:29], v[32:33], v[28:29]
	v_lshlrev_b32_e32 v33, 16, v31
	v_and_b32_e32 v31, 0xffff0000, v31
	v_mul_f32_e32 v32, v33, v33
	v_mul_f32_e32 v30, v31, v31
	v_pk_add_f32 v[30:31], v[32:33], v[30:31]
	v_lshlrev_b32_e32 v33, 16, v24
	v_mul_f32_e32 v32, v33, v33
	v_mul_f32_e32 v34, v35, v35
	v_lshlrev_b32_e32 v37, 16, v25
	v_and_b32_e32 v25, 0xffff0000, v25
	v_mul_f32_e32 v36, v37, v37
	v_mul_f32_e32 v24, v25, v25
	v_lshlrev_b32_e32 v39, 16, v26
	v_and_b32_e32 v41, 0xffff0000, v26
	v_pk_add_f32 v[28:29], v[30:31], v[28:29]
	v_pk_add_f32 v[30:31], v[32:33], v[34:35]
	v_mul_f32_e32 v38, v39, v39
	v_mul_f32_e32 v40, v41, v41
	v_lshlrev_b32_e32 v43, 16, v27
	v_and_b32_e32 v27, 0xffff0000, v27
	v_pk_add_f32 v[28:29], v[30:31], v[28:29]
	v_pk_add_f32 v[24:25], v[36:37], v[24:25]
	v_mul_f32_e32 v42, v43, v43
	v_mul_f32_e32 v26, v27, v27
	v_pk_add_f32 v[24:25], v[24:25], v[28:29]
	v_pk_add_f32 v[28:29], v[38:39], v[40:41]
	v_pk_add_f32 v[26:27], v[42:43], v[26:27]
	v_pk_add_f32 v[24:25], v[28:29], v[24:25]
	s_nop 0
	v_pk_add_f32 v[24:25], v[26:27], v[24:25]
	v_mov_b32_e32 v27, v25
	v_mov_b32_e32 v26, v24
	s_nop 1
	v_permlane32_swap_b32_e32 v25, v27
	v_permlane32_swap_b32_e32 v24, v26
	s_waitcnt lgkmcnt(0)
	v_pk_add_f32 v[24:25], v[24:25], v[26:27]
	v_mov_b32_e32 v27, v25
	v_mov_b32_e32 v26, v24
	s_nop 1
	v_permlane16_swap_b32_e32 v25, v27
	v_permlane16_swap_b32_e32 v24, v26
	s_waitcnt lgkmcnt(0)
	v_pk_add_f32 v[24:25], v[24:25], v[26:27]
	s_nop 1
	v_mov_b32_dpp v27, v25 row_ror:8 row_mask:0xf bank_mask:0xf
	v_mov_b32_dpp v26, v24 row_ror:8 row_mask:0xf bank_mask:0xf
	s_waitcnt lgkmcnt(0)
	v_pk_add_f32 v[24:25], v[24:25], v[26:27]
	s_nop 1
	v_mov_b32_dpp v27, v25 row_ror:4 row_mask:0xf bank_mask:0xf
	v_mov_b32_dpp v26, v24 row_ror:4 row_mask:0xf bank_mask:0xf
	s_waitcnt lgkmcnt(0)
	v_pk_add_f32 v[24:25], v[24:25], v[26:27]
	s_nop 1
	v_mov_b32_dpp v27, v25 quad_perm:[2,3,0,1] row_mask:0xf bank_mask:0xf
	v_mov_b32_dpp v26, v24 quad_perm:[2,3,0,1] row_mask:0xf bank_mask:0xf
	s_waitcnt lgkmcnt(0)
	v_pk_add_f32 v[24:25], v[24:25], v[26:27]
	ds_bpermute_b32 v27, v123, v25
	ds_bpermute_b32 v26, v123, v24
	s_and_saveexec_b64 s[48:49], s[38:39]
	s_cbranch_execz .LBB0_1177
	s_waitcnt lgkmcnt(0)
	v_pk_add_f32 v[24:25], v[24:25], v[26:27]
	s_nop 0
	v_pk_mul_f32 v[24:25], v[24:25], s[36:37] op_sel_hi:[1,0]
	s_nop 0
	v_fma_f32 v24, -v25, v25, v24
	v_max_f32_e32 v24, 0, v24
	v_add_f32_e32 v24, 0x358637bd, v24
	v_mul_f32_e32 v26, 0x4b800000, v24
	v_cmp_gt_f32_e64 s[46:47], s33, v24
	s_nop 1
	v_cndmask_b32_e64 v24, v24, v26, s[46:47]
	v_rsq_f32_e32 v24, v24
	s_nop 0
	v_mul_f32_e32 v26, 0x45800000, v24
	v_cndmask_b32_e64 v24, v24, v26, s[46:47]
	v_cndmask_b32_e64 v27, 0, v24, s[44:45]
	v_cndmask_b32_e64 v26, 0, v25, s[44:45]
	ds_write_b64 v60, v[26:27] offset:32
.LBB0_1177:
	s_or_b64 exec, exec, s[48:49]
	s_waitcnt vmcnt(5)
	v_and_b32_e32 v25, 0xffff0000, v20
	s_waitcnt lgkmcnt(1)
	v_and_b32_e32 v27, 0xffff0000, v21
	v_lshlrev_b32_e32 v21, 16, v21
	v_lshlrev_b32_e32 v20, 16, v20
	v_lshlrev_b32_e32 v29, 16, v22
	v_and_b32_e32 v31, 0xffff0000, v22
	v_mul_f32_e32 v32, v20, v20
	v_mov_b32_e32 v22, v21
	v_mov_b32_e32 v33, v21
	s_waitcnt lgkmcnt(0)
	v_mul_f32_e32 v26, v25, v25
	v_mul_f32_e32 v182, v27, v27
	v_pk_add_f32 v[26:27], v[32:33], v[26:27]
	v_pk_mul_f32 v[32:33], v[20:21], v[22:23] op_sel:[1,0] op_sel_hi:[0,1]
	v_pk_add_f32 v[20:21], v[20:21], v[24:25] op_sel:[1,0] op_sel_hi:[0,1]
	v_mov_b32_e32 v33, v21
	v_mul_f32_e32 v28, v29, v29
	v_mul_f32_e32 v30, v31, v31
	v_pk_add_f32 v[20:21], v[32:33], v[182:183]
	v_pk_add_f32 v[24:25], v[28:29], v[30:31]
	v_pk_add_f32 v[20:21], v[26:27], v[20:21]
	s_waitcnt vmcnt(4)
	v_and_b32_e32 v27, 0xffff0000, v16
	v_pk_add_f32 v[20:21], v[24:25], v[20:21]
	v_lshlrev_b32_e32 v25, 16, v23
	v_and_b32_e32 v23, 0xffff0000, v23
	v_mul_f32_e32 v24, v25, v25
	v_mul_f32_e32 v22, v23, v23
	v_pk_add_f32 v[22:23], v[24:25], v[22:23]
	v_lshlrev_b32_e32 v25, 16, v16
	v_mul_f32_e32 v24, v25, v25
	v_mul_f32_e32 v26, v27, v27
	v_lshlrev_b32_e32 v29, 16, v17
	v_and_b32_e32 v17, 0xffff0000, v17
	v_mul_f32_e32 v28, v29, v29
	v_mul_f32_e32 v16, v17, v17
	v_lshlrev_b32_e32 v31, 16, v18
	v_and_b32_e32 v33, 0xffff0000, v18
	v_pk_add_f32 v[20:21], v[22:23], v[20:21]
	v_pk_add_f32 v[22:23], v[24:25], v[26:27]
	v_mul_f32_e32 v30, v31, v31
	v_mul_f32_e32 v32, v33, v33
	v_lshlrev_b32_e32 v35, 16, v19
	v_and_b32_e32 v19, 0xffff0000, v19
	v_pk_add_f32 v[20:21], v[22:23], v[20:21]
	v_pk_add_f32 v[16:17], v[28:29], v[16:17]
	v_mul_f32_e32 v34, v35, v35
	v_mul_f32_e32 v18, v19, v19
	v_pk_add_f32 v[16:17], v[16:17], v[20:21]
	v_pk_add_f32 v[20:21], v[30:31], v[32:33]
	v_pk_add_f32 v[18:19], v[34:35], v[18:19]
	v_pk_add_f32 v[16:17], v[20:21], v[16:17]
	s_nop 0
	v_pk_add_f32 v[16:17], v[18:19], v[16:17]
	v_mov_b32_e32 v19, v17
	v_mov_b32_e32 v18, v16
	s_nop 1
	v_permlane32_swap_b32_e32 v17, v19
	v_permlane32_swap_b32_e32 v16, v18
	s_waitcnt lgkmcnt(0)
	v_pk_add_f32 v[16:17], v[16:17], v[18:19]
	v_mov_b32_e32 v19, v17
	v_mov_b32_e32 v18, v16
	s_nop 1
	v_permlane16_swap_b32_e32 v17, v19
	v_permlane16_swap_b32_e32 v16, v18
	s_waitcnt lgkmcnt(0)
	v_pk_add_f32 v[16:17], v[16:17], v[18:19]
	s_nop 1
	v_mov_b32_dpp v19, v17 row_ror:8 row_mask:0xf bank_mask:0xf
	v_mov_b32_dpp v18, v16 row_ror:8 row_mask:0xf bank_mask:0xf
	s_waitcnt lgkmcnt(0)
	v_pk_add_f32 v[16:17], v[16:17], v[18:19]
	s_nop 1
	v_mov_b32_dpp v19, v17 row_ror:4 row_mask:0xf bank_mask:0xf
	v_mov_b32_dpp v18, v16 row_ror:4 row_mask:0xf bank_mask:0xf
	s_waitcnt lgkmcnt(0)
	v_pk_add_f32 v[16:17], v[16:17], v[18:19]
	s_nop 1
	v_mov_b32_dpp v19, v17 quad_perm:[2,3,0,1] row_mask:0xf bank_mask:0xf
	v_mov_b32_dpp v18, v16 quad_perm:[2,3,0,1] row_mask:0xf bank_mask:0xf
	s_waitcnt lgkmcnt(0)
	v_pk_add_f32 v[16:17], v[16:17], v[18:19]
	ds_bpermute_b32 v19, v123, v17
	ds_bpermute_b32 v18, v123, v16
	s_and_saveexec_b64 s[46:47], s[38:39]
	s_cbranch_execz .LBB0_1179
; DI float bflo(unsigned u) { return __uint_as_float(u << 16); }
; DI float bfhi(unsigned u) { return __uint_as_float(u & 0xffff0000u); }
; DI float wave_sum(float v) {
; #pragma unroll
;   for (int o = 32; o; o >>= 1) v += __shfl_xor(v, o, 64);
;   return v;
; DI void sgu_ln_items(const Params& p, int e, char* smem) {
;     ...
;     for (int b8 = 0; b8 < 32; b8 += 8) {
;       u32x4 q[8][2];
; #pragma unroll
;       for (int k = 0; k < 8; ++k) {
;         const int i = wave * 32 + b8 + k;
;         const int ic = i < nvalid ? i : 0;
;         const u16* src = uv + (size_t)(rowbase + ic) * 2048 + 1024 + lane * 8;
;         q[k][0] = *(const u32x4*)src;
;         q[k][1] = *(const u32x4*)(src + 512);
;       }
; #pragma unroll
;       for (int k = 0; k < 8; ++k) {
;         const int i = wave * 32 + b8 + k;
;         float s = 0.f, s2 = 0.f;
; #pragma unroll
;         for (int j = 0; j < 2; ++j)
; #pragma unroll
;           for (int w4 = 0; w4 < 4; ++w4) {
;             const float lo = bflo(q[k][j][w4]), hi = bfhi(q[k][j][w4]);
;             s += lo + hi; s2 += lo * lo + hi * hi;
;           }
;         s = wave_sum(s); s2 = wave_sum(s2);
;         const float mu = s * (1.f / 1024.f);
;         const float var = fmaxf(s2 * (1.f / 1024.f) - mu * mu, 0.f);
;         const float rstd = rsqrtf(var + 1e-6f);
;         if (lane == 0) st[i] = i < nvalid ? make_float2(mu, rstd) : make_float2(0.f, 0.f);
;       }
	s_waitcnt lgkmcnt(0)
	v_pk_add_f32 v[16:17], v[16:17], v[18:19]
	s_nop 0
	v_pk_mul_f32 v[16:17], v[16:17], s[36:37] op_sel_hi:[1,0]
	s_nop 0
	v_fma_f32 v16, -v17, v17, v16
	v_max_f32_e32 v16, 0, v16
	v_add_f32_e32 v16, 0x358637bd, v16
	v_mul_f32_e32 v18, 0x4b800000, v16
	v_cmp_gt_f32_e64 s[44:45], s33, v16
	s_nop 1
	v_cndmask_b32_e64 v16, v16, v18, s[44:45]
	v_rsq_f32_e32 v16, v16
	s_nop 0
	v_mul_f32_e32 v18, 0x45800000, v16
	v_cndmask_b32_e64 v16, v16, v18, s[44:45]
	v_cndmask_b32_e64 v19, 0, v16, s[42:43]
	v_cndmask_b32_e64 v18, 0, v17, s[42:43]
	ds_write_b64 v60, v[18:19] offset:40
.LBB0_1179:
	s_or_b64 exec, exec, s[46:47]
	s_waitcnt vmcnt(3)
	v_and_b32_e32 v17, 0xffff0000, v12
	s_waitcnt lgkmcnt(1)
	v_and_b32_e32 v19, 0xffff0000, v13
	v_lshlrev_b32_e32 v13, 16, v13
	v_lshlrev_b32_e32 v12, 16, v12
	v_lshlrev_b32_e32 v21, 16, v14
	v_and_b32_e32 v23, 0xffff0000, v14
	v_mul_f32_e32 v24, v12, v12
	v_mov_b32_e32 v14, v13
	v_mov_b32_e32 v25, v13
	s_waitcnt lgkmcnt(0)
	v_mul_f32_e32 v18, v17, v17
	v_mul_f32_e32 v182, v19, v19
	v_pk_add_f32 v[18:19], v[24:25], v[18:19]
	v_pk_mul_f32 v[24:25], v[12:13], v[14:15] op_sel:[1,0] op_sel_hi:[0,1]
	v_pk_add_f32 v[12:13], v[12:13], v[16:17] op_sel:[1,0] op_sel_hi:[0,1]
	v_mov_b32_e32 v25, v13
	v_mul_f32_e32 v20, v21, v21
	v_mul_f32_e32 v22, v23, v23
	v_pk_add_f32 v[12:13], v[24:25], v[182:183]
	v_pk_add_f32 v[16:17], v[20:21], v[22:23]
	v_pk_add_f32 v[12:13], v[18:19], v[12:13]
	s_waitcnt vmcnt(2)
	v_and_b32_e32 v19, 0xffff0000, v8
	v_pk_add_f32 v[12:13], v[16:17], v[12:13]
	v_lshlrev_b32_e32 v17, 16, v15
	v_and_b32_e32 v15, 0xffff0000, v15
	v_mul_f32_e32 v16, v17, v17
	v_mul_f32_e32 v14, v15, v15
	v_pk_add_f32 v[14:15], v[16:17], v[14:15]
	v_lshlrev_b32_e32 v17, 16, v8
	v_mul_f32_e32 v16, v17, v17
	v_mul_f32_e32 v18, v19, v19
	v_lshlrev_b32_e32 v21, 16, v9
	v_and_b32_e32 v9, 0xffff0000, v9
	v_mul_f32_e32 v20, v21, v21
	v_mul_f32_e32 v8, v9, v9
	v_lshlrev_b32_e32 v23, 16, v10
	v_and_b32_e32 v25, 0xffff0000, v10
	v_pk_add_f32 v[12:13], v[14:15], v[12:13]
	v_pk_add_f32 v[14:15], v[16:17], v[18:19]
	v_mul_f32_e32 v22, v23, v23
	v_mul_f32_e32 v24, v25, v25
	v_lshlrev_b32_e32 v27, 16, v11
	v_and_b32_e32 v11, 0xffff0000, v11
	v_pk_add_f32 v[12:13], v[14:15], v[12:13]
	v_pk_add_f32 v[8:9], v[20:21], v[8:9]
	v_mul_f32_e32 v26, v27, v27
	v_mul_f32_e32 v10, v11, v11
	v_pk_add_f32 v[8:9], v[8:9], v[12:13]
	v_pk_add_f32 v[12:13], v[22:23], v[24:25]
	v_pk_add_f32 v[10:11], v[26:27], v[10:11]
	v_pk_add_f32 v[8:9], v[12:13], v[8:9]
	s_nop 0
	v_pk_add_f32 v[8:9], v[10:11], v[8:9]
	v_mov_b32_e32 v11, v9
	v_mov_b32_e32 v10, v8
	s_nop 1
	v_permlane32_swap_b32_e32 v9, v11
	v_permlane32_swap_b32_e32 v8, v10
	s_waitcnt lgkmcnt(0)
	v_pk_add_f32 v[8:9], v[8:9], v[10:11]
	v_mov_b32_e32 v11, v9
	v_mov_b32_e32 v10, v8
	s_nop 1
	v_permlane16_swap_b32_e32 v9, v11
	v_permlane16_swap_b32_e32 v8, v10
	s_waitcnt lgkmcnt(0)
	v_pk_add_f32 v[8:9], v[8:9], v[10:11]
	s_nop 1
	v_mov_b32_dpp v11, v9 row_ror:8 row_mask:0xf bank_mask:0xf
	v_mov_b32_dpp v10, v8 row_ror:8 row_mask:0xf bank_mask:0xf
	s_waitcnt lgkmcnt(0)
	v_pk_add_f32 v[8:9], v[8:9], v[10:11]
	s_nop 1
	v_mov_b32_dpp v11, v9 row_ror:4 row_mask:0xf bank_mask:0xf
	v_mov_b32_dpp v10, v8 row_ror:4 row_mask:0xf bank_mask:0xf
	s_waitcnt lgkmcnt(0)
	v_pk_add_f32 v[8:9], v[8:9], v[10:11]
	s_nop 1
	v_mov_b32_dpp v11, v9 quad_perm:[2,3,0,1] row_mask:0xf bank_mask:0xf
	v_mov_b32_dpp v10, v8 quad_perm:[2,3,0,1] row_mask:0xf bank_mask:0xf
	s_waitcnt lgkmcnt(0)
	v_pk_add_f32 v[8:9], v[8:9], v[10:11]
	ds_bpermute_b32 v11, v123, v9
	ds_bpermute_b32 v10, v123, v8
	s_and_saveexec_b64 s[44:45], s[38:39]
	s_cbranch_execz .LBB0_1181
	s_waitcnt lgkmcnt(0)
	v_pk_add_f32 v[8:9], v[8:9], v[10:11]
	s_nop 0
	v_pk_mul_f32 v[8:9], v[8:9], s[36:37] op_sel_hi:[1,0]
	s_nop 0
	v_fma_f32 v8, -v9, v9, v8
	v_max_f32_e32 v8, 0, v8
	v_add_f32_e32 v8, 0x358637bd, v8
	v_mul_f32_e32 v10, 0x4b800000, v8
	v_cmp_gt_f32_e64 s[42:43], s33, v8
	s_nop 1
	v_cndmask_b32_e64 v8, v8, v10, s[42:43]
	v_rsq_f32_e32 v8, v8
	s_nop 0
	v_mul_f32_e32 v10, 0x45800000, v8
	v_cndmask_b32_e64 v8, v8, v10, s[42:43]
	v_cndmask_b32_e64 v11, 0, v8, s[40:41]
	v_cndmask_b32_e64 v10, 0, v9, s[40:41]
	ds_write_b64 v60, v[10:11] offset:48
; DI float bflo(unsigned u) { return __uint_as_float(u << 16); }
; DI float bfhi(unsigned u) { return __uint_as_float(u & 0xffff0000u); }
; DI float wave_sum(float v) {
; #pragma unroll
;   for (int o = 32; o; o >>= 1) v += __shfl_xor(v, o, 64);
;   return v;
; DI void sgu_ln_items(const Params& p, int e, char* smem) {
;     ...
;     for (int b8 = 0; b8 < 32; b8 += 8) {
;       u32x4 q[8][2];
; #pragma unroll
;       for (int k = 0; k < 8; ++k) {
;         const int i = wave * 32 + b8 + k;
;         const int ic = i < nvalid ? i : 0;
;         const u16* src = uv + (size_t)(rowbase + ic) * 2048 + 1024 + lane * 8;
;         q[k][0] = *(const u32x4*)src;
;         q[k][1] = *(const u32x4*)(src + 512);
;       }
; #pragma unroll
;       for (int k = 0; k < 8; ++k) {
;         const int i = wave * 32 + b8 + k;
;         float s = 0.f, s2 = 0.f;
; #pragma unroll
;         for (int j = 0; j < 2; ++j)
; #pragma unroll
;           for (int w4 = 0; w4 < 4; ++w4) {
;             const float lo = bflo(q[k][j][w4]), hi = bfhi(q[k][j][w4]);
;             s += lo + hi; s2 += lo * lo + hi * hi;
;           }
;         s = wave_sum(s); s2 = wave_sum(s2);
;         const float mu = s * (1.f / 1024.f);
;         const float var = fmaxf(s2 * (1.f / 1024.f) - mu * mu, 0.f);
;         const float rstd = rsqrtf(var + 1e-6f);
;         if (lane == 0) st[i] = i < nvalid ? make_float2(mu, rstd) : make_float2(0.f, 0.f);
;       }
.LBB0_1181:
	s_or_b64 exec, exec, s[44:45]
	s_waitcnt vmcnt(1)
	v_and_b32_e32 v9, 0xffff0000, v4
	s_waitcnt lgkmcnt(1)
	v_and_b32_e32 v11, 0xffff0000, v5
	v_lshlrev_b32_e32 v5, 16, v5
	v_lshlrev_b32_e32 v4, 16, v4
	v_lshlrev_b32_e32 v13, 16, v6
	v_and_b32_e32 v15, 0xffff0000, v6
	v_mul_f32_e32 v16, v4, v4
	v_mov_b32_e32 v6, v5
	v_mov_b32_e32 v17, v5
	s_waitcnt lgkmcnt(0)
	v_mul_f32_e32 v10, v9, v9
	v_mul_f32_e32 v182, v11, v11
	v_pk_add_f32 v[10:11], v[16:17], v[10:11]
	v_pk_mul_f32 v[16:17], v[4:5], v[6:7] op_sel:[1,0] op_sel_hi:[0,1]
	v_pk_add_f32 v[4:5], v[4:5], v[8:9] op_sel:[1,0] op_sel_hi:[0,1]
	v_mov_b32_e32 v17, v5
	v_mul_f32_e32 v12, v13, v13
	v_mul_f32_e32 v14, v15, v15
	v_pk_add_f32 v[4:5], v[16:17], v[182:183]
	v_pk_add_f32 v[8:9], v[12:13], v[14:15]
	v_pk_add_f32 v[4:5], v[10:11], v[4:5]
	s_waitcnt vmcnt(0)
	v_and_b32_e32 v11, 0xffff0000, v0
	v_pk_add_f32 v[4:5], v[8:9], v[4:5]
	v_lshlrev_b32_e32 v9, 16, v7
	v_and_b32_e32 v7, 0xffff0000, v7
	v_mul_f32_e32 v8, v9, v9
	v_mul_f32_e32 v6, v7, v7
	v_pk_add_f32 v[6:7], v[8:9], v[6:7]
	v_lshlrev_b32_e32 v9, 16, v0
	v_mul_f32_e32 v8, v9, v9
	v_mul_f32_e32 v10, v11, v11
	v_lshlrev_b32_e32 v13, 16, v1
	v_and_b32_e32 v1, 0xffff0000, v1
	v_mul_f32_e32 v12, v13, v13
	v_mul_f32_e32 v0, v1, v1
	v_lshlrev_b32_e32 v15, 16, v2
	v_and_b32_e32 v17, 0xffff0000, v2
	v_pk_add_f32 v[4:5], v[6:7], v[4:5]
	v_pk_add_f32 v[6:7], v[8:9], v[10:11]
	v_mul_f32_e32 v14, v15, v15
	v_mul_f32_e32 v16, v17, v17
	v_lshlrev_b32_e32 v19, 16, v3
	v_and_b32_e32 v3, 0xffff0000, v3
	v_pk_add_f32 v[4:5], v[6:7], v[4:5]
	v_pk_add_f32 v[0:1], v[12:13], v[0:1]
	v_mul_f32_e32 v18, v19, v19
	v_mul_f32_e32 v2, v3, v3
	v_pk_add_f32 v[0:1], v[0:1], v[4:5]
	v_pk_add_f32 v[4:5], v[14:15], v[16:17]
	v_pk_add_f32 v[2:3], v[18:19], v[2:3]
	v_pk_add_f32 v[0:1], v[4:5], v[0:1]
	s_nop 0
	v_pk_add_f32 v[0:1], v[2:3], v[0:1]
	v_mov_b32_e32 v3, v1
	v_mov_b32_e32 v2, v0
	s_nop 1
	v_permlane32_swap_b32_e32 v1, v3
	v_permlane32_swap_b32_e32 v0, v2
	s_waitcnt lgkmcnt(0)
	v_pk_add_f32 v[0:1], v[0:1], v[2:3]
	v_mov_b32_e32 v3, v1
	v_mov_b32_e32 v2, v0
	s_nop 1
	v_permlane16_swap_b32_e32 v1, v3
	v_permlane16_swap_b32_e32 v0, v2
	s_waitcnt lgkmcnt(0)
	v_pk_add_f32 v[0:1], v[0:1], v[2:3]
	s_nop 1
	v_mov_b32_dpp v3, v1 row_ror:8 row_mask:0xf bank_mask:0xf
	v_mov_b32_dpp v2, v0 row_ror:8 row_mask:0xf bank_mask:0xf
	s_waitcnt lgkmcnt(0)
	v_pk_add_f32 v[0:1], v[0:1], v[2:3]
	s_nop 1
	v_mov_b32_dpp v3, v1 row_ror:4 row_mask:0xf bank_mask:0xf
	v_mov_b32_dpp v2, v0 row_ror:4 row_mask:0xf bank_mask:0xf
	s_waitcnt lgkmcnt(0)
	v_pk_add_f32 v[0:1], v[0:1], v[2:3]
	s_nop 1
	v_mov_b32_dpp v3, v1 quad_perm:[2,3,0,1] row_mask:0xf bank_mask:0xf
	v_mov_b32_dpp v2, v0 quad_perm:[2,3,0,1] row_mask:0xf bank_mask:0xf
	s_waitcnt lgkmcnt(0)
	v_pk_add_f32 v[0:1], v[0:1], v[2:3]
	ds_bpermute_b32 v3, v123, v1
	ds_bpermute_b32 v2, v123, v0
	s_and_saveexec_b64 s[42:43], s[38:39]
	s_cbranch_execz .LBB0_1166
	s_waitcnt lgkmcnt(0)
	v_pk_add_f32 v[0:1], v[0:1], v[2:3]
	s_nop 0
	v_pk_mul_f32 v[0:1], v[0:1], s[36:37] op_sel_hi:[1,0]
	s_nop 0
	v_fma_f32 v0, -v1, v1, v0
	v_max_f32_e32 v0, 0, v0
	v_add_f32_e32 v0, 0x358637bd, v0
	v_mul_f32_e32 v2, 0x4b800000, v0
	v_cmp_gt_f32_e64 s[40:41], s33, v0
	s_nop 1
	v_cndmask_b32_e64 v0, v0, v2, s[40:41]
	v_rsq_f32_e32 v0, v0
	s_nop 0
	v_mul_f32_e32 v2, 0x45800000, v0
	v_cndmask_b32_e64 v0, v0, v2, s[40:41]
	v_cndmask_b32_e32 v3, 0, v0, vcc
	v_cndmask_b32_e32 v2, 0, v1, vcc
	ds_write_b64 v60, v[2:3] offset:56
	s_branch .LBB0_1166

; DI int get_tid() { int t = threadIdx.x; asm volatile("" : "+v"(t)); return t; }
; DI int get_bid() { int b = blockIdx.x; asm volatile("" : "+s"(b)); return b; }
; DI float bflo(unsigned u) { return __uint_as_float(u << 16); }
; DI float bfhi(unsigned u) { return __uint_as_float(u & 0xffff0000u); }
; DI float wave_sum(float v) {
; #pragma unroll
;   for (int o = 32; o; o >>= 1) v += __shfl_xor(v, o, 64);
;   return v;
; DI void resid_norm(const Params& p, int layer, const u16* __restrict__ y) {
;     ...
;   for (int r = get_bid() * 4 + (get_tid() >> 6); r < M_TOK; r += gridDim.x * 4) {
;     const float* x;
;     if (layer == 0) x = r < M_PROMPT ? p.x_prompt + (size_t)r * 1024 : p.x_sample + (size_t)(r - M_PROMPT) * 1024;
;     else x = p.out + (size_t)r * 1024;
;     float4 yv[4], xv[4]; float ss = 0.f;
; #pragma unroll
;     for (int i = 0; i < 4; ++i) {
;       { const uint2 yq = *(const uint2*)(y + (size_t)r * 1024 + lane * 4 + 256 * i); yv[i] = make_float4(bflo(yq.x), bfhi(yq.x), bflo(yq.y), bfhi(yq.y)); }
;       { const f32x4 t4 = __builtin_nontemporal_load((const f32x4*)(x + lane * 4 + 256 * i)); xv[i] = make_float4(t4[0], t4[1], t4[2], t4[3]); }
;       ss += yv[i].x * yv[i].x + yv[i].y * yv[i].y + yv[i].z * yv[i].z + yv[i].w * yv[i].w;
;     }
;     ss = wave_sum(ss);
;     const float rs = rsqrtf(ss * (1.f / 1024.f) + 1e-6f);
;     float ss2 = 0.f;
; #pragma unroll
;     for (int i = 0; i < 4; ++i) {
;       const float4 gg = *(const float4*)(gpost + lane * 4 + 256 * i);
;       xv[i].x += yv[i].x * rs * gg.x; xv[i].y += yv[i].y * rs * gg.y; xv[i].z += yv[i].z * rs * gg.z; xv[i].w += yv[i].w * rs * gg.w;
;       __builtin_nontemporal_store((f32x4){xv[i].x, xv[i].y, xv[i].z, xv[i].w}, (f32x4*)(p.out + (size_t)r * 1024 + lane * 4 + 256 * i));
;       ss2 += xv[i].x * xv[i].x + xv[i].y * xv[i].y + xv[i].z * xv[i].z + xv[i].w * xv[i].w;
.LBB0_1267:
	s_or_b64 exec, exec, s[42:43]
	v_lshlrev_b64 v[12:13], 11, v[0:1]
	v_lshl_add_u64 v[24:25], v[2:3], 0, v[12:13]
	global_load_dwordx2 v[32:33], v[24:25], off
	global_load_dwordx2 v[34:35], v[24:25], off offset:512
	global_load_dwordx2 v[36:37], v[24:25], off offset:1024
	global_load_dwordx2 v[38:39], v[24:25], off offset:1536
	v_lshl_add_u64 v[40:41], v[16:17], 0, v[182:183]
	global_load_dwordx4 v[24:27], v[4:5], off
	global_load_dwordx4 v[28:31], v[40:41], off nt
	v_add_u32_e32 v0, s3, v0
	s_waitcnt vmcnt(5)
	v_and_b32_e32 v43, 0xffff0000, v32
	s_waitcnt vmcnt(4)
	v_and_b32_e32 v47, 0xffff0000, v34
	v_lshlrev_b32_e32 v42, 16, v32
	v_lshlrev_b32_e32 v44, 16, v33
	v_and_b32_e32 v45, 0xffff0000, v33
	v_lshlrev_b32_e32 v46, 16, v34
	s_waitcnt vmcnt(3)
	v_and_b32_e32 v51, 0xffff0000, v36
	s_waitcnt vmcnt(2)
	v_and_b32_e32 v55, 0xffff0000, v38
	v_mov_b32_e32 v32, v43
	v_mov_b32_e32 v33, v47
	v_lshlrev_b32_e32 v48, 16, v35
	v_lshlrev_b32_e32 v50, 16, v36
	v_lshlrev_b32_e32 v54, 16, v38
	v_mov_b32_e32 v16, v42
	v_mov_b32_e32 v17, v46
	v_mov_b32_e32 v58, v51
	v_mov_b32_e32 v59, v55
	v_pk_mul_f32 v[32:33], v[32:33], v[32:33]
	v_and_b32_e32 v49, 0xffff0000, v35
	v_lshlrev_b32_e32 v52, 16, v37
	v_lshlrev_b32_e32 v56, 16, v39
	v_and_b32_e32 v57, 0xffff0000, v39
	v_mov_b32_e32 v34, v44
	v_mov_b32_e32 v35, v48
	v_mov_b32_e32 v38, v50
	v_mov_b32_e32 v39, v54
	v_pk_mul_f32 v[58:59], v[58:59], v[58:59]
	v_pk_fma_f32 v[16:17], v[16:17], v[16:17], v[32:33]
	v_and_b32_e32 v53, 0xffff0000, v37
	v_mov_b32_e32 v36, v45
	v_mov_b32_e32 v37, v49
	v_mov_b32_e32 v60, v52
	v_mov_b32_e32 v61, v56
	v_pk_fma_f32 v[32:33], v[38:39], v[38:39], v[58:59]
	v_pk_fma_f32 v[16:17], v[34:35], v[34:35], v[16:17]
	v_mov_b32_e32 v62, v53
	v_mov_b32_e32 v63, v57
	v_pk_fma_f32 v[32:33], v[60:61], v[60:61], v[32:33]
	v_pk_fma_f32 v[16:17], v[36:37], v[36:37], v[16:17]
	v_pk_fma_f32 v[32:33], v[62:63], v[62:63], v[32:33]
	v_add_f32_e32 v1, v16, v17
	v_add_f32_e32 v1, v1, v32
	v_add_f32_e32 v1, v1, v33
	v_mov_b32_e32 v16, v1
	s_nop 1
	v_permlane32_swap_b32_e32 v1, v16
	v_lshl_add_u64 v[58:59], v[10:11], 0, v[14:15]
	s_waitcnt lgkmcnt(0)
	v_add_f32_e32 v1, v1, v16
	v_mov_b32_e32 v16, v1
	s_nop 1
	v_permlane16_swap_b32_e32 v1, v16
	s_waitcnt lgkmcnt(0)
	v_add_f32_e32 v1, v1, v16
	s_nop 1
	v_mov_b32_dpp v16, v1 row_ror:8 row_mask:0xf bank_mask:0xf
	s_waitcnt lgkmcnt(0)
	v_add_f32_e32 v1, v1, v16
	s_nop 1
	v_mov_b32_dpp v16, v1 row_ror:4 row_mask:0xf bank_mask:0xf
	s_waitcnt lgkmcnt(0)
	v_add_f32_e32 v1, v1, v16
	s_nop 1
	v_mov_b32_dpp v16, v1 quad_perm:[2,3,0,1] row_mask:0xf bank_mask:0xf
	s_waitcnt lgkmcnt(0)
	v_add_f32_e32 v1, v1, v16
	s_nop 1
	v_mov_b32_dpp v16, v1 quad_perm:[1,0,3,2] row_mask:0xf bank_mask:0xf
	s_waitcnt lgkmcnt(0)
	v_add_f32_e32 v1, v1, v16
	v_fmamk_f32 v1, v1, 0x3a800000, v184
	v_mul_f32_e32 v14, 0x4b800000, v1
	v_cmp_gt_f32_e32 vcc, s33, v1
	s_nop 1
	v_cndmask_b32_e32 v1, v1, v14, vcc
	v_rsq_f32_e32 v1, v1
	global_load_dwordx4 v[14:17], v[40:41], off offset:1024 nt
	global_load_dwordx4 v[32:35], v[40:41], off offset:2048 nt
	global_load_dwordx4 v[36:39], v[40:41], off offset:3072 nt
	v_mul_f32_e32 v40, 0x45800000, v1
	v_cndmask_b32_e32 v40, v1, v40, vcc
	v_pk_mul_f32 v[42:43], v[40:41], v[42:43] op_sel_hi:[0,1]
	v_pk_mul_f32 v[44:45], v[40:41], v[44:45] op_sel_hi:[0,1]
	s_waitcnt vmcnt(3)
	v_pk_fma_f32 v[24:25], v[24:25], v[42:43], v[28:29]
	v_pk_fma_f32 v[26:27], v[26:27], v[44:45], v[30:31]
	global_store_dwordx4 v[58:59], v[24:27], off nt
	global_load_dwordx4 v[28:31], v[4:5], off offset:1024
	v_pk_mul_f32 v[42:43], v[40:41], v[46:47] op_sel_hi:[0,1]
	v_pk_mul_f32 v[44:45], v[40:41], v[48:49] op_sel_hi:[0,1]
	v_mov_b32_e32 v46, v27
	s_waitcnt vmcnt(0)
	v_pk_fma_f32 v[14:15], v[28:29], v[42:43], v[14:15]
	v_pk_fma_f32 v[16:17], v[30:31], v[44:45], v[16:17]
	global_store_dwordx4 v[58:59], v[14:17], off offset:1024 nt
	global_load_dwordx4 v[28:31], v[4:5], off offset:2048
	v_pk_mul_f32 v[42:43], v[40:41], v[50:51] op_sel_hi:[0,1]
	v_pk_mul_f32 v[44:45], v[40:41], v[52:53] op_sel_hi:[0,1]
	v_mov_b32_e32 v47, v17
	s_waitcnt vmcnt(0)
; DI void st_bf4(u16* p, float a, float b, float c, float d) { *(uint2*)p = make_uint2(pk2(a, b), pk2(c, d)); }
; DI float wave_sum(float v) {
; #pragma unroll
;   for (int o = 32; o; o >>= 1) v += __shfl_xor(v, o, 64);
;   return v;
; DI void resid_norm(const Params& p, int layer, const u16* __restrict__ y) {
;     ...
;       xv[i].x += yv[i].x * rs * gg.x; xv[i].y += yv[i].y * rs * gg.y; xv[i].z += yv[i].z * rs * gg.z; xv[i].w += yv[i].w * rs * gg.w;
;       __builtin_nontemporal_store((f32x4){xv[i].x, xv[i].y, xv[i].z, xv[i].w}, (f32x4*)(p.out + (size_t)r * 1024 + lane * 4 + 256 * i));
;       ss2 += xv[i].x * xv[i].x + xv[i].y * xv[i].y + xv[i].z * xv[i].z + xv[i].w * xv[i].w;
;     }
;     if (layer < 3) {
;       ss2 = wave_sum(ss2);
;       const float rs2 = rsqrtf(ss2 * (1.f / 1024.f) + 1e-6f);
; #pragma unroll
;       for (int i = 0; i < 4; ++i) {
;         const float4 gg = *(const float4*)(gpre + lane * 4 + 256 * i);
;         st_bf4(h + (size_t)r * 1024 + lane * 4 + 256 * i, xv[i].x * rs2 * gg.x, xv[i].y * rs2 * gg.y, xv[i].z * rs2 * gg.z, xv[i].w * rs2 * gg.w);
;       }
;     }
	v_pk_fma_f32 v[28:29], v[28:29], v[42:43], v[32:33]
	v_pk_fma_f32 v[30:31], v[44:45], v[30:31], v[34:35]
	global_store_dwordx4 v[58:59], v[28:31], off offset:2048 nt
	global_load_dwordx4 v[32:35], v[4:5], off offset:3072
	v_pk_mul_f32 v[42:43], v[40:41], v[54:55] op_sel_hi:[0,1]
	v_pk_mul_f32 v[40:41], v[40:41], v[56:57] op_sel_hi:[0,1]
	v_mov_b32_e32 v44, v26
	v_mov_b32_e32 v45, v16
	s_waitcnt vmcnt(0)
	v_pk_fma_f32 v[32:33], v[42:43], v[32:33], v[36:37]
	v_pk_fma_f32 v[34:35], v[40:41], v[34:35], v[38:39]
	global_store_dwordx4 v[58:59], v[32:35], off offset:3072 nt
	global_load_dwordx4 v[36:39], v[6:7], off
	v_mov_b32_e32 v42, v25
	v_mov_b32_e32 v43, v15
	v_mov_b32_e32 v40, v24
	v_mov_b32_e32 v41, v14
	v_pk_mul_f32 v[42:43], v[42:43], v[42:43]
	s_nop 0
	v_pk_fma_f32 v[40:41], v[40:41], v[40:41], v[42:43]
	v_mov_b32_e32 v42, v29
	v_pk_fma_f32 v[40:41], v[44:45], v[44:45], v[40:41]
	v_mov_b32_e32 v43, v33
	v_pk_fma_f32 v[40:41], v[46:47], v[46:47], v[40:41]
	v_pk_mul_f32 v[42:43], v[42:43], v[42:43]
	v_add_f32_e32 v1, v40, v41
	v_mov_b32_e32 v40, v28
	v_mov_b32_e32 v41, v32
	v_mov_b32_e32 v44, v30
	v_mov_b32_e32 v45, v34
	v_pk_fma_f32 v[40:41], v[40:41], v[40:41], v[42:43]
	v_mov_b32_e32 v46, v31
	v_mov_b32_e32 v47, v35
	v_pk_fma_f32 v[40:41], v[44:45], v[44:45], v[40:41]
	s_nop 0
	v_pk_fma_f32 v[40:41], v[46:47], v[46:47], v[40:41]
	s_nop 0
	v_add_f32_e32 v1, v40, v1
	v_add_f32_e32 v1, v1, v41
	v_mov_b32_e32 v40, v1
	s_nop 1
	v_permlane32_swap_b32_e32 v1, v40
	s_waitcnt lgkmcnt(0)
	v_add_f32_e32 v1, v1, v40
	v_mov_b32_e32 v40, v1
	s_nop 1
	v_permlane16_swap_b32_e32 v1, v40
	s_waitcnt lgkmcnt(0)
	v_add_f32_e32 v1, v1, v40
	s_nop 1
	v_mov_b32_dpp v40, v1 row_ror:8 row_mask:0xf bank_mask:0xf
	s_waitcnt lgkmcnt(0)
	v_add_f32_e32 v1, v1, v40
	s_nop 1
	v_mov_b32_dpp v40, v1 row_ror:4 row_mask:0xf bank_mask:0xf
	s_waitcnt lgkmcnt(0)
	v_add_f32_e32 v1, v1, v40
	s_nop 1
	v_mov_b32_dpp v40, v1 quad_perm:[2,3,0,1] row_mask:0xf bank_mask:0xf
	s_waitcnt lgkmcnt(0)
	v_add_f32_e32 v1, v1, v40
	s_nop 1
	v_mov_b32_dpp v40, v1 quad_perm:[1,0,3,2] row_mask:0xf bank_mask:0xf
	s_waitcnt lgkmcnt(0)
	v_add_f32_e32 v1, v1, v40
	v_fmamk_f32 v1, v1, 0x3a800000, v184
	v_mul_f32_e32 v40, 0x4b800000, v1
	v_cmp_gt_f32_e32 vcc, s33, v1
	s_nop 1
	v_cndmask_b32_e32 v1, v1, v40, vcc
	v_rsq_f32_e32 v1, v1
	v_lshl_add_u64 v[40:41], v[8:9], 0, v[12:13]
	v_mul_f32_e32 v12, 0x45800000, v1
	v_cndmask_b32_e32 v42, v1, v12, vcc
	v_pk_mul_f32 v[12:13], v[24:25], v[42:43] op_sel_hi:[1,0]
	v_pk_mul_f32 v[24:25], v[26:27], v[42:43] op_sel_hi:[1,0]
	v_cmp_lt_i32_e32 vcc, s64, v0
	s_or_b64 s[40:41], vcc, s[40:41]
	s_waitcnt vmcnt(0)
	v_pk_mul_f32 v[12:13], v[36:37], v[12:13]
	v_pk_mul_f32 v[24:25], v[38:39], v[24:25]
	v_cvt_pk_bf16_f32 v12, v12, v13
	v_cvt_pk_bf16_f32 v13, v24, v25
	global_store_dwordx2 v[40:41], v[12:13], off
	global_load_dwordx4 v[24:27], v[6:7], off offset:1024
	v_pk_mul_f32 v[12:13], v[14:15], v[42:43] op_sel_hi:[1,0]
	v_pk_mul_f32 v[14:15], v[16:17], v[42:43] op_sel_hi:[1,0]
	v_pk_mul_f32 v[16:17], v[28:29], v[42:43] op_sel_hi:[1,0]
	s_waitcnt vmcnt(0)
	v_pk_mul_f32 v[12:13], v[24:25], v[12:13]
	v_pk_mul_f32 v[14:15], v[26:27], v[14:15]
	v_cvt_pk_bf16_f32 v12, v12, v13
	v_cvt_pk_bf16_f32 v13, v14, v15
	global_store_dwordx2 v[40:41], v[12:13], off offset:512
	global_load_dwordx4 v[12:15], v[6:7], off offset:2048
	v_pk_mul_f32 v[24:25], v[30:31], v[42:43] op_sel_hi:[1,0]
	s_waitcnt vmcnt(0)
	v_pk_mul_f32 v[12:13], v[16:17], v[12:13]
	v_pk_mul_f32 v[14:15], v[24:25], v[14:15]
	v_cvt_pk_bf16_f32 v12, v12, v13
	v_cvt_pk_bf16_f32 v13, v14, v15
	global_store_dwordx2 v[40:41], v[12:13], off offset:1024
	global_load_dwordx4 v[12:15], v[6:7], off offset:3072
	v_pk_mul_f32 v[16:17], v[32:33], v[42:43] op_sel_hi:[1,0]
	v_pk_mul_f32 v[24:25], v[34:35], v[42:43] op_sel_hi:[1,0]
	s_waitcnt vmcnt(0)
	v_pk_mul_f32 v[12:13], v[16:17], v[12:13]
	v_pk_mul_f32 v[14:15], v[24:25], v[14:15]
	v_cvt_pk_bf16_f32 v12, v12, v13
	v_cvt_pk_bf16_f32 v13, v14, v15
	global_store_dwordx2 v[40:41], v[12:13], off offset:1536
	s_andn2_b64 exec, exec, s[40:41]
	s_cbranch_execz .LBB0_1272

; DI int get_tid() { int t = threadIdx.x; asm volatile("" : "+v"(t)); return t; }
; DI int get_bid() { int b = blockIdx.x; asm volatile("" : "+s"(b)); return b; }
; DI void st_bf4(u16* p, float a, float b, float c, float d) { *(uint2*)p = make_uint2(pk2(a, b), pk2(c, d)); }
; DI float wave_sum(float v) {
; #pragma unroll
;   for (int o = 32; o; o >>= 1) v += __shfl_xor(v, o, 64);
;   return v;
; DI void prenorm0(const Params& p) {
;     ...
;   for (int r = get_bid() * 4 + (get_tid() >> 6); r < M_TOK; r += gridDim.x * 4) {
;     const float* x = r < M_PROMPT ? p.x_prompt + (size_t)r * 1024 : p.x_sample + (size_t)(r - M_PROMPT) * 1024;
;     float4 v[4]; float ss = 0.f;
; #pragma unroll
;     for (int i = 0; i < 4; ++i) { v[i] = *(const float4*)(x + lane * 4 + 256 * i); ss += v[i].x * v[i].x + v[i].y * v[i].y + v[i].z * v[i].z + v[i].w * v[i].w; }
;     ss = wave_sum(ss);
;     const float rs = rsqrtf(ss * (1.f / 1024.f) + 1e-6f);
; #pragma unroll
;     for (int i = 0; i < 4; ++i) {
;       const float4 gg = *(const float4*)(p.norm_pre + lane * 4 + 256 * i);
;       st_bf4(h + (size_t)r * 1024 + lane * 4 + 256 * i, v[i].x * rs * gg.x, v[i].y * rs * gg.y, v[i].z * rs * gg.z, v[i].w * rs * gg.w);
;     }
;   }
.LBB0_1781:
	s_or_b64 exec, exec, s[42:43]
	v_lshl_add_u64 v[6:7], v[6:7], 0, v[182:183]
	v_lshlrev_b64 v[14:15], 11, v[0:1]
	v_lshl_add_u64 v[34:35], v[2:3], 0, v[14:15]
	global_load_dwordx4 v[14:17], v[6:7], off
	global_load_dwordx4 v[18:21], v[4:5], off
	global_load_dwordx4 v[22:25], v[6:7], off offset:1024
	v_add_u32_e32 v0, s3, v0
	s_waitcnt vmcnt(2)
	v_mov_b32_e32 v32, v15
	v_mov_b32_e32 v30, v14
	s_waitcnt vmcnt(0)
	v_mov_b32_e32 v33, v23
	v_mov_b32_e32 v31, v22
	v_pk_mul_f32 v[32:33], v[32:33], v[32:33]
	v_mov_b32_e32 v26, v16
	v_mov_b32_e32 v27, v24
	v_pk_fma_f32 v[30:31], v[30:31], v[30:31], v[32:33]
	v_mov_b32_e32 v28, v17
	v_mov_b32_e32 v29, v25
	v_pk_fma_f32 v[26:27], v[26:27], v[26:27], v[30:31]
	s_nop 0
	v_pk_fma_f32 v[36:37], v[28:29], v[28:29], v[26:27]
	global_load_dwordx4 v[26:29], v[6:7], off offset:2048
	global_load_dwordx4 v[30:33], v[6:7], off offset:3072
	v_add_f32_e32 v1, v36, v37
	s_waitcnt vmcnt(1)
	v_mov_b32_e32 v42, v27
	s_waitcnt vmcnt(0)
	v_mov_b32_e32 v43, v31
	v_mov_b32_e32 v40, v26
	v_mov_b32_e32 v41, v30
	v_pk_mul_f32 v[42:43], v[42:43], v[42:43]
	v_mov_b32_e32 v6, v28
	v_mov_b32_e32 v7, v32
	v_pk_fma_f32 v[40:41], v[40:41], v[40:41], v[42:43]
	v_mov_b32_e32 v38, v29
	v_mov_b32_e32 v39, v33
	v_pk_fma_f32 v[6:7], v[6:7], v[6:7], v[40:41]
	s_nop 0
	v_pk_fma_f32 v[6:7], v[38:39], v[38:39], v[6:7]
	s_nop 0
	v_add_f32_e32 v1, v1, v6
	v_add_f32_e32 v1, v1, v7
	v_mov_b32_e32 v6, v1
	s_nop 1
	v_permlane32_swap_b32_e32 v1, v6
	s_waitcnt lgkmcnt(0)
	v_add_f32_e32 v1, v1, v6
	v_mov_b32_e32 v6, v1
	s_nop 1
	v_permlane16_swap_b32_e32 v1, v6
	s_waitcnt lgkmcnt(0)
	v_add_f32_e32 v1, v1, v6
	s_nop 1
	v_mov_b32_dpp v6, v1 row_ror:8 row_mask:0xf bank_mask:0xf
	s_waitcnt lgkmcnt(0)
	v_add_f32_e32 v1, v1, v6
	s_nop 1
	v_mov_b32_dpp v6, v1 row_ror:4 row_mask:0xf bank_mask:0xf
	s_waitcnt lgkmcnt(0)
	v_add_f32_e32 v1, v1, v6
	s_nop 1
	v_mov_b32_dpp v6, v1 quad_perm:[2,3,0,1] row_mask:0xf bank_mask:0xf
	s_waitcnt lgkmcnt(0)
	v_add_f32_e32 v1, v1, v6
	s_nop 1
	v_mov_b32_dpp v6, v1 quad_perm:[1,0,3,2] row_mask:0xf bank_mask:0xf
	s_waitcnt lgkmcnt(0)
	v_add_f32_e32 v1, v1, v6
	v_fmamk_f32 v1, v1, 0x3a800000, v184
	v_cmp_gt_f32_e32 vcc, s33, v1
	v_mul_f32_e32 v6, 0x4b800000, v1
	s_nop 0
	v_cndmask_b32_e32 v1, v1, v6, vcc
	v_rsq_f32_e32 v1, v1
	s_nop 0
	v_mul_f32_e32 v6, 0x45800000, v1
	v_cndmask_b32_e32 v6, v1, v6, vcc
	v_pk_mul_f32 v[14:15], v[14:15], v[6:7] op_sel_hi:[1,0]
	v_pk_mul_f32 v[16:17], v[16:17], v[6:7] op_sel_hi:[1,0]
	v_pk_mul_f32 v[14:15], v[18:19], v[14:15]
	v_pk_mul_f32 v[16:17], v[20:21], v[16:17]
	v_cvt_pk_bf16_f32 v14, v14, v15
	v_cvt_pk_bf16_f32 v15, v16, v17
	global_store_dwordx2 v[34:35], v[14:15], off
	global_load_dwordx4 v[14:17], v[4:5], off offset:1024
	v_pk_mul_f32 v[18:19], v[22:23], v[6:7] op_sel_hi:[1,0]
	v_cmp_lt_i32_e32 vcc, s64, v0
	s_or_b64 s[40:41], vcc, s[40:41]
	s_waitcnt vmcnt(0)
	v_pk_mul_f32 v[14:15], v[14:15], v[18:19]
	v_pk_mul_f32 v[18:19], v[24:25], v[6:7] op_sel_hi:[1,0]
	v_cvt_pk_bf16_f32 v14, v14, v15
	v_pk_mul_f32 v[16:17], v[16:17], v[18:19]
	v_pk_mul_f32 v[18:19], v[26:27], v[6:7] op_sel_hi:[1,0]
	v_cvt_pk_bf16_f32 v15, v16, v17
	global_store_dwordx2 v[34:35], v[14:15], off offset:512
	global_load_dwordx4 v[14:17], v[4:5], off offset:2048
	s_waitcnt vmcnt(0)
	v_pk_mul_f32 v[14:15], v[18:19], v[14:15]
	v_pk_mul_f32 v[18:19], v[28:29], v[6:7] op_sel_hi:[1,0]
	v_cvt_pk_bf16_f32 v14, v14, v15
	v_pk_mul_f32 v[16:17], v[18:19], v[16:17]
	v_pk_mul_f32 v[18:19], v[30:31], v[6:7] op_sel_hi:[1,0]
	v_cvt_pk_bf16_f32 v15, v16, v17
	global_store_dwordx2 v[34:35], v[14:15], off offset:1024
	global_load_dwordx4 v[14:17], v[4:5], off offset:3072
	v_pk_mul_f32 v[6:7], v[32:33], v[6:7] op_sel_hi:[1,0]
	s_waitcnt vmcnt(0)
	v_pk_mul_f32 v[14:15], v[18:19], v[14:15]
	v_pk_mul_f32 v[6:7], v[6:7], v[16:17]
	v_cvt_pk_bf16_f32 v14, v14, v15
	v_cvt_pk_bf16_f32 v15, v6, v7
	global_store_dwordx2 v[34:35], v[14:15], off offset:1536
	s_andn2_b64 exec, exec, s[40:41]
	s_cbranch_execz .LBB0_1786
